# in-proj epilogues: row scales read with 8 ds_read_b128 up front and rope cos/sin fetched in one burst; GEMM tile prologues no longer drain the previous tile's stores
# speedup vs baseline: 1.0769x; 1.0180x over previous
.LBB0_285:
	v_mov_b32_e32 v134, v210
	s_mul_hi_i32 s1, s0, 0x38e38e39
	v_bfe_i32 v2, v134, 27, 1
	v_lshlrev_b32_e32 v137, 4, v134
	v_lshrrev_b32_e32 v2, 22, v2
	v_add_u32_e32 v2, v137, v2
	v_and_b32_e32 v2, 0xfffffc00, v2
	v_sub_u32_e32 v2, v137, v2
	v_lshrrev_b32_e32 v3, 4, v2
	v_bitop3_b32 v3, v3, v2, 32 bitop3:0x6c
	v_ashrrev_i32_e32 v2, 31, v2
	v_ashrrev_i32_e32 v1, 31, v134
	v_lshrrev_b32_e32 v2, 26, v2
	v_lshrrev_b32_e32 v1, 26, v1
	v_add_u32_e32 v2, v3, v2
	v_add_u32_e32 v1, v134, v1
	v_ashrrev_i32_e32 v2, 6, v2
	v_ashrrev_i32_e32 v1, 6, v1
	v_mul_i32_i24_e32 v5, 64, v2
	v_lshlrev_b32_e32 v4, 3, v1
	v_lshlrev_b32_e32 v1, 5, v1
	v_sub_u32_e32 v3, v3, v5
	v_and_b32_e32 v1, 32, v1
	v_ashrrev_i16_sdwa v3, v252, sext(v3) dst_sel:DWORD dst_unused:UNUSED_PAD src0_sel:DWORD src1_sel:BYTE_0
	v_add_u32_e32 v138, 0x2000, v137
	v_add_u32_sdwa v1, v1, sext(v3) dst_sel:DWORD dst_unused:UNUSED_PAD src0_sel:DWORD src1_sel:WORD_0
	v_ashrrev_i32_e32 v3, 31, v138
	v_lshrrev_b32_e32 v3, 22, v3
	v_add_u32_e32 v3, v138, v3
	v_ashrrev_i32_e32 v3, 10, v3
	v_mul_i32_i24_e32 v5, 0x400, v3
	s_lshr_b32 s8, s1, 31
	s_ashr_i32 s1, s1, 2
	v_sub_u32_e32 v5, v138, v5
	s_add_i32 s1, s1, s8
	v_lshrrev_b32_e32 v6, 4, v5
	s_mul_i32 s1, s1, 18
	v_bitop3_b32 v5, v6, v5, 32 bitop3:0x6c
	s_sub_i32 s29, s0, s1
	v_ashrrev_i32_e32 v7, 31, v5
	s_lshl_b32 s8, s29, 8
	v_lshrrev_b32_e32 v7, 26, v7
	v_add_u32_e32 v7, v5, v7
	s_ashr_i32 s9, s8, 31
	v_and_b32_e32 v4, 0x1ffff0, v4
	v_lshrrev_b32_e32 v8, 6, v7
	v_and_b32_e32 v7, 0xc0, v7
	s_lshl_b64 s[0:1], s[8:9], 11
	v_lshlrev_b32_e32 v6, 3, v3
	v_lshlrev_b32_e32 v3, 5, v3
	v_sub_u32_e32 v5, v5, v7
	v_add_lshl_u32 v2, v2, v4, 11
	s_add_u32 s0, s69, s0
	v_readlane_b32 s14, v254, 50
	v_add_u32_e32 v143, 0x10000, v137
	v_and_b32_e32 v3, 32, v3
	v_ashrrev_i16_sdwa v5, v252, sext(v5) dst_sel:DWORD dst_unused:UNUSED_PAD src0_sel:DWORD src1_sel:BYTE_0
	v_lshl_add_u32 v132, v1, 1, v2
	v_and_b32_e32 v1, 0x1ffff0, v6
	s_addc_u32 s1, s14, s1
	v_readfirstlane_b32 s12, v143
	v_add_u32_e32 v144, 0x12000, v137
	v_add_u32_sdwa v3, v3, sext(v5) dst_sel:DWORD dst_unused:UNUSED_PAD src0_sel:DWORD src1_sel:WORD_0
	v_add_lshl_u32 v1, v8, v1, 11
	s_mov_b64 s[10:11], s[0:1]
	s_mov_b32 m0, s12
	v_readfirstlane_b32 s12, v144
	v_lshl_add_u32 v130, v3, 1, v1
	s_waitcnt lgkmcnt(0)
	s_barrier
	s_lshl_b64 s[16:17], s[6:7], 11
	global_load_lds_dwordx4 v132, s[10:11]
	s_mov_b32 m0, s12
	v_readfirstlane_b32 s7, v137
	global_load_lds_dwordx4 v130, s[10:11]
	s_add_u32 s10, s21, s16
	s_addc_u32 s11, s22, s17
	s_mov_b64 s[12:13], s[10:11]
	s_mov_b32 m0, s7
	v_readfirstlane_b32 s7, v138
	v_add_u32_e32 v146, 0x14000, v137
	global_load_lds_dwordx4 v132, s[12:13]
	s_mov_b32 m0, s7
	v_readfirstlane_b32 s7, v146
	global_load_lds_dwordx4 v130, s[12:13]
	s_or_b32 s12, s8, 0x80
	s_ashr_i32 s13, s12, 31
	s_lshl_b64 s[12:13], s[12:13], 11
	s_add_u32 s12, s69, s12
	s_addc_u32 s13, s14, s13
	v_add_u32_e32 v147, 0x16000, v137
	s_mov_b64 s[14:15], s[12:13]
	s_mov_b32 m0, s7
	v_readfirstlane_b32 s7, v147
	v_add_u32_e32 v148, 0x4000, v137
	global_load_lds_dwordx4 v132, s[14:15]
	s_mov_b32 m0, s7
	v_readfirstlane_b32 s7, v148
	global_load_lds_dwordx4 v130, s[14:15]
	s_or_b32 s14, s6, 0x80
	s_ashr_i32 s15, s14, 31
	s_lshl_b64 s[14:15], s[14:15], 11
	s_add_u32 s14, s21, s14
	s_addc_u32 s15, s22, s15
	v_add_u32_e32 v149, 0x6000, v137
	s_mov_b64 s[18:19], s[14:15]
	s_mov_b32 m0, s7
	v_readfirstlane_b32 s7, v149
	v_ashrrev_i32_e32 v2, 8, v134
	global_load_lds_dwordx4 v132, s[18:19]
	s_mov_b32 m0, s7
	v_cmp_eq_u32_e32 vcc, 1, v2
	global_load_lds_dwordx4 v130, s[18:19]
	s_and_saveexec_b64 s[18:19], vcc
	s_cbranch_execz .LBB0_287
	s_barrier

.LBB0_291:
	s_or_b64 exec, exec, s[0:1]
	v_lshl_or_b32 v144, v135, 2, v136
	v_lshl_add_u32 v143, v144, 2, v220
	s_cmp_gt_i32 s29, 8
	s_cbranch_scc1 .Lrp_A0_skip
	v_and_b32_e32 v216, 64, v134
	v_cmp_gt_u32_e64 s[10:11], 8, v1
	v_cmp_eq_u32_e32 vcc, 0, v216
	s_nop 1
	s_and_b64 vcc, vcc, s[10:11]
	s_and_saveexec_b64 s[10:11], vcc
	s_cbranch_execz .Lrp_A0_join
	v_readlane_b32 s12, v254, 53
	v_add_u32_e32 v216, s6, v144
	v_lshlrev_b32_e32 v217, 3, v1
	s_nop 0
	v_and_b32_e32 v216, s12, v216
	v_lshl_or_b32 v216, v216, 6, v217
	v_add_u32_e32 v217, 0x2000, v216
	global_load_dwordx2 v[146:147], v216, s[4:5]
	global_load_dwordx2 v[148:149], v216, s[4:5] offset:64
	global_load_dwordx2 v[150:151], v216, s[4:5] offset:128
	global_load_dwordx2 v[152:153], v216, s[4:5] offset:192
	global_load_dwordx2 v[154:155], v216, s[4:5] offset:1024
	global_load_dwordx2 v[156:157], v216, s[4:5] offset:1088
	global_load_dwordx2 v[158:159], v216, s[4:5] offset:1152
	global_load_dwordx2 v[160:161], v216, s[4:5] offset:1216
	global_load_dwordx2 v[162:163], v216, s[4:5] offset:2048
	global_load_dwordx2 v[164:165], v216, s[4:5] offset:2112
	global_load_dwordx2 v[166:167], v216, s[4:5] offset:2176
	global_load_dwordx2 v[168:169], v216, s[4:5] offset:2240
	global_load_dwordx2 v[170:171], v216, s[4:5] offset:3072
	global_load_dwordx2 v[172:173], v216, s[4:5] offset:3136
	global_load_dwordx2 v[174:175], v216, s[4:5] offset:3200
	global_load_dwordx2 v[176:177], v216, s[4:5] offset:3264
	global_load_dwordx2 v[178:179], v217, s[4:5]
	global_load_dwordx2 v[180:181], v217, s[4:5] offset:64
	global_load_dwordx2 v[182:183], v217, s[4:5] offset:128
	global_load_dwordx2 v[184:185], v217, s[4:5] offset:192
	global_load_dwordx2 v[186:187], v217, s[4:5] offset:1024
	global_load_dwordx2 v[188:189], v217, s[4:5] offset:1088
	global_load_dwordx2 v[190:191], v217, s[4:5] offset:1152
	global_load_dwordx2 v[192:193], v217, s[4:5] offset:1216
	global_load_dwordx2 v[194:195], v217, s[4:5] offset:2048
	global_load_dwordx2 v[196:197], v217, s[4:5] offset:2112
	global_load_dwordx2 v[198:199], v217, s[4:5] offset:2176
	global_load_dwordx2 v[200:201], v217, s[4:5] offset:2240
	global_load_dwordx2 v[202:203], v217, s[4:5] offset:3072
	global_load_dwordx2 v[204:205], v217, s[4:5] offset:3136
	global_load_dwordx2 v[206:207], v217, s[4:5] offset:3200
	global_load_dwordx2 v[208:209], v217, s[4:5] offset:3264

.Lrp_A0_skip:
	s_barrier
	ds_read_b128 v[212:215], v143
	ds_read_b128 v[224:227], v143 offset:64
	ds_read_b128 v[228:231], v143 offset:128
	ds_read_b128 v[232:235], v143 offset:192
	ds_read_b128 v[236:239], v143 offset:512
	ds_read_b128 v[240:243], v143 offset:576
	ds_read_b128 v[244:247], v143 offset:640
	ds_read_b128 v[248:251], v143 offset:704
	s_cmp_eq_u32 s29, 9
	s_cselect_b32 s0, 0, 2
	s_cmp_gt_i32 s29, 8
	v_and_b32_e32 v131, 64, v134
	v_mov_b32_e32 v132, v126
	v_mov_b32_e32 v133, v118
	v_mov_b32_e32 v136, v122
	v_mov_b32_e32 v137, v114
	s_cselect_b32 s7, s0, 1
	s_waitcnt lgkmcnt(0)
	v_mov_b32_e32 v130, v212
	v_pk_mul_f32 v[134:135], v[132:133], v[130:131] op_sel_hi:[1,0]
	v_mov_b32_e32 v132, v122
	v_pk_mul_f32 v[136:137], v[136:137], v[130:131] op_sel_hi:[1,0]
	v_cmp_eq_u32_e32 vcc, 0, v131
	v_cmp_gt_u32_e64 s[0:1], 8, v1
	v_pk_mul_f32 v[132:133], v[132:133], v[130:131] op_sel_hi:[1,0]
	v_mov_b32_e32 v130, v134
	v_mov_b32_e32 v131, v137
	s_cmp_gt_i32 s7, 1
	s_mov_b64 s[10:11], -1
	s_cbranch_scc0 .LBB0_293
	v_mul_f32_e32 v114, 0xbfb8aa3b, v137
	v_exp_f32_e32 v114, v114
	v_mul_f32_e32 v118, 0xbfb8aa3b, v133
	v_mul_f32_e32 v122, 0xbfb8aa3b, v132
	v_exp_f32_e32 v118, v118
	v_add_f32_e32 v114, 1.0, v114
	v_rcp_f32_e32 v139, v114
	v_mul_f32_e32 v114, 0xbfb8aa3b, v134
	v_exp_f32_e32 v114, v114
	v_exp_f32_e32 v122, v122
	v_add_f32_e32 v118, 1.0, v118
	v_rcp_f32_e32 v141, v118
	v_add_f32_e32 v114, 1.0, v114
	v_rcp_f32_e32 v138, v114
	v_add_f32_e32 v114, 1.0, v122
	v_rcp_f32_e32 v140, v114
	s_mov_b64 s[10:11], 0
	v_pk_mul_f32 v[138:139], v[130:131], v[138:139]
	v_pk_mul_f32 v[140:141], v[132:133], v[140:141]
.LBB0_293:
	s_and_b64 s[0:1], vcc, s[0:1]
	s_andn2_b64 vcc, exec, s[10:11]
	v_add_u32_e32 v142, s6, v144
	s_cbranch_vccnz .LBB0_299
	s_cmp_eq_u32 s7, 1
	s_cbranch_scc0 .LBB0_298
	s_and_saveexec_b64 s[10:11], s[0:1]
	s_cbranch_execz .LBB0_297
	v_readlane_b32 s12, v254, 53
	v_lshlrev_b32_e32 v118, 3, v1
	s_nop 0
	v_and_b32_e32 v114, s12, v142
	v_lshl_or_b32 v114, v114, 6, v118
	s_waitcnt vmcnt(0)
	v_mov_b32_e32 v138, v146
	v_mov_b32_e32 v139, v147
	v_pk_mul_f32 v[136:137], v[136:137], v[138:139]
	v_pk_mul_f32 v[132:133], v[132:133], v[138:139] op_sel:[0,1]
	s_nop 0
	v_pk_fma_f32 v[130:131], v[130:131], v[138:139], v[132:133] op_sel_hi:[1,0,1] neg_lo:[0,0,1] neg_hi:[0,0,1]
	v_pk_fma_f32 v[132:133], v[134:135], v[138:139], v[136:137] op_sel:[0,1,0] op_sel_hi:[1,0,1]

.LBB0_299:
	v_lshl_or_b32 v134, v145, 5, v1
	v_mul_lo_u32 v135, v144, s3
	v_cvt_pk_bf16_f32 v114, v139, s0
	v_lshl_add_u32 v118, v134, 1, v135
	ds_write_b16 v118, v114
	v_cvt_pk_bf16_f32 v114, v141, s0
	ds_write_b16 v118, v114 offset:32
	v_cvt_pk_bf16_f32 v114, v138, s0
	ds_write_b16 v118, v114 offset:256
	v_cvt_pk_bf16_f32 v114, v140, s0
	v_or_b32_e32 v136, 1, v144
	ds_write_b16 v118, v114 offset:288
	v_lshl_add_u32 v114, v136, 2, v220
	v_mov_b32_e32 v130, v213
	v_mov_b32_e32 v118, v127
	v_mov_b32_e32 v114, v123
	s_cmp_gt_i32 s7, 1
	s_mov_b64 s[10:11], -1
	v_pk_mul_f32 v[126:127], v[118:119], v[130:131] op_sel_hi:[1,0]
	v_mov_b32_e32 v118, v123
	v_pk_mul_f32 v[122:123], v[114:115], v[130:131] op_sel_hi:[1,0]
	v_pk_mul_f32 v[118:119], v[118:119], v[130:131] op_sel_hi:[1,0]
	v_mov_b32_e32 v114, v126
	v_mov_b32_e32 v115, v123
	s_cbranch_scc0 .LBB0_301
	v_mul_f32_e32 v130, 0xbfb8aa3b, v123
	v_exp_f32_e32 v130, v130
	v_mul_f32_e32 v131, 0xbfb8aa3b, v119
	v_exp_f32_e32 v131, v131
	v_mul_f32_e32 v133, 0xbfb8aa3b, v118
	v_add_f32_e32 v130, 1.0, v130
	v_exp_f32_e32 v137, v133
	v_add_f32_e32 v132, 1.0, v131
	v_rcp_f32_e32 v131, v130
	v_mul_f32_e32 v130, 0xbfb8aa3b, v126
	v_exp_f32_e32 v130, v130
	v_rcp_f32_e32 v133, v132
	v_add_f32_e32 v132, 1.0, v137
	v_rcp_f32_e32 v132, v132
	v_add_f32_e32 v130, 1.0, v130
	v_rcp_f32_e32 v130, v130
	s_mov_b64 s[10:11], 0
	v_pk_mul_f32 v[132:133], v[118:119], v[132:133]
	v_pk_mul_f32 v[130:131], v[114:115], v[130:131]
.LBB0_301:
	s_andn2_b64 vcc, exec, s[10:11]
	s_cbranch_vccnz .LBB0_307
	s_cmp_eq_u32 s7, 1
	s_cbranch_scc0 .LBB0_306
	s_and_saveexec_b64 s[10:11], s[0:1]
	s_cbranch_execz .LBB0_305
	v_add_u32_e32 v130, s6, v136
	v_readlane_b32 s12, v254, 53
	v_lshlrev_b32_e32 v131, 3, v1
	s_nop 0
	v_and_b32_e32 v130, s12, v130
	v_lshl_or_b32 v130, v130, 6, v131
	s_waitcnt vmcnt(0)
	v_mov_b32_e32 v130, v148
	v_mov_b32_e32 v131, v149
	v_pk_mul_f32 v[122:123], v[122:123], v[130:131]
	v_pk_mul_f32 v[118:119], v[118:119], v[130:131] op_sel:[0,1]
	s_nop 0
	v_pk_fma_f32 v[114:115], v[114:115], v[130:131], v[118:119] op_sel_hi:[1,0,1] neg_lo:[0,0,1] neg_hi:[0,0,1]
	v_pk_fma_f32 v[118:119], v[126:127], v[130:131], v[122:123] op_sel:[0,1,0] op_sel_hi:[1,0,1]

.LBB0_307:
	v_add_u32_e32 v135, 0x210, v135
	v_cvt_pk_bf16_f32 v114, v131, s0
	v_lshl_add_u32 v115, v134, 1, v135
	ds_write_b16 v115, v114
	v_cvt_pk_bf16_f32 v114, v133, s0
	ds_write_b16 v115, v114 offset:32
	v_cvt_pk_bf16_f32 v114, v130, s0
	ds_write_b16 v115, v114 offset:256
	v_cvt_pk_bf16_f32 v114, v132, s0
	v_or_b32_e32 v136, 2, v144
	ds_write_b16 v115, v114 offset:288
	v_lshl_add_u32 v114, v136, 2, v220
	v_mov_b32_e32 v114, v214
	v_mov_b32_e32 v118, v128
	v_mov_b32_e32 v119, v120
	v_mov_b32_e32 v126, v124
	v_mov_b32_e32 v127, v120
	v_mov_b32_e32 v130, v124
	v_mov_b32_e32 v131, v116
	v_pk_mul_f32 v[122:123], v[118:119], v[114:115] op_sel_hi:[1,0]
	v_pk_mul_f32 v[118:119], v[126:127], v[114:115] op_sel_hi:[1,0]
	v_pk_mul_f32 v[126:127], v[130:131], v[114:115] op_sel_hi:[1,0]
	v_mov_b32_e32 v114, v122
	v_mov_b32_e32 v115, v127
	s_cmp_gt_i32 s7, 1
	s_mov_b64 s[10:11], -1
	s_cbranch_scc0 .LBB0_309
	v_mul_f32_e32 v116, 0xbfb8aa3b, v127
	v_exp_f32_e32 v116, v116
	v_mul_f32_e32 v120, 0xbfb8aa3b, v119
	v_mul_f32_e32 v124, 0xbfb8aa3b, v118
	v_exp_f32_e32 v120, v120
	v_add_f32_e32 v116, 1.0, v116
	v_rcp_f32_e32 v131, v116
	v_mul_f32_e32 v116, 0xbfb8aa3b, v122
	v_exp_f32_e32 v116, v116
	v_exp_f32_e32 v124, v124
	v_add_f32_e32 v120, 1.0, v120
	v_rcp_f32_e32 v133, v120
	v_add_f32_e32 v116, 1.0, v116
	v_rcp_f32_e32 v130, v116
	v_add_f32_e32 v116, 1.0, v124
	v_rcp_f32_e32 v132, v116
	s_mov_b64 s[10:11], 0
	v_pk_mul_f32 v[130:131], v[114:115], v[130:131]
	v_pk_mul_f32 v[132:133], v[118:119], v[132:133]
.LBB0_309:
	s_andn2_b64 vcc, exec, s[10:11]
	s_cbranch_vccnz .LBB0_315
	s_cmp_eq_u32 s7, 1
	s_cbranch_scc0 .LBB0_314
	s_and_saveexec_b64 s[10:11], s[0:1]
	s_cbranch_execz .LBB0_313
	v_add_u32_e32 v116, s6, v136
	v_readlane_b32 s12, v254, 53
	v_lshlrev_b32_e32 v120, 3, v1
	s_nop 0
	v_and_b32_e32 v116, s12, v116
	v_lshl_or_b32 v116, v116, 6, v120
	s_waitcnt vmcnt(0)
	v_mov_b32_e32 v130, v150
	v_mov_b32_e32 v131, v151
	v_pk_mul_f32 v[126:127], v[126:127], v[130:131]
	v_pk_mul_f32 v[118:119], v[118:119], v[130:131] op_sel:[0,1]
	s_nop 0
	v_pk_fma_f32 v[114:115], v[114:115], v[130:131], v[118:119] op_sel_hi:[1,0,1] neg_lo:[0,0,1] neg_hi:[0,0,1]
	v_pk_fma_f32 v[118:119], v[122:123], v[130:131], v[126:127] op_sel:[0,1,0] op_sel_hi:[1,0,1]

.LBB0_315:
	v_add_u32_e32 v126, 0x210, v135
	v_cvt_pk_bf16_f32 v114, v131, s0
	v_lshl_add_u32 v115, v134, 1, v126
	ds_write_b16 v115, v114
	v_cvt_pk_bf16_f32 v114, v133, s0
	ds_write_b16 v115, v114 offset:32
	v_cvt_pk_bf16_f32 v114, v130, s0
	ds_write_b16 v115, v114 offset:256
	v_cvt_pk_bf16_f32 v114, v132, s0
	v_or_b32_e32 v127, 3, v144
	ds_write_b16 v115, v114 offset:288
	v_lshl_add_u32 v114, v127, 2, v220
	v_mov_b32_e32 v114, v215
	v_mov_b32_e32 v120, v129
	v_mov_b32_e32 v116, v125
	s_cmp_gt_i32 s7, 1
	s_mov_b64 s[10:11], -1
	v_pk_mul_f32 v[118:119], v[120:121], v[114:115] op_sel_hi:[1,0]
	v_mov_b32_e32 v120, v125
	v_pk_mul_f32 v[122:123], v[116:117], v[114:115] op_sel_hi:[1,0]
	v_pk_mul_f32 v[116:117], v[120:121], v[114:115] op_sel_hi:[1,0]
	v_mov_b32_e32 v114, v118
	v_mov_b32_e32 v115, v123
	s_cbranch_scc0 .LBB0_317
	v_mul_f32_e32 v120, 0xbfb8aa3b, v123
	v_exp_f32_e32 v120, v120
	v_mul_f32_e32 v121, 0xbfb8aa3b, v117
	v_exp_f32_e32 v121, v121
	v_mul_f32_e32 v125, 0xbfb8aa3b, v116
	v_add_f32_e32 v120, 1.0, v120
	v_exp_f32_e32 v128, v125
	v_add_f32_e32 v124, 1.0, v121
	v_rcp_f32_e32 v121, v120
	v_mul_f32_e32 v120, 0xbfb8aa3b, v118
	v_exp_f32_e32 v120, v120
	v_rcp_f32_e32 v125, v124
	v_add_f32_e32 v124, 1.0, v128
	v_rcp_f32_e32 v124, v124
	v_add_f32_e32 v120, 1.0, v120
	v_rcp_f32_e32 v120, v120
	s_mov_b64 s[10:11], 0
	v_pk_mul_f32 v[124:125], v[116:117], v[124:125]
	v_pk_mul_f32 v[120:121], v[114:115], v[120:121]
.LBB0_317:
	s_andn2_b64 vcc, exec, s[10:11]
	s_cbranch_vccnz .LBB0_323
	s_cmp_eq_u32 s7, 1
	s_cbranch_scc0 .LBB0_322
	s_and_saveexec_b64 s[10:11], s[0:1]
	s_cbranch_execz .LBB0_321
	v_add_u32_e32 v120, s6, v127
	v_readlane_b32 s12, v254, 53
	v_lshlrev_b32_e32 v121, 3, v1
	s_nop 0
	v_and_b32_e32 v120, s12, v120
	v_lshl_or_b32 v120, v120, 6, v121
	s_waitcnt vmcnt(0)
	v_mov_b32_e32 v120, v152
	v_mov_b32_e32 v121, v153
	v_pk_mul_f32 v[122:123], v[122:123], v[120:121]
	v_pk_mul_f32 v[116:117], v[116:117], v[120:121] op_sel:[0,1]
	s_nop 0
	v_pk_fma_f32 v[114:115], v[114:115], v[120:121], v[116:117] op_sel_hi:[1,0,1] neg_lo:[0,0,1] neg_hi:[0,0,1]
	v_pk_fma_f32 v[116:117], v[118:119], v[120:121], v[122:123] op_sel:[0,1,0] op_sel_hi:[1,0,1]

.LBB0_323:
	v_add_u32_e32 v126, 0x210, v126
	v_cvt_pk_bf16_f32 v114, v121, s0
	v_lshl_add_u32 v115, v134, 1, v126
	ds_write_b16 v115, v114
	v_cvt_pk_bf16_f32 v114, v125, s0
	ds_write_b16 v115, v114 offset:32
	v_cvt_pk_bf16_f32 v114, v120, s0
	ds_write_b16 v115, v114 offset:256
	v_cvt_pk_bf16_f32 v114, v124, s0
	v_or_b32_e32 v127, 16, v144
	ds_write_b16 v115, v114 offset:288
	v_lshl_add_u32 v114, v127, 2, v220
	v_mov_b32_e32 v114, v224
	v_mov_b32_e32 v116, v110
	v_mov_b32_e32 v117, v102
	v_mov_b32_e32 v120, v106
	v_mov_b32_e32 v121, v102
	v_mov_b32_e32 v122, v106
	v_mov_b32_e32 v123, v98
	v_pk_mul_f32 v[118:119], v[116:117], v[114:115] op_sel_hi:[1,0]
	v_pk_mul_f32 v[116:117], v[120:121], v[114:115] op_sel_hi:[1,0]
	v_pk_mul_f32 v[120:121], v[122:123], v[114:115] op_sel_hi:[1,0]
	v_mov_b32_e32 v114, v118
	v_mov_b32_e32 v115, v121
	s_cmp_gt_i32 s7, 1
	s_mov_b64 s[10:11], -1
	s_cbranch_scc0 .LBB0_325
	v_mul_f32_e32 v98, 0xbfb8aa3b, v121
	v_exp_f32_e32 v98, v98
	v_mul_f32_e32 v102, 0xbfb8aa3b, v117
	v_mul_f32_e32 v106, 0xbfb8aa3b, v116
	v_exp_f32_e32 v102, v102
	v_add_f32_e32 v98, 1.0, v98
	v_rcp_f32_e32 v123, v98
	v_mul_f32_e32 v98, 0xbfb8aa3b, v118
	v_exp_f32_e32 v98, v98
	v_exp_f32_e32 v106, v106
	v_add_f32_e32 v102, 1.0, v102
	v_rcp_f32_e32 v125, v102
	v_add_f32_e32 v98, 1.0, v98
	v_rcp_f32_e32 v122, v98
	v_add_f32_e32 v98, 1.0, v106
	v_rcp_f32_e32 v124, v98
	s_mov_b64 s[10:11], 0
	v_pk_mul_f32 v[122:123], v[114:115], v[122:123]
	v_pk_mul_f32 v[124:125], v[116:117], v[124:125]
.LBB0_325:
	s_andn2_b64 vcc, exec, s[10:11]
	s_cbranch_vccnz .LBB0_331
	s_cmp_eq_u32 s7, 1
	s_cbranch_scc0 .LBB0_330
	s_and_saveexec_b64 s[10:11], s[0:1]
	s_cbranch_execz .LBB0_329
	v_add_u32_e32 v98, s6, v127
	v_readlane_b32 s12, v254, 53
	v_lshlrev_b32_e32 v102, 3, v1
	s_nop 0
	v_and_b32_e32 v98, s12, v98
	v_lshl_or_b32 v98, v98, 6, v102
	s_waitcnt vmcnt(0)
	v_mov_b32_e32 v122, v154
	v_mov_b32_e32 v123, v155
	v_pk_mul_f32 v[120:121], v[120:121], v[122:123]
	v_pk_mul_f32 v[116:117], v[116:117], v[122:123] op_sel:[0,1]
	s_nop 0
	v_pk_fma_f32 v[114:115], v[114:115], v[122:123], v[116:117] op_sel_hi:[1,0,1] neg_lo:[0,0,1] neg_hi:[0,0,1]
	v_pk_fma_f32 v[116:117], v[118:119], v[122:123], v[120:121] op_sel:[0,1,0] op_sel_hi:[1,0,1]

.LBB0_331:
	v_add_u32_e32 v118, 0x1ad0, v126
	v_cvt_pk_bf16_f32 v98, v123, s0
	v_lshl_add_u32 v102, v134, 1, v118
	ds_write_b16 v102, v98
	v_cvt_pk_bf16_f32 v98, v125, s0
	ds_write_b16 v102, v98 offset:32
	v_cvt_pk_bf16_f32 v98, v122, s0
	ds_write_b16 v102, v98 offset:256
	v_cvt_pk_bf16_f32 v98, v124, s0
	v_or_b32_e32 v119, 17, v144
	ds_write_b16 v102, v98 offset:288
	v_lshl_add_u32 v98, v119, 2, v220
	v_mov_b32_e32 v114, v225
	v_mov_b32_e32 v102, v111
	v_mov_b32_e32 v98, v107
	s_cmp_gt_i32 s7, 1
	s_mov_b64 s[10:11], -1
	v_pk_mul_f32 v[110:111], v[102:103], v[114:115] op_sel_hi:[1,0]
	v_mov_b32_e32 v102, v107
	v_pk_mul_f32 v[106:107], v[98:99], v[114:115] op_sel_hi:[1,0]
	v_pk_mul_f32 v[102:103], v[102:103], v[114:115] op_sel_hi:[1,0]
	v_mov_b32_e32 v98, v110
	v_mov_b32_e32 v99, v107
	s_cbranch_scc0 .LBB0_333
	v_mul_f32_e32 v114, 0xbfb8aa3b, v107
	v_exp_f32_e32 v114, v114
	v_mul_f32_e32 v115, 0xbfb8aa3b, v103
	v_exp_f32_e32 v115, v115
	v_mul_f32_e32 v117, 0xbfb8aa3b, v102
	v_add_f32_e32 v114, 1.0, v114
	v_exp_f32_e32 v120, v117
	v_add_f32_e32 v116, 1.0, v115
	v_rcp_f32_e32 v115, v114
	v_mul_f32_e32 v114, 0xbfb8aa3b, v110
	v_exp_f32_e32 v114, v114
	v_rcp_f32_e32 v117, v116
	v_add_f32_e32 v116, 1.0, v120
	v_rcp_f32_e32 v116, v116
	v_add_f32_e32 v114, 1.0, v114
	v_rcp_f32_e32 v114, v114
	s_mov_b64 s[10:11], 0
	v_pk_mul_f32 v[116:117], v[102:103], v[116:117]
	v_pk_mul_f32 v[114:115], v[98:99], v[114:115]
.LBB0_333:
	s_andn2_b64 vcc, exec, s[10:11]
	s_cbranch_vccnz .LBB0_339
	s_cmp_eq_u32 s7, 1
	s_cbranch_scc0 .LBB0_338
	s_and_saveexec_b64 s[10:11], s[0:1]
	s_cbranch_execz .LBB0_337
	v_add_u32_e32 v114, s6, v119
	v_readlane_b32 s12, v254, 53
	v_lshlrev_b32_e32 v115, 3, v1
	s_nop 0
	v_and_b32_e32 v114, s12, v114
	v_lshl_or_b32 v114, v114, 6, v115
	s_waitcnt vmcnt(0)
	v_mov_b32_e32 v114, v156
	v_mov_b32_e32 v115, v157
	v_pk_mul_f32 v[106:107], v[106:107], v[114:115]
	v_pk_mul_f32 v[102:103], v[102:103], v[114:115] op_sel:[0,1]
	s_nop 0
	v_pk_fma_f32 v[98:99], v[98:99], v[114:115], v[102:103] op_sel_hi:[1,0,1] neg_lo:[0,0,1] neg_hi:[0,0,1]
	v_pk_fma_f32 v[102:103], v[110:111], v[114:115], v[106:107] op_sel:[0,1,0] op_sel_hi:[1,0,1]

.LBB0_339:
	v_add_u32_e32 v118, 0x210, v118
	v_cvt_pk_bf16_f32 v98, v115, s0
	v_lshl_add_u32 v99, v134, 1, v118
	ds_write_b16 v99, v98
	v_cvt_pk_bf16_f32 v98, v117, s0
	ds_write_b16 v99, v98 offset:32
	v_cvt_pk_bf16_f32 v98, v114, s0
	ds_write_b16 v99, v98 offset:256
	v_cvt_pk_bf16_f32 v98, v116, s0
	v_or_b32_e32 v119, 18, v144
	ds_write_b16 v99, v98 offset:288
	v_lshl_add_u32 v98, v119, 2, v220
	v_mov_b32_e32 v98, v226
	v_mov_b32_e32 v102, v112
	v_mov_b32_e32 v103, v104
	v_mov_b32_e32 v110, v108
	v_mov_b32_e32 v111, v104
	v_mov_b32_e32 v114, v108
	v_mov_b32_e32 v115, v100
	v_pk_mul_f32 v[106:107], v[102:103], v[98:99] op_sel_hi:[1,0]
	v_pk_mul_f32 v[102:103], v[110:111], v[98:99] op_sel_hi:[1,0]
	v_pk_mul_f32 v[110:111], v[114:115], v[98:99] op_sel_hi:[1,0]
	v_mov_b32_e32 v98, v106
	v_mov_b32_e32 v99, v111
	s_cmp_gt_i32 s7, 1
	s_mov_b64 s[10:11], -1
	s_cbranch_scc0 .LBB0_341
	v_mul_f32_e32 v100, 0xbfb8aa3b, v111
	v_exp_f32_e32 v100, v100
	v_mul_f32_e32 v104, 0xbfb8aa3b, v103
	v_mul_f32_e32 v108, 0xbfb8aa3b, v102
	v_exp_f32_e32 v104, v104
	v_add_f32_e32 v100, 1.0, v100
	v_rcp_f32_e32 v115, v100
	v_mul_f32_e32 v100, 0xbfb8aa3b, v106
	v_exp_f32_e32 v100, v100
	v_exp_f32_e32 v108, v108
	v_add_f32_e32 v104, 1.0, v104
	v_rcp_f32_e32 v117, v104
	v_add_f32_e32 v100, 1.0, v100
	v_rcp_f32_e32 v114, v100
	v_add_f32_e32 v100, 1.0, v108
	v_rcp_f32_e32 v116, v100
	s_mov_b64 s[10:11], 0
	v_pk_mul_f32 v[114:115], v[98:99], v[114:115]
	v_pk_mul_f32 v[116:117], v[102:103], v[116:117]
.LBB0_341:
	s_andn2_b64 vcc, exec, s[10:11]
	s_cbranch_vccnz .LBB0_347
	s_cmp_eq_u32 s7, 1
	s_cbranch_scc0 .LBB0_346
	s_and_saveexec_b64 s[10:11], s[0:1]
	s_cbranch_execz .LBB0_345
	v_add_u32_e32 v100, s6, v119
	v_readlane_b32 s12, v254, 53
	v_lshlrev_b32_e32 v104, 3, v1
	s_nop 0
	v_and_b32_e32 v100, s12, v100
	v_lshl_or_b32 v100, v100, 6, v104
	s_waitcnt vmcnt(0)
	v_mov_b32_e32 v114, v158
	v_mov_b32_e32 v115, v159
	v_pk_mul_f32 v[110:111], v[110:111], v[114:115]
	v_pk_mul_f32 v[102:103], v[102:103], v[114:115] op_sel:[0,1]
	s_nop 0
	v_pk_fma_f32 v[98:99], v[98:99], v[114:115], v[102:103] op_sel_hi:[1,0,1] neg_lo:[0,0,1] neg_hi:[0,0,1]
	v_pk_fma_f32 v[102:103], v[106:107], v[114:115], v[110:111] op_sel:[0,1,0] op_sel_hi:[1,0,1]

.LBB0_347:
	v_add_u32_e32 v110, 0x210, v118
	v_cvt_pk_bf16_f32 v98, v115, s0
	v_lshl_add_u32 v99, v134, 1, v110
	ds_write_b16 v99, v98
	v_cvt_pk_bf16_f32 v98, v117, s0
	ds_write_b16 v99, v98 offset:32
	v_cvt_pk_bf16_f32 v98, v114, s0
	ds_write_b16 v99, v98 offset:256
	v_cvt_pk_bf16_f32 v98, v116, s0
	v_or_b32_e32 v111, 19, v144
	ds_write_b16 v99, v98 offset:288
	v_lshl_add_u32 v98, v111, 2, v220
	v_mov_b32_e32 v98, v227
	v_mov_b32_e32 v104, v113
	v_mov_b32_e32 v100, v109
	s_cmp_gt_i32 s7, 1
	s_mov_b64 s[10:11], -1
	v_pk_mul_f32 v[102:103], v[104:105], v[98:99] op_sel_hi:[1,0]
	v_mov_b32_e32 v104, v109
	v_pk_mul_f32 v[106:107], v[100:101], v[98:99] op_sel_hi:[1,0]
	v_pk_mul_f32 v[100:101], v[104:105], v[98:99] op_sel_hi:[1,0]
	v_mov_b32_e32 v98, v102
	v_mov_b32_e32 v99, v107
	s_cbranch_scc0 .LBB0_349
	v_mul_f32_e32 v104, 0xbfb8aa3b, v107
	v_exp_f32_e32 v104, v104
	v_mul_f32_e32 v105, 0xbfb8aa3b, v101
	v_exp_f32_e32 v105, v105
	v_mul_f32_e32 v109, 0xbfb8aa3b, v100
	v_add_f32_e32 v104, 1.0, v104
	v_exp_f32_e32 v112, v109
	v_add_f32_e32 v108, 1.0, v105
	v_rcp_f32_e32 v105, v104
	v_mul_f32_e32 v104, 0xbfb8aa3b, v102
	v_exp_f32_e32 v104, v104
	v_rcp_f32_e32 v109, v108
	v_add_f32_e32 v108, 1.0, v112
	v_rcp_f32_e32 v108, v108
	v_add_f32_e32 v104, 1.0, v104
	v_rcp_f32_e32 v104, v104
	s_mov_b64 s[10:11], 0
	v_pk_mul_f32 v[108:109], v[100:101], v[108:109]
	v_pk_mul_f32 v[104:105], v[98:99], v[104:105]
.LBB0_349:
	s_andn2_b64 vcc, exec, s[10:11]
	s_cbranch_vccnz .LBB0_355
	s_cmp_eq_u32 s7, 1
	s_cbranch_scc0 .LBB0_354
	s_and_saveexec_b64 s[10:11], s[0:1]
	s_cbranch_execz .LBB0_353
	v_add_u32_e32 v104, s6, v111
	v_readlane_b32 s12, v254, 53
	v_lshlrev_b32_e32 v105, 3, v1
	s_nop 0
	v_and_b32_e32 v104, s12, v104
	v_lshl_or_b32 v104, v104, 6, v105
	s_waitcnt vmcnt(0)
	v_mov_b32_e32 v104, v160
	v_mov_b32_e32 v105, v161
	v_pk_mul_f32 v[106:107], v[106:107], v[104:105]
	v_pk_mul_f32 v[100:101], v[100:101], v[104:105] op_sel:[0,1]
	s_nop 0
	v_pk_fma_f32 v[98:99], v[98:99], v[104:105], v[100:101] op_sel_hi:[1,0,1] neg_lo:[0,0,1] neg_hi:[0,0,1]
	v_pk_fma_f32 v[100:101], v[102:103], v[104:105], v[106:107] op_sel:[0,1,0] op_sel_hi:[1,0,1]

.LBB0_355:
	v_add_u32_e32 v110, 0x210, v110
	v_cvt_pk_bf16_f32 v98, v105, s0
	v_lshl_add_u32 v99, v134, 1, v110
	ds_write_b16 v99, v98
	v_cvt_pk_bf16_f32 v98, v109, s0
	ds_write_b16 v99, v98 offset:32
	v_cvt_pk_bf16_f32 v98, v104, s0
	ds_write_b16 v99, v98 offset:256
	v_cvt_pk_bf16_f32 v98, v108, s0
	v_or_b32_e32 v111, 32, v144
	ds_write_b16 v99, v98 offset:288
	v_lshl_add_u32 v98, v111, 2, v220
	v_mov_b32_e32 v98, v228
	v_mov_b32_e32 v100, v94
	v_mov_b32_e32 v101, v86
	v_mov_b32_e32 v104, v90
	v_mov_b32_e32 v105, v86
	v_mov_b32_e32 v106, v90
	v_mov_b32_e32 v107, v82
	v_pk_mul_f32 v[102:103], v[100:101], v[98:99] op_sel_hi:[1,0]
	v_pk_mul_f32 v[100:101], v[104:105], v[98:99] op_sel_hi:[1,0]
	v_pk_mul_f32 v[104:105], v[106:107], v[98:99] op_sel_hi:[1,0]
	v_mov_b32_e32 v98, v102
	v_mov_b32_e32 v99, v105
	s_cmp_gt_i32 s7, 1
	s_mov_b64 s[10:11], -1
	s_cbranch_scc0 .LBB0_357
	v_mul_f32_e32 v82, 0xbfb8aa3b, v105
	v_exp_f32_e32 v82, v82
	v_mul_f32_e32 v86, 0xbfb8aa3b, v101
	v_mul_f32_e32 v90, 0xbfb8aa3b, v100
	v_exp_f32_e32 v86, v86
	v_add_f32_e32 v82, 1.0, v82
	v_rcp_f32_e32 v107, v82
	v_mul_f32_e32 v82, 0xbfb8aa3b, v102
	v_exp_f32_e32 v82, v82
	v_exp_f32_e32 v90, v90
	v_add_f32_e32 v86, 1.0, v86
	v_rcp_f32_e32 v109, v86
	v_add_f32_e32 v82, 1.0, v82
	v_rcp_f32_e32 v106, v82
	v_add_f32_e32 v82, 1.0, v90
	v_rcp_f32_e32 v108, v82
	s_mov_b64 s[10:11], 0
	v_pk_mul_f32 v[106:107], v[98:99], v[106:107]
	v_pk_mul_f32 v[108:109], v[100:101], v[108:109]
.LBB0_357:
	s_andn2_b64 vcc, exec, s[10:11]
	s_cbranch_vccnz .LBB0_363
	s_cmp_eq_u32 s7, 1
	s_cbranch_scc0 .LBB0_362
	s_and_saveexec_b64 s[10:11], s[0:1]
	s_cbranch_execz .LBB0_361
	v_add_u32_e32 v82, s6, v111
	v_readlane_b32 s12, v254, 53
	v_lshlrev_b32_e32 v86, 3, v1
	s_nop 0
	v_and_b32_e32 v82, s12, v82
	v_lshl_or_b32 v82, v82, 6, v86
	s_waitcnt vmcnt(0)
	v_mov_b32_e32 v106, v162
	v_mov_b32_e32 v107, v163
	v_pk_mul_f32 v[104:105], v[104:105], v[106:107]
	v_pk_mul_f32 v[100:101], v[100:101], v[106:107] op_sel:[0,1]
	s_nop 0
	v_pk_fma_f32 v[98:99], v[98:99], v[106:107], v[100:101] op_sel_hi:[1,0,1] neg_lo:[0,0,1] neg_hi:[0,0,1]
	v_pk_fma_f32 v[100:101], v[102:103], v[106:107], v[104:105] op_sel:[0,1,0] op_sel_hi:[1,0,1]

.LBB0_363:
	v_add_u32_e32 v102, 0x1ad0, v110
	v_cvt_pk_bf16_f32 v82, v107, s0
	v_lshl_add_u32 v86, v134, 1, v102
	ds_write_b16 v86, v82
	v_cvt_pk_bf16_f32 v82, v109, s0
	ds_write_b16 v86, v82 offset:32
	v_cvt_pk_bf16_f32 v82, v106, s0
	ds_write_b16 v86, v82 offset:256
	v_cvt_pk_bf16_f32 v82, v108, s0
	v_or_b32_e32 v103, 33, v144
	ds_write_b16 v86, v82 offset:288
	v_lshl_add_u32 v82, v103, 2, v220
	v_mov_b32_e32 v98, v229
	v_mov_b32_e32 v86, v95
	v_mov_b32_e32 v82, v91
	s_cmp_gt_i32 s7, 1
	s_mov_b64 s[10:11], -1
	v_pk_mul_f32 v[94:95], v[86:87], v[98:99] op_sel_hi:[1,0]
	v_mov_b32_e32 v86, v91
	v_pk_mul_f32 v[90:91], v[82:83], v[98:99] op_sel_hi:[1,0]
	v_pk_mul_f32 v[86:87], v[86:87], v[98:99] op_sel_hi:[1,0]
	v_mov_b32_e32 v82, v94
	v_mov_b32_e32 v83, v91
	s_cbranch_scc0 .LBB0_365
	v_mul_f32_e32 v98, 0xbfb8aa3b, v91
	v_exp_f32_e32 v98, v98
	v_mul_f32_e32 v99, 0xbfb8aa3b, v87
	v_exp_f32_e32 v99, v99
	v_mul_f32_e32 v101, 0xbfb8aa3b, v86
	v_add_f32_e32 v98, 1.0, v98
	v_exp_f32_e32 v104, v101
	v_add_f32_e32 v100, 1.0, v99
	v_rcp_f32_e32 v99, v98
	v_mul_f32_e32 v98, 0xbfb8aa3b, v94
	v_exp_f32_e32 v98, v98
	v_rcp_f32_e32 v101, v100
	v_add_f32_e32 v100, 1.0, v104
	v_rcp_f32_e32 v100, v100
	v_add_f32_e32 v98, 1.0, v98
	v_rcp_f32_e32 v98, v98
	s_mov_b64 s[10:11], 0
	v_pk_mul_f32 v[100:101], v[86:87], v[100:101]
	v_pk_mul_f32 v[98:99], v[82:83], v[98:99]
.LBB0_365:
	s_andn2_b64 vcc, exec, s[10:11]
	s_cbranch_vccnz .LBB0_371
	s_cmp_eq_u32 s7, 1
	s_cbranch_scc0 .LBB0_370
	s_and_saveexec_b64 s[10:11], s[0:1]
	s_cbranch_execz .LBB0_369
	v_add_u32_e32 v98, s6, v103
	v_readlane_b32 s12, v254, 53
	v_lshlrev_b32_e32 v99, 3, v1
	s_nop 0
	v_and_b32_e32 v98, s12, v98
	v_lshl_or_b32 v98, v98, 6, v99
	s_waitcnt vmcnt(0)
	v_mov_b32_e32 v98, v164
	v_mov_b32_e32 v99, v165
	v_pk_mul_f32 v[90:91], v[90:91], v[98:99]
	v_pk_mul_f32 v[86:87], v[86:87], v[98:99] op_sel:[0,1]
	s_nop 0
	v_pk_fma_f32 v[82:83], v[82:83], v[98:99], v[86:87] op_sel_hi:[1,0,1] neg_lo:[0,0,1] neg_hi:[0,0,1]
	v_pk_fma_f32 v[86:87], v[94:95], v[98:99], v[90:91] op_sel:[0,1,0] op_sel_hi:[1,0,1]

.LBB0_371:
	v_add_u32_e32 v102, 0x210, v102
	v_cvt_pk_bf16_f32 v82, v99, s0
	v_lshl_add_u32 v83, v134, 1, v102
	ds_write_b16 v83, v82
	v_cvt_pk_bf16_f32 v82, v101, s0
	ds_write_b16 v83, v82 offset:32
	v_cvt_pk_bf16_f32 v82, v98, s0
	ds_write_b16 v83, v82 offset:256
	v_cvt_pk_bf16_f32 v82, v100, s0
	v_or_b32_e32 v103, 34, v144
	ds_write_b16 v83, v82 offset:288
	v_lshl_add_u32 v82, v103, 2, v220
	v_mov_b32_e32 v82, v230
	v_mov_b32_e32 v86, v96
	v_mov_b32_e32 v87, v88
	v_mov_b32_e32 v94, v92
	v_mov_b32_e32 v95, v88
	v_mov_b32_e32 v98, v92
	v_mov_b32_e32 v99, v84
	v_pk_mul_f32 v[90:91], v[86:87], v[82:83] op_sel_hi:[1,0]
	v_pk_mul_f32 v[86:87], v[94:95], v[82:83] op_sel_hi:[1,0]
	v_pk_mul_f32 v[94:95], v[98:99], v[82:83] op_sel_hi:[1,0]
	v_mov_b32_e32 v82, v90
	v_mov_b32_e32 v83, v95
	s_cmp_gt_i32 s7, 1
	s_mov_b64 s[10:11], -1
	s_cbranch_scc0 .LBB0_373
	v_mul_f32_e32 v84, 0xbfb8aa3b, v95
	v_exp_f32_e32 v84, v84
	v_mul_f32_e32 v88, 0xbfb8aa3b, v87
	v_mul_f32_e32 v92, 0xbfb8aa3b, v86
	v_exp_f32_e32 v88, v88
	v_add_f32_e32 v84, 1.0, v84
	v_rcp_f32_e32 v99, v84
	v_mul_f32_e32 v84, 0xbfb8aa3b, v90
	v_exp_f32_e32 v84, v84
	v_exp_f32_e32 v92, v92
	v_add_f32_e32 v88, 1.0, v88
	v_rcp_f32_e32 v101, v88
	v_add_f32_e32 v84, 1.0, v84
	v_rcp_f32_e32 v98, v84
	v_add_f32_e32 v84, 1.0, v92
	v_rcp_f32_e32 v100, v84
	s_mov_b64 s[10:11], 0
	v_pk_mul_f32 v[98:99], v[82:83], v[98:99]
	v_pk_mul_f32 v[100:101], v[86:87], v[100:101]
.LBB0_373:
	s_andn2_b64 vcc, exec, s[10:11]
	s_cbranch_vccnz .LBB0_379
	s_cmp_eq_u32 s7, 1
	s_cbranch_scc0 .LBB0_378
	s_and_saveexec_b64 s[10:11], s[0:1]
	s_cbranch_execz .LBB0_377
	v_add_u32_e32 v84, s6, v103
	v_readlane_b32 s12, v254, 53
	v_lshlrev_b32_e32 v88, 3, v1
	s_nop 0
	v_and_b32_e32 v84, s12, v84
	v_lshl_or_b32 v84, v84, 6, v88
	s_waitcnt vmcnt(0)
	v_mov_b32_e32 v98, v166
	v_mov_b32_e32 v99, v167
	v_pk_mul_f32 v[94:95], v[94:95], v[98:99]
	v_pk_mul_f32 v[86:87], v[86:87], v[98:99] op_sel:[0,1]
	s_nop 0
	v_pk_fma_f32 v[82:83], v[82:83], v[98:99], v[86:87] op_sel_hi:[1,0,1] neg_lo:[0,0,1] neg_hi:[0,0,1]
	v_pk_fma_f32 v[86:87], v[90:91], v[98:99], v[94:95] op_sel:[0,1,0] op_sel_hi:[1,0,1]

.LBB0_379:
	v_add_u32_e32 v94, 0x210, v102
	v_cvt_pk_bf16_f32 v82, v99, s0
	v_lshl_add_u32 v83, v134, 1, v94
	ds_write_b16 v83, v82
	v_cvt_pk_bf16_f32 v82, v101, s0
	ds_write_b16 v83, v82 offset:32
	v_cvt_pk_bf16_f32 v82, v98, s0
	ds_write_b16 v83, v82 offset:256
	v_cvt_pk_bf16_f32 v82, v100, s0
	v_or_b32_e32 v95, 35, v144
	ds_write_b16 v83, v82 offset:288
	v_lshl_add_u32 v82, v95, 2, v220
	v_mov_b32_e32 v82, v231
	v_mov_b32_e32 v88, v97
	v_mov_b32_e32 v84, v93
	s_cmp_gt_i32 s7, 1
	s_mov_b64 s[10:11], -1
	v_pk_mul_f32 v[86:87], v[88:89], v[82:83] op_sel_hi:[1,0]
	v_mov_b32_e32 v88, v93
	v_pk_mul_f32 v[90:91], v[84:85], v[82:83] op_sel_hi:[1,0]
	v_pk_mul_f32 v[84:85], v[88:89], v[82:83] op_sel_hi:[1,0]
	v_mov_b32_e32 v82, v86
	v_mov_b32_e32 v83, v91
	s_cbranch_scc0 .LBB0_381
	v_mul_f32_e32 v88, 0xbfb8aa3b, v91
	v_exp_f32_e32 v88, v88
	v_mul_f32_e32 v89, 0xbfb8aa3b, v85
	v_exp_f32_e32 v89, v89
	v_mul_f32_e32 v93, 0xbfb8aa3b, v84
	v_add_f32_e32 v88, 1.0, v88
	v_exp_f32_e32 v96, v93
	v_add_f32_e32 v92, 1.0, v89
	v_rcp_f32_e32 v89, v88
	v_mul_f32_e32 v88, 0xbfb8aa3b, v86
	v_exp_f32_e32 v88, v88
	v_rcp_f32_e32 v93, v92
	v_add_f32_e32 v92, 1.0, v96
	v_rcp_f32_e32 v92, v92
	v_add_f32_e32 v88, 1.0, v88
	v_rcp_f32_e32 v88, v88
	s_mov_b64 s[10:11], 0
	v_pk_mul_f32 v[92:93], v[84:85], v[92:93]
	v_pk_mul_f32 v[88:89], v[82:83], v[88:89]
.LBB0_381:
	s_andn2_b64 vcc, exec, s[10:11]
	s_cbranch_vccnz .LBB0_387
	s_cmp_eq_u32 s7, 1
	s_cbranch_scc0 .LBB0_386
	s_and_saveexec_b64 s[10:11], s[0:1]
	s_cbranch_execz .LBB0_385
	v_add_u32_e32 v88, s6, v95
	v_readlane_b32 s12, v254, 53
	v_lshlrev_b32_e32 v89, 3, v1
	s_nop 0
	v_and_b32_e32 v88, s12, v88
	v_lshl_or_b32 v88, v88, 6, v89
	s_waitcnt vmcnt(0)
	v_mov_b32_e32 v88, v168
	v_mov_b32_e32 v89, v169
	v_pk_mul_f32 v[90:91], v[90:91], v[88:89]
	v_pk_mul_f32 v[84:85], v[84:85], v[88:89] op_sel:[0,1]
	s_nop 0
	v_pk_fma_f32 v[82:83], v[82:83], v[88:89], v[84:85] op_sel_hi:[1,0,1] neg_lo:[0,0,1] neg_hi:[0,0,1]
	v_pk_fma_f32 v[84:85], v[86:87], v[88:89], v[90:91] op_sel:[0,1,0] op_sel_hi:[1,0,1]

.LBB0_387:
	v_add_u32_e32 v94, 0x210, v94
	v_cvt_pk_bf16_f32 v82, v89, s0
	v_lshl_add_u32 v83, v134, 1, v94
	ds_write_b16 v83, v82
	v_cvt_pk_bf16_f32 v82, v93, s0
	ds_write_b16 v83, v82 offset:32
	v_cvt_pk_bf16_f32 v82, v88, s0
	ds_write_b16 v83, v82 offset:256
	v_cvt_pk_bf16_f32 v82, v92, s0
	v_or_b32_e32 v95, 48, v144
	ds_write_b16 v83, v82 offset:288
	v_lshl_add_u32 v82, v95, 2, v220
	v_mov_b32_e32 v82, v232
	v_mov_b32_e32 v84, v78
	v_mov_b32_e32 v85, v70
	v_mov_b32_e32 v88, v74
	v_mov_b32_e32 v89, v70
	v_mov_b32_e32 v90, v74
	v_mov_b32_e32 v91, v66
	v_pk_mul_f32 v[86:87], v[84:85], v[82:83] op_sel_hi:[1,0]
	v_pk_mul_f32 v[84:85], v[88:89], v[82:83] op_sel_hi:[1,0]
	v_pk_mul_f32 v[88:89], v[90:91], v[82:83] op_sel_hi:[1,0]
	v_mov_b32_e32 v82, v86
	v_mov_b32_e32 v83, v89
	s_cmp_gt_i32 s7, 1
	s_mov_b64 s[10:11], -1
	s_cbranch_scc0 .LBB0_389
	v_mul_f32_e32 v66, 0xbfb8aa3b, v89
	v_exp_f32_e32 v66, v66
	v_mul_f32_e32 v70, 0xbfb8aa3b, v85
	v_mul_f32_e32 v74, 0xbfb8aa3b, v84
	v_exp_f32_e32 v70, v70
	v_add_f32_e32 v66, 1.0, v66
	v_rcp_f32_e32 v91, v66
	v_mul_f32_e32 v66, 0xbfb8aa3b, v86
	v_exp_f32_e32 v66, v66
	v_exp_f32_e32 v74, v74
	v_add_f32_e32 v70, 1.0, v70
	v_rcp_f32_e32 v93, v70
	v_add_f32_e32 v66, 1.0, v66
	v_rcp_f32_e32 v90, v66
	v_add_f32_e32 v66, 1.0, v74
	v_rcp_f32_e32 v92, v66
	s_mov_b64 s[10:11], 0
	v_pk_mul_f32 v[90:91], v[82:83], v[90:91]
	v_pk_mul_f32 v[92:93], v[84:85], v[92:93]
.LBB0_389:
	s_andn2_b64 vcc, exec, s[10:11]
	s_cbranch_vccnz .LBB0_395
	s_cmp_eq_u32 s7, 1
	s_cbranch_scc0 .LBB0_394
	s_and_saveexec_b64 s[10:11], s[0:1]
	s_cbranch_execz .LBB0_393
	v_add_u32_e32 v66, s6, v95
	v_readlane_b32 s12, v254, 53
	v_lshlrev_b32_e32 v70, 3, v1
	s_nop 0
	v_and_b32_e32 v66, s12, v66
	v_lshl_or_b32 v66, v66, 6, v70
	s_waitcnt vmcnt(0)
	v_mov_b32_e32 v90, v170
	v_mov_b32_e32 v91, v171
	v_pk_mul_f32 v[88:89], v[88:89], v[90:91]
	v_pk_mul_f32 v[84:85], v[84:85], v[90:91] op_sel:[0,1]
	s_nop 0
	v_pk_fma_f32 v[82:83], v[82:83], v[90:91], v[84:85] op_sel_hi:[1,0,1] neg_lo:[0,0,1] neg_hi:[0,0,1]
	v_pk_fma_f32 v[84:85], v[86:87], v[90:91], v[88:89] op_sel:[0,1,0] op_sel_hi:[1,0,1]

.LBB0_395:
	v_add_u32_e32 v86, 0x1ad0, v94
	v_cvt_pk_bf16_f32 v66, v91, s0
	v_lshl_add_u32 v70, v134, 1, v86
	ds_write_b16 v70, v66
	v_cvt_pk_bf16_f32 v66, v93, s0
	ds_write_b16 v70, v66 offset:32
	v_cvt_pk_bf16_f32 v66, v90, s0
	ds_write_b16 v70, v66 offset:256
	v_cvt_pk_bf16_f32 v66, v92, s0
	v_or_b32_e32 v87, 49, v144
	ds_write_b16 v70, v66 offset:288
	v_lshl_add_u32 v66, v87, 2, v220
	v_mov_b32_e32 v82, v233
	v_mov_b32_e32 v70, v79
	v_mov_b32_e32 v66, v75
	s_cmp_gt_i32 s7, 1
	s_mov_b64 s[10:11], -1
	v_pk_mul_f32 v[78:79], v[70:71], v[82:83] op_sel_hi:[1,0]
	v_mov_b32_e32 v70, v75
	v_pk_mul_f32 v[74:75], v[66:67], v[82:83] op_sel_hi:[1,0]
	v_pk_mul_f32 v[70:71], v[70:71], v[82:83] op_sel_hi:[1,0]
	v_mov_b32_e32 v66, v78
	v_mov_b32_e32 v67, v75
	s_cbranch_scc0 .LBB0_397
	v_mul_f32_e32 v82, 0xbfb8aa3b, v75
	v_exp_f32_e32 v82, v82
	v_mul_f32_e32 v83, 0xbfb8aa3b, v71
	v_exp_f32_e32 v83, v83
	v_mul_f32_e32 v85, 0xbfb8aa3b, v70
	v_add_f32_e32 v82, 1.0, v82
	v_exp_f32_e32 v88, v85
	v_add_f32_e32 v84, 1.0, v83
	v_rcp_f32_e32 v83, v82
	v_mul_f32_e32 v82, 0xbfb8aa3b, v78
	v_exp_f32_e32 v82, v82
	v_rcp_f32_e32 v85, v84
	v_add_f32_e32 v84, 1.0, v88
	v_rcp_f32_e32 v84, v84
	v_add_f32_e32 v82, 1.0, v82
	v_rcp_f32_e32 v82, v82
	s_mov_b64 s[10:11], 0
	v_pk_mul_f32 v[84:85], v[70:71], v[84:85]
	v_pk_mul_f32 v[82:83], v[66:67], v[82:83]
.LBB0_397:
	s_andn2_b64 vcc, exec, s[10:11]
	s_cbranch_vccnz .LBB0_403
	s_cmp_eq_u32 s7, 1
	s_cbranch_scc0 .LBB0_402
	s_and_saveexec_b64 s[10:11], s[0:1]
	s_cbranch_execz .LBB0_401
	v_add_u32_e32 v82, s6, v87
	v_readlane_b32 s12, v254, 53
	v_lshlrev_b32_e32 v83, 3, v1
	s_nop 0
	v_and_b32_e32 v82, s12, v82
	v_lshl_or_b32 v82, v82, 6, v83
	s_waitcnt vmcnt(0)
	v_mov_b32_e32 v82, v172
	v_mov_b32_e32 v83, v173
	v_pk_mul_f32 v[74:75], v[74:75], v[82:83]
	v_pk_mul_f32 v[70:71], v[70:71], v[82:83] op_sel:[0,1]
	s_nop 0
	v_pk_fma_f32 v[66:67], v[66:67], v[82:83], v[70:71] op_sel_hi:[1,0,1] neg_lo:[0,0,1] neg_hi:[0,0,1]
	v_pk_fma_f32 v[70:71], v[78:79], v[82:83], v[74:75] op_sel:[0,1,0] op_sel_hi:[1,0,1]

.LBB0_403:
	v_add_u32_e32 v86, 0x210, v86
	v_cvt_pk_bf16_f32 v66, v83, s0
	v_lshl_add_u32 v67, v134, 1, v86
	ds_write_b16 v67, v66
	v_cvt_pk_bf16_f32 v66, v85, s0
	ds_write_b16 v67, v66 offset:32
	v_cvt_pk_bf16_f32 v66, v82, s0
	ds_write_b16 v67, v66 offset:256
	v_cvt_pk_bf16_f32 v66, v84, s0
	v_or_b32_e32 v87, 50, v144
	ds_write_b16 v67, v66 offset:288
	v_lshl_add_u32 v66, v87, 2, v220
	v_mov_b32_e32 v66, v234
	v_mov_b32_e32 v70, v80
	v_mov_b32_e32 v71, v72
	v_mov_b32_e32 v78, v76
	v_mov_b32_e32 v79, v72
	v_mov_b32_e32 v82, v76
	v_mov_b32_e32 v83, v68
	v_pk_mul_f32 v[74:75], v[70:71], v[66:67] op_sel_hi:[1,0]
	v_pk_mul_f32 v[70:71], v[78:79], v[66:67] op_sel_hi:[1,0]
	v_pk_mul_f32 v[78:79], v[82:83], v[66:67] op_sel_hi:[1,0]
	v_mov_b32_e32 v66, v74
	v_mov_b32_e32 v67, v79
	s_cmp_gt_i32 s7, 1
	s_mov_b64 s[10:11], -1
	s_cbranch_scc0 .LBB0_405
	v_mul_f32_e32 v68, 0xbfb8aa3b, v79
	v_exp_f32_e32 v68, v68
	v_mul_f32_e32 v72, 0xbfb8aa3b, v71
	v_mul_f32_e32 v76, 0xbfb8aa3b, v70
	v_exp_f32_e32 v72, v72
	v_add_f32_e32 v68, 1.0, v68
	v_rcp_f32_e32 v83, v68
	v_mul_f32_e32 v68, 0xbfb8aa3b, v74
	v_exp_f32_e32 v68, v68
	v_exp_f32_e32 v76, v76
	v_add_f32_e32 v72, 1.0, v72
	v_rcp_f32_e32 v85, v72
	v_add_f32_e32 v68, 1.0, v68
	v_rcp_f32_e32 v82, v68
	v_add_f32_e32 v68, 1.0, v76
	v_rcp_f32_e32 v84, v68
	s_mov_b64 s[10:11], 0
	v_pk_mul_f32 v[82:83], v[66:67], v[82:83]
	v_pk_mul_f32 v[84:85], v[70:71], v[84:85]
.LBB0_405:
	s_andn2_b64 vcc, exec, s[10:11]
	s_cbranch_vccnz .LBB0_411
	s_cmp_eq_u32 s7, 1
	s_cbranch_scc0 .LBB0_410
	s_and_saveexec_b64 s[10:11], s[0:1]
	s_cbranch_execz .LBB0_409
	v_add_u32_e32 v68, s6, v87
	v_readlane_b32 s12, v254, 53
	v_lshlrev_b32_e32 v72, 3, v1
	s_nop 0
	v_and_b32_e32 v68, s12, v68
	v_lshl_or_b32 v68, v68, 6, v72
	s_waitcnt vmcnt(0)
	v_mov_b32_e32 v82, v174
	v_mov_b32_e32 v83, v175
	v_pk_mul_f32 v[78:79], v[78:79], v[82:83]
	v_pk_mul_f32 v[70:71], v[70:71], v[82:83] op_sel:[0,1]
	s_nop 0
	v_pk_fma_f32 v[66:67], v[66:67], v[82:83], v[70:71] op_sel_hi:[1,0,1] neg_lo:[0,0,1] neg_hi:[0,0,1]
	v_pk_fma_f32 v[70:71], v[74:75], v[82:83], v[78:79] op_sel:[0,1,0] op_sel_hi:[1,0,1]

.LBB0_411:
	v_add_u32_e32 v78, 0x210, v86
	v_cvt_pk_bf16_f32 v66, v83, s0
	v_lshl_add_u32 v67, v134, 1, v78
	ds_write_b16 v67, v66
	v_cvt_pk_bf16_f32 v66, v85, s0
	ds_write_b16 v67, v66 offset:32
	v_cvt_pk_bf16_f32 v66, v82, s0
	ds_write_b16 v67, v66 offset:256
	v_cvt_pk_bf16_f32 v66, v84, s0
	v_or_b32_e32 v79, 51, v144
	ds_write_b16 v67, v66 offset:288
	v_lshl_add_u32 v66, v79, 2, v220
	v_mov_b32_e32 v66, v235
	v_mov_b32_e32 v72, v81
	v_mov_b32_e32 v68, v77
	s_cmp_gt_i32 s7, 1
	s_mov_b64 s[10:11], -1
	v_pk_mul_f32 v[70:71], v[72:73], v[66:67] op_sel_hi:[1,0]
	v_mov_b32_e32 v72, v77
	v_pk_mul_f32 v[74:75], v[68:69], v[66:67] op_sel_hi:[1,0]
	v_pk_mul_f32 v[68:69], v[72:73], v[66:67] op_sel_hi:[1,0]
	v_mov_b32_e32 v66, v70
	v_mov_b32_e32 v67, v75
	s_cbranch_scc0 .LBB0_413
	v_mul_f32_e32 v72, 0xbfb8aa3b, v75
	v_exp_f32_e32 v72, v72
	v_mul_f32_e32 v73, 0xbfb8aa3b, v69
	v_exp_f32_e32 v73, v73
	v_mul_f32_e32 v77, 0xbfb8aa3b, v68
	v_add_f32_e32 v72, 1.0, v72
	v_exp_f32_e32 v80, v77
	v_add_f32_e32 v76, 1.0, v73
	v_rcp_f32_e32 v73, v72
	v_mul_f32_e32 v72, 0xbfb8aa3b, v70
	v_exp_f32_e32 v72, v72
	v_rcp_f32_e32 v77, v76
	v_add_f32_e32 v76, 1.0, v80
	v_rcp_f32_e32 v76, v76
	v_add_f32_e32 v72, 1.0, v72
	v_rcp_f32_e32 v72, v72
	s_mov_b64 s[10:11], 0
	v_pk_mul_f32 v[76:77], v[68:69], v[76:77]
	v_pk_mul_f32 v[72:73], v[66:67], v[72:73]
.LBB0_413:
	s_andn2_b64 vcc, exec, s[10:11]
	s_cbranch_vccnz .LBB0_419
	s_cmp_eq_u32 s7, 1
	s_cbranch_scc0 .LBB0_418
	s_and_saveexec_b64 s[10:11], s[0:1]
	s_cbranch_execz .LBB0_417
	v_add_u32_e32 v72, s6, v79
	v_readlane_b32 s12, v254, 53
	v_lshlrev_b32_e32 v73, 3, v1
	s_nop 0
	v_and_b32_e32 v72, s12, v72
	v_lshl_or_b32 v72, v72, 6, v73
	s_waitcnt vmcnt(0)
	v_mov_b32_e32 v72, v176
	v_mov_b32_e32 v73, v177
	v_pk_mul_f32 v[74:75], v[74:75], v[72:73]
	v_pk_mul_f32 v[68:69], v[68:69], v[72:73] op_sel:[0,1]
	s_nop 0
	v_pk_fma_f32 v[66:67], v[66:67], v[72:73], v[68:69] op_sel_hi:[1,0,1] neg_lo:[0,0,1] neg_hi:[0,0,1]
	v_pk_fma_f32 v[68:69], v[70:71], v[72:73], v[74:75] op_sel:[0,1,0] op_sel_hi:[1,0,1]

.LBB0_419:
	v_add_u32_e32 v78, 0x210, v78
	v_cvt_pk_bf16_f32 v66, v73, s0
	v_lshl_add_u32 v67, v134, 1, v78
	ds_write_b16 v67, v66
	v_cvt_pk_bf16_f32 v66, v77, s0
	ds_write_b16 v67, v66 offset:32
	v_cvt_pk_bf16_f32 v66, v72, s0
	ds_write_b16 v67, v66 offset:256
	v_cvt_pk_bf16_f32 v66, v76, s0
	ds_write_b16 v67, v66 offset:288
	v_mov_b32_e32 v66, v236
	v_mov_b32_e32 v68, v62
	v_mov_b32_e32 v69, v54
	v_mov_b32_e32 v72, v58
	v_mov_b32_e32 v73, v54
	v_mov_b32_e32 v74, v58
	v_mov_b32_e32 v75, v50
	v_pk_mul_f32 v[70:71], v[68:69], v[66:67] op_sel_hi:[1,0]
	v_pk_mul_f32 v[68:69], v[72:73], v[66:67] op_sel_hi:[1,0]
	v_pk_mul_f32 v[72:73], v[74:75], v[66:67] op_sel_hi:[1,0]
	v_mov_b32_e32 v66, v70
	v_mov_b32_e32 v67, v73
	s_cmp_gt_i32 s7, 1
	s_mov_b64 s[10:11], -1
	s_cbranch_scc0 .LBB0_421
	v_mul_f32_e32 v50, 0xbfb8aa3b, v73
	v_exp_f32_e32 v50, v50
	v_mul_f32_e32 v54, 0xbfb8aa3b, v69
	v_mul_f32_e32 v58, 0xbfb8aa3b, v68
	v_exp_f32_e32 v54, v54
	v_add_f32_e32 v50, 1.0, v50
	v_rcp_f32_e32 v75, v50
	v_mul_f32_e32 v50, 0xbfb8aa3b, v70
	v_exp_f32_e32 v50, v50
	v_exp_f32_e32 v58, v58
	v_add_f32_e32 v54, 1.0, v54
	v_rcp_f32_e32 v77, v54
	v_add_f32_e32 v50, 1.0, v50
	v_rcp_f32_e32 v74, v50
	v_add_f32_e32 v50, 1.0, v58
	v_rcp_f32_e32 v76, v50
	s_mov_b64 s[10:11], 0
	v_pk_mul_f32 v[74:75], v[66:67], v[74:75]
	v_pk_mul_f32 v[76:77], v[68:69], v[76:77]
.LBB0_421:
	s_andn2_b64 vcc, exec, s[10:11]
	s_cbranch_vccnz .LBB0_427
	s_cmp_eq_u32 s7, 1
	s_cbranch_scc0 .LBB0_426
	s_and_saveexec_b64 s[10:11], s[0:1]
	s_cbranch_execz .LBB0_425
	v_add_u32_e32 v50, 0x80, v142
	v_readlane_b32 s12, v254, 53
	v_lshlrev_b32_e32 v54, 3, v1
	s_nop 0
	v_and_b32_e32 v50, s12, v50
	v_lshl_or_b32 v50, v50, 6, v54
	s_waitcnt vmcnt(0)
	v_mov_b32_e32 v74, v178
	v_mov_b32_e32 v75, v179
	v_pk_mul_f32 v[72:73], v[72:73], v[74:75]
	v_pk_mul_f32 v[68:69], v[68:69], v[74:75] op_sel:[0,1]
	s_nop 0
	v_pk_fma_f32 v[66:67], v[66:67], v[74:75], v[68:69] op_sel_hi:[1,0,1] neg_lo:[0,0,1] neg_hi:[0,0,1]
	v_pk_fma_f32 v[68:69], v[70:71], v[74:75], v[72:73] op_sel:[0,1,0] op_sel_hi:[1,0,1]

.LBB0_427:
	v_add_u32_e32 v70, 0x9ed0, v78
	v_cvt_pk_bf16_f32 v50, v75, s0
	v_lshl_add_u32 v54, v134, 1, v70
	v_mov_b32_e32 v66, v237
	ds_write_b16 v54, v50
	v_cvt_pk_bf16_f32 v50, v77, s0
	ds_write_b16 v54, v50 offset:32
	v_cvt_pk_bf16_f32 v50, v74, s0
	ds_write_b16 v54, v50 offset:256
	v_cvt_pk_bf16_f32 v50, v76, s0
	ds_write_b16 v54, v50 offset:288
	v_mov_b32_e32 v54, v63
	v_mov_b32_e32 v50, v59
	v_pk_mul_f32 v[62:63], v[54:55], v[66:67] op_sel_hi:[1,0]
	v_mov_b32_e32 v54, v59
	v_pk_mul_f32 v[58:59], v[50:51], v[66:67] op_sel_hi:[1,0]
	v_pk_mul_f32 v[54:55], v[54:55], v[66:67] op_sel_hi:[1,0]
	v_mov_b32_e32 v50, v62
	v_mov_b32_e32 v51, v59
	s_cmp_gt_i32 s7, 1
	s_mov_b64 s[10:11], -1
	s_cbranch_scc0 .LBB0_429
	v_mul_f32_e32 v66, 0xbfb8aa3b, v59
	v_exp_f32_e32 v66, v66
	v_mul_f32_e32 v67, 0xbfb8aa3b, v55
	v_exp_f32_e32 v67, v67
	v_mul_f32_e32 v69, 0xbfb8aa3b, v54
	v_add_f32_e32 v66, 1.0, v66
	v_exp_f32_e32 v71, v69
	v_add_f32_e32 v68, 1.0, v67
	v_rcp_f32_e32 v67, v66
	v_mul_f32_e32 v66, 0xbfb8aa3b, v62
	v_exp_f32_e32 v66, v66
	v_rcp_f32_e32 v69, v68
	v_add_f32_e32 v68, 1.0, v71
	v_rcp_f32_e32 v68, v68
	v_add_f32_e32 v66, 1.0, v66
	v_rcp_f32_e32 v66, v66
	s_mov_b64 s[10:11], 0
	v_pk_mul_f32 v[68:69], v[54:55], v[68:69]
	v_pk_mul_f32 v[66:67], v[50:51], v[66:67]
.LBB0_429:
	s_andn2_b64 vcc, exec, s[10:11]
	s_cbranch_vccnz .LBB0_435
	s_cmp_eq_u32 s7, 1
	s_cbranch_scc0 .LBB0_434
	s_and_saveexec_b64 s[10:11], s[0:1]
	s_cbranch_execz .LBB0_433
	v_add_u32_e32 v66, 0x81, v142
	v_readlane_b32 s12, v254, 53
	v_lshlrev_b32_e32 v67, 3, v1
	s_nop 0
	v_and_b32_e32 v66, s12, v66
	v_lshl_or_b32 v66, v66, 6, v67
	s_waitcnt vmcnt(0)
	v_mov_b32_e32 v66, v180
	v_mov_b32_e32 v67, v181
	v_pk_mul_f32 v[58:59], v[58:59], v[66:67]
	v_pk_mul_f32 v[54:55], v[54:55], v[66:67] op_sel:[0,1]
	s_nop 0
	v_pk_fma_f32 v[50:51], v[50:51], v[66:67], v[54:55] op_sel_hi:[1,0,1] neg_lo:[0,0,1] neg_hi:[0,0,1]
	v_pk_fma_f32 v[54:55], v[62:63], v[66:67], v[58:59] op_sel:[0,1,0] op_sel_hi:[1,0,1]

.LBB0_435:
	v_add_u32_e32 v70, 0x210, v70
	v_cvt_pk_bf16_f32 v50, v67, s0
	v_lshl_add_u32 v51, v134, 1, v70
	ds_write_b16 v51, v50
	v_cvt_pk_bf16_f32 v50, v69, s0
	ds_write_b16 v51, v50 offset:32
	v_cvt_pk_bf16_f32 v50, v66, s0
	ds_write_b16 v51, v50 offset:256
	v_cvt_pk_bf16_f32 v50, v68, s0
	ds_write_b16 v51, v50 offset:288
	v_mov_b32_e32 v50, v238
	v_mov_b32_e32 v54, v64
	v_mov_b32_e32 v55, v56
	v_mov_b32_e32 v62, v60
	v_mov_b32_e32 v63, v56
	v_mov_b32_e32 v66, v60
	v_mov_b32_e32 v67, v52
	v_pk_mul_f32 v[58:59], v[54:55], v[50:51] op_sel_hi:[1,0]
	v_pk_mul_f32 v[54:55], v[62:63], v[50:51] op_sel_hi:[1,0]
	v_pk_mul_f32 v[62:63], v[66:67], v[50:51] op_sel_hi:[1,0]
	v_mov_b32_e32 v50, v58
	v_mov_b32_e32 v51, v63
	s_cmp_gt_i32 s7, 1
	s_mov_b64 s[10:11], -1
	s_cbranch_scc0 .LBB0_437
	v_mul_f32_e32 v52, 0xbfb8aa3b, v63
	v_exp_f32_e32 v52, v52
	v_mul_f32_e32 v56, 0xbfb8aa3b, v55
	v_mul_f32_e32 v60, 0xbfb8aa3b, v54
	v_exp_f32_e32 v56, v56
	v_add_f32_e32 v52, 1.0, v52
	v_rcp_f32_e32 v67, v52
	v_mul_f32_e32 v52, 0xbfb8aa3b, v58
	v_exp_f32_e32 v52, v52
	v_exp_f32_e32 v60, v60
	v_add_f32_e32 v56, 1.0, v56
	v_rcp_f32_e32 v69, v56
	v_add_f32_e32 v52, 1.0, v52
	v_rcp_f32_e32 v66, v52
	v_add_f32_e32 v52, 1.0, v60
	v_rcp_f32_e32 v68, v52
	s_mov_b64 s[10:11], 0
	v_pk_mul_f32 v[66:67], v[50:51], v[66:67]
	v_pk_mul_f32 v[68:69], v[54:55], v[68:69]
.LBB0_437:
	s_andn2_b64 vcc, exec, s[10:11]
	s_cbranch_vccnz .LBB0_443
	s_cmp_eq_u32 s7, 1
	s_cbranch_scc0 .LBB0_442
	s_and_saveexec_b64 s[10:11], s[0:1]
	s_cbranch_execz .LBB0_441
	v_add_u32_e32 v52, 0x82, v142
	v_readlane_b32 s12, v254, 53
	v_lshlrev_b32_e32 v56, 3, v1
	s_nop 0
	v_and_b32_e32 v52, s12, v52
	v_lshl_or_b32 v52, v52, 6, v56
	s_waitcnt vmcnt(0)
	v_mov_b32_e32 v66, v182
	v_mov_b32_e32 v67, v183
	v_pk_mul_f32 v[62:63], v[62:63], v[66:67]
	v_pk_mul_f32 v[54:55], v[54:55], v[66:67] op_sel:[0,1]
	s_nop 0
	v_pk_fma_f32 v[50:51], v[50:51], v[66:67], v[54:55] op_sel_hi:[1,0,1] neg_lo:[0,0,1] neg_hi:[0,0,1]
	v_pk_fma_f32 v[54:55], v[58:59], v[66:67], v[62:63] op_sel:[0,1,0] op_sel_hi:[1,0,1]

.LBB0_443:
	v_add_u32_e32 v62, 0x210, v70
	v_cvt_pk_bf16_f32 v50, v67, s0
	v_lshl_add_u32 v51, v134, 1, v62
	ds_write_b16 v51, v50
	v_cvt_pk_bf16_f32 v50, v69, s0
	ds_write_b16 v51, v50 offset:32
	v_cvt_pk_bf16_f32 v50, v66, s0
	ds_write_b16 v51, v50 offset:256
	v_cvt_pk_bf16_f32 v50, v68, s0
	ds_write_b16 v51, v50 offset:288
	v_mov_b32_e32 v50, v239
	v_mov_b32_e32 v56, v65
	v_mov_b32_e32 v52, v61
	s_cmp_gt_i32 s7, 1
	s_mov_b64 s[10:11], -1
	v_pk_mul_f32 v[54:55], v[56:57], v[50:51] op_sel_hi:[1,0]
	v_mov_b32_e32 v56, v61
	v_pk_mul_f32 v[58:59], v[52:53], v[50:51] op_sel_hi:[1,0]
	v_pk_mul_f32 v[52:53], v[56:57], v[50:51] op_sel_hi:[1,0]
	v_mov_b32_e32 v50, v54
	v_mov_b32_e32 v51, v59
	s_cbranch_scc0 .LBB0_445
	v_mul_f32_e32 v56, 0xbfb8aa3b, v59
	v_exp_f32_e32 v56, v56
	v_mul_f32_e32 v57, 0xbfb8aa3b, v53
	v_exp_f32_e32 v57, v57
	v_mul_f32_e32 v61, 0xbfb8aa3b, v52
	v_add_f32_e32 v56, 1.0, v56
	v_exp_f32_e32 v63, v61
	v_add_f32_e32 v60, 1.0, v57
	v_rcp_f32_e32 v57, v56
	v_mul_f32_e32 v56, 0xbfb8aa3b, v54
	v_exp_f32_e32 v56, v56
	v_rcp_f32_e32 v61, v60
	v_add_f32_e32 v60, 1.0, v63
	v_rcp_f32_e32 v60, v60
	v_add_f32_e32 v56, 1.0, v56
	v_rcp_f32_e32 v56, v56
	s_mov_b64 s[10:11], 0
	v_pk_mul_f32 v[60:61], v[52:53], v[60:61]
	v_pk_mul_f32 v[56:57], v[50:51], v[56:57]
.LBB0_445:
	s_andn2_b64 vcc, exec, s[10:11]
	s_cbranch_vccnz .LBB0_451
	s_cmp_eq_u32 s7, 1
	s_cbranch_scc0 .LBB0_450
	s_and_saveexec_b64 s[10:11], s[0:1]
	s_cbranch_execz .LBB0_449
	v_add_u32_e32 v56, 0x83, v142
	v_readlane_b32 s12, v254, 53
	v_lshlrev_b32_e32 v57, 3, v1
	s_nop 0
	v_and_b32_e32 v56, s12, v56
	v_lshl_or_b32 v56, v56, 6, v57
	s_waitcnt vmcnt(0)
	v_mov_b32_e32 v56, v184
	v_mov_b32_e32 v57, v185
	v_pk_mul_f32 v[58:59], v[58:59], v[56:57]
	v_pk_mul_f32 v[52:53], v[52:53], v[56:57] op_sel:[0,1]
	s_nop 0
	v_pk_fma_f32 v[50:51], v[50:51], v[56:57], v[52:53] op_sel_hi:[1,0,1] neg_lo:[0,0,1] neg_hi:[0,0,1]
	v_pk_fma_f32 v[52:53], v[54:55], v[56:57], v[58:59] op_sel:[0,1,0] op_sel_hi:[1,0,1]

.LBB0_451:
	v_add_u32_e32 v62, 0x210, v62
	v_cvt_pk_bf16_f32 v50, v57, s0
	v_lshl_add_u32 v51, v134, 1, v62
	ds_write_b16 v51, v50
	v_cvt_pk_bf16_f32 v50, v61, s0
	ds_write_b16 v51, v50 offset:32
	v_cvt_pk_bf16_f32 v50, v56, s0
	ds_write_b16 v51, v50 offset:256
	v_cvt_pk_bf16_f32 v50, v60, s0
	ds_write_b16 v51, v50 offset:288
	v_mov_b32_e32 v50, v240
	v_mov_b32_e32 v52, v46
	v_mov_b32_e32 v53, v38
	v_mov_b32_e32 v56, v42
	v_mov_b32_e32 v57, v38
	v_mov_b32_e32 v58, v42
	v_mov_b32_e32 v59, v34
	v_pk_mul_f32 v[54:55], v[52:53], v[50:51] op_sel_hi:[1,0]
	v_pk_mul_f32 v[52:53], v[56:57], v[50:51] op_sel_hi:[1,0]
	v_pk_mul_f32 v[56:57], v[58:59], v[50:51] op_sel_hi:[1,0]
	v_mov_b32_e32 v50, v54
	v_mov_b32_e32 v51, v57
	s_cmp_gt_i32 s7, 1
	s_mov_b64 s[10:11], -1
	s_cbranch_scc0 .LBB0_453
	v_mul_f32_e32 v34, 0xbfb8aa3b, v57
	v_exp_f32_e32 v34, v34
	v_mul_f32_e32 v38, 0xbfb8aa3b, v53
	v_mul_f32_e32 v42, 0xbfb8aa3b, v52
	v_exp_f32_e32 v38, v38
	v_add_f32_e32 v34, 1.0, v34
	v_rcp_f32_e32 v59, v34
	v_mul_f32_e32 v34, 0xbfb8aa3b, v54
	v_exp_f32_e32 v34, v34
	v_exp_f32_e32 v42, v42
	v_add_f32_e32 v38, 1.0, v38
	v_rcp_f32_e32 v61, v38
	v_add_f32_e32 v34, 1.0, v34
	v_rcp_f32_e32 v58, v34
	v_add_f32_e32 v34, 1.0, v42
	v_rcp_f32_e32 v60, v34
	s_mov_b64 s[10:11], 0
	v_pk_mul_f32 v[58:59], v[50:51], v[58:59]
	v_pk_mul_f32 v[60:61], v[52:53], v[60:61]
.LBB0_453:
	s_andn2_b64 vcc, exec, s[10:11]
	s_cbranch_vccnz .LBB0_459
	s_cmp_eq_u32 s7, 1
	s_cbranch_scc0 .LBB0_458
	s_and_saveexec_b64 s[10:11], s[0:1]
	s_cbranch_execz .LBB0_457
	v_add_u32_e32 v34, 0x90, v142
	v_readlane_b32 s12, v254, 53
	v_lshlrev_b32_e32 v38, 3, v1
	s_nop 0
	v_and_b32_e32 v34, s12, v34
	v_lshl_or_b32 v34, v34, 6, v38
	s_waitcnt vmcnt(0)
	v_mov_b32_e32 v58, v186
	v_mov_b32_e32 v59, v187
	v_pk_mul_f32 v[56:57], v[56:57], v[58:59]
	v_pk_mul_f32 v[52:53], v[52:53], v[58:59] op_sel:[0,1]
	s_nop 0
	v_pk_fma_f32 v[50:51], v[50:51], v[58:59], v[52:53] op_sel_hi:[1,0,1] neg_lo:[0,0,1] neg_hi:[0,0,1]
	v_pk_fma_f32 v[52:53], v[54:55], v[58:59], v[56:57] op_sel:[0,1,0] op_sel_hi:[1,0,1]

.LBB0_459:
	v_add_u32_e32 v54, 0x1ad0, v62
	v_cvt_pk_bf16_f32 v34, v59, s0
	v_lshl_add_u32 v38, v134, 1, v54
	v_mov_b32_e32 v50, v241
	ds_write_b16 v38, v34
	v_cvt_pk_bf16_f32 v34, v61, s0
	ds_write_b16 v38, v34 offset:32
	v_cvt_pk_bf16_f32 v34, v58, s0
	ds_write_b16 v38, v34 offset:256
	v_cvt_pk_bf16_f32 v34, v60, s0
	ds_write_b16 v38, v34 offset:288
	v_mov_b32_e32 v38, v47
	v_mov_b32_e32 v34, v43
	v_pk_mul_f32 v[46:47], v[38:39], v[50:51] op_sel_hi:[1,0]
	v_mov_b32_e32 v38, v43
	v_pk_mul_f32 v[42:43], v[34:35], v[50:51] op_sel_hi:[1,0]
	v_pk_mul_f32 v[38:39], v[38:39], v[50:51] op_sel_hi:[1,0]
	v_mov_b32_e32 v34, v46
	v_mov_b32_e32 v35, v43
	s_cmp_gt_i32 s7, 1
	s_mov_b64 s[10:11], -1
	s_cbranch_scc0 .LBB0_461
	v_mul_f32_e32 v50, 0xbfb8aa3b, v43
	v_exp_f32_e32 v50, v50
	v_mul_f32_e32 v51, 0xbfb8aa3b, v39
	v_exp_f32_e32 v51, v51
	v_mul_f32_e32 v53, 0xbfb8aa3b, v38
	v_add_f32_e32 v50, 1.0, v50
	v_exp_f32_e32 v55, v53
	v_add_f32_e32 v52, 1.0, v51
	v_rcp_f32_e32 v51, v50
	v_mul_f32_e32 v50, 0xbfb8aa3b, v46
	v_exp_f32_e32 v50, v50
	v_rcp_f32_e32 v53, v52
	v_add_f32_e32 v52, 1.0, v55
	v_rcp_f32_e32 v52, v52
	v_add_f32_e32 v50, 1.0, v50
	v_rcp_f32_e32 v50, v50
	s_mov_b64 s[10:11], 0
	v_pk_mul_f32 v[52:53], v[38:39], v[52:53]
	v_pk_mul_f32 v[50:51], v[34:35], v[50:51]
.LBB0_461:
	s_andn2_b64 vcc, exec, s[10:11]
	s_cbranch_vccnz .LBB0_467
	s_cmp_eq_u32 s7, 1
	s_cbranch_scc0 .LBB0_466
	s_and_saveexec_b64 s[10:11], s[0:1]
	s_cbranch_execz .LBB0_465
	v_add_u32_e32 v50, 0x91, v142
	v_readlane_b32 s12, v254, 53
	v_lshlrev_b32_e32 v51, 3, v1
	s_nop 0
	v_and_b32_e32 v50, s12, v50
	v_lshl_or_b32 v50, v50, 6, v51
	s_waitcnt vmcnt(0)
	v_mov_b32_e32 v50, v188
	v_mov_b32_e32 v51, v189
	v_pk_mul_f32 v[42:43], v[42:43], v[50:51]
	v_pk_mul_f32 v[38:39], v[38:39], v[50:51] op_sel:[0,1]
	s_nop 0
	v_pk_fma_f32 v[34:35], v[34:35], v[50:51], v[38:39] op_sel_hi:[1,0,1] neg_lo:[0,0,1] neg_hi:[0,0,1]
	v_pk_fma_f32 v[38:39], v[46:47], v[50:51], v[42:43] op_sel:[0,1,0] op_sel_hi:[1,0,1]

.LBB0_467:
	v_add_u32_e32 v54, 0x210, v54
	v_cvt_pk_bf16_f32 v34, v51, s0
	v_lshl_add_u32 v35, v134, 1, v54
	ds_write_b16 v35, v34
	v_cvt_pk_bf16_f32 v34, v53, s0
	ds_write_b16 v35, v34 offset:32
	v_cvt_pk_bf16_f32 v34, v50, s0
	ds_write_b16 v35, v34 offset:256
	v_cvt_pk_bf16_f32 v34, v52, s0
	ds_write_b16 v35, v34 offset:288
	v_mov_b32_e32 v34, v242
	v_mov_b32_e32 v38, v48
	v_mov_b32_e32 v39, v40
	v_mov_b32_e32 v46, v44
	v_mov_b32_e32 v47, v40
	v_mov_b32_e32 v50, v44
	v_mov_b32_e32 v51, v36
	v_pk_mul_f32 v[42:43], v[38:39], v[34:35] op_sel_hi:[1,0]
	v_pk_mul_f32 v[38:39], v[46:47], v[34:35] op_sel_hi:[1,0]
	v_pk_mul_f32 v[46:47], v[50:51], v[34:35] op_sel_hi:[1,0]
	v_mov_b32_e32 v34, v42
	v_mov_b32_e32 v35, v47
	s_cmp_gt_i32 s7, 1
	s_mov_b64 s[10:11], -1
	s_cbranch_scc0 .LBB0_469
	v_mul_f32_e32 v36, 0xbfb8aa3b, v47
	v_exp_f32_e32 v36, v36
	v_mul_f32_e32 v40, 0xbfb8aa3b, v39
	v_mul_f32_e32 v44, 0xbfb8aa3b, v38
	v_exp_f32_e32 v40, v40
	v_add_f32_e32 v36, 1.0, v36
	v_rcp_f32_e32 v51, v36
	v_mul_f32_e32 v36, 0xbfb8aa3b, v42
	v_exp_f32_e32 v36, v36
	v_exp_f32_e32 v44, v44
	v_add_f32_e32 v40, 1.0, v40
	v_rcp_f32_e32 v53, v40
	v_add_f32_e32 v36, 1.0, v36
	v_rcp_f32_e32 v50, v36
	v_add_f32_e32 v36, 1.0, v44
	v_rcp_f32_e32 v52, v36
	s_mov_b64 s[10:11], 0
	v_pk_mul_f32 v[50:51], v[34:35], v[50:51]
	v_pk_mul_f32 v[52:53], v[38:39], v[52:53]
.LBB0_469:
	s_andn2_b64 vcc, exec, s[10:11]
	s_cbranch_vccnz .LBB0_475
	s_cmp_eq_u32 s7, 1
	s_cbranch_scc0 .LBB0_474
	s_and_saveexec_b64 s[10:11], s[0:1]
	s_cbranch_execz .LBB0_473
	v_add_u32_e32 v36, 0x92, v142
	v_readlane_b32 s12, v254, 53
	v_lshlrev_b32_e32 v40, 3, v1
	s_nop 0
	v_and_b32_e32 v36, s12, v36
	v_lshl_or_b32 v36, v36, 6, v40
	s_waitcnt vmcnt(0)
	v_mov_b32_e32 v50, v190
	v_mov_b32_e32 v51, v191
	v_pk_mul_f32 v[46:47], v[46:47], v[50:51]
	v_pk_mul_f32 v[38:39], v[38:39], v[50:51] op_sel:[0,1]
	s_nop 0
	v_pk_fma_f32 v[34:35], v[34:35], v[50:51], v[38:39] op_sel_hi:[1,0,1] neg_lo:[0,0,1] neg_hi:[0,0,1]
	v_pk_fma_f32 v[38:39], v[42:43], v[50:51], v[46:47] op_sel:[0,1,0] op_sel_hi:[1,0,1]

.LBB0_475:
	v_add_u32_e32 v46, 0x210, v54
	v_cvt_pk_bf16_f32 v34, v51, s0
	v_lshl_add_u32 v35, v134, 1, v46
	ds_write_b16 v35, v34
	v_cvt_pk_bf16_f32 v34, v53, s0
	ds_write_b16 v35, v34 offset:32
	v_cvt_pk_bf16_f32 v34, v50, s0
	ds_write_b16 v35, v34 offset:256
	v_cvt_pk_bf16_f32 v34, v52, s0
	ds_write_b16 v35, v34 offset:288
	v_mov_b32_e32 v34, v243
	v_mov_b32_e32 v40, v49
	v_mov_b32_e32 v36, v45
	s_cmp_gt_i32 s7, 1
	s_mov_b64 s[10:11], -1
	v_pk_mul_f32 v[38:39], v[40:41], v[34:35] op_sel_hi:[1,0]
	v_mov_b32_e32 v40, v45
	v_pk_mul_f32 v[42:43], v[36:37], v[34:35] op_sel_hi:[1,0]
	v_pk_mul_f32 v[36:37], v[40:41], v[34:35] op_sel_hi:[1,0]
	v_mov_b32_e32 v34, v38
	v_mov_b32_e32 v35, v43
	s_cbranch_scc0 .LBB0_477
	v_mul_f32_e32 v40, 0xbfb8aa3b, v43
	v_exp_f32_e32 v40, v40
	v_mul_f32_e32 v41, 0xbfb8aa3b, v37
	v_exp_f32_e32 v41, v41
	v_mul_f32_e32 v45, 0xbfb8aa3b, v36
	v_add_f32_e32 v40, 1.0, v40
	v_exp_f32_e32 v47, v45
	v_add_f32_e32 v44, 1.0, v41
	v_rcp_f32_e32 v41, v40
	v_mul_f32_e32 v40, 0xbfb8aa3b, v38
	v_exp_f32_e32 v40, v40
	v_rcp_f32_e32 v45, v44
	v_add_f32_e32 v44, 1.0, v47
	v_rcp_f32_e32 v44, v44
	v_add_f32_e32 v40, 1.0, v40
	v_rcp_f32_e32 v40, v40
	s_mov_b64 s[10:11], 0
	v_pk_mul_f32 v[44:45], v[36:37], v[44:45]
	v_pk_mul_f32 v[40:41], v[34:35], v[40:41]
.LBB0_477:
	s_andn2_b64 vcc, exec, s[10:11]
	s_cbranch_vccnz .LBB0_483
	s_cmp_eq_u32 s7, 1
	s_cbranch_scc0 .LBB0_482
	s_and_saveexec_b64 s[10:11], s[0:1]
	s_cbranch_execz .LBB0_481
	v_add_u32_e32 v40, 0x93, v142
	v_readlane_b32 s12, v254, 53
	v_lshlrev_b32_e32 v41, 3, v1
	s_nop 0
	v_and_b32_e32 v40, s12, v40
	v_lshl_or_b32 v40, v40, 6, v41
	s_waitcnt vmcnt(0)
	v_mov_b32_e32 v40, v192
	v_mov_b32_e32 v41, v193
	v_pk_mul_f32 v[42:43], v[42:43], v[40:41]
	v_pk_mul_f32 v[36:37], v[36:37], v[40:41] op_sel:[0,1]
	s_nop 0
	v_pk_fma_f32 v[34:35], v[34:35], v[40:41], v[36:37] op_sel_hi:[1,0,1] neg_lo:[0,0,1] neg_hi:[0,0,1]
	v_pk_fma_f32 v[36:37], v[38:39], v[40:41], v[42:43] op_sel:[0,1,0] op_sel_hi:[1,0,1]

.LBB0_483:
	v_add_u32_e32 v46, 0x210, v46
	v_cvt_pk_bf16_f32 v34, v41, s0
	v_lshl_add_u32 v35, v134, 1, v46
	ds_write_b16 v35, v34
	v_cvt_pk_bf16_f32 v34, v45, s0
	ds_write_b16 v35, v34 offset:32
	v_cvt_pk_bf16_f32 v34, v40, s0
	ds_write_b16 v35, v34 offset:256
	v_cvt_pk_bf16_f32 v34, v44, s0
	ds_write_b16 v35, v34 offset:288
	v_mov_b32_e32 v34, v244
	v_mov_b32_e32 v36, v30
	v_mov_b32_e32 v37, v22
	v_mov_b32_e32 v40, v26
	v_mov_b32_e32 v41, v22
	v_mov_b32_e32 v42, v26
	v_mov_b32_e32 v43, v18
	v_pk_mul_f32 v[38:39], v[36:37], v[34:35] op_sel_hi:[1,0]
	v_pk_mul_f32 v[36:37], v[40:41], v[34:35] op_sel_hi:[1,0]
	v_pk_mul_f32 v[40:41], v[42:43], v[34:35] op_sel_hi:[1,0]
	v_mov_b32_e32 v34, v38
	v_mov_b32_e32 v35, v41
	s_cmp_gt_i32 s7, 1
	s_mov_b64 s[10:11], -1
	s_cbranch_scc0 .LBB0_485
	v_mul_f32_e32 v18, 0xbfb8aa3b, v41
	v_exp_f32_e32 v18, v18
	v_mul_f32_e32 v22, 0xbfb8aa3b, v37
	v_mul_f32_e32 v26, 0xbfb8aa3b, v36
	v_exp_f32_e32 v22, v22
	v_add_f32_e32 v18, 1.0, v18
	v_rcp_f32_e32 v43, v18
	v_mul_f32_e32 v18, 0xbfb8aa3b, v38
	v_exp_f32_e32 v18, v18
	v_exp_f32_e32 v26, v26
	v_add_f32_e32 v22, 1.0, v22
	v_rcp_f32_e32 v45, v22
	v_add_f32_e32 v18, 1.0, v18
	v_rcp_f32_e32 v42, v18
	v_add_f32_e32 v18, 1.0, v26
	v_rcp_f32_e32 v44, v18
	s_mov_b64 s[10:11], 0
	v_pk_mul_f32 v[42:43], v[34:35], v[42:43]
	v_pk_mul_f32 v[44:45], v[36:37], v[44:45]
.LBB0_485:
	s_andn2_b64 vcc, exec, s[10:11]
	s_cbranch_vccnz .LBB0_491
	s_cmp_eq_u32 s7, 1
	s_cbranch_scc0 .LBB0_490
	s_and_saveexec_b64 s[10:11], s[0:1]
	s_cbranch_execz .LBB0_489
	v_add_u32_e32 v18, 0xa0, v142
	v_readlane_b32 s12, v254, 53
	v_lshlrev_b32_e32 v22, 3, v1
	s_nop 0
	v_and_b32_e32 v18, s12, v18
	v_lshl_or_b32 v18, v18, 6, v22
	s_waitcnt vmcnt(0)
	v_mov_b32_e32 v42, v194
	v_mov_b32_e32 v43, v195
	v_pk_mul_f32 v[40:41], v[40:41], v[42:43]
	v_pk_mul_f32 v[36:37], v[36:37], v[42:43] op_sel:[0,1]
	s_nop 0
	v_pk_fma_f32 v[34:35], v[34:35], v[42:43], v[36:37] op_sel_hi:[1,0,1] neg_lo:[0,0,1] neg_hi:[0,0,1]
	v_pk_fma_f32 v[36:37], v[38:39], v[42:43], v[40:41] op_sel:[0,1,0] op_sel_hi:[1,0,1]

.LBB0_491:
	v_add_u32_e32 v38, 0x1ad0, v46
	v_cvt_pk_bf16_f32 v18, v43, s0
	v_lshl_add_u32 v22, v134, 1, v38
	v_mov_b32_e32 v34, v245
	ds_write_b16 v22, v18
	v_cvt_pk_bf16_f32 v18, v45, s0
	ds_write_b16 v22, v18 offset:32
	v_cvt_pk_bf16_f32 v18, v42, s0
	ds_write_b16 v22, v18 offset:256
	v_cvt_pk_bf16_f32 v18, v44, s0
	ds_write_b16 v22, v18 offset:288
	v_mov_b32_e32 v22, v31
	v_mov_b32_e32 v18, v27
	v_pk_mul_f32 v[30:31], v[22:23], v[34:35] op_sel_hi:[1,0]
	v_mov_b32_e32 v22, v27
	v_pk_mul_f32 v[26:27], v[18:19], v[34:35] op_sel_hi:[1,0]
	v_pk_mul_f32 v[22:23], v[22:23], v[34:35] op_sel_hi:[1,0]
	v_mov_b32_e32 v18, v30
	v_mov_b32_e32 v19, v27
	s_cmp_gt_i32 s7, 1
	s_mov_b64 s[10:11], -1
	s_cbranch_scc0 .LBB0_493
	v_mul_f32_e32 v34, 0xbfb8aa3b, v27
	v_exp_f32_e32 v34, v34
	v_mul_f32_e32 v35, 0xbfb8aa3b, v23
	v_exp_f32_e32 v35, v35
	v_mul_f32_e32 v37, 0xbfb8aa3b, v22
	v_add_f32_e32 v34, 1.0, v34
	v_exp_f32_e32 v39, v37
	v_add_f32_e32 v36, 1.0, v35
	v_rcp_f32_e32 v35, v34
	v_mul_f32_e32 v34, 0xbfb8aa3b, v30
	v_exp_f32_e32 v34, v34
	v_rcp_f32_e32 v37, v36
	v_add_f32_e32 v36, 1.0, v39
	v_rcp_f32_e32 v36, v36
	v_add_f32_e32 v34, 1.0, v34
	v_rcp_f32_e32 v34, v34
	s_mov_b64 s[10:11], 0
	v_pk_mul_f32 v[36:37], v[22:23], v[36:37]
	v_pk_mul_f32 v[34:35], v[18:19], v[34:35]
.LBB0_493:
	s_andn2_b64 vcc, exec, s[10:11]
	s_cbranch_vccnz .LBB0_499
	s_cmp_eq_u32 s7, 1
	s_cbranch_scc0 .LBB0_498
	s_and_saveexec_b64 s[10:11], s[0:1]
	s_cbranch_execz .LBB0_497
	v_add_u32_e32 v34, 0xa1, v142
	v_readlane_b32 s12, v254, 53
	v_lshlrev_b32_e32 v35, 3, v1
	s_nop 0
	v_and_b32_e32 v34, s12, v34
	v_lshl_or_b32 v34, v34, 6, v35
	s_waitcnt vmcnt(0)
	v_mov_b32_e32 v34, v196
	v_mov_b32_e32 v35, v197
	v_pk_mul_f32 v[26:27], v[26:27], v[34:35]
	v_pk_mul_f32 v[22:23], v[22:23], v[34:35] op_sel:[0,1]
	s_nop 0
	v_pk_fma_f32 v[18:19], v[18:19], v[34:35], v[22:23] op_sel_hi:[1,0,1] neg_lo:[0,0,1] neg_hi:[0,0,1]
	v_pk_fma_f32 v[22:23], v[30:31], v[34:35], v[26:27] op_sel:[0,1,0] op_sel_hi:[1,0,1]

.LBB0_499:
	v_add_u32_e32 v38, 0x210, v38
	v_cvt_pk_bf16_f32 v18, v35, s0
	v_lshl_add_u32 v19, v134, 1, v38
	ds_write_b16 v19, v18
	v_cvt_pk_bf16_f32 v18, v37, s0
	ds_write_b16 v19, v18 offset:32
	v_cvt_pk_bf16_f32 v18, v34, s0
	ds_write_b16 v19, v18 offset:256
	v_cvt_pk_bf16_f32 v18, v36, s0
	ds_write_b16 v19, v18 offset:288
	v_mov_b32_e32 v18, v246
	v_mov_b32_e32 v22, v32
	v_mov_b32_e32 v23, v24
	v_mov_b32_e32 v30, v28
	v_mov_b32_e32 v31, v24
	v_mov_b32_e32 v34, v28
	v_mov_b32_e32 v35, v20
	v_pk_mul_f32 v[26:27], v[22:23], v[18:19] op_sel_hi:[1,0]
	v_pk_mul_f32 v[22:23], v[30:31], v[18:19] op_sel_hi:[1,0]
	v_pk_mul_f32 v[30:31], v[34:35], v[18:19] op_sel_hi:[1,0]
	v_mov_b32_e32 v18, v26
	v_mov_b32_e32 v19, v31
	s_cmp_gt_i32 s7, 1
	s_mov_b64 s[10:11], -1
	s_cbranch_scc0 .LBB0_501
	v_mul_f32_e32 v20, 0xbfb8aa3b, v31
	v_exp_f32_e32 v20, v20
	v_mul_f32_e32 v24, 0xbfb8aa3b, v23
	v_mul_f32_e32 v28, 0xbfb8aa3b, v22
	v_exp_f32_e32 v24, v24
	v_add_f32_e32 v20, 1.0, v20
	v_rcp_f32_e32 v35, v20
	v_mul_f32_e32 v20, 0xbfb8aa3b, v26
	v_exp_f32_e32 v20, v20
	v_exp_f32_e32 v28, v28
	v_add_f32_e32 v24, 1.0, v24
	v_rcp_f32_e32 v37, v24
	v_add_f32_e32 v20, 1.0, v20
	v_rcp_f32_e32 v34, v20
	v_add_f32_e32 v20, 1.0, v28
	v_rcp_f32_e32 v36, v20
	s_mov_b64 s[10:11], 0
	v_pk_mul_f32 v[34:35], v[18:19], v[34:35]
	v_pk_mul_f32 v[36:37], v[22:23], v[36:37]
.LBB0_501:
	s_andn2_b64 vcc, exec, s[10:11]
	s_cbranch_vccnz .LBB0_507
	s_cmp_eq_u32 s7, 1
	s_cbranch_scc0 .LBB0_506
	s_and_saveexec_b64 s[10:11], s[0:1]
	s_cbranch_execz .LBB0_505
	v_add_u32_e32 v20, 0xa2, v142
	v_readlane_b32 s12, v254, 53
	v_lshlrev_b32_e32 v24, 3, v1
	s_nop 0
	v_and_b32_e32 v20, s12, v20
	v_lshl_or_b32 v20, v20, 6, v24
	s_waitcnt vmcnt(0)
	v_mov_b32_e32 v34, v198
	v_mov_b32_e32 v35, v199
	v_pk_mul_f32 v[30:31], v[30:31], v[34:35]
	v_pk_mul_f32 v[22:23], v[22:23], v[34:35] op_sel:[0,1]
	s_nop 0
	v_pk_fma_f32 v[18:19], v[18:19], v[34:35], v[22:23] op_sel_hi:[1,0,1] neg_lo:[0,0,1] neg_hi:[0,0,1]
	v_pk_fma_f32 v[22:23], v[26:27], v[34:35], v[30:31] op_sel:[0,1,0] op_sel_hi:[1,0,1]

.LBB0_507:
	v_add_u32_e32 v30, 0x210, v38
	v_cvt_pk_bf16_f32 v18, v35, s0
	v_lshl_add_u32 v19, v134, 1, v30
	ds_write_b16 v19, v18
	v_cvt_pk_bf16_f32 v18, v37, s0
	ds_write_b16 v19, v18 offset:32
	v_cvt_pk_bf16_f32 v18, v34, s0
	ds_write_b16 v19, v18 offset:256
	v_cvt_pk_bf16_f32 v18, v36, s0
	ds_write_b16 v19, v18 offset:288
	v_mov_b32_e32 v18, v247
	v_mov_b32_e32 v24, v33
	v_mov_b32_e32 v20, v29
	s_cmp_gt_i32 s7, 1
	s_mov_b64 s[10:11], -1
	v_pk_mul_f32 v[22:23], v[24:25], v[18:19] op_sel_hi:[1,0]
	v_mov_b32_e32 v24, v29
	v_pk_mul_f32 v[26:27], v[20:21], v[18:19] op_sel_hi:[1,0]
	v_pk_mul_f32 v[20:21], v[24:25], v[18:19] op_sel_hi:[1,0]
	v_mov_b32_e32 v18, v22
	v_mov_b32_e32 v19, v27
	s_cbranch_scc0 .LBB0_509
	v_mul_f32_e32 v24, 0xbfb8aa3b, v27
	v_exp_f32_e32 v24, v24
	v_mul_f32_e32 v25, 0xbfb8aa3b, v21
	v_exp_f32_e32 v25, v25
	v_mul_f32_e32 v29, 0xbfb8aa3b, v20
	v_add_f32_e32 v24, 1.0, v24
	v_exp_f32_e32 v31, v29
	v_add_f32_e32 v28, 1.0, v25
	v_rcp_f32_e32 v25, v24
	v_mul_f32_e32 v24, 0xbfb8aa3b, v22
	v_exp_f32_e32 v24, v24
	v_rcp_f32_e32 v29, v28
	v_add_f32_e32 v28, 1.0, v31
	v_rcp_f32_e32 v28, v28
	v_add_f32_e32 v24, 1.0, v24
	v_rcp_f32_e32 v24, v24
	s_mov_b64 s[10:11], 0
	v_pk_mul_f32 v[28:29], v[20:21], v[28:29]
	v_pk_mul_f32 v[24:25], v[18:19], v[24:25]
.LBB0_509:
	s_andn2_b64 vcc, exec, s[10:11]
	s_cbranch_vccnz .LBB0_515
	s_cmp_eq_u32 s7, 1
	s_cbranch_scc0 .LBB0_514
	s_and_saveexec_b64 s[10:11], s[0:1]
	s_cbranch_execz .LBB0_513
	v_add_u32_e32 v24, 0xa3, v142
	v_readlane_b32 s12, v254, 53
	v_lshlrev_b32_e32 v25, 3, v1
	s_nop 0
	v_and_b32_e32 v24, s12, v24
	v_lshl_or_b32 v24, v24, 6, v25
	s_waitcnt vmcnt(0)
	v_mov_b32_e32 v24, v200
	v_mov_b32_e32 v25, v201
	v_pk_mul_f32 v[26:27], v[26:27], v[24:25]
	v_pk_mul_f32 v[20:21], v[20:21], v[24:25] op_sel:[0,1]
	s_nop 0
	v_pk_fma_f32 v[18:19], v[18:19], v[24:25], v[20:21] op_sel_hi:[1,0,1] neg_lo:[0,0,1] neg_hi:[0,0,1]
	v_pk_fma_f32 v[20:21], v[22:23], v[24:25], v[26:27] op_sel:[0,1,0] op_sel_hi:[1,0,1]

.LBB0_515:
	v_add_u32_e32 v30, 0x210, v30
	v_cvt_pk_bf16_f32 v18, v25, s0
	v_lshl_add_u32 v19, v134, 1, v30
	ds_write_b16 v19, v18
	v_cvt_pk_bf16_f32 v18, v29, s0
	ds_write_b16 v19, v18 offset:32
	v_cvt_pk_bf16_f32 v18, v24, s0
	ds_write_b16 v19, v18 offset:256
	v_cvt_pk_bf16_f32 v18, v28, s0
	ds_write_b16 v19, v18 offset:288
	v_mov_b32_e32 v18, v248
	v_mov_b32_e32 v20, v14
	v_mov_b32_e32 v21, v6
	v_mov_b32_e32 v24, v10
	v_mov_b32_e32 v25, v6
	v_mov_b32_e32 v26, v10
	v_mov_b32_e32 v27, v2
	v_pk_mul_f32 v[22:23], v[20:21], v[18:19] op_sel_hi:[1,0]
	v_pk_mul_f32 v[20:21], v[24:25], v[18:19] op_sel_hi:[1,0]
	v_pk_mul_f32 v[24:25], v[26:27], v[18:19] op_sel_hi:[1,0]
	v_mov_b32_e32 v18, v22
	v_mov_b32_e32 v19, v25
	s_cmp_gt_i32 s7, 1
	s_mov_b64 s[10:11], -1
	s_cbranch_scc0 .LBB0_517
	v_mul_f32_e32 v2, 0xbfb8aa3b, v25
	v_exp_f32_e32 v2, v2
	v_mul_f32_e32 v6, 0xbfb8aa3b, v21
	v_mul_f32_e32 v10, 0xbfb8aa3b, v20
	v_exp_f32_e32 v6, v6
	v_add_f32_e32 v2, 1.0, v2
	v_rcp_f32_e32 v27, v2
	v_mul_f32_e32 v2, 0xbfb8aa3b, v22
	v_exp_f32_e32 v2, v2
	v_exp_f32_e32 v10, v10
	v_add_f32_e32 v6, 1.0, v6
	v_rcp_f32_e32 v29, v6
	v_add_f32_e32 v2, 1.0, v2
	v_rcp_f32_e32 v26, v2
	v_add_f32_e32 v2, 1.0, v10
	v_rcp_f32_e32 v28, v2
	s_mov_b64 s[10:11], 0
	v_pk_mul_f32 v[26:27], v[18:19], v[26:27]
	v_pk_mul_f32 v[28:29], v[20:21], v[28:29]
.LBB0_517:
	s_andn2_b64 vcc, exec, s[10:11]
	s_cbranch_vccnz .LBB0_523
	s_cmp_eq_u32 s7, 1
	s_cbranch_scc0 .LBB0_522
	s_and_saveexec_b64 s[10:11], s[0:1]
	s_cbranch_execz .LBB0_521
	v_add_u32_e32 v2, 0xb0, v142
	v_readlane_b32 s12, v254, 53
	v_lshlrev_b32_e32 v6, 3, v1
	s_nop 0
	v_and_b32_e32 v2, s12, v2
	v_lshl_or_b32 v2, v2, 6, v6
	s_waitcnt vmcnt(0)
	v_mov_b32_e32 v26, v202
	v_mov_b32_e32 v27, v203
	v_pk_mul_f32 v[24:25], v[24:25], v[26:27]
	v_pk_mul_f32 v[20:21], v[20:21], v[26:27] op_sel:[0,1]
	s_nop 0
	v_pk_fma_f32 v[18:19], v[18:19], v[26:27], v[20:21] op_sel_hi:[1,0,1] neg_lo:[0,0,1] neg_hi:[0,0,1]
	v_pk_fma_f32 v[20:21], v[22:23], v[26:27], v[24:25] op_sel:[0,1,0] op_sel_hi:[1,0,1]

.LBB0_523:
	v_add_u32_e32 v22, 0x1ad0, v30
	v_cvt_pk_bf16_f32 v2, v27, s0
	v_lshl_add_u32 v6, v134, 1, v22
	v_mov_b32_e32 v18, v249
	ds_write_b16 v6, v2
	v_cvt_pk_bf16_f32 v2, v29, s0
	ds_write_b16 v6, v2 offset:32
	v_cvt_pk_bf16_f32 v2, v26, s0
	ds_write_b16 v6, v2 offset:256
	v_cvt_pk_bf16_f32 v2, v28, s0
	ds_write_b16 v6, v2 offset:288
	v_mov_b32_e32 v6, v15
	v_mov_b32_e32 v2, v11
	v_pk_mul_f32 v[14:15], v[6:7], v[18:19] op_sel_hi:[1,0]
	v_mov_b32_e32 v6, v11
	v_pk_mul_f32 v[10:11], v[2:3], v[18:19] op_sel_hi:[1,0]
	v_pk_mul_f32 v[6:7], v[6:7], v[18:19] op_sel_hi:[1,0]
	v_mov_b32_e32 v2, v14
	v_mov_b32_e32 v3, v11
	s_cmp_gt_i32 s7, 1
	s_mov_b64 s[10:11], -1
	s_cbranch_scc0 .LBB0_525
	v_mul_f32_e32 v18, 0xbfb8aa3b, v11
	v_exp_f32_e32 v18, v18
	v_mul_f32_e32 v19, 0xbfb8aa3b, v7
	v_exp_f32_e32 v19, v19
	v_mul_f32_e32 v21, 0xbfb8aa3b, v6
	v_add_f32_e32 v18, 1.0, v18
	v_exp_f32_e32 v23, v21
	v_add_f32_e32 v20, 1.0, v19
	v_rcp_f32_e32 v19, v18
	v_mul_f32_e32 v18, 0xbfb8aa3b, v14
	v_exp_f32_e32 v18, v18
	v_rcp_f32_e32 v21, v20
	v_add_f32_e32 v20, 1.0, v23
	v_rcp_f32_e32 v20, v20
	v_add_f32_e32 v18, 1.0, v18
	v_rcp_f32_e32 v18, v18
	s_mov_b64 s[10:11], 0
	v_pk_mul_f32 v[20:21], v[6:7], v[20:21]
	v_pk_mul_f32 v[18:19], v[2:3], v[18:19]
.LBB0_525:
	s_andn2_b64 vcc, exec, s[10:11]
	s_cbranch_vccnz .LBB0_531
	s_cmp_eq_u32 s7, 1
	s_cbranch_scc0 .LBB0_530
	s_and_saveexec_b64 s[10:11], s[0:1]
	s_cbranch_execz .LBB0_529
	v_add_u32_e32 v18, 0xb1, v142
	v_readlane_b32 s12, v254, 53
	v_lshlrev_b32_e32 v19, 3, v1
	s_nop 0
	v_and_b32_e32 v18, s12, v18
	v_lshl_or_b32 v18, v18, 6, v19
	s_waitcnt vmcnt(0)
	v_mov_b32_e32 v18, v204
	v_mov_b32_e32 v19, v205
	v_pk_mul_f32 v[10:11], v[10:11], v[18:19]
	v_pk_mul_f32 v[6:7], v[6:7], v[18:19] op_sel:[0,1]
	s_nop 0
	v_pk_fma_f32 v[2:3], v[2:3], v[18:19], v[6:7] op_sel_hi:[1,0,1] neg_lo:[0,0,1] neg_hi:[0,0,1]
	v_pk_fma_f32 v[6:7], v[14:15], v[18:19], v[10:11] op_sel:[0,1,0] op_sel_hi:[1,0,1]

.LBB0_531:
	v_add_u32_e32 v22, 0x210, v22
	v_cvt_pk_bf16_f32 v2, v19, s0
	v_lshl_add_u32 v3, v134, 1, v22
	ds_write_b16 v3, v2
	v_cvt_pk_bf16_f32 v2, v21, s0
	ds_write_b16 v3, v2 offset:32
	v_cvt_pk_bf16_f32 v2, v18, s0
	ds_write_b16 v3, v2 offset:256
	v_cvt_pk_bf16_f32 v2, v20, s0
	ds_write_b16 v3, v2 offset:288
	v_mov_b32_e32 v2, v250
	v_mov_b32_e32 v6, v16
	v_mov_b32_e32 v7, v8
	v_mov_b32_e32 v14, v12
	v_mov_b32_e32 v15, v8
	v_mov_b32_e32 v18, v12
	v_mov_b32_e32 v19, v4
	v_pk_mul_f32 v[10:11], v[6:7], v[2:3] op_sel_hi:[1,0]
	v_pk_mul_f32 v[6:7], v[14:15], v[2:3] op_sel_hi:[1,0]
	v_pk_mul_f32 v[14:15], v[18:19], v[2:3] op_sel_hi:[1,0]
	v_mov_b32_e32 v2, v10
	v_mov_b32_e32 v3, v15
	s_cmp_gt_i32 s7, 1
	s_mov_b64 s[10:11], -1
	s_cbranch_scc0 .LBB0_533
	v_mul_f32_e32 v4, 0xbfb8aa3b, v15
	v_exp_f32_e32 v4, v4
	v_mul_f32_e32 v8, 0xbfb8aa3b, v7
	v_mul_f32_e32 v12, 0xbfb8aa3b, v6
	v_exp_f32_e32 v8, v8
	v_add_f32_e32 v4, 1.0, v4
	v_rcp_f32_e32 v19, v4
	v_mul_f32_e32 v4, 0xbfb8aa3b, v10
	v_exp_f32_e32 v4, v4
	v_exp_f32_e32 v12, v12
	v_add_f32_e32 v8, 1.0, v8
	v_rcp_f32_e32 v21, v8
	v_add_f32_e32 v4, 1.0, v4
	v_rcp_f32_e32 v18, v4
	v_add_f32_e32 v4, 1.0, v12
	v_rcp_f32_e32 v20, v4
	s_mov_b64 s[10:11], 0
	v_pk_mul_f32 v[18:19], v[2:3], v[18:19]
	v_pk_mul_f32 v[20:21], v[6:7], v[20:21]
.LBB0_533:
	s_andn2_b64 vcc, exec, s[10:11]
	s_cbranch_vccnz .LBB0_539
	s_cmp_eq_u32 s7, 1
	s_cbranch_scc0 .LBB0_538
	s_and_saveexec_b64 s[10:11], s[0:1]
	s_cbranch_execz .LBB0_537
	v_add_u32_e32 v4, 0xb2, v142
	v_readlane_b32 s12, v254, 53
	v_lshlrev_b32_e32 v8, 3, v1
	s_nop 0
	v_and_b32_e32 v4, s12, v4
	v_lshl_or_b32 v4, v4, 6, v8
	s_waitcnt vmcnt(0)
	v_mov_b32_e32 v18, v206
	v_mov_b32_e32 v19, v207
	v_pk_mul_f32 v[14:15], v[14:15], v[18:19]
	v_pk_mul_f32 v[6:7], v[6:7], v[18:19] op_sel:[0,1]
	s_nop 0
	v_pk_fma_f32 v[2:3], v[2:3], v[18:19], v[6:7] op_sel_hi:[1,0,1] neg_lo:[0,0,1] neg_hi:[0,0,1]
	v_pk_fma_f32 v[6:7], v[10:11], v[18:19], v[14:15] op_sel:[0,1,0] op_sel_hi:[1,0,1]

.LBB0_539:
	v_add_u32_e32 v3, 0x210, v22
	v_cvt_pk_bf16_f32 v2, v19, s0
	v_lshl_add_u32 v14, v134, 1, v3
	ds_write_b16 v14, v2
	v_cvt_pk_bf16_f32 v2, v21, s0
	ds_write_b16 v14, v2 offset:32
	v_cvt_pk_bf16_f32 v2, v18, s0
	ds_write_b16 v14, v2 offset:256
	v_cvt_pk_bf16_f32 v2, v20, s0
	ds_write_b16 v14, v2 offset:288
	v_mov_b32_e32 v2, v251
	v_mov_b32_e32 v8, v17
	v_mov_b32_e32 v4, v13
	s_cmp_gt_i32 s7, 1
	s_mov_b64 s[10:11], -1
	v_pk_mul_f32 v[6:7], v[8:9], v[2:3] op_sel_hi:[1,0]
	v_mov_b32_e32 v8, v13
	v_pk_mul_f32 v[10:11], v[4:5], v[2:3] op_sel_hi:[1,0]
	v_pk_mul_f32 v[4:5], v[8:9], v[2:3] op_sel_hi:[1,0]
	v_mov_b32_e32 v2, v6
	v_mov_b32_e32 v3, v11
	s_cbranch_scc0 .LBB0_541
	v_mul_f32_e32 v8, 0xbfb8aa3b, v11
	v_exp_f32_e32 v8, v8
	v_mul_f32_e32 v9, 0xbfb8aa3b, v5
	v_exp_f32_e32 v9, v9
	v_mul_f32_e32 v13, 0xbfb8aa3b, v4
	v_add_f32_e32 v8, 1.0, v8
	v_exp_f32_e32 v15, v13
	v_add_f32_e32 v12, 1.0, v9
	v_rcp_f32_e32 v9, v8
	v_mul_f32_e32 v8, 0xbfb8aa3b, v6
	v_exp_f32_e32 v8, v8
	v_rcp_f32_e32 v13, v12
	v_add_f32_e32 v12, 1.0, v15
	v_rcp_f32_e32 v12, v12
	v_add_f32_e32 v8, 1.0, v8
	v_rcp_f32_e32 v8, v8
	s_mov_b64 s[10:11], 0
	v_pk_mul_f32 v[12:13], v[4:5], v[12:13]
	v_pk_mul_f32 v[8:9], v[2:3], v[8:9]
.LBB0_541:
	s_andn2_b64 vcc, exec, s[10:11]
	s_cbranch_vccnz .LBB0_547
	s_cmp_eq_u32 s7, 1
	s_cbranch_scc0 .LBB0_546
	s_and_saveexec_b64 s[10:11], s[0:1]
	s_cbranch_execz .LBB0_545
	v_add_u32_e32 v8, 0xb3, v142
	v_readlane_b32 s0, v254, 53
	v_lshlrev_b32_e32 v1, 3, v1
	s_nop 0
	v_and_b32_e32 v8, s0, v8
	v_lshl_or_b32 v1, v8, 6, v1
	s_waitcnt vmcnt(0)
	v_mov_b32_e32 v8, v208
	v_mov_b32_e32 v9, v209
	v_pk_mul_f32 v[10:11], v[10:11], v[8:9]
	v_pk_mul_f32 v[4:5], v[4:5], v[8:9] op_sel:[0,1]
	s_nop 0
	v_pk_fma_f32 v[2:3], v[2:3], v[8:9], v[4:5] op_sel_hi:[1,0,1] neg_lo:[0,0,1] neg_hi:[0,0,1]
	v_pk_fma_f32 v[4:5], v[6:7], v[8:9], v[10:11] op_sel:[0,1,0] op_sel_hi:[1,0,1]

.LBB0_706:
	v_mov_b32_e32 v1, v210
	s_ashr_i32 s1, s0, 31
	v_bfe_i32 v3, v1, 27, 1
	v_lshlrev_b32_e32 v138, 4, v1
	v_lshrrev_b32_e32 v3, 22, v3
	v_add_u32_e32 v3, v138, v3
	v_and_b32_e32 v3, 0xfffffc00, v3
	v_sub_u32_e32 v3, v138, v3
	v_lshrrev_b32_e32 v4, 4, v3
	v_bitop3_b32 v4, v4, v3, 32 bitop3:0x6c
	v_ashrrev_i32_e32 v3, 31, v3
	v_ashrrev_i32_e32 v2, 31, v1
	v_lshrrev_b32_e32 v3, 26, v3
	v_lshrrev_b32_e32 v2, 26, v2
	v_add_u32_e32 v3, v4, v3
	v_add_u32_e32 v2, v1, v2
	v_ashrrev_i32_e32 v3, 6, v3
	v_ashrrev_i32_e32 v2, 6, v2
	v_mul_i32_i24_e32 v6, 64, v3
	v_lshlrev_b32_e32 v5, 3, v2
	v_lshlrev_b32_e32 v2, 5, v2
	v_sub_u32_e32 v4, v4, v6
	v_and_b32_e32 v2, 32, v2
	v_ashrrev_i16_sdwa v4, v252, sext(v4) dst_sel:DWORD dst_unused:UNUSED_PAD src0_sel:DWORD src1_sel:BYTE_0
	v_add_u32_e32 v139, 0x2000, v138
	v_add_u32_sdwa v2, v2, sext(v4) dst_sel:DWORD dst_unused:UNUSED_PAD src0_sel:DWORD src1_sel:WORD_0
	v_ashrrev_i32_e32 v4, 31, v139
	v_lshrrev_b32_e32 v4, 22, v4
	v_add_u32_e32 v4, v139, v4
	v_ashrrev_i32_e32 v4, 10, v4
	s_lshr_b32 s1, s1, 30
	v_mul_i32_i24_e32 v6, 0x400, v4
	s_add_i32 s1, s0, s1
	v_sub_u32_e32 v6, v139, v6
	s_and_b32 s1, s1, 0xfffffc
	v_lshrrev_b32_e32 v7, 4, v6
	s_sub_i32 s1, s0, s1
	v_bitop3_b32 v6, v7, v6, 32 bitop3:0x6c
	s_lshl_b32 s0, s4, 8
	s_lshl_b32 s4, s1, 8
	v_ashrrev_i32_e32 v8, 31, v6
	v_lshrrev_b32_e32 v8, 26, v8
	s_ashr_i32 s5, s4, 31
	v_add_u32_e32 v8, v6, v8
	s_lshl_b64 s[6:7], s[4:5], 12
	v_and_b32_e32 v5, 0xffff0, v5
	v_lshrrev_b32_e32 v9, 6, v8
	v_and_b32_e32 v8, 0xc0, v8
	s_add_u32 s6, s19, s6
	v_add_u32_e32 v144, 0x10000, v138
	v_lshlrev_b32_e32 v7, 3, v4
	v_lshlrev_b32_e32 v4, 5, v4
	v_sub_u32_e32 v6, v6, v8
	v_add_lshl_u32 v3, v3, v5, 12
	s_addc_u32 s7, s20, s7
	v_readfirstlane_b32 s1, v144
	v_add_u32_e32 v145, 0x12000, v138
	v_and_b32_e32 v7, 0xffff0, v7
	v_and_b32_e32 v4, 32, v4
	v_ashrrev_i16_sdwa v6, v252, sext(v6) dst_sel:DWORD dst_unused:UNUSED_PAD src0_sel:DWORD src1_sel:BYTE_0
	v_lshl_add_u32 v132, v2, 1, v3
	s_mov_b64 s[8:9], s[6:7]
	s_mov_b32 m0, s1
	v_readfirstlane_b32 s1, v145
	v_add_u32_sdwa v4, v4, sext(v6) dst_sel:DWORD dst_unused:UNUSED_PAD src0_sel:DWORD src1_sel:WORD_0
	v_add_lshl_u32 v2, v9, v7, 12
	s_barrier
	v_lshl_add_u32 v130, v4, 1, v2
	global_load_lds_dwordx4 v132, s[8:9]
	s_mov_b32 m0, s1
	s_ashr_i32 s1, s0, 31
	s_lshl_b64 s[14:15], s[0:1], 12
	v_readlane_b32 s16, v254, 58
	global_load_lds_dwordx4 v130, s[8:9]
	s_add_u32 s8, s16, s14
	v_readlane_b32 s17, v254, 59
	s_addc_u32 s9, s17, s15
	v_readfirstlane_b32 s1, v138
	s_mov_b64 s[10:11], s[8:9]
	s_mov_b32 m0, s1
	v_readfirstlane_b32 s1, v139
	v_add_u32_e32 v146, 0x14000, v138
	global_load_lds_dwordx4 v132, s[10:11]
	s_mov_b32 m0, s1
	v_readfirstlane_b32 s1, v146
	global_load_lds_dwordx4 v130, s[10:11]
	s_or_b32 s10, s4, 0x80
	s_ashr_i32 s11, s10, 31
	s_lshl_b64 s[10:11], s[10:11], 12
	s_add_u32 s10, s19, s10
	s_addc_u32 s11, s20, s11
	v_add_u32_e32 v147, 0x16000, v138
	s_mov_b64 s[12:13], s[10:11]
	s_mov_b32 m0, s1
	v_readfirstlane_b32 s1, v147
	v_add_u32_e32 v148, 0x4000, v138
	global_load_lds_dwordx4 v132, s[12:13]
	s_mov_b32 m0, s1
	v_readfirstlane_b32 s1, v148
	global_load_lds_dwordx4 v130, s[12:13]
	s_or_b32 s12, s0, 0x80
	s_ashr_i32 s13, s12, 31
	s_lshl_b64 s[12:13], s[12:13], 12
	s_add_u32 s12, s16, s12
	s_addc_u32 s13, s17, s13
	v_add_u32_e32 v149, 0x6000, v138
	s_mov_b64 s[16:17], s[12:13]
	s_mov_b32 m0, s1
	v_readfirstlane_b32 s1, v149
	v_ashrrev_i32_e32 v2, 8, v1
	global_load_lds_dwordx4 v132, s[16:17]
	s_mov_b32 m0, s1
	v_cmp_eq_u32_e32 vcc, 1, v2
	global_load_lds_dwordx4 v130, s[16:17]
	s_and_saveexec_b64 s[16:17], vcc
	s_cbranch_execz .LBB0_708
	s_barrier
.LBB0_708:
	s_or_b64 exec, exec, s[16:17]
	s_add_u32 s16, s6, 0x80
	v_add_u32_e32 v150, 0x18000, v138
	v_mov_b32_e32 v133, v0
	s_addc_u32 s17, s7, 0
	v_readfirstlane_b32 s1, v150
	v_mov_b32_e32 v131, v0
	s_waitcnt vmcnt(4)
	s_barrier
	s_mov_b32 m0, s1
	v_lshl_add_u64 v[4:5], s[16:17], 0, v[132:133]
	v_add_u32_e32 v151, 0x1a000, v138
	global_load_lds_dwordx4 v[4:5], off
	v_lshl_add_u64 v[4:5], s[16:17], 0, v[130:131]
	v_readfirstlane_b32 s1, v151
	s_add_u32 s16, s8, 0x80
	v_add_u32_e32 v152, 0x8000, v138
	s_mov_b32 m0, s1
	s_addc_u32 s17, s9, 0
	v_readfirstlane_b32 s1, v152
	global_load_lds_dwordx4 v[4:5], off
	s_mov_b32 m0, s1
	v_lshl_add_u64 v[4:5], s[16:17], 0, v[132:133]
	v_add_u32_e32 v153, 0xa000, v138
	global_load_lds_dwordx4 v[4:5], off
	v_lshl_add_u64 v[4:5], s[16:17], 0, v[130:131]
	v_readfirstlane_b32 s1, v153
	s_add_u32 s16, s10, 0x80
	v_add_u32_e32 v154, 0x1c000, v138
	s_mov_b32 m0, s1
	s_addc_u32 s17, s11, 0
	v_readfirstlane_b32 s1, v154
	v_add_u32_e32 v155, 0x1e000, v138
	global_load_lds_dwordx4 v[4:5], off
	s_mov_b32 m0, s1
	v_lshl_add_u64 v[4:5], s[16:17], 0, v[132:133]
	v_readfirstlane_b32 s1, v155
	global_load_lds_dwordx4 v[4:5], off
	v_lshl_add_u64 v[4:5], s[16:17], 0, v[130:131]
	s_mov_b32 m0, s1
	v_bfe_u32 v136, v1, 4, 2
	global_load_lds_dwordx4 v[4:5], off
	v_bfe_u32 v134, v1, 6, 2
	v_and_b32_e32 v135, 15, v1
	v_lshlrev_b32_e32 v4, 4, v136
	v_lshlrev_b32_e32 v6, 2, v1
	v_lshlrev_b32_e32 v3, 12, v134
	v_lshl_or_b32 v5, v135, 6, v4
	v_and_b32_e32 v6, 32, v6
	v_bitop3_b32 v156, v5, v3, v6 bitop3:0xde
	v_lshlrev_b32_e32 v3, 6, v1
	s_movk_i32 s1, 0x3c0
	v_lshlrev_b32_e32 v137, 6, v2
	v_lshlrev_b32_e32 v2, 13, v2
	v_and_or_b32 v3, v3, s1, v4
	s_add_u32 s1, s12, 0x100
	s_waitcnt vmcnt(6)
	v_bitop3_b32 v140, v5, v2, v6 bitop3:0xde
	v_bitop3_b32 v2, v2, v3, v6 bitop3:0xf6
	s_addc_u32 s16, s13, 0
	v_or_b32_e32 v143, 0x800, v2
	v_or_b32_e32 v142, 0x1000, v2
	v_or_b32_e32 v141, 0x1800, v2
	s_add_u32 s17, s21, s14
	v_mov_b32_e32 v2, 0
	v_or_b32_e32 v157, 0x400, v156
	v_or_b32_e32 v158, 0x800, v156
	v_or_b32_e32 v159, 0xc00, v156
	s_addc_u32 s23, s22, s15
	s_mov_b32 s24, -2
	s_mov_b64 s[14:15], 0
	v_mov_b32_e32 v3, v2
	v_mov_b32_e32 v4, v2
	v_mov_b32_e32 v5, v2
	v_mov_b32_e32 v6, v2
	v_mov_b32_e32 v7, v2
	v_mov_b32_e32 v8, v2
	v_mov_b32_e32 v9, v2
	v_mov_b32_e32 v10, v2
	v_mov_b32_e32 v11, v2
	v_mov_b32_e32 v12, v2
	v_mov_b32_e32 v13, v2
	v_mov_b32_e32 v14, v2
	v_mov_b32_e32 v15, v2
	v_mov_b32_e32 v16, v2
	v_mov_b32_e32 v17, v2
	v_mov_b32_e32 v18, v2
	v_mov_b32_e32 v19, v2
	v_mov_b32_e32 v20, v2
	v_mov_b32_e32 v21, v2
	v_mov_b32_e32 v22, v2
	v_mov_b32_e32 v23, v2
	v_mov_b32_e32 v24, v2
	v_mov_b32_e32 v25, v2
	v_mov_b32_e32 v26, v2
	v_mov_b32_e32 v27, v2
	v_mov_b32_e32 v28, v2
	v_mov_b32_e32 v29, v2
	v_mov_b32_e32 v30, v2
	v_mov_b32_e32 v31, v2
	v_mov_b32_e32 v32, v2
	v_mov_b32_e32 v33, v2
	v_mov_b32_e32 v34, v2
	v_mov_b32_e32 v35, v2
	v_mov_b32_e32 v36, v2
	v_mov_b32_e32 v37, v2
	v_mov_b32_e32 v38, v2
	v_mov_b32_e32 v39, v2
	v_mov_b32_e32 v40, v2
	v_mov_b32_e32 v41, v2
	v_mov_b32_e32 v42, v2
	v_mov_b32_e32 v43, v2
	v_mov_b32_e32 v44, v2
	v_mov_b32_e32 v45, v2
	v_mov_b32_e32 v46, v2
	v_mov_b32_e32 v47, v2
	v_mov_b32_e32 v48, v2
	v_mov_b32_e32 v49, v2
	v_mov_b32_e32 v50, v2
	v_mov_b32_e32 v51, v2
	v_mov_b32_e32 v52, v2
	v_mov_b32_e32 v53, v2
	v_mov_b32_e32 v54, v2
	v_mov_b32_e32 v55, v2
	v_mov_b32_e32 v56, v2
	v_mov_b32_e32 v57, v2
	v_mov_b32_e32 v58, v2
	v_mov_b32_e32 v59, v2
	v_mov_b32_e32 v60, v2
	v_mov_b32_e32 v61, v2
	v_mov_b32_e32 v62, v2
	v_mov_b32_e32 v63, v2
	v_mov_b32_e32 v64, v2
	v_mov_b32_e32 v65, v2
	v_mov_b32_e32 v66, v2
	v_mov_b32_e32 v67, v2
	v_mov_b32_e32 v68, v2
	v_mov_b32_e32 v69, v2
	v_mov_b32_e32 v70, v2
	v_mov_b32_e32 v71, v2
	v_mov_b32_e32 v72, v2
	v_mov_b32_e32 v73, v2
	v_mov_b32_e32 v74, v2
	v_mov_b32_e32 v75, v2
	v_mov_b32_e32 v76, v2
	v_mov_b32_e32 v77, v2
	v_mov_b32_e32 v78, v2
	v_mov_b32_e32 v79, v2
	v_mov_b32_e32 v80, v2
	v_mov_b32_e32 v81, v2
	v_mov_b32_e32 v82, v2
	v_mov_b32_e32 v83, v2
	v_mov_b32_e32 v84, v2
	v_mov_b32_e32 v85, v2
	v_mov_b32_e32 v86, v2
	v_mov_b32_e32 v87, v2
	v_mov_b32_e32 v88, v2
	v_mov_b32_e32 v89, v2
	v_mov_b32_e32 v90, v2
	v_mov_b32_e32 v91, v2
	v_mov_b32_e32 v92, v2
	v_mov_b32_e32 v93, v2
	v_mov_b32_e32 v94, v2
	v_mov_b32_e32 v95, v2
	v_mov_b32_e32 v96, v2
	v_mov_b32_e32 v97, v2
	v_mov_b32_e32 v98, v2
	v_mov_b32_e32 v99, v2
	v_mov_b32_e32 v100, v2
	v_mov_b32_e32 v101, v2
	v_mov_b32_e32 v102, v2
	v_mov_b32_e32 v103, v2
	v_mov_b32_e32 v104, v2
	v_mov_b32_e32 v105, v2
	v_mov_b32_e32 v106, v2
	v_mov_b32_e32 v107, v2
	v_mov_b32_e32 v108, v2
	v_mov_b32_e32 v109, v2
	v_mov_b32_e32 v110, v2
	v_mov_b32_e32 v111, v2
	v_mov_b32_e32 v112, v2
	v_mov_b32_e32 v113, v2
	v_mov_b32_e32 v114, v2
	v_mov_b32_e32 v115, v2
	v_mov_b32_e32 v116, v2
	v_mov_b32_e32 v117, v2
	v_mov_b32_e32 v118, v2
	v_mov_b32_e32 v119, v2
	v_mov_b32_e32 v120, v2
	v_mov_b32_e32 v121, v2
	v_mov_b32_e32 v122, v2
	v_mov_b32_e32 v123, v2
	v_mov_b32_e32 v124, v2
	v_mov_b32_e32 v125, v2
	v_mov_b32_e32 v126, v2
	v_mov_b32_e32 v127, v2
	v_mov_b32_e32 v128, v2
	v_mov_b32_e32 v129, v2
	s_barrier
.LBB0_709:
	v_or_b32_e32 v160, 0x10000, v156
	v_or_b32_e32 v162, 0x10000, v158
	v_or_b32_e32 v161, 0x10000, v157
	ds_read_b128 v[170:173], v160
	ds_read_b128 v[174:177], v161
	v_or_b32_e32 v163, 0x10000, v159
	ds_read_b128 v[178:181], v162
	ds_read_b128 v[182:185], v163
	s_add_u32 s25, s17, s14
	s_addc_u32 s27, s23, s15
	s_add_u32 s26, s25, 0x80
	v_add_u32_e32 v164, 0xc000, v138
	s_addc_u32 s27, s27, 0
	v_readfirstlane_b32 s25, v164
	v_add_u32_e32 v165, 0xe000, v138
	ds_read_b128 v[186:189], v140
	ds_read_b128 v[190:193], v140 offset:1024
	ds_read_b128 v[194:197], v143
	ds_read_b128 v[198:201], v143 offset:1024
	ds_read_b128 v[202:205], v142
	ds_read_b128 v[206:209], v142 offset:1024
	ds_read_b128 v[212:215], v141
	ds_read_b128 v[224:227], v141 offset:1024
	s_mov_b32 m0, s25
	v_lshl_add_u64 v[166:167], s[26:27], 0, v[132:133]
	v_readfirstlane_b32 s25, v165
	global_load_lds_dwordx4 v[166:167], off
	v_lshl_add_u64 v[166:167], s[26:27], 0, v[130:131]
	s_mov_b32 m0, s25
	s_nop 0
	global_load_lds_dwordx4 v[166:167], off
	s_waitcnt lgkmcnt(8)
	s_barrier
	s_waitcnt lgkmcnt(0)
	s_setprio 1
	s_waitcnt lgkmcnt(0)
	v_mfma_f32_16x16x32_bf16 v[126:129], v[186:189], v[170:173], v[126:129]
	v_mfma_f32_16x16x32_bf16 v[122:125], v[186:189], v[178:181], v[122:125]
	v_mfma_f32_16x16x32_bf16 v[118:121], v[194:197], v[170:173], v[118:121]
	v_mfma_f32_16x16x32_bf16 v[114:117], v[194:197], v[178:181], v[114:117]
	v_mfma_f32_16x16x32_bf16 v[110:113], v[202:205], v[170:173], v[110:113]
	v_mfma_f32_16x16x32_bf16 v[106:109], v[202:205], v[178:181], v[106:109]
	v_mfma_f32_16x16x32_bf16 v[102:105], v[212:215], v[170:173], v[102:105]
	v_mfma_f32_16x16x32_bf16 v[98:101], v[212:215], v[178:181], v[98:101]
	v_mfma_f32_16x16x32_bf16 v[126:129], v[190:193], v[174:177], v[126:129]
	v_mfma_f32_16x16x32_bf16 v[122:125], v[190:193], v[182:185], v[122:125]
	v_mfma_f32_16x16x32_bf16 v[118:121], v[198:201], v[174:177], v[118:121]
	v_mfma_f32_16x16x32_bf16 v[114:117], v[198:201], v[182:185], v[114:117]
	v_mfma_f32_16x16x32_bf16 v[110:113], v[206:209], v[174:177], v[110:113]
	v_mfma_f32_16x16x32_bf16 v[106:109], v[206:209], v[182:185], v[106:109]
	v_mfma_f32_16x16x32_bf16 v[102:105], v[224:227], v[174:177], v[102:105]
	v_mfma_f32_16x16x32_bf16 v[98:101], v[224:227], v[182:185], v[98:101]
	s_setprio 0
	s_barrier
	s_add_u32 s25, s6, s14
	s_addc_u32 s28, s7, s15
	s_add_u32 s26, s25, 0x100
	v_or_b32_e32 v166, 0x14000, v156
	v_or_b32_e32 v168, 0x14000, v158
	s_addc_u32 s27, s28, 0
	v_readfirstlane_b32 s29, v144
	v_or_b32_e32 v167, 0x14000, v157
	ds_read_b128 v[228:231], v166
	ds_read_b128 v[232:235], v167
	v_or_b32_e32 v169, 0x14000, v159
	ds_read_b128 v[236:239], v168
	ds_read_b128 v[240:243], v169
	s_mov_b32 m0, s29
	v_lshl_add_u64 v[216:217], s[26:27], 0, v[132:133]
	global_load_lds_dwordx4 v[216:217], off
	v_lshl_add_u64 v[216:217], s[26:27], 0, v[130:131]
	v_readfirstlane_b32 s26, v145
	s_mov_b32 m0, s26
	s_nop 0
	global_load_lds_dwordx4 v[216:217], off
	s_barrier
	s_waitcnt lgkmcnt(0)
	s_setprio 1
	s_waitcnt lgkmcnt(0)
	v_mfma_f32_16x16x32_bf16 v[94:97], v[186:189], v[228:231], v[94:97]
	v_mfma_f32_16x16x32_bf16 v[90:93], v[186:189], v[236:239], v[90:93]
	v_mfma_f32_16x16x32_bf16 v[86:89], v[194:197], v[228:231], v[86:89]
	v_mfma_f32_16x16x32_bf16 v[82:85], v[194:197], v[236:239], v[82:85]
	v_mfma_f32_16x16x32_bf16 v[78:81], v[202:205], v[228:231], v[78:81]
	v_mfma_f32_16x16x32_bf16 v[74:77], v[202:205], v[236:239], v[74:77]
	v_mfma_f32_16x16x32_bf16 v[70:73], v[212:215], v[228:231], v[70:73]
	v_mfma_f32_16x16x32_bf16 v[66:69], v[212:215], v[236:239], v[66:69]
	v_mfma_f32_16x16x32_bf16 v[94:97], v[190:193], v[232:235], v[94:97]
	v_mfma_f32_16x16x32_bf16 v[90:93], v[190:193], v[240:243], v[90:93]
	v_mfma_f32_16x16x32_bf16 v[86:89], v[198:201], v[232:235], v[86:89]
	v_mfma_f32_16x16x32_bf16 v[82:85], v[198:201], v[240:243], v[82:85]
	v_mfma_f32_16x16x32_bf16 v[78:81], v[206:209], v[232:235], v[78:81]
	v_mfma_f32_16x16x32_bf16 v[74:77], v[206:209], v[240:243], v[74:77]
	v_mfma_f32_16x16x32_bf16 v[70:73], v[224:227], v[232:235], v[70:73]
	v_mfma_f32_16x16x32_bf16 v[66:69], v[224:227], v[240:243], v[66:69]
	s_setprio 0
	s_add_u32 s29, s8, s14
	s_addc_u32 s30, s9, s15
	s_add_u32 s26, s29, 0x100
	s_addc_u32 s27, s30, 0
	v_readfirstlane_b32 s31, v138
	s_barrier
	ds_read_b128 v[186:189], v140 offset:16384
	ds_read_b128 v[190:193], v140 offset:17408
	ds_read_b128 v[194:197], v143 offset:16384
	ds_read_b128 v[198:201], v143 offset:17408
	ds_read_b128 v[202:205], v142 offset:16384
	ds_read_b128 v[206:209], v142 offset:17408
	ds_read_b128 v[212:215], v141 offset:16384
	ds_read_b128 v[224:227], v141 offset:17408
	s_mov_b32 m0, s31
	v_lshl_add_u64 v[216:217], s[26:27], 0, v[132:133]
	global_load_lds_dwordx4 v[216:217], off
	v_lshl_add_u64 v[216:217], s[26:27], 0, v[130:131]
	v_readfirstlane_b32 s26, v139
	s_mov_b32 m0, s26
	s_nop 0
	global_load_lds_dwordx4 v[216:217], off
	s_barrier
	s_waitcnt lgkmcnt(0)
	s_setprio 1
	s_waitcnt lgkmcnt(0)
	v_mfma_f32_16x16x32_bf16 v[62:65], v[186:189], v[170:173], v[62:65]
	v_mfma_f32_16x16x32_bf16 v[58:61], v[186:189], v[178:181], v[58:61]
	v_mfma_f32_16x16x32_bf16 v[54:57], v[194:197], v[170:173], v[54:57]
	v_mfma_f32_16x16x32_bf16 v[50:53], v[194:197], v[178:181], v[50:53]
	v_mfma_f32_16x16x32_bf16 v[46:49], v[202:205], v[170:173], v[46:49]
	v_mfma_f32_16x16x32_bf16 v[42:45], v[202:205], v[178:181], v[42:45]
	v_mfma_f32_16x16x32_bf16 v[38:41], v[212:215], v[170:173], v[38:41]
	v_mfma_f32_16x16x32_bf16 v[34:37], v[212:215], v[178:181], v[34:37]
	v_mfma_f32_16x16x32_bf16 v[62:65], v[190:193], v[174:177], v[62:65]
	v_mfma_f32_16x16x32_bf16 v[58:61], v[190:193], v[182:185], v[58:61]
	v_mfma_f32_16x16x32_bf16 v[54:57], v[198:201], v[174:177], v[54:57]
	v_mfma_f32_16x16x32_bf16 v[50:53], v[198:201], v[182:185], v[50:53]
	v_mfma_f32_16x16x32_bf16 v[46:49], v[206:209], v[174:177], v[46:49]
	v_mfma_f32_16x16x32_bf16 v[42:45], v[206:209], v[182:185], v[42:45]
	v_mfma_f32_16x16x32_bf16 v[38:41], v[224:227], v[174:177], v[38:41]
	v_mfma_f32_16x16x32_bf16 v[34:37], v[224:227], v[182:185], v[34:37]
	s_setprio 0
	s_barrier
	s_add_u32 s31, s10, s14
	s_addc_u32 s34, s11, s15
	s_add_u32 s26, s31, 0x100
	s_addc_u32 s27, s34, 0
	v_readfirstlane_b32 s35, v146
	s_mov_b32 m0, s35
	v_lshl_add_u64 v[170:171], s[26:27], 0, v[132:133]
	global_load_lds_dwordx4 v[170:171], off
	v_lshl_add_u64 v[170:171], s[26:27], 0, v[130:131]
	v_readfirstlane_b32 s26, v147
	s_mov_b32 m0, s26
	s_nop 0
	global_load_lds_dwordx4 v[170:171], off
	s_waitcnt vmcnt(6)
	s_barrier
	s_setprio 1
	v_mfma_f32_16x16x32_bf16 v[30:33], v[186:189], v[228:231], v[30:33]
	v_mfma_f32_16x16x32_bf16 v[26:29], v[186:189], v[236:239], v[26:29]
	v_mfma_f32_16x16x32_bf16 v[22:25], v[194:197], v[228:231], v[22:25]
	v_mfma_f32_16x16x32_bf16 v[18:21], v[194:197], v[236:239], v[18:21]
	v_mfma_f32_16x16x32_bf16 v[14:17], v[202:205], v[228:231], v[14:17]
	v_mfma_f32_16x16x32_bf16 v[10:13], v[202:205], v[236:239], v[10:13]
	v_mfma_f32_16x16x32_bf16 v[6:9], v[212:215], v[228:231], v[6:9]
	v_mfma_f32_16x16x32_bf16 v[2:5], v[212:215], v[236:239], v[2:5]
	v_mfma_f32_16x16x32_bf16 v[30:33], v[190:193], v[232:235], v[30:33]
	v_mfma_f32_16x16x32_bf16 v[26:29], v[190:193], v[240:243], v[26:29]
	v_mfma_f32_16x16x32_bf16 v[22:25], v[198:201], v[232:235], v[22:25]
	v_mfma_f32_16x16x32_bf16 v[18:21], v[198:201], v[240:243], v[18:21]
	v_mfma_f32_16x16x32_bf16 v[14:17], v[206:209], v[232:235], v[14:17]
	v_mfma_f32_16x16x32_bf16 v[10:13], v[206:209], v[240:243], v[10:13]
	v_mfma_f32_16x16x32_bf16 v[6:9], v[224:227], v[232:235], v[6:9]
	v_mfma_f32_16x16x32_bf16 v[2:5], v[224:227], v[240:243], v[2:5]
	s_setprio 0
	v_or_b32_e32 v170, 0x18000, v156
	v_or_b32_e32 v172, 0x18000, v158
	s_barrier
	v_or_b32_e32 v171, 0x18000, v157
	ds_read_b128 v[178:181], v170
	ds_read_b128 v[182:185], v171
	v_or_b32_e32 v173, 0x18000, v159
	ds_read_b128 v[186:189], v172
	ds_read_b128 v[190:193], v173
	s_add_u32 s26, s1, s14
	s_addc_u32 s27, s16, s15
	v_readfirstlane_b32 s35, v148
	ds_read_b128 v[194:197], v140 offset:32768
	ds_read_b128 v[198:201], v140 offset:33792
	ds_read_b128 v[202:205], v143 offset:32768
	ds_read_b128 v[206:209], v143 offset:33792
	ds_read_b128 v[212:215], v142 offset:32768
	ds_read_b128 v[224:227], v142 offset:33792
	ds_read_b128 v[228:231], v141 offset:32768
	ds_read_b128 v[232:235], v141 offset:33792
	s_mov_b32 m0, s35
	v_lshl_add_u64 v[174:175], s[26:27], 0, v[132:133]
	global_load_lds_dwordx4 v[174:175], off
	v_lshl_add_u64 v[174:175], s[26:27], 0, v[130:131]
	v_readfirstlane_b32 s26, v149
	s_mov_b32 m0, s26
	s_nop 0
	global_load_lds_dwordx4 v[174:175], off
	s_waitcnt lgkmcnt(8)
	s_barrier
	s_waitcnt lgkmcnt(0)
	s_setprio 1
	s_waitcnt lgkmcnt(0)
	v_mfma_f32_16x16x32_bf16 v[126:129], v[194:197], v[178:181], v[126:129]
	v_mfma_f32_16x16x32_bf16 v[122:125], v[194:197], v[186:189], v[122:125]
	v_mfma_f32_16x16x32_bf16 v[118:121], v[202:205], v[178:181], v[118:121]
	v_mfma_f32_16x16x32_bf16 v[114:117], v[202:205], v[186:189], v[114:117]
	v_mfma_f32_16x16x32_bf16 v[110:113], v[212:215], v[178:181], v[110:113]
	v_mfma_f32_16x16x32_bf16 v[106:109], v[212:215], v[186:189], v[106:109]
	v_mfma_f32_16x16x32_bf16 v[102:105], v[228:231], v[178:181], v[102:105]
	v_mfma_f32_16x16x32_bf16 v[98:101], v[228:231], v[186:189], v[98:101]
	v_mfma_f32_16x16x32_bf16 v[126:129], v[198:201], v[182:185], v[126:129]
	v_mfma_f32_16x16x32_bf16 v[122:125], v[198:201], v[190:193], v[122:125]
	v_mfma_f32_16x16x32_bf16 v[118:121], v[206:209], v[182:185], v[118:121]
	v_mfma_f32_16x16x32_bf16 v[114:117], v[206:209], v[190:193], v[114:117]
	v_mfma_f32_16x16x32_bf16 v[110:113], v[224:227], v[182:185], v[110:113]
	v_mfma_f32_16x16x32_bf16 v[106:109], v[224:227], v[190:193], v[106:109]
	v_mfma_f32_16x16x32_bf16 v[102:105], v[232:235], v[182:185], v[102:105]
	v_mfma_f32_16x16x32_bf16 v[98:101], v[232:235], v[190:193], v[98:101]
	s_setprio 0
	s_barrier
	s_add_u32 s26, s25, 0x180
	v_or_b32_e32 v174, 0x1c000, v156
	v_or_b32_e32 v176, 0x1c000, v158
	s_addc_u32 s27, s28, 0
	v_readfirstlane_b32 s25, v150
	v_or_b32_e32 v175, 0x1c000, v157
	ds_read_b128 v[236:239], v174
	ds_read_b128 v[240:243], v175
	v_or_b32_e32 v177, 0x1c000, v159
	ds_read_b128 v[244:247], v176
	ds_read_b128 v[248:251], v177
	s_mov_b32 m0, s25
	v_lshl_add_u64 v[216:217], s[26:27], 0, v[132:133]
	v_readfirstlane_b32 s25, v151
	global_load_lds_dwordx4 v[216:217], off
	v_lshl_add_u64 v[216:217], s[26:27], 0, v[130:131]
	s_mov_b32 m0, s25
	s_nop 0
	global_load_lds_dwordx4 v[216:217], off
	s_barrier
	s_waitcnt lgkmcnt(0)
	s_setprio 1
	s_waitcnt lgkmcnt(0)
	v_mfma_f32_16x16x32_bf16 v[94:97], v[194:197], v[236:239], v[94:97]
	v_mfma_f32_16x16x32_bf16 v[90:93], v[194:197], v[244:247], v[90:93]
	v_mfma_f32_16x16x32_bf16 v[86:89], v[202:205], v[236:239], v[86:89]
	v_mfma_f32_16x16x32_bf16 v[82:85], v[202:205], v[244:247], v[82:85]
	v_mfma_f32_16x16x32_bf16 v[78:81], v[212:215], v[236:239], v[78:81]
	v_mfma_f32_16x16x32_bf16 v[74:77], v[212:215], v[244:247], v[74:77]
	v_mfma_f32_16x16x32_bf16 v[70:73], v[228:231], v[236:239], v[70:73]
	v_mfma_f32_16x16x32_bf16 v[66:69], v[228:231], v[244:247], v[66:69]
	v_mfma_f32_16x16x32_bf16 v[94:97], v[198:201], v[240:243], v[94:97]
	v_mfma_f32_16x16x32_bf16 v[90:93], v[198:201], v[248:251], v[90:93]
	v_mfma_f32_16x16x32_bf16 v[86:89], v[206:209], v[240:243], v[86:89]
	v_mfma_f32_16x16x32_bf16 v[82:85], v[206:209], v[248:251], v[82:85]
	v_mfma_f32_16x16x32_bf16 v[78:81], v[224:227], v[240:243], v[78:81]
	v_mfma_f32_16x16x32_bf16 v[74:77], v[224:227], v[248:251], v[74:77]
	v_mfma_f32_16x16x32_bf16 v[70:73], v[232:235], v[240:243], v[70:73]
	v_mfma_f32_16x16x32_bf16 v[66:69], v[232:235], v[248:251], v[66:69]
	s_setprio 0
	s_add_u32 s26, s29, 0x180
	s_addc_u32 s27, s30, 0
	v_readfirstlane_b32 s25, v152
	s_barrier
	ds_read_b128 v[194:197], v140 offset:49152
	ds_read_b128 v[198:201], v140 offset:50176
	ds_read_b128 v[202:205], v143 offset:49152
	ds_read_b128 v[206:209], v143 offset:50176
	ds_read_b128 v[212:215], v142 offset:49152
	ds_read_b128 v[224:227], v142 offset:50176
	ds_read_b128 v[228:231], v141 offset:49152
	ds_read_b128 v[232:235], v141 offset:50176
	s_mov_b32 m0, s25
	v_lshl_add_u64 v[216:217], s[26:27], 0, v[132:133]
	v_readfirstlane_b32 s25, v153
	global_load_lds_dwordx4 v[216:217], off
	v_lshl_add_u64 v[216:217], s[26:27], 0, v[130:131]
	s_mov_b32 m0, s25
	s_nop 0
	global_load_lds_dwordx4 v[216:217], off
	s_barrier
	s_waitcnt lgkmcnt(0)
	s_setprio 1
	s_waitcnt lgkmcnt(0)
	v_mfma_f32_16x16x32_bf16 v[62:65], v[194:197], v[178:181], v[62:65]
	v_mfma_f32_16x16x32_bf16 v[58:61], v[194:197], v[186:189], v[58:61]
	v_mfma_f32_16x16x32_bf16 v[54:57], v[202:205], v[178:181], v[54:57]
	v_mfma_f32_16x16x32_bf16 v[50:53], v[202:205], v[186:189], v[50:53]
	v_mfma_f32_16x16x32_bf16 v[46:49], v[212:215], v[178:181], v[46:49]
	v_mfma_f32_16x16x32_bf16 v[42:45], v[212:215], v[186:189], v[42:45]
	v_mfma_f32_16x16x32_bf16 v[38:41], v[228:231], v[178:181], v[38:41]
	v_mfma_f32_16x16x32_bf16 v[34:37], v[228:231], v[186:189], v[34:37]
	v_mfma_f32_16x16x32_bf16 v[62:65], v[198:201], v[182:185], v[62:65]
	v_mfma_f32_16x16x32_bf16 v[58:61], v[198:201], v[190:193], v[58:61]
	v_mfma_f32_16x16x32_bf16 v[54:57], v[206:209], v[182:185], v[54:57]
	v_mfma_f32_16x16x32_bf16 v[50:53], v[206:209], v[190:193], v[50:53]
	v_mfma_f32_16x16x32_bf16 v[46:49], v[224:227], v[182:185], v[46:49]
	v_mfma_f32_16x16x32_bf16 v[42:45], v[224:227], v[190:193], v[42:45]
	v_mfma_f32_16x16x32_bf16 v[38:41], v[232:235], v[182:185], v[38:41]
	v_mfma_f32_16x16x32_bf16 v[34:37], v[232:235], v[190:193], v[34:37]
	s_setprio 0
	s_barrier
	s_add_u32 s26, s31, 0x180
	s_addc_u32 s27, s34, 0
	v_readfirstlane_b32 s25, v154
	s_mov_b32 m0, s25
	v_lshl_add_u64 v[178:179], s[26:27], 0, v[132:133]
	v_readfirstlane_b32 s25, v155
	global_load_lds_dwordx4 v[178:179], off
	v_lshl_add_u64 v[178:179], s[26:27], 0, v[130:131]
	s_mov_b32 m0, s25
	s_nop 0
	global_load_lds_dwordx4 v[178:179], off
	s_waitcnt vmcnt(6)
	s_barrier
	s_setprio 1
	v_mfma_f32_16x16x32_bf16 v[30:33], v[194:197], v[236:239], v[30:33]
	v_mfma_f32_16x16x32_bf16 v[26:29], v[194:197], v[244:247], v[26:29]
	v_mfma_f32_16x16x32_bf16 v[22:25], v[202:205], v[236:239], v[22:25]
	v_mfma_f32_16x16x32_bf16 v[18:21], v[202:205], v[244:247], v[18:21]
	v_mfma_f32_16x16x32_bf16 v[14:17], v[212:215], v[236:239], v[14:17]
	v_mfma_f32_16x16x32_bf16 v[10:13], v[212:215], v[244:247], v[10:13]
	v_mfma_f32_16x16x32_bf16 v[6:9], v[228:231], v[236:239], v[6:9]
	v_mfma_f32_16x16x32_bf16 v[2:5], v[228:231], v[244:247], v[2:5]
	v_mfma_f32_16x16x32_bf16 v[30:33], v[198:201], v[240:243], v[30:33]
	v_mfma_f32_16x16x32_bf16 v[26:29], v[198:201], v[248:251], v[26:29]
	v_mfma_f32_16x16x32_bf16 v[22:25], v[206:209], v[240:243], v[22:25]
	v_mfma_f32_16x16x32_bf16 v[18:21], v[206:209], v[248:251], v[18:21]
	v_mfma_f32_16x16x32_bf16 v[14:17], v[224:227], v[240:243], v[14:17]
	v_mfma_f32_16x16x32_bf16 v[10:13], v[224:227], v[248:251], v[10:13]
	v_mfma_f32_16x16x32_bf16 v[6:9], v[232:235], v[240:243], v[6:9]
	v_mfma_f32_16x16x32_bf16 v[2:5], v[232:235], v[248:251], v[2:5]
	s_setprio 0
	s_add_i32 s24, s24, 2
	s_add_u32 s14, s14, 0x100
	s_addc_u32 s15, s15, 0
	s_cmp_lt_u32 s24, 28
	s_barrier
	s_cbranch_scc1 .LBB0_709
	s_add_u32 s6, s12, 0xf80
	s_addc_u32 s7, s13, 0
	v_readfirstlane_b32 s1, v164
	ds_read_b128 v[144:147], v160
	ds_read_b128 v[148:151], v161
	ds_read_b128 v[152:155], v162
	ds_read_b128 v[156:159], v163
	ds_read_b128 v[160:163], v140
	ds_read_b128 v[178:181], v140 offset:1024
	ds_read_b128 v[182:185], v143
	ds_read_b128 v[186:189], v143 offset:1024
	ds_read_b128 v[190:193], v142
	ds_read_b128 v[194:197], v142 offset:1024
	ds_read_b128 v[198:201], v141
	ds_read_b128 v[202:205], v141 offset:1024
	s_mov_b32 m0, s1
	v_lshl_add_u64 v[132:133], s[6:7], 0, v[132:133]
	v_readfirstlane_b32 s1, v165
	global_load_lds_dwordx4 v[132:133], off
	v_lshl_add_u64 v[130:131], s[6:7], 0, v[130:131]
	s_mov_b32 m0, s1
	s_nop 0
	global_load_lds_dwordx4 v[130:131], off
	s_barrier
	s_waitcnt lgkmcnt(0)
	s_setprio 1
	s_waitcnt lgkmcnt(0)
	v_mfma_f32_16x16x32_bf16 v[126:129], v[160:163], v[144:147], v[126:129]
	v_mfma_f32_16x16x32_bf16 v[122:125], v[160:163], v[152:155], v[122:125]
	v_mfma_f32_16x16x32_bf16 v[118:121], v[182:185], v[144:147], v[118:121]
	v_mfma_f32_16x16x32_bf16 v[114:117], v[182:185], v[152:155], v[114:117]
	v_mfma_f32_16x16x32_bf16 v[110:113], v[190:193], v[144:147], v[110:113]
	v_mfma_f32_16x16x32_bf16 v[106:109], v[190:193], v[152:155], v[106:109]
	v_mfma_f32_16x16x32_bf16 v[98:101], v[198:201], v[152:155], v[98:101]
	v_mfma_f32_16x16x32_bf16 v[126:129], v[178:181], v[148:151], v[126:129]
	v_mfma_f32_16x16x32_bf16 v[122:125], v[178:181], v[156:159], v[122:125]
	v_mfma_f32_16x16x32_bf16 v[118:121], v[186:189], v[148:151], v[118:121]
	v_mfma_f32_16x16x32_bf16 v[114:117], v[186:189], v[156:159], v[114:117]
	v_mfma_f32_16x16x32_bf16 v[110:113], v[194:197], v[148:151], v[110:113]
	v_mfma_f32_16x16x32_bf16 v[106:109], v[194:197], v[156:159], v[106:109]
	v_mfma_f32_16x16x32_bf16 v[102:105], v[198:201], v[144:147], v[102:105]
	v_mfma_f32_16x16x32_bf16 v[98:101], v[202:205], v[156:159], v[98:101]
	v_mfma_f32_16x16x32_bf16 v[130:133], v[202:205], v[148:151], v[102:105]
	s_setprio 0
	s_barrier
	s_nop 2
	ds_read_b128 v[102:105], v166
	ds_read_b128 v[164:167], v167
	ds_read_b128 v[206:209], v168
	ds_read_b128 v[212:215], v169
	s_barrier
	s_waitcnt lgkmcnt(0)
	s_setprio 1
	s_waitcnt lgkmcnt(1)
	v_mfma_f32_16x16x32_bf16 v[90:93], v[160:163], v[206:209], v[90:93]
	v_mfma_f32_16x16x32_bf16 v[94:97], v[160:163], v[102:105], v[94:97]
	s_waitcnt lgkmcnt(0)
	v_mfma_f32_16x16x32_bf16 v[90:93], v[178:181], v[212:215], v[90:93]
	v_mfma_f32_16x16x32_bf16 v[86:89], v[182:185], v[102:105], v[86:89]
	v_mfma_f32_16x16x32_bf16 v[82:85], v[182:185], v[206:209], v[82:85]
	v_mfma_f32_16x16x32_bf16 v[78:81], v[190:193], v[102:105], v[78:81]
	v_mfma_f32_16x16x32_bf16 v[74:77], v[190:193], v[206:209], v[74:77]
	v_mfma_f32_16x16x32_bf16 v[70:73], v[198:201], v[102:105], v[70:73]
	v_mfma_f32_16x16x32_bf16 v[66:69], v[198:201], v[206:209], v[66:69]
	v_mfma_f32_16x16x32_bf16 v[224:227], v[178:181], v[164:167], v[94:97]
	v_mfma_f32_16x16x32_bf16 v[160:163], v[186:189], v[164:167], v[86:89]
	v_mfma_f32_16x16x32_bf16 v[178:181], v[186:189], v[212:215], v[82:85]
	v_mfma_f32_16x16x32_bf16 v[182:185], v[194:197], v[164:167], v[78:81]
	v_mfma_f32_16x16x32_bf16 v[186:189], v[194:197], v[212:215], v[74:77]
	v_mfma_f32_16x16x32_bf16 v[190:193], v[202:205], v[164:167], v[70:73]
	v_mfma_f32_16x16x32_bf16 v[194:197], v[202:205], v[212:215], v[66:69]
	s_setprio 0
	s_barrier
	s_nop 0
	ds_read_b128 v[66:69], v140 offset:16384
	ds_read_b128 v[70:73], v140 offset:17408
	ds_read_b128 v[74:77], v143 offset:16384
	ds_read_b128 v[78:81], v143 offset:17408
	ds_read_b128 v[82:85], v142 offset:16384
	ds_read_b128 v[86:89], v142 offset:17408
	ds_read_b128 v[94:97], v141 offset:16384
	ds_read_b128 v[198:201], v141 offset:17408
	s_waitcnt vmcnt(4)
	s_barrier
	s_waitcnt lgkmcnt(0)
	s_setprio 1
	s_waitcnt lgkmcnt(7)
	v_mfma_f32_16x16x32_bf16 v[62:65], v[66:69], v[144:147], v[62:65]
	v_mfma_f32_16x16x32_bf16 v[58:61], v[66:69], v[152:155], v[58:61]
	s_waitcnt lgkmcnt(5)
	v_mfma_f32_16x16x32_bf16 v[54:57], v[74:77], v[144:147], v[54:57]
	v_mfma_f32_16x16x32_bf16 v[50:53], v[74:77], v[152:155], v[50:53]
	s_waitcnt lgkmcnt(3)
	v_mfma_f32_16x16x32_bf16 v[46:49], v[82:85], v[144:147], v[46:49]
	v_mfma_f32_16x16x32_bf16 v[42:45], v[82:85], v[152:155], v[42:45]
	s_waitcnt lgkmcnt(1)
	v_mfma_f32_16x16x32_bf16 v[38:41], v[94:97], v[144:147], v[38:41]
	v_mfma_f32_16x16x32_bf16 v[34:37], v[94:97], v[152:155], v[34:37]
	v_mfma_f32_16x16x32_bf16 v[62:65], v[70:73], v[148:151], v[62:65]
	v_mfma_f32_16x16x32_bf16 v[58:61], v[70:73], v[156:159], v[58:61]
	v_mfma_f32_16x16x32_bf16 v[54:57], v[78:81], v[148:151], v[54:57]
	v_mfma_f32_16x16x32_bf16 v[50:53], v[78:81], v[156:159], v[50:53]
	v_mfma_f32_16x16x32_bf16 v[46:49], v[86:89], v[148:151], v[46:49]
	v_mfma_f32_16x16x32_bf16 v[42:45], v[86:89], v[156:159], v[42:45]
	s_waitcnt lgkmcnt(0)
	v_mfma_f32_16x16x32_bf16 v[38:41], v[198:201], v[148:151], v[38:41]
	v_mfma_f32_16x16x32_bf16 v[34:37], v[198:201], v[156:159], v[34:37]
	s_setprio 0
	s_setprio 1
	v_mfma_f32_16x16x32_bf16 v[30:33], v[66:69], v[102:105], v[30:33]
	v_mfma_f32_16x16x32_bf16 v[26:29], v[66:69], v[206:209], v[26:29]
	v_mfma_f32_16x16x32_bf16 v[22:25], v[74:77], v[102:105], v[22:25]
	v_mfma_f32_16x16x32_bf16 v[18:21], v[74:77], v[206:209], v[18:21]
	v_mfma_f32_16x16x32_bf16 v[14:17], v[82:85], v[102:105], v[14:17]
	v_mfma_f32_16x16x32_bf16 v[10:13], v[82:85], v[206:209], v[10:13]
	v_mfma_f32_16x16x32_bf16 v[6:9], v[94:97], v[102:105], v[6:9]
	v_mfma_f32_16x16x32_bf16 v[2:5], v[94:97], v[206:209], v[2:5]
	v_mfma_f32_16x16x32_bf16 v[144:147], v[70:73], v[164:167], v[30:33]
	v_mfma_f32_16x16x32_bf16 v[148:151], v[70:73], v[212:215], v[26:29]
	v_mfma_f32_16x16x32_bf16 v[152:155], v[78:81], v[164:167], v[22:25]
	v_mfma_f32_16x16x32_bf16 v[156:159], v[78:81], v[212:215], v[18:21]
	v_mfma_f32_16x16x32_bf16 v[202:205], v[86:89], v[164:167], v[14:17]
	v_mfma_f32_16x16x32_bf16 v[228:231], v[86:89], v[212:215], v[10:13]
	v_mfma_f32_16x16x32_bf16 v[164:167], v[198:201], v[164:167], v[6:9]
	v_mfma_f32_16x16x32_bf16 v[198:201], v[198:201], v[212:215], v[2:5]
	s_setprio 0
	s_barrier
	s_nop 0
	ds_read_b128 v[2:5], v170
	ds_read_b128 v[6:9], v171
	ds_read_b128 v[168:171], v172
	ds_read_b128 v[206:209], v173
	ds_read_b128 v[10:13], v140 offset:32768
	ds_read_b128 v[14:17], v140 offset:33792
	ds_read_b128 v[18:21], v143 offset:32768
	ds_read_b128 v[22:25], v143 offset:33792
	ds_read_b128 v[26:29], v142 offset:32768
	ds_read_b128 v[30:33], v142 offset:33792
	ds_read_b128 v[212:215], v141 offset:32768
	ds_read_b128 v[232:235], v141 offset:33792
	s_waitcnt vmcnt(2)
	s_barrier
	s_waitcnt lgkmcnt(0)
	s_setprio 1
	s_waitcnt lgkmcnt(7)
	v_mfma_f32_16x16x32_bf16 v[66:69], v[10:13], v[2:5], v[126:129]
	s_waitcnt lgkmcnt(6)
	v_mfma_f32_16x16x32_bf16 v[94:97], v[14:17], v[6:9], v[66:69]
	v_mfma_f32_16x16x32_bf16 v[66:69], v[10:13], v[168:171], v[122:125]
	v_mfma_f32_16x16x32_bf16 v[102:105], v[14:17], v[206:209], v[66:69]
	s_waitcnt lgkmcnt(5)
	v_mfma_f32_16x16x32_bf16 v[66:69], v[18:21], v[2:5], v[118:121]
	s_waitcnt lgkmcnt(4)
	v_mfma_f32_16x16x32_bf16 v[82:85], v[22:25], v[6:9], v[66:69]
	v_mfma_f32_16x16x32_bf16 v[66:69], v[18:21], v[168:171], v[114:117]
	v_mfma_f32_16x16x32_bf16 v[86:89], v[22:25], v[206:209], v[66:69]
	s_waitcnt lgkmcnt(3)
	v_mfma_f32_16x16x32_bf16 v[66:69], v[26:29], v[2:5], v[110:113]
	s_waitcnt lgkmcnt(2)
	v_mfma_f32_16x16x32_bf16 v[74:77], v[30:33], v[6:9], v[66:69]
	v_mfma_f32_16x16x32_bf16 v[66:69], v[26:29], v[168:171], v[106:109]
	v_mfma_f32_16x16x32_bf16 v[78:81], v[30:33], v[206:209], v[66:69]
	s_waitcnt lgkmcnt(1)
	v_mfma_f32_16x16x32_bf16 v[66:69], v[212:215], v[2:5], v[130:133]
	v_mfma_f32_16x16x32_bf16 v[70:73], v[212:215], v[168:171], v[98:101]
	s_waitcnt lgkmcnt(0)
	v_mfma_f32_16x16x32_bf16 v[66:69], v[232:235], v[6:9], v[66:69]
	v_mfma_f32_16x16x32_bf16 v[70:73], v[232:235], v[206:209], v[70:73]
	s_setprio 0
	s_barrier
	ds_read_b128 v[130:133], v174
	ds_read_b128 v[172:175], v175
	ds_read_b128 v[236:239], v176
	ds_read_b128 v[240:243], v177
	s_waitcnt vmcnt(0)
	s_barrier
	s_waitcnt lgkmcnt(0)
	s_setprio 1
	s_waitcnt lgkmcnt(3)
	v_mfma_f32_16x16x32_bf16 v[98:101], v[10:13], v[130:133], v[224:227]
	s_waitcnt lgkmcnt(1)
	v_mfma_f32_16x16x32_bf16 v[10:13], v[10:13], v[236:239], v[90:93]
	s_waitcnt lgkmcnt(0)
	v_mfma_f32_16x16x32_bf16 v[126:129], v[14:17], v[240:243], v[10:13]
	v_mfma_f32_16x16x32_bf16 v[10:13], v[18:21], v[130:133], v[160:163]
	v_mfma_f32_16x16x32_bf16 v[114:117], v[22:25], v[172:175], v[10:13]
	v_mfma_f32_16x16x32_bf16 v[10:13], v[18:21], v[236:239], v[178:181]
	v_mfma_f32_16x16x32_bf16 v[118:121], v[22:25], v[240:243], v[10:13]
	v_mfma_f32_16x16x32_bf16 v[10:13], v[26:29], v[130:133], v[182:185]
	v_mfma_f32_16x16x32_bf16 v[106:109], v[30:33], v[172:175], v[10:13]
	v_mfma_f32_16x16x32_bf16 v[10:13], v[26:29], v[236:239], v[186:189]
	v_mfma_f32_16x16x32_bf16 v[110:113], v[30:33], v[240:243], v[10:13]
	v_mfma_f32_16x16x32_bf16 v[10:13], v[212:215], v[130:133], v[190:193]
	v_mfma_f32_16x16x32_bf16 v[90:93], v[232:235], v[172:175], v[10:13]
	v_mfma_f32_16x16x32_bf16 v[10:13], v[212:215], v[236:239], v[194:197]
	v_mfma_f32_16x16x32_bf16 v[122:125], v[14:17], v[172:175], v[98:101]
	v_mfma_f32_16x16x32_bf16 v[98:101], v[232:235], v[240:243], v[10:13]
	s_setprio 0
	s_barrier
	ds_read_b128 v[160:163], v140 offset:49152
	ds_read_b128 v[176:179], v140 offset:50176
	ds_read_b128 v[180:183], v143 offset:49152
	ds_read_b128 v[184:187], v143 offset:50176
	ds_read_b128 v[188:191], v142 offset:49152
	ds_read_b128 v[192:195], v142 offset:50176
	ds_read_b128 v[212:215], v141 offset:49152
	ds_read_b128 v[138:141], v141 offset:50176
	s_barrier
	s_waitcnt lgkmcnt(0)
	s_setprio 1
	s_waitcnt lgkmcnt(7)
	v_mfma_f32_16x16x32_bf16 v[10:13], v[160:163], v[2:5], v[62:65]
	s_waitcnt lgkmcnt(6)
	v_mfma_f32_16x16x32_bf16 v[26:29], v[176:179], v[6:9], v[10:13]
	v_mfma_f32_16x16x32_bf16 v[10:13], v[160:163], v[168:171], v[58:61]
	v_mfma_f32_16x16x32_bf16 v[30:33], v[176:179], v[206:209], v[10:13]
	s_waitcnt lgkmcnt(5)
	v_mfma_f32_16x16x32_bf16 v[10:13], v[180:183], v[2:5], v[54:57]
	s_waitcnt lgkmcnt(4)
	v_mfma_f32_16x16x32_bf16 v[18:21], v[184:187], v[6:9], v[10:13]
	v_mfma_f32_16x16x32_bf16 v[10:13], v[180:183], v[168:171], v[50:53]
	v_mfma_f32_16x16x32_bf16 v[22:25], v[184:187], v[206:209], v[10:13]
	s_waitcnt lgkmcnt(3)
	v_mfma_f32_16x16x32_bf16 v[10:13], v[188:191], v[2:5], v[46:49]
	s_waitcnt lgkmcnt(1)
	v_mfma_f32_16x16x32_bf16 v[2:5], v[212:215], v[2:5], v[38:41]
	v_mfma_f32_16x16x32_bf16 v[10:13], v[192:195], v[6:9], v[10:13]
	v_mfma_f32_16x16x32_bf16 v[14:17], v[188:191], v[168:171], v[42:45]
	s_waitcnt lgkmcnt(0)
	v_mfma_f32_16x16x32_bf16 v[2:5], v[138:141], v[6:9], v[2:5]
	v_mfma_f32_16x16x32_bf16 v[6:9], v[212:215], v[168:171], v[34:37]
	v_mfma_f32_16x16x32_bf16 v[14:17], v[192:195], v[206:209], v[14:17]
	v_mfma_f32_16x16x32_bf16 v[6:9], v[138:141], v[206:209], v[6:9]
	s_setprio 0
	s_setprio 1
	v_mfma_f32_16x16x32_bf16 v[34:37], v[160:163], v[130:133], v[144:147]
	v_mfma_f32_16x16x32_bf16 v[58:61], v[176:179], v[172:175], v[34:37]
	v_mfma_f32_16x16x32_bf16 v[34:37], v[160:163], v[236:239], v[148:151]
	v_mfma_f32_16x16x32_bf16 v[62:65], v[176:179], v[240:243], v[34:37]
	v_mfma_f32_16x16x32_bf16 v[34:37], v[180:183], v[130:133], v[152:155]
	v_mfma_f32_16x16x32_bf16 v[50:53], v[184:187], v[172:175], v[34:37]
	v_mfma_f32_16x16x32_bf16 v[34:37], v[180:183], v[236:239], v[156:159]
	v_mfma_f32_16x16x32_bf16 v[54:57], v[184:187], v[240:243], v[34:37]
	v_mfma_f32_16x16x32_bf16 v[34:37], v[188:191], v[130:133], v[202:205]
	v_mfma_f32_16x16x32_bf16 v[42:45], v[192:195], v[172:175], v[34:37]
	v_mfma_f32_16x16x32_bf16 v[34:37], v[188:191], v[236:239], v[228:231]
	v_mfma_f32_16x16x32_bf16 v[46:49], v[192:195], v[240:243], v[34:37]
	v_mfma_f32_16x16x32_bf16 v[34:37], v[212:215], v[130:133], v[164:167]
	v_mfma_f32_16x16x32_bf16 v[38:41], v[212:215], v[236:239], v[198:201]
	v_mfma_f32_16x16x32_bf16 v[34:37], v[138:141], v[172:175], v[34:37]
	v_mfma_f32_16x16x32_bf16 v[38:41], v[138:141], v[240:243], v[38:41]
	s_setprio 0
	s_movk_i32 s1, 0x100
	v_cmp_gt_u32_e32 vcc, s1, v1
	s_barrier
	s_and_saveexec_b64 s[6:7], vcc
	s_cbranch_execz .LBB0_712
	s_barrier

.LBB0_844:
	v_mov_b32_e32 v134, v210
	s_mul_hi_i32 s7, s6, 0x2aaaaaab
	v_bfe_i32 v2, v134, 27, 1
	v_lshlrev_b32_e32 v137, 4, v134
	v_lshrrev_b32_e32 v2, 22, v2
	v_add_u32_e32 v2, v137, v2
	v_and_b32_e32 v2, 0xfffffc00, v2
	v_sub_u32_e32 v2, v137, v2
	v_lshrrev_b32_e32 v3, 4, v2
	v_bitop3_b32 v3, v3, v2, 32 bitop3:0x6c
	v_ashrrev_i32_e32 v2, 31, v2
	v_ashrrev_i32_e32 v1, 31, v134
	v_lshrrev_b32_e32 v2, 26, v2
	v_lshrrev_b32_e32 v1, 26, v1
	v_add_u32_e32 v2, v3, v2
	v_add_u32_e32 v1, v134, v1
	v_ashrrev_i32_e32 v2, 6, v2
	v_ashrrev_i32_e32 v1, 6, v1
	v_mul_i32_i24_e32 v5, 64, v2
	v_lshlrev_b32_e32 v4, 3, v1
	v_lshlrev_b32_e32 v1, 5, v1
	v_sub_u32_e32 v3, v3, v5
	v_and_b32_e32 v1, 32, v1
	v_ashrrev_i16_sdwa v3, v252, sext(v3) dst_sel:DWORD dst_unused:UNUSED_PAD src0_sel:DWORD src1_sel:BYTE_0
	v_add_u32_e32 v138, 0x2000, v137
	v_add_u32_sdwa v1, v1, sext(v3) dst_sel:DWORD dst_unused:UNUSED_PAD src0_sel:DWORD src1_sel:WORD_0
	v_ashrrev_i32_e32 v3, 31, v138
	v_lshrrev_b32_e32 v3, 22, v3
	v_add_u32_e32 v3, v138, v3
	v_ashrrev_i32_e32 v3, 10, v3
	v_mul_i32_i24_e32 v5, 0x400, v3
	s_lshr_b32 s8, s7, 31
	s_lshr_b32 s7, s7, 2
	v_sub_u32_e32 v5, v138, v5
	s_add_i32 s7, s7, s8
	v_lshrrev_b32_e32 v6, 4, v5
	s_mul_i32 s7, s7, 24
	v_bitop3_b32 v5, v6, v5, 32 bitop3:0x6c
	s_sub_i32 s31, s6, s7
	v_ashrrev_i32_e32 v7, 31, v5
	s_lshl_b32 s6, s31, 8
	v_lshrrev_b32_e32 v7, 26, v7
	v_add_u32_e32 v7, v5, v7
	s_ashr_i32 s7, s6, 31
	v_and_b32_e32 v4, 0x1ffff0, v4
	v_lshrrev_b32_e32 v8, 6, v7
	v_and_b32_e32 v7, 0xc0, v7
	s_lshl_b64 s[8:9], s[6:7], 11
	v_lshlrev_b32_e32 v6, 3, v3
	v_lshlrev_b32_e32 v3, 5, v3
	v_sub_u32_e32 v5, v5, v7
	v_add_lshl_u32 v2, v2, v4, 11
	s_add_u32 s8, s21, s8
	v_add_u32_e32 v144, 0x10000, v137
	v_and_b32_e32 v3, 32, v3
	v_ashrrev_i16_sdwa v5, v252, sext(v5) dst_sel:DWORD dst_unused:UNUSED_PAD src0_sel:DWORD src1_sel:BYTE_0
	v_lshl_add_u32 v132, v1, 1, v2
	v_and_b32_e32 v1, 0x1ffff0, v6
	s_addc_u32 s9, s22, s9
	v_readfirstlane_b32 s12, v144
	v_add_u32_e32 v145, 0x12000, v137
	v_add_u32_sdwa v3, v3, sext(v5) dst_sel:DWORD dst_unused:UNUSED_PAD src0_sel:DWORD src1_sel:WORD_0
	v_add_lshl_u32 v1, v8, v1, 11
	s_mov_b64 s[10:11], s[8:9]
	s_mov_b32 m0, s12
	v_readfirstlane_b32 s12, v145
	v_lshl_add_u32 v130, v3, 1, v1
	s_waitcnt lgkmcnt(0)
	s_barrier
	s_lshl_b64 s[16:17], s[4:5], 11
	global_load_lds_dwordx4 v132, s[10:11]
	s_mov_b32 m0, s12
	v_readfirstlane_b32 s5, v137
	global_load_lds_dwordx4 v130, s[10:11]
	s_add_u32 s10, s23, s16
	s_addc_u32 s11, s24, s17
	s_mov_b64 s[12:13], s[10:11]
	s_mov_b32 m0, s5
	v_readfirstlane_b32 s5, v138
	v_add_u32_e32 v146, 0x14000, v137
	global_load_lds_dwordx4 v132, s[12:13]
	s_mov_b32 m0, s5
	v_readfirstlane_b32 s5, v146
	global_load_lds_dwordx4 v130, s[12:13]
	s_or_b32 s12, s6, 0x80
	s_ashr_i32 s13, s12, 31
	s_lshl_b64 s[12:13], s[12:13], 11
	s_add_u32 s12, s21, s12
	s_addc_u32 s13, s22, s13
	v_add_u32_e32 v147, 0x16000, v137
	s_mov_b64 s[14:15], s[12:13]
	s_mov_b32 m0, s5
	v_readfirstlane_b32 s5, v147
	v_add_u32_e32 v148, 0x4000, v137
	global_load_lds_dwordx4 v132, s[14:15]
	s_mov_b32 m0, s5
	v_readfirstlane_b32 s5, v148
	global_load_lds_dwordx4 v130, s[14:15]
	s_or_b32 s14, s4, 0x80
	s_ashr_i32 s15, s14, 31
	s_lshl_b64 s[14:15], s[14:15], 11
	s_add_u32 s14, s23, s14
	s_addc_u32 s15, s24, s15
	v_add_u32_e32 v149, 0x6000, v137
	s_mov_b64 s[18:19], s[14:15]
	s_mov_b32 m0, s5
	v_readfirstlane_b32 s5, v149
	v_ashrrev_i32_e32 v2, 8, v134
	global_load_lds_dwordx4 v132, s[18:19]
	s_mov_b32 m0, s5
	v_cmp_eq_u32_e32 vcc, 1, v2
	global_load_lds_dwordx4 v130, s[18:19]
	s_and_saveexec_b64 s[18:19], vcc
	s_cbranch_execz .LBB0_846
	s_barrier

.LBB0_850:
	s_or_b64 exec, exec, s[8:9]
	v_lshl_or_b32 v138, v135, 2, v136
	v_lshl_add_u32 v140, v138, 2, v220
	s_barrier
	ds_read_b128 v[212:215], v140
	ds_read_b128 v[224:227], v140 offset:64
	ds_read_b128 v[228:231], v140 offset:128
	ds_read_b128 v[232:235], v140 offset:192
	ds_read_b128 v[236:239], v140 offset:512
	ds_read_b128 v[240:243], v140 offset:576
	ds_read_b128 v[244:247], v140 offset:640
	ds_read_b128 v[248:251], v140 offset:704
	s_cmp_lt_i32 s31, 16
	s_cselect_b32 s5, 0, 2
	s_cmp_gt_i32 s31, 7
	s_cselect_b32 s5, s5, 1
	v_mov_b32_e32 v130, v118
	v_mov_b32_e32 v131, v114
	v_mov_b32_e32 v134, v126
	v_mov_b32_e32 v135, v122
	s_waitcnt lgkmcnt(0)
	v_mov_b32_e32 v132, v212
	v_pk_mul_f32 v[130:131], v[130:131], v[132:133] op_sel_hi:[1,0]
	v_pk_mul_f32 v[132:133], v[134:135], v[132:133] op_sel_hi:[1,0]
	s_cmp_gt_i32 s5, 1
	s_mov_b64 s[8:9], -1
	s_cbranch_scc0 .LBB0_852
	v_mul_f32_e32 v114, 0xbfb8aa3b, v131
	v_exp_f32_e32 v114, v114
	v_mul_f32_e32 v118, 0xbfb8aa3b, v130
	v_mul_f32_e32 v122, 0xbfb8aa3b, v132
	v_exp_f32_e32 v118, v118
	v_add_f32_e32 v114, 1.0, v114
	v_rcp_f32_e32 v135, v114
	v_mul_f32_e32 v114, 0xbfb8aa3b, v133
	v_exp_f32_e32 v114, v114
	v_exp_f32_e32 v122, v122
	v_add_f32_e32 v118, 1.0, v118
	v_rcp_f32_e32 v134, v118
	v_add_f32_e32 v114, 1.0, v114
	v_rcp_f32_e32 v143, v114
	v_add_f32_e32 v114, 1.0, v122
	v_rcp_f32_e32 v142, v114
	v_pk_mul_f32 v[136:137], v[130:131], v[134:135]
	s_mov_b64 s[8:9], 0
	v_pk_mul_f32 v[134:135], v[132:133], v[142:143]
.LBB0_852:
	s_andn2_b64 vcc, exec, s[8:9]
	v_lshlrev_b32_e32 v139, 5, v139
	s_cbranch_vccnz .LBB0_856
	s_cmp_eq_u32 s5, 1
	s_cbranch_scc0 .LBB0_855
	v_add_u32_e32 v114, s4, v138
	v_readlane_b32 s8, v254, 53
	s_nop 1
	v_and_b32_e32 v114, s8, v114
	v_lshlrev_b32_e32 v114, 7, v114
	v_or3_b32 v114, v114, v139, v1
	v_lshlrev_b32_e32 v114, 3, v114
	global_load_dwordx2 v[146:147], v114, s[0:1] offset:128
	global_load_dwordx2 v[148:149], v114, s[0:1]
	global_load_dwordx2 v[150:151], v114, s[0:1] offset:1152
	global_load_dwordx2 v[152:153], v114, s[0:1] offset:1024
	global_load_dwordx2 v[154:155], v114, s[0:1] offset:2176
	global_load_dwordx2 v[156:157], v114, s[0:1] offset:2048
	global_load_dwordx2 v[158:159], v114, s[0:1] offset:3200
	global_load_dwordx2 v[160:161], v114, s[0:1] offset:3072
	v_add_u32_e32 v141, 0x4000, v114
	global_load_dwordx2 v[162:163], v141, s[0:1] offset:128
	global_load_dwordx2 v[164:165], v141, s[0:1]
	global_load_dwordx2 v[166:167], v141, s[0:1] offset:1152
	global_load_dwordx2 v[168:169], v141, s[0:1] offset:1024
	global_load_dwordx2 v[170:171], v141, s[0:1] offset:2176
	global_load_dwordx2 v[172:173], v141, s[0:1] offset:2048
	global_load_dwordx2 v[174:175], v141, s[0:1] offset:3200
	global_load_dwordx2 v[176:177], v141, s[0:1] offset:3072
	v_add_u32_e32 v141, 0x8000, v114
	global_load_dwordx2 v[178:179], v141, s[0:1] offset:128
	global_load_dwordx2 v[180:181], v141, s[0:1]
	global_load_dwordx2 v[182:183], v141, s[0:1] offset:1152
	global_load_dwordx2 v[184:185], v141, s[0:1] offset:1024
	global_load_dwordx2 v[186:187], v141, s[0:1] offset:2176
	global_load_dwordx2 v[188:189], v141, s[0:1] offset:2048
	global_load_dwordx2 v[190:191], v141, s[0:1] offset:3200
	global_load_dwordx2 v[192:193], v141, s[0:1] offset:3072
	v_add_u32_e32 v141, 0xc000, v114
	global_load_dwordx2 v[194:195], v141, s[0:1] offset:128
	global_load_dwordx2 v[196:197], v141, s[0:1]
	global_load_dwordx2 v[198:199], v141, s[0:1] offset:1152
	global_load_dwordx2 v[200:201], v141, s[0:1] offset:1024
	global_load_dwordx2 v[202:203], v141, s[0:1] offset:2176
	global_load_dwordx2 v[204:205], v141, s[0:1] offset:2048
	global_load_dwordx2 v[206:207], v141, s[0:1] offset:3200
	global_load_dwordx2 v[208:209], v141, s[0:1] offset:3072
	s_waitcnt vmcnt(0)
	v_mov_b32_e32 v134, v146
	v_mov_b32_e32 v135, v147
	v_mov_b32_e32 v136, v148
	v_mov_b32_e32 v137, v149
	s_waitcnt vmcnt(1)
	v_mov_b32_e32 v142, v134
	s_waitcnt vmcnt(0)
	v_mov_b32_e32 v143, v136
	v_mov_b32_e32 v136, v135
	v_pk_mul_f32 v[134:135], v[130:131], v[136:137]
	v_pk_mul_f32 v[136:137], v[132:133], v[136:137]
	v_pk_fma_f32 v[132:133], v[132:133], v[142:143], v[134:135]
	v_pk_fma_f32 v[130:131], v[130:131], v[142:143], v[136:137] neg_lo:[0,0,1] neg_hi:[0,0,1]

.LBB0_856:
	v_or_b32_e32 v130, v139, v1
	v_mul_lo_u32 v131, v138, s3
	v_cvt_pk_bf16_f32 v114, v137, s0
	v_lshl_add_u32 v118, v130, 1, v131
	ds_write_b16 v118, v114
	v_cvt_pk_bf16_f32 v114, v136, s0
	ds_write_b16 v118, v114 offset:32
	v_cvt_pk_bf16_f32 v114, v135, s0
	ds_write_b16 v118, v114 offset:256
	v_cvt_pk_bf16_f32 v114, v134, s0
	v_or_b32_e32 v132, 1, v138
	ds_write_b16 v118, v114 offset:288
	v_lshl_add_u32 v114, v132, 2, v220
	v_mov_b32_e32 v118, v213
	v_mov_b32_e32 v114, v119
	v_mov_b32_e32 v122, v127
	s_cmp_gt_i32 s5, 1
	s_mov_b64 s[8:9], -1
	v_pk_mul_f32 v[114:115], v[114:115], v[118:119] op_sel_hi:[1,0]
	v_pk_mul_f32 v[118:119], v[122:123], v[118:119] op_sel_hi:[1,0]
	s_cbranch_scc0 .LBB0_858
	v_mul_f32_e32 v122, 0xbfb8aa3b, v115
	v_exp_f32_e32 v122, v122
	v_mul_f32_e32 v123, 0xbfb8aa3b, v114
	v_exp_f32_e32 v123, v123
	s_mov_b64 s[8:9], 0
	v_add_f32_e32 v122, 1.0, v122
	v_add_f32_e32 v126, 1.0, v123
	v_rcp_f32_e32 v123, v122
	v_mul_f32_e32 v122, 0xbfb8aa3b, v119
	v_exp_f32_e32 v127, v122
	v_mul_f32_e32 v122, 0xbfb8aa3b, v118
	v_exp_f32_e32 v133, v122
	v_rcp_f32_e32 v122, v126
	v_add_f32_e32 v126, 1.0, v127
	v_rcp_f32_e32 v135, v126
	v_add_f32_e32 v126, 1.0, v133
	v_rcp_f32_e32 v134, v126
	v_pk_mul_f32 v[126:127], v[114:115], v[122:123]
	v_pk_mul_f32 v[122:123], v[118:119], v[134:135]
.LBB0_858:
	s_andn2_b64 vcc, exec, s[8:9]
	s_cbranch_vccnz .LBB0_862
	s_cmp_eq_u32 s5, 1
	s_cbranch_scc0 .LBB0_861
	v_add_u32_e32 v122, s4, v132
	v_readlane_b32 s8, v254, 53
	s_nop 1
	v_and_b32_e32 v122, s8, v122
	v_lshlrev_b32_e32 v122, 7, v122
	v_or3_b32 v122, v122, v139, v1
	v_lshlrev_b32_e32 v126, 3, v122
	v_mov_b32_e32 v122, v150
	v_mov_b32_e32 v123, v151
	v_mov_b32_e32 v126, v152
	v_mov_b32_e32 v127, v153
	s_nop 0
	s_waitcnt vmcnt(1)
	v_mov_b32_e32 v132, v122
	s_waitcnt vmcnt(0)
	v_mov_b32_e32 v133, v126
	v_mov_b32_e32 v126, v123
	v_pk_mul_f32 v[122:123], v[114:115], v[126:127]
	v_pk_mul_f32 v[126:127], v[118:119], v[126:127]
	v_pk_fma_f32 v[118:119], v[118:119], v[132:133], v[122:123]
	v_pk_fma_f32 v[114:115], v[114:115], v[132:133], v[126:127] neg_lo:[0,0,1] neg_hi:[0,0,1]

.LBB0_862:
	v_add_u32_e32 v131, 0x210, v131
	v_cvt_pk_bf16_f32 v114, v127, s0
	v_lshl_add_u32 v115, v130, 1, v131
	ds_write_b16 v115, v114
	v_cvt_pk_bf16_f32 v114, v126, s0
	ds_write_b16 v115, v114 offset:32
	v_cvt_pk_bf16_f32 v114, v123, s0
	ds_write_b16 v115, v114 offset:256
	v_cvt_pk_bf16_f32 v114, v122, s0
	v_or_b32_e32 v132, 2, v138
	ds_write_b16 v115, v114 offset:288
	v_lshl_add_u32 v114, v132, 2, v220
	v_mov_b32_e32 v118, v214
	v_mov_b32_e32 v114, v120
	v_mov_b32_e32 v115, v116
	v_mov_b32_e32 v122, v128
	v_mov_b32_e32 v123, v124
	v_pk_mul_f32 v[114:115], v[114:115], v[118:119] op_sel_hi:[1,0]
	v_pk_mul_f32 v[118:119], v[122:123], v[118:119] op_sel_hi:[1,0]
	s_cmp_gt_i32 s5, 1
	s_mov_b64 s[8:9], -1
	s_cbranch_scc0 .LBB0_864
	v_mul_f32_e32 v116, 0xbfb8aa3b, v115
	v_exp_f32_e32 v116, v116
	v_mul_f32_e32 v120, 0xbfb8aa3b, v114
	v_mul_f32_e32 v122, 0xbfb8aa3b, v118
	v_exp_f32_e32 v120, v120
	v_add_f32_e32 v116, 1.0, v116
	v_rcp_f32_e32 v123, v116
	v_mul_f32_e32 v116, 0xbfb8aa3b, v119
	v_exp_f32_e32 v116, v116
	v_exp_f32_e32 v124, v122
	v_add_f32_e32 v120, 1.0, v120
	v_rcp_f32_e32 v122, v120
	v_add_f32_e32 v116, 1.0, v116
	v_rcp_f32_e32 v135, v116
	v_add_f32_e32 v116, 1.0, v124
	v_rcp_f32_e32 v134, v116
	v_pk_mul_f32 v[126:127], v[114:115], v[122:123]
	s_mov_b64 s[8:9], 0
	v_pk_mul_f32 v[122:123], v[118:119], v[134:135]
.LBB0_864:
	s_andn2_b64 vcc, exec, s[8:9]
	s_cbranch_vccnz .LBB0_868
	s_cmp_eq_u32 s5, 1
	s_cbranch_scc0 .LBB0_867
	v_add_u32_e32 v116, s4, v132
	v_readlane_b32 s8, v254, 53
	s_nop 1
	v_and_b32_e32 v116, s8, v116
	v_lshlrev_b32_e32 v116, 7, v116
	v_or3_b32 v116, v116, v139, v1
	v_lshlrev_b32_e32 v116, 3, v116
	v_mov_b32_e32 v122, v154
	v_mov_b32_e32 v123, v155
	v_mov_b32_e32 v126, v156
	v_mov_b32_e32 v127, v157
	s_waitcnt vmcnt(1)
	v_mov_b32_e32 v132, v122
	s_waitcnt vmcnt(0)
	v_mov_b32_e32 v133, v126
	v_mov_b32_e32 v126, v123
	v_pk_mul_f32 v[122:123], v[114:115], v[126:127]
	v_pk_mul_f32 v[126:127], v[118:119], v[126:127]
	v_pk_fma_f32 v[118:119], v[118:119], v[132:133], v[122:123]
	v_pk_fma_f32 v[114:115], v[114:115], v[132:133], v[126:127] neg_lo:[0,0,1] neg_hi:[0,0,1]

.LBB0_868:
	v_cvt_pk_bf16_f32 v114, v127, s0
	v_add_u32_e32 v127, 0x210, v131
	v_lshl_add_u32 v115, v130, 1, v127
	ds_write_b16 v115, v114
	v_cvt_pk_bf16_f32 v114, v126, s0
	ds_write_b16 v115, v114 offset:32
	v_cvt_pk_bf16_f32 v114, v123, s0
	ds_write_b16 v115, v114 offset:256
	v_cvt_pk_bf16_f32 v114, v122, s0
	v_or_b32_e32 v122, 3, v138
	ds_write_b16 v115, v114 offset:288
	v_lshl_add_u32 v114, v122, 2, v220
	v_mov_b32_e32 v118, v215
	v_mov_b32_e32 v116, v121
	v_mov_b32_e32 v124, v129
	s_cmp_gt_i32 s5, 1
	s_mov_b64 s[8:9], -1
	v_pk_mul_f32 v[114:115], v[116:117], v[118:119] op_sel_hi:[1,0]
	v_pk_mul_f32 v[116:117], v[124:125], v[118:119] op_sel_hi:[1,0]
	s_cbranch_scc0 .LBB0_870
	v_mul_f32_e32 v118, 0xbfb8aa3b, v115
	v_exp_f32_e32 v118, v118
	v_mul_f32_e32 v119, 0xbfb8aa3b, v114
	v_exp_f32_e32 v119, v119
	s_mov_b64 s[8:9], 0
	v_add_f32_e32 v118, 1.0, v118
	v_add_f32_e32 v120, 1.0, v119
	v_rcp_f32_e32 v119, v118
	v_mul_f32_e32 v118, 0xbfb8aa3b, v117
	v_exp_f32_e32 v121, v118
	v_mul_f32_e32 v118, 0xbfb8aa3b, v116
	v_exp_f32_e32 v123, v118
	v_rcp_f32_e32 v118, v120
	v_add_f32_e32 v120, 1.0, v121
	v_rcp_f32_e32 v125, v120
	v_add_f32_e32 v120, 1.0, v123
	v_rcp_f32_e32 v124, v120
	v_pk_mul_f32 v[120:121], v[114:115], v[118:119]
	v_pk_mul_f32 v[118:119], v[116:117], v[124:125]
.LBB0_870:
	s_andn2_b64 vcc, exec, s[8:9]
	s_cbranch_vccnz .LBB0_874
	s_cmp_eq_u32 s5, 1
	s_cbranch_scc0 .LBB0_873
	v_add_u32_e32 v118, s4, v122
	v_readlane_b32 s8, v254, 53
	s_nop 1
	v_and_b32_e32 v118, s8, v118
	v_lshlrev_b32_e32 v118, 7, v118
	v_or3_b32 v118, v118, v139, v1
	v_lshlrev_b32_e32 v120, 3, v118
	v_mov_b32_e32 v118, v158
	v_mov_b32_e32 v119, v159
	v_mov_b32_e32 v120, v160
	v_mov_b32_e32 v121, v161
	s_nop 0
	s_waitcnt vmcnt(1)
	v_mov_b32_e32 v122, v118
	s_waitcnt vmcnt(0)
	v_mov_b32_e32 v123, v120
	v_mov_b32_e32 v120, v119
	v_pk_mul_f32 v[118:119], v[114:115], v[120:121]
	v_pk_mul_f32 v[120:121], v[116:117], v[120:121]
	v_pk_fma_f32 v[116:117], v[116:117], v[122:123], v[118:119]
	v_pk_fma_f32 v[114:115], v[114:115], v[122:123], v[120:121] neg_lo:[0,0,1] neg_hi:[0,0,1]

.LBB0_874:
	v_add_u32_e32 v122, 0x210, v127
	v_cvt_pk_bf16_f32 v114, v121, s0
	v_lshl_add_u32 v115, v130, 1, v122
	ds_write_b16 v115, v114
	v_cvt_pk_bf16_f32 v114, v120, s0
	ds_write_b16 v115, v114 offset:32
	v_cvt_pk_bf16_f32 v114, v119, s0
	ds_write_b16 v115, v114 offset:256
	v_cvt_pk_bf16_f32 v114, v118, s0
	v_or_b32_e32 v123, 16, v138
	ds_write_b16 v115, v114 offset:288
	v_lshl_add_u32 v114, v123, 2, v220
	v_mov_b32_e32 v116, v224
	v_mov_b32_e32 v114, v102
	v_mov_b32_e32 v115, v98
	v_mov_b32_e32 v118, v110
	v_mov_b32_e32 v119, v106
	v_pk_mul_f32 v[114:115], v[114:115], v[116:117] op_sel_hi:[1,0]
	v_pk_mul_f32 v[116:117], v[118:119], v[116:117] op_sel_hi:[1,0]
	s_cmp_gt_i32 s5, 1
	s_mov_b64 s[8:9], -1
	s_cbranch_scc0 .LBB0_876
	v_mul_f32_e32 v98, 0xbfb8aa3b, v115
	v_exp_f32_e32 v98, v98
	v_mul_f32_e32 v102, 0xbfb8aa3b, v114
	v_mul_f32_e32 v106, 0xbfb8aa3b, v116
	v_exp_f32_e32 v102, v102
	v_add_f32_e32 v98, 1.0, v98
	v_rcp_f32_e32 v119, v98
	v_mul_f32_e32 v98, 0xbfb8aa3b, v117
	v_exp_f32_e32 v98, v98
	v_exp_f32_e32 v106, v106
	v_add_f32_e32 v102, 1.0, v102
	v_rcp_f32_e32 v118, v102
	v_add_f32_e32 v98, 1.0, v98
	v_rcp_f32_e32 v125, v98
	v_add_f32_e32 v98, 1.0, v106
	v_rcp_f32_e32 v124, v98
	v_pk_mul_f32 v[120:121], v[114:115], v[118:119]
	s_mov_b64 s[8:9], 0
	v_pk_mul_f32 v[118:119], v[116:117], v[124:125]
.LBB0_876:
	s_andn2_b64 vcc, exec, s[8:9]
	s_cbranch_vccnz .LBB0_880
	s_cmp_eq_u32 s5, 1
	s_cbranch_scc0 .LBB0_879
	v_add_u32_e32 v98, s4, v123
	v_readlane_b32 s8, v254, 53
	s_nop 1
	v_and_b32_e32 v98, s8, v98
	v_lshlrev_b32_e32 v98, 7, v98
	v_or3_b32 v98, v98, v139, v1
	v_lshlrev_b32_e32 v98, 3, v98
	v_mov_b32_e32 v118, v162
	v_mov_b32_e32 v119, v163
	v_mov_b32_e32 v120, v164
	v_mov_b32_e32 v121, v165
	s_waitcnt vmcnt(1)
	v_mov_b32_e32 v124, v118
	s_waitcnt vmcnt(0)
	v_mov_b32_e32 v125, v120
	v_mov_b32_e32 v120, v119
	v_pk_mul_f32 v[118:119], v[114:115], v[120:121]
	v_pk_mul_f32 v[120:121], v[116:117], v[120:121]
	v_pk_fma_f32 v[116:117], v[116:117], v[124:125], v[118:119]
	v_pk_fma_f32 v[114:115], v[114:115], v[124:125], v[120:121] neg_lo:[0,0,1] neg_hi:[0,0,1]

.LBB0_880:
	v_add_u32_e32 v114, 0x1ad0, v122
	v_cvt_pk_bf16_f32 v98, v121, s0
	v_lshl_add_u32 v102, v130, 1, v114
	ds_write_b16 v102, v98
	v_cvt_pk_bf16_f32 v98, v120, s0
	ds_write_b16 v102, v98 offset:32
	v_cvt_pk_bf16_f32 v98, v119, s0
	ds_write_b16 v102, v98 offset:256
	v_cvt_pk_bf16_f32 v98, v118, s0
	v_or_b32_e32 v115, 17, v138
	ds_write_b16 v102, v98 offset:288
	v_lshl_add_u32 v98, v115, 2, v220
	v_mov_b32_e32 v102, v225
	v_mov_b32_e32 v98, v103
	v_mov_b32_e32 v106, v111
	s_cmp_gt_i32 s5, 1
	s_mov_b64 s[8:9], -1
	v_pk_mul_f32 v[98:99], v[98:99], v[102:103] op_sel_hi:[1,0]
	v_pk_mul_f32 v[102:103], v[106:107], v[102:103] op_sel_hi:[1,0]
	s_cbranch_scc0 .LBB0_882
	v_mul_f32_e32 v106, 0xbfb8aa3b, v99
	v_exp_f32_e32 v106, v106
	v_mul_f32_e32 v107, 0xbfb8aa3b, v98
	v_exp_f32_e32 v107, v107
	s_mov_b64 s[8:9], 0
	v_add_f32_e32 v106, 1.0, v106
	v_add_f32_e32 v110, 1.0, v107
	v_rcp_f32_e32 v107, v106
	v_mul_f32_e32 v106, 0xbfb8aa3b, v103
	v_exp_f32_e32 v111, v106
	v_mul_f32_e32 v106, 0xbfb8aa3b, v102
	v_exp_f32_e32 v116, v106
	v_rcp_f32_e32 v106, v110
	v_add_f32_e32 v110, 1.0, v111
	v_rcp_f32_e32 v117, v110
	v_add_f32_e32 v110, 1.0, v116
	v_rcp_f32_e32 v116, v110
	v_pk_mul_f32 v[110:111], v[98:99], v[106:107]
	v_pk_mul_f32 v[106:107], v[102:103], v[116:117]
.LBB0_882:
	s_andn2_b64 vcc, exec, s[8:9]
	s_cbranch_vccnz .LBB0_886
	s_cmp_eq_u32 s5, 1
	s_cbranch_scc0 .LBB0_885
	v_add_u32_e32 v106, s4, v115
	v_readlane_b32 s8, v254, 53
	s_nop 1
	v_and_b32_e32 v106, s8, v106
	v_lshlrev_b32_e32 v106, 7, v106
	v_or3_b32 v106, v106, v139, v1
	v_lshlrev_b32_e32 v110, 3, v106
	v_mov_b32_e32 v106, v166
	v_mov_b32_e32 v107, v167
	v_mov_b32_e32 v110, v168
	v_mov_b32_e32 v111, v169
	s_nop 0
	s_waitcnt vmcnt(1)
	v_mov_b32_e32 v116, v106
	s_waitcnt vmcnt(0)
	v_mov_b32_e32 v117, v110
	v_mov_b32_e32 v110, v107
	v_pk_mul_f32 v[106:107], v[98:99], v[110:111]
	v_pk_mul_f32 v[110:111], v[102:103], v[110:111]
	v_pk_fma_f32 v[102:103], v[102:103], v[116:117], v[106:107]
	v_pk_fma_f32 v[98:99], v[98:99], v[116:117], v[110:111] neg_lo:[0,0,1] neg_hi:[0,0,1]

.LBB0_886:
	v_add_u32_e32 v114, 0x210, v114
	v_cvt_pk_bf16_f32 v98, v111, s0
	v_lshl_add_u32 v99, v130, 1, v114
	ds_write_b16 v99, v98
	v_cvt_pk_bf16_f32 v98, v110, s0
	ds_write_b16 v99, v98 offset:32
	v_cvt_pk_bf16_f32 v98, v107, s0
	ds_write_b16 v99, v98 offset:256
	v_cvt_pk_bf16_f32 v98, v106, s0
	v_or_b32_e32 v115, 18, v138
	ds_write_b16 v99, v98 offset:288
	v_lshl_add_u32 v98, v115, 2, v220
	v_mov_b32_e32 v102, v226
	v_mov_b32_e32 v98, v104
	v_mov_b32_e32 v99, v100
	v_mov_b32_e32 v106, v112
	v_mov_b32_e32 v107, v108
	v_pk_mul_f32 v[98:99], v[98:99], v[102:103] op_sel_hi:[1,0]
	v_pk_mul_f32 v[102:103], v[106:107], v[102:103] op_sel_hi:[1,0]
	s_cmp_gt_i32 s5, 1
	s_mov_b64 s[8:9], -1
	s_cbranch_scc0 .LBB0_888
	v_mul_f32_e32 v100, 0xbfb8aa3b, v99
	v_exp_f32_e32 v100, v100
	v_mul_f32_e32 v104, 0xbfb8aa3b, v98
	v_mul_f32_e32 v106, 0xbfb8aa3b, v102
	v_exp_f32_e32 v104, v104
	v_add_f32_e32 v100, 1.0, v100
	v_rcp_f32_e32 v107, v100
	v_mul_f32_e32 v100, 0xbfb8aa3b, v103
	v_exp_f32_e32 v100, v100
	v_exp_f32_e32 v108, v106
	v_add_f32_e32 v104, 1.0, v104
	v_rcp_f32_e32 v106, v104
	v_add_f32_e32 v100, 1.0, v100
	v_rcp_f32_e32 v117, v100
	v_add_f32_e32 v100, 1.0, v108
	v_rcp_f32_e32 v116, v100
	v_pk_mul_f32 v[110:111], v[98:99], v[106:107]
	s_mov_b64 s[8:9], 0
	v_pk_mul_f32 v[106:107], v[102:103], v[116:117]
.LBB0_888:
	s_andn2_b64 vcc, exec, s[8:9]
	s_cbranch_vccnz .LBB0_892
	s_cmp_eq_u32 s5, 1
	s_cbranch_scc0 .LBB0_891
	v_add_u32_e32 v100, s4, v115
	v_readlane_b32 s8, v254, 53
	s_nop 1
	v_and_b32_e32 v100, s8, v100
	v_lshlrev_b32_e32 v100, 7, v100
	v_or3_b32 v100, v100, v139, v1
	v_lshlrev_b32_e32 v100, 3, v100
	v_mov_b32_e32 v106, v170
	v_mov_b32_e32 v107, v171
	v_mov_b32_e32 v110, v172
	v_mov_b32_e32 v111, v173
	s_waitcnt vmcnt(1)
	v_mov_b32_e32 v116, v106
	s_waitcnt vmcnt(0)
	v_mov_b32_e32 v117, v110
	v_mov_b32_e32 v110, v107
	v_pk_mul_f32 v[106:107], v[98:99], v[110:111]
	v_pk_mul_f32 v[110:111], v[102:103], v[110:111]
	v_pk_fma_f32 v[102:103], v[102:103], v[116:117], v[106:107]
	v_pk_fma_f32 v[98:99], v[98:99], v[116:117], v[110:111] neg_lo:[0,0,1] neg_hi:[0,0,1]

.LBB0_892:
	v_cvt_pk_bf16_f32 v98, v111, s0
	v_add_u32_e32 v111, 0x210, v114
	v_lshl_add_u32 v99, v130, 1, v111
	ds_write_b16 v99, v98
	v_cvt_pk_bf16_f32 v98, v110, s0
	ds_write_b16 v99, v98 offset:32
	v_cvt_pk_bf16_f32 v98, v107, s0
	ds_write_b16 v99, v98 offset:256
	v_cvt_pk_bf16_f32 v98, v106, s0
	v_or_b32_e32 v106, 19, v138
	ds_write_b16 v99, v98 offset:288
	v_lshl_add_u32 v98, v106, 2, v220
	v_mov_b32_e32 v102, v227
	v_mov_b32_e32 v100, v105
	v_mov_b32_e32 v108, v113
	s_cmp_gt_i32 s5, 1
	s_mov_b64 s[8:9], -1
	v_pk_mul_f32 v[98:99], v[100:101], v[102:103] op_sel_hi:[1,0]
	v_pk_mul_f32 v[100:101], v[108:109], v[102:103] op_sel_hi:[1,0]
	s_cbranch_scc0 .LBB0_894
	v_mul_f32_e32 v102, 0xbfb8aa3b, v99
	v_exp_f32_e32 v102, v102
	v_mul_f32_e32 v103, 0xbfb8aa3b, v98
	v_exp_f32_e32 v103, v103
	s_mov_b64 s[8:9], 0
	v_add_f32_e32 v102, 1.0, v102
	v_add_f32_e32 v104, 1.0, v103
	v_rcp_f32_e32 v103, v102
	v_mul_f32_e32 v102, 0xbfb8aa3b, v101
	v_exp_f32_e32 v105, v102
	v_mul_f32_e32 v102, 0xbfb8aa3b, v100
	v_exp_f32_e32 v107, v102
	v_rcp_f32_e32 v102, v104
	v_add_f32_e32 v104, 1.0, v105
	v_rcp_f32_e32 v109, v104
	v_add_f32_e32 v104, 1.0, v107
	v_rcp_f32_e32 v108, v104
	v_pk_mul_f32 v[104:105], v[98:99], v[102:103]
	v_pk_mul_f32 v[102:103], v[100:101], v[108:109]
.LBB0_894:
	s_andn2_b64 vcc, exec, s[8:9]
	s_cbranch_vccnz .LBB0_898
	s_cmp_eq_u32 s5, 1
	s_cbranch_scc0 .LBB0_897
	v_add_u32_e32 v102, s4, v106
	v_readlane_b32 s8, v254, 53
	s_nop 1
	v_and_b32_e32 v102, s8, v102
	v_lshlrev_b32_e32 v102, 7, v102
	v_or3_b32 v102, v102, v139, v1
	v_lshlrev_b32_e32 v104, 3, v102
	v_mov_b32_e32 v102, v174
	v_mov_b32_e32 v103, v175
	v_mov_b32_e32 v104, v176
	v_mov_b32_e32 v105, v177
	s_nop 0
	s_waitcnt vmcnt(1)
	v_mov_b32_e32 v106, v102
	s_waitcnt vmcnt(0)
	v_mov_b32_e32 v107, v104
	v_mov_b32_e32 v104, v103
	v_pk_mul_f32 v[102:103], v[98:99], v[104:105]
	v_pk_mul_f32 v[104:105], v[100:101], v[104:105]
	v_pk_fma_f32 v[100:101], v[100:101], v[106:107], v[102:103]
	v_pk_fma_f32 v[98:99], v[98:99], v[106:107], v[104:105] neg_lo:[0,0,1] neg_hi:[0,0,1]

.LBB0_898:
	v_add_u32_e32 v106, 0x210, v111
	v_cvt_pk_bf16_f32 v98, v105, s0
	v_lshl_add_u32 v99, v130, 1, v106
	ds_write_b16 v99, v98
	v_cvt_pk_bf16_f32 v98, v104, s0
	ds_write_b16 v99, v98 offset:32
	v_cvt_pk_bf16_f32 v98, v103, s0
	ds_write_b16 v99, v98 offset:256
	v_cvt_pk_bf16_f32 v98, v102, s0
	v_or_b32_e32 v107, 32, v138
	ds_write_b16 v99, v98 offset:288
	v_lshl_add_u32 v98, v107, 2, v220
	v_mov_b32_e32 v100, v228
	v_mov_b32_e32 v98, v86
	v_mov_b32_e32 v99, v82
	v_mov_b32_e32 v102, v94
	v_mov_b32_e32 v103, v90
	v_pk_mul_f32 v[98:99], v[98:99], v[100:101] op_sel_hi:[1,0]
	v_pk_mul_f32 v[100:101], v[102:103], v[100:101] op_sel_hi:[1,0]
	s_cmp_gt_i32 s5, 1
	s_mov_b64 s[8:9], -1
	s_cbranch_scc0 .LBB0_900
	v_mul_f32_e32 v82, 0xbfb8aa3b, v99
	v_exp_f32_e32 v82, v82
	v_mul_f32_e32 v86, 0xbfb8aa3b, v98
	v_mul_f32_e32 v90, 0xbfb8aa3b, v100
	v_exp_f32_e32 v86, v86
	v_add_f32_e32 v82, 1.0, v82
	v_rcp_f32_e32 v103, v82
	v_mul_f32_e32 v82, 0xbfb8aa3b, v101
	v_exp_f32_e32 v82, v82
	v_exp_f32_e32 v90, v90
	v_add_f32_e32 v86, 1.0, v86
	v_rcp_f32_e32 v102, v86
	v_add_f32_e32 v82, 1.0, v82
	v_rcp_f32_e32 v109, v82
	v_add_f32_e32 v82, 1.0, v90
	v_rcp_f32_e32 v108, v82
	v_pk_mul_f32 v[104:105], v[98:99], v[102:103]
	s_mov_b64 s[8:9], 0
	v_pk_mul_f32 v[102:103], v[100:101], v[108:109]
.LBB0_900:
	s_andn2_b64 vcc, exec, s[8:9]
	s_cbranch_vccnz .LBB0_904
	s_cmp_eq_u32 s5, 1
	s_cbranch_scc0 .LBB0_903
	v_add_u32_e32 v82, s4, v107
	v_readlane_b32 s8, v254, 53
	s_nop 1
	v_and_b32_e32 v82, s8, v82
	v_lshlrev_b32_e32 v82, 7, v82
	v_or3_b32 v82, v82, v139, v1
	v_lshlrev_b32_e32 v82, 3, v82
	v_mov_b32_e32 v102, v178
	v_mov_b32_e32 v103, v179
	v_mov_b32_e32 v104, v180
	v_mov_b32_e32 v105, v181
	s_waitcnt vmcnt(1)
	v_mov_b32_e32 v108, v102
	s_waitcnt vmcnt(0)
	v_mov_b32_e32 v109, v104
	v_mov_b32_e32 v104, v103
	v_pk_mul_f32 v[102:103], v[98:99], v[104:105]
	v_pk_mul_f32 v[104:105], v[100:101], v[104:105]
	v_pk_fma_f32 v[100:101], v[100:101], v[108:109], v[102:103]
	v_pk_fma_f32 v[98:99], v[98:99], v[108:109], v[104:105] neg_lo:[0,0,1] neg_hi:[0,0,1]

.LBB0_904:
	v_add_u32_e32 v98, 0x1ad0, v106
	v_cvt_pk_bf16_f32 v82, v105, s0
	v_lshl_add_u32 v86, v130, 1, v98
	ds_write_b16 v86, v82
	v_cvt_pk_bf16_f32 v82, v104, s0
	ds_write_b16 v86, v82 offset:32
	v_cvt_pk_bf16_f32 v82, v103, s0
	ds_write_b16 v86, v82 offset:256
	v_cvt_pk_bf16_f32 v82, v102, s0
	v_or_b32_e32 v99, 33, v138
	ds_write_b16 v86, v82 offset:288
	v_lshl_add_u32 v82, v99, 2, v220
	v_mov_b32_e32 v86, v229
	v_mov_b32_e32 v82, v87
	v_mov_b32_e32 v90, v95
	s_cmp_gt_i32 s5, 1
	s_mov_b64 s[8:9], -1
	v_pk_mul_f32 v[82:83], v[82:83], v[86:87] op_sel_hi:[1,0]
	v_pk_mul_f32 v[86:87], v[90:91], v[86:87] op_sel_hi:[1,0]
	s_cbranch_scc0 .LBB0_906
	v_mul_f32_e32 v90, 0xbfb8aa3b, v83
	v_exp_f32_e32 v90, v90
	v_mul_f32_e32 v91, 0xbfb8aa3b, v82
	v_exp_f32_e32 v91, v91
	s_mov_b64 s[8:9], 0
	v_add_f32_e32 v90, 1.0, v90
	v_add_f32_e32 v94, 1.0, v91
	v_rcp_f32_e32 v91, v90
	v_mul_f32_e32 v90, 0xbfb8aa3b, v87
	v_exp_f32_e32 v95, v90
	v_mul_f32_e32 v90, 0xbfb8aa3b, v86
	v_exp_f32_e32 v100, v90
	v_rcp_f32_e32 v90, v94
	v_add_f32_e32 v94, 1.0, v95
	v_rcp_f32_e32 v101, v94
	v_add_f32_e32 v94, 1.0, v100
	v_rcp_f32_e32 v100, v94
	v_pk_mul_f32 v[94:95], v[82:83], v[90:91]
	v_pk_mul_f32 v[90:91], v[86:87], v[100:101]
.LBB0_906:
	s_andn2_b64 vcc, exec, s[8:9]
	s_cbranch_vccnz .LBB0_910
	s_cmp_eq_u32 s5, 1
	s_cbranch_scc0 .LBB0_909
	v_add_u32_e32 v90, s4, v99
	v_readlane_b32 s8, v254, 53
	s_nop 1
	v_and_b32_e32 v90, s8, v90
	v_lshlrev_b32_e32 v90, 7, v90
	v_or3_b32 v90, v90, v139, v1
	v_lshlrev_b32_e32 v94, 3, v90
	v_mov_b32_e32 v90, v182
	v_mov_b32_e32 v91, v183
	v_mov_b32_e32 v94, v184
	v_mov_b32_e32 v95, v185
	s_nop 0
	s_waitcnt vmcnt(1)
	v_mov_b32_e32 v100, v90
	s_waitcnt vmcnt(0)
	v_mov_b32_e32 v101, v94
	v_mov_b32_e32 v94, v91
	v_pk_mul_f32 v[90:91], v[82:83], v[94:95]
	v_pk_mul_f32 v[94:95], v[86:87], v[94:95]
	v_pk_fma_f32 v[86:87], v[86:87], v[100:101], v[90:91]
	v_pk_fma_f32 v[82:83], v[82:83], v[100:101], v[94:95] neg_lo:[0,0,1] neg_hi:[0,0,1]

.LBB0_910:
	v_add_u32_e32 v98, 0x210, v98
	v_cvt_pk_bf16_f32 v82, v95, s0
	v_lshl_add_u32 v83, v130, 1, v98
	ds_write_b16 v83, v82
	v_cvt_pk_bf16_f32 v82, v94, s0
	ds_write_b16 v83, v82 offset:32
	v_cvt_pk_bf16_f32 v82, v91, s0
	ds_write_b16 v83, v82 offset:256
	v_cvt_pk_bf16_f32 v82, v90, s0
	v_or_b32_e32 v99, 34, v138
	ds_write_b16 v83, v82 offset:288
	v_lshl_add_u32 v82, v99, 2, v220
	v_mov_b32_e32 v86, v230
	v_mov_b32_e32 v82, v88
	v_mov_b32_e32 v83, v84
	v_mov_b32_e32 v90, v96
	v_mov_b32_e32 v91, v92
	v_pk_mul_f32 v[82:83], v[82:83], v[86:87] op_sel_hi:[1,0]
	v_pk_mul_f32 v[86:87], v[90:91], v[86:87] op_sel_hi:[1,0]
	s_cmp_gt_i32 s5, 1
	s_mov_b64 s[8:9], -1
	s_cbranch_scc0 .LBB0_912
	v_mul_f32_e32 v84, 0xbfb8aa3b, v83
	v_exp_f32_e32 v84, v84
	v_mul_f32_e32 v88, 0xbfb8aa3b, v82
	v_mul_f32_e32 v90, 0xbfb8aa3b, v86
	v_exp_f32_e32 v88, v88
	v_add_f32_e32 v84, 1.0, v84
	v_rcp_f32_e32 v91, v84
	v_mul_f32_e32 v84, 0xbfb8aa3b, v87
	v_exp_f32_e32 v84, v84
	v_exp_f32_e32 v92, v90
	v_add_f32_e32 v88, 1.0, v88
	v_rcp_f32_e32 v90, v88
	v_add_f32_e32 v84, 1.0, v84
	v_rcp_f32_e32 v101, v84
	v_add_f32_e32 v84, 1.0, v92
	v_rcp_f32_e32 v100, v84
	v_pk_mul_f32 v[94:95], v[82:83], v[90:91]
	s_mov_b64 s[8:9], 0
	v_pk_mul_f32 v[90:91], v[86:87], v[100:101]
.LBB0_912:
	s_andn2_b64 vcc, exec, s[8:9]
	s_cbranch_vccnz .LBB0_916
	s_cmp_eq_u32 s5, 1
	s_cbranch_scc0 .LBB0_915
	v_add_u32_e32 v84, s4, v99
	v_readlane_b32 s8, v254, 53
	s_nop 1
	v_and_b32_e32 v84, s8, v84
	v_lshlrev_b32_e32 v84, 7, v84
	v_or3_b32 v84, v84, v139, v1
	v_lshlrev_b32_e32 v84, 3, v84
	v_mov_b32_e32 v90, v186
	v_mov_b32_e32 v91, v187
	v_mov_b32_e32 v94, v188
	v_mov_b32_e32 v95, v189
	s_waitcnt vmcnt(1)
	v_mov_b32_e32 v100, v90
	s_waitcnt vmcnt(0)
	v_mov_b32_e32 v101, v94
	v_mov_b32_e32 v94, v91
	v_pk_mul_f32 v[90:91], v[82:83], v[94:95]
	v_pk_mul_f32 v[94:95], v[86:87], v[94:95]
	v_pk_fma_f32 v[86:87], v[86:87], v[100:101], v[90:91]
	v_pk_fma_f32 v[82:83], v[82:83], v[100:101], v[94:95] neg_lo:[0,0,1] neg_hi:[0,0,1]

.LBB0_916:
	v_cvt_pk_bf16_f32 v82, v95, s0
	v_add_u32_e32 v95, 0x210, v98
	v_lshl_add_u32 v83, v130, 1, v95
	ds_write_b16 v83, v82
	v_cvt_pk_bf16_f32 v82, v94, s0
	ds_write_b16 v83, v82 offset:32
	v_cvt_pk_bf16_f32 v82, v91, s0
	ds_write_b16 v83, v82 offset:256
	v_cvt_pk_bf16_f32 v82, v90, s0
	v_or_b32_e32 v90, 35, v138
	ds_write_b16 v83, v82 offset:288
	v_lshl_add_u32 v82, v90, 2, v220
	v_mov_b32_e32 v86, v231
	v_mov_b32_e32 v84, v89
	v_mov_b32_e32 v92, v97
	s_cmp_gt_i32 s5, 1
	s_mov_b64 s[8:9], -1
	v_pk_mul_f32 v[82:83], v[84:85], v[86:87] op_sel_hi:[1,0]
	v_pk_mul_f32 v[84:85], v[92:93], v[86:87] op_sel_hi:[1,0]
	s_cbranch_scc0 .LBB0_918
	v_mul_f32_e32 v86, 0xbfb8aa3b, v83
	v_exp_f32_e32 v86, v86
	v_mul_f32_e32 v87, 0xbfb8aa3b, v82
	v_exp_f32_e32 v87, v87
	s_mov_b64 s[8:9], 0
	v_add_f32_e32 v86, 1.0, v86
	v_add_f32_e32 v88, 1.0, v87
	v_rcp_f32_e32 v87, v86
	v_mul_f32_e32 v86, 0xbfb8aa3b, v85
	v_exp_f32_e32 v89, v86
	v_mul_f32_e32 v86, 0xbfb8aa3b, v84
	v_exp_f32_e32 v91, v86
	v_rcp_f32_e32 v86, v88
	v_add_f32_e32 v88, 1.0, v89
	v_rcp_f32_e32 v93, v88
	v_add_f32_e32 v88, 1.0, v91
	v_rcp_f32_e32 v92, v88
	v_pk_mul_f32 v[88:89], v[82:83], v[86:87]
	v_pk_mul_f32 v[86:87], v[84:85], v[92:93]
.LBB0_918:
	s_andn2_b64 vcc, exec, s[8:9]
	s_cbranch_vccnz .LBB0_922
	s_cmp_eq_u32 s5, 1
	s_cbranch_scc0 .LBB0_921
	v_add_u32_e32 v86, s4, v90
	v_readlane_b32 s8, v254, 53
	s_nop 1
	v_and_b32_e32 v86, s8, v86
	v_lshlrev_b32_e32 v86, 7, v86
	v_or3_b32 v86, v86, v139, v1
	v_lshlrev_b32_e32 v88, 3, v86
	v_mov_b32_e32 v86, v190
	v_mov_b32_e32 v87, v191
	v_mov_b32_e32 v88, v192
	v_mov_b32_e32 v89, v193
	s_nop 0
	s_waitcnt vmcnt(1)
	v_mov_b32_e32 v90, v86
	s_waitcnt vmcnt(0)
	v_mov_b32_e32 v91, v88
	v_mov_b32_e32 v88, v87
	v_pk_mul_f32 v[86:87], v[82:83], v[88:89]
	v_pk_mul_f32 v[88:89], v[84:85], v[88:89]
	v_pk_fma_f32 v[84:85], v[84:85], v[90:91], v[86:87]
	v_pk_fma_f32 v[82:83], v[82:83], v[90:91], v[88:89] neg_lo:[0,0,1] neg_hi:[0,0,1]

.LBB0_922:
	v_add_u32_e32 v90, 0x210, v95
	v_cvt_pk_bf16_f32 v82, v89, s0
	v_lshl_add_u32 v83, v130, 1, v90
	ds_write_b16 v83, v82
	v_cvt_pk_bf16_f32 v82, v88, s0
	ds_write_b16 v83, v82 offset:32
	v_cvt_pk_bf16_f32 v82, v87, s0
	ds_write_b16 v83, v82 offset:256
	v_cvt_pk_bf16_f32 v82, v86, s0
	v_or_b32_e32 v91, 48, v138
	ds_write_b16 v83, v82 offset:288
	v_lshl_add_u32 v82, v91, 2, v220
	v_mov_b32_e32 v84, v232
	v_mov_b32_e32 v82, v70
	v_mov_b32_e32 v83, v66
	v_mov_b32_e32 v86, v78
	v_mov_b32_e32 v87, v74
	v_pk_mul_f32 v[82:83], v[82:83], v[84:85] op_sel_hi:[1,0]
	v_pk_mul_f32 v[84:85], v[86:87], v[84:85] op_sel_hi:[1,0]
	s_cmp_gt_i32 s5, 1
	s_mov_b64 s[8:9], -1
	s_cbranch_scc0 .LBB0_924
	v_mul_f32_e32 v66, 0xbfb8aa3b, v83
	v_exp_f32_e32 v66, v66
	v_mul_f32_e32 v70, 0xbfb8aa3b, v82
	v_mul_f32_e32 v74, 0xbfb8aa3b, v84
	v_exp_f32_e32 v70, v70
	v_add_f32_e32 v66, 1.0, v66
	v_rcp_f32_e32 v87, v66
	v_mul_f32_e32 v66, 0xbfb8aa3b, v85
	v_exp_f32_e32 v66, v66
	v_exp_f32_e32 v74, v74
	v_add_f32_e32 v70, 1.0, v70
	v_rcp_f32_e32 v86, v70
	v_add_f32_e32 v66, 1.0, v66
	v_rcp_f32_e32 v93, v66
	v_add_f32_e32 v66, 1.0, v74
	v_rcp_f32_e32 v92, v66
	v_pk_mul_f32 v[88:89], v[82:83], v[86:87]
	s_mov_b64 s[8:9], 0
	v_pk_mul_f32 v[86:87], v[84:85], v[92:93]
.LBB0_924:
	s_andn2_b64 vcc, exec, s[8:9]
	s_cbranch_vccnz .LBB0_928
	s_cmp_eq_u32 s5, 1
	s_cbranch_scc0 .LBB0_927
	v_add_u32_e32 v66, s4, v91
	v_readlane_b32 s8, v254, 53
	s_nop 1
	v_and_b32_e32 v66, s8, v66
	v_lshlrev_b32_e32 v66, 7, v66
	v_or3_b32 v66, v66, v139, v1
	v_lshlrev_b32_e32 v66, 3, v66
	v_mov_b32_e32 v86, v194
	v_mov_b32_e32 v87, v195
	v_mov_b32_e32 v88, v196
	v_mov_b32_e32 v89, v197
	s_waitcnt vmcnt(1)
	v_mov_b32_e32 v92, v86
	s_waitcnt vmcnt(0)
	v_mov_b32_e32 v93, v88
	v_mov_b32_e32 v88, v87
	v_pk_mul_f32 v[86:87], v[82:83], v[88:89]
	v_pk_mul_f32 v[88:89], v[84:85], v[88:89]
	v_pk_fma_f32 v[84:85], v[84:85], v[92:93], v[86:87]
	v_pk_fma_f32 v[82:83], v[82:83], v[92:93], v[88:89] neg_lo:[0,0,1] neg_hi:[0,0,1]

.LBB0_928:
	v_add_u32_e32 v82, 0x1ad0, v90
	v_cvt_pk_bf16_f32 v66, v89, s0
	v_lshl_add_u32 v70, v130, 1, v82
	ds_write_b16 v70, v66
	v_cvt_pk_bf16_f32 v66, v88, s0
	ds_write_b16 v70, v66 offset:32
	v_cvt_pk_bf16_f32 v66, v87, s0
	ds_write_b16 v70, v66 offset:256
	v_cvt_pk_bf16_f32 v66, v86, s0
	v_or_b32_e32 v83, 49, v138
	ds_write_b16 v70, v66 offset:288
	v_lshl_add_u32 v66, v83, 2, v220
	v_mov_b32_e32 v70, v233
	v_mov_b32_e32 v66, v71
	v_mov_b32_e32 v74, v79
	s_cmp_gt_i32 s5, 1
	s_mov_b64 s[8:9], -1
	v_pk_mul_f32 v[66:67], v[66:67], v[70:71] op_sel_hi:[1,0]
	v_pk_mul_f32 v[70:71], v[74:75], v[70:71] op_sel_hi:[1,0]
	s_cbranch_scc0 .LBB0_930
	v_mul_f32_e32 v74, 0xbfb8aa3b, v67
	v_exp_f32_e32 v74, v74
	v_mul_f32_e32 v75, 0xbfb8aa3b, v66
	v_exp_f32_e32 v75, v75
	s_mov_b64 s[8:9], 0
	v_add_f32_e32 v74, 1.0, v74
	v_add_f32_e32 v78, 1.0, v75
	v_rcp_f32_e32 v75, v74
	v_mul_f32_e32 v74, 0xbfb8aa3b, v71
	v_exp_f32_e32 v79, v74
	v_mul_f32_e32 v74, 0xbfb8aa3b, v70
	v_exp_f32_e32 v84, v74
	v_rcp_f32_e32 v74, v78
	v_add_f32_e32 v78, 1.0, v79
	v_rcp_f32_e32 v85, v78
	v_add_f32_e32 v78, 1.0, v84
	v_rcp_f32_e32 v84, v78
	v_pk_mul_f32 v[78:79], v[66:67], v[74:75]
	v_pk_mul_f32 v[74:75], v[70:71], v[84:85]
.LBB0_930:
	s_andn2_b64 vcc, exec, s[8:9]
	s_cbranch_vccnz .LBB0_934
	s_cmp_eq_u32 s5, 1
	s_cbranch_scc0 .LBB0_933
	v_add_u32_e32 v74, s4, v83
	v_readlane_b32 s8, v254, 53
	s_nop 1
	v_and_b32_e32 v74, s8, v74
	v_lshlrev_b32_e32 v74, 7, v74
	v_or3_b32 v74, v74, v139, v1
	v_lshlrev_b32_e32 v78, 3, v74
	v_mov_b32_e32 v74, v198
	v_mov_b32_e32 v75, v199
	v_mov_b32_e32 v78, v200
	v_mov_b32_e32 v79, v201
	s_nop 0
	s_waitcnt vmcnt(1)
	v_mov_b32_e32 v84, v74
	s_waitcnt vmcnt(0)
	v_mov_b32_e32 v85, v78
	v_mov_b32_e32 v78, v75
	v_pk_mul_f32 v[74:75], v[66:67], v[78:79]
	v_pk_mul_f32 v[78:79], v[70:71], v[78:79]
	v_pk_fma_f32 v[70:71], v[70:71], v[84:85], v[74:75]
	v_pk_fma_f32 v[66:67], v[66:67], v[84:85], v[78:79] neg_lo:[0,0,1] neg_hi:[0,0,1]

.LBB0_934:
	v_add_u32_e32 v82, 0x210, v82
	v_cvt_pk_bf16_f32 v66, v79, s0
	v_lshl_add_u32 v67, v130, 1, v82
	ds_write_b16 v67, v66
	v_cvt_pk_bf16_f32 v66, v78, s0
	ds_write_b16 v67, v66 offset:32
	v_cvt_pk_bf16_f32 v66, v75, s0
	ds_write_b16 v67, v66 offset:256
	v_cvt_pk_bf16_f32 v66, v74, s0
	v_or_b32_e32 v83, 50, v138
	ds_write_b16 v67, v66 offset:288
	v_lshl_add_u32 v66, v83, 2, v220
	v_mov_b32_e32 v70, v234
	v_mov_b32_e32 v66, v72
	v_mov_b32_e32 v67, v68
	v_mov_b32_e32 v74, v80
	v_mov_b32_e32 v75, v76
	v_pk_mul_f32 v[66:67], v[66:67], v[70:71] op_sel_hi:[1,0]
	v_pk_mul_f32 v[70:71], v[74:75], v[70:71] op_sel_hi:[1,0]
	s_cmp_gt_i32 s5, 1
	s_mov_b64 s[8:9], -1
	s_cbranch_scc0 .LBB0_936
	v_mul_f32_e32 v68, 0xbfb8aa3b, v67
	v_exp_f32_e32 v68, v68
	v_mul_f32_e32 v72, 0xbfb8aa3b, v66
	v_mul_f32_e32 v74, 0xbfb8aa3b, v70
	v_exp_f32_e32 v72, v72
	v_add_f32_e32 v68, 1.0, v68
	v_rcp_f32_e32 v75, v68
	v_mul_f32_e32 v68, 0xbfb8aa3b, v71
	v_exp_f32_e32 v68, v68
	v_exp_f32_e32 v76, v74
	v_add_f32_e32 v72, 1.0, v72
	v_rcp_f32_e32 v74, v72
	v_add_f32_e32 v68, 1.0, v68
	v_rcp_f32_e32 v85, v68
	v_add_f32_e32 v68, 1.0, v76
	v_rcp_f32_e32 v84, v68
	v_pk_mul_f32 v[78:79], v[66:67], v[74:75]
	s_mov_b64 s[8:9], 0
	v_pk_mul_f32 v[74:75], v[70:71], v[84:85]
.LBB0_936:
	s_andn2_b64 vcc, exec, s[8:9]
	s_cbranch_vccnz .LBB0_940
	s_cmp_eq_u32 s5, 1
	s_cbranch_scc0 .LBB0_939
	v_add_u32_e32 v68, s4, v83
	v_readlane_b32 s8, v254, 53
	s_nop 1
	v_and_b32_e32 v68, s8, v68
	v_lshlrev_b32_e32 v68, 7, v68
	v_or3_b32 v68, v68, v139, v1
	v_lshlrev_b32_e32 v68, 3, v68
	v_mov_b32_e32 v74, v202
	v_mov_b32_e32 v75, v203
	v_mov_b32_e32 v78, v204
	v_mov_b32_e32 v79, v205
	s_waitcnt vmcnt(1)
	v_mov_b32_e32 v84, v74
	s_waitcnt vmcnt(0)
	v_mov_b32_e32 v85, v78
	v_mov_b32_e32 v78, v75
	v_pk_mul_f32 v[74:75], v[66:67], v[78:79]
	v_pk_mul_f32 v[78:79], v[70:71], v[78:79]
	v_pk_fma_f32 v[70:71], v[70:71], v[84:85], v[74:75]
	v_pk_fma_f32 v[66:67], v[66:67], v[84:85], v[78:79] neg_lo:[0,0,1] neg_hi:[0,0,1]

.LBB0_940:
	v_cvt_pk_bf16_f32 v66, v79, s0
	v_add_u32_e32 v79, 0x210, v82
	v_lshl_add_u32 v67, v130, 1, v79
	ds_write_b16 v67, v66
	v_cvt_pk_bf16_f32 v66, v78, s0
	ds_write_b16 v67, v66 offset:32
	v_cvt_pk_bf16_f32 v66, v75, s0
	ds_write_b16 v67, v66 offset:256
	v_cvt_pk_bf16_f32 v66, v74, s0
	v_or_b32_e32 v74, 51, v138
	ds_write_b16 v67, v66 offset:288
	v_lshl_add_u32 v66, v74, 2, v220
	v_mov_b32_e32 v70, v235
	v_mov_b32_e32 v68, v73
	v_mov_b32_e32 v76, v81
	s_cmp_gt_i32 s5, 1
	s_mov_b64 s[8:9], -1
	v_pk_mul_f32 v[66:67], v[68:69], v[70:71] op_sel_hi:[1,0]
	v_pk_mul_f32 v[68:69], v[76:77], v[70:71] op_sel_hi:[1,0]
	s_cbranch_scc0 .LBB0_942
	v_mul_f32_e32 v70, 0xbfb8aa3b, v67
	v_exp_f32_e32 v70, v70
	v_mul_f32_e32 v71, 0xbfb8aa3b, v66
	v_exp_f32_e32 v71, v71
	s_mov_b64 s[8:9], 0
	v_add_f32_e32 v70, 1.0, v70
	v_add_f32_e32 v72, 1.0, v71
	v_rcp_f32_e32 v71, v70
	v_mul_f32_e32 v70, 0xbfb8aa3b, v69
	v_exp_f32_e32 v73, v70
	v_mul_f32_e32 v70, 0xbfb8aa3b, v68
	v_exp_f32_e32 v75, v70
	v_rcp_f32_e32 v70, v72
	v_add_f32_e32 v72, 1.0, v73
	v_rcp_f32_e32 v77, v72
	v_add_f32_e32 v72, 1.0, v75
	v_rcp_f32_e32 v76, v72
	v_pk_mul_f32 v[72:73], v[66:67], v[70:71]
	v_pk_mul_f32 v[70:71], v[68:69], v[76:77]
.LBB0_942:
	s_andn2_b64 vcc, exec, s[8:9]
	s_cbranch_vccnz .LBB0_946
	s_cmp_eq_u32 s5, 1
	s_cbranch_scc0 .LBB0_945
	v_add_u32_e32 v70, s4, v74
	v_readlane_b32 s8, v254, 53
	s_nop 1
	v_and_b32_e32 v70, s8, v70
	v_lshlrev_b32_e32 v70, 7, v70
	v_or3_b32 v70, v70, v139, v1
	v_lshlrev_b32_e32 v72, 3, v70
	v_mov_b32_e32 v70, v206
	v_mov_b32_e32 v71, v207
	v_mov_b32_e32 v72, v208
	v_mov_b32_e32 v73, v209
	s_nop 0
	s_waitcnt vmcnt(1)
	v_mov_b32_e32 v74, v70
	s_waitcnt vmcnt(0)
	v_mov_b32_e32 v75, v72
	v_mov_b32_e32 v72, v71
	v_pk_mul_f32 v[70:71], v[66:67], v[72:73]
	v_pk_mul_f32 v[72:73], v[68:69], v[72:73]
	v_pk_fma_f32 v[68:69], v[68:69], v[74:75], v[70:71]
	v_pk_fma_f32 v[66:67], v[66:67], v[74:75], v[72:73] neg_lo:[0,0,1] neg_hi:[0,0,1]

.LBB0_946:
	v_add_u32_e32 v74, 0x210, v79
	v_cvt_pk_bf16_f32 v66, v73, s0
	v_lshl_add_u32 v67, v130, 1, v74
	v_mov_b32_e32 v68, v236
	ds_write_b16 v67, v66
	v_cvt_pk_bf16_f32 v66, v72, s0
	ds_write_b16 v67, v66 offset:32
	v_cvt_pk_bf16_f32 v66, v71, s0
	ds_write_b16 v67, v66 offset:256
	v_cvt_pk_bf16_f32 v66, v70, s0
	ds_write_b16 v67, v66 offset:288
	v_mov_b32_e32 v66, v54
	v_mov_b32_e32 v67, v50
	v_mov_b32_e32 v70, v62
	v_mov_b32_e32 v71, v58
	v_pk_mul_f32 v[66:67], v[66:67], v[68:69] op_sel_hi:[1,0]
	v_pk_mul_f32 v[68:69], v[70:71], v[68:69] op_sel_hi:[1,0]
	s_cmp_gt_i32 s5, 1
	s_mov_b64 s[8:9], -1
	s_cbranch_scc0 .LBB0_948
	v_mul_f32_e32 v50, 0xbfb8aa3b, v67
	v_exp_f32_e32 v50, v50
	v_mul_f32_e32 v54, 0xbfb8aa3b, v66
	v_mul_f32_e32 v58, 0xbfb8aa3b, v68
	v_exp_f32_e32 v54, v54
	v_add_f32_e32 v50, 1.0, v50
	v_rcp_f32_e32 v71, v50
	v_mul_f32_e32 v50, 0xbfb8aa3b, v69
	v_exp_f32_e32 v50, v50
	v_exp_f32_e32 v58, v58
	v_add_f32_e32 v54, 1.0, v54
	v_rcp_f32_e32 v70, v54
	v_add_f32_e32 v50, 1.0, v50
	v_rcp_f32_e32 v77, v50
	v_add_f32_e32 v50, 1.0, v58
	v_rcp_f32_e32 v76, v50
	v_pk_mul_f32 v[72:73], v[66:67], v[70:71]
	s_mov_b64 s[8:9], 0
	v_pk_mul_f32 v[70:71], v[68:69], v[76:77]
.LBB0_948:
	s_andn2_b64 vcc, exec, s[8:9]
	s_cbranch_vccnz .LBB0_952
	s_cmp_eq_u32 s5, 1
	s_cbranch_scc0 .LBB0_951
	v_add_u32_e32 v50, s4, v138
	v_add_u32_e32 v50, 0x80, v50
	v_readlane_b32 s8, v254, 53
	s_nop 1
	v_and_b32_e32 v50, s8, v50
	v_lshlrev_b32_e32 v50, 7, v50
	v_or3_b32 v50, v50, v139, v1
	v_lshlrev_b32_e32 v50, 3, v50
	global_load_dwordx2 v[146:147], v50, s[0:1] offset:128
	global_load_dwordx2 v[148:149], v50, s[0:1]
	global_load_dwordx2 v[150:151], v50, s[0:1] offset:1152
	global_load_dwordx2 v[152:153], v50, s[0:1] offset:1024
	global_load_dwordx2 v[154:155], v50, s[0:1] offset:2176
	global_load_dwordx2 v[156:157], v50, s[0:1] offset:2048
	global_load_dwordx2 v[158:159], v50, s[0:1] offset:3200
	global_load_dwordx2 v[160:161], v50, s[0:1] offset:3072
	v_add_u32_e32 v141, 0x4000, v50
	global_load_dwordx2 v[162:163], v141, s[0:1] offset:128
	global_load_dwordx2 v[164:165], v141, s[0:1]
	global_load_dwordx2 v[166:167], v141, s[0:1] offset:1152
	global_load_dwordx2 v[168:169], v141, s[0:1] offset:1024
	global_load_dwordx2 v[170:171], v141, s[0:1] offset:2176
	global_load_dwordx2 v[172:173], v141, s[0:1] offset:2048
	global_load_dwordx2 v[174:175], v141, s[0:1] offset:3200
	global_load_dwordx2 v[176:177], v141, s[0:1] offset:3072
	v_add_u32_e32 v141, 0x8000, v50
	global_load_dwordx2 v[178:179], v141, s[0:1] offset:128
	global_load_dwordx2 v[180:181], v141, s[0:1]
	global_load_dwordx2 v[182:183], v141, s[0:1] offset:1152
	global_load_dwordx2 v[184:185], v141, s[0:1] offset:1024
	global_load_dwordx2 v[186:187], v141, s[0:1] offset:2176
	global_load_dwordx2 v[188:189], v141, s[0:1] offset:2048
	global_load_dwordx2 v[190:191], v141, s[0:1] offset:3200
	global_load_dwordx2 v[192:193], v141, s[0:1] offset:3072
	v_add_u32_e32 v141, 0xc000, v50
	global_load_dwordx2 v[194:195], v141, s[0:1] offset:128
	global_load_dwordx2 v[196:197], v141, s[0:1]
	global_load_dwordx2 v[198:199], v141, s[0:1] offset:1152
	global_load_dwordx2 v[200:201], v141, s[0:1] offset:1024
	global_load_dwordx2 v[202:203], v141, s[0:1] offset:2176
	global_load_dwordx2 v[204:205], v141, s[0:1] offset:2048
	global_load_dwordx2 v[206:207], v141, s[0:1] offset:3200
	global_load_dwordx2 v[208:209], v141, s[0:1] offset:3072
	s_waitcnt vmcnt(0)
	v_mov_b32_e32 v70, v146
	v_mov_b32_e32 v71, v147
	v_mov_b32_e32 v72, v148
	v_mov_b32_e32 v73, v149
	s_waitcnt vmcnt(1)
	v_mov_b32_e32 v76, v70
	s_waitcnt vmcnt(0)
	v_mov_b32_e32 v77, v72
	v_mov_b32_e32 v72, v71
	v_pk_mul_f32 v[70:71], v[66:67], v[72:73]
	v_pk_mul_f32 v[72:73], v[68:69], v[72:73]
	v_pk_fma_f32 v[68:69], v[68:69], v[76:77], v[70:71]
	v_pk_fma_f32 v[66:67], v[66:67], v[76:77], v[72:73] neg_lo:[0,0,1] neg_hi:[0,0,1]

.LBB0_952:
	v_add_u32_e32 v66, 0x9ed0, v74
	v_cvt_pk_bf16_f32 v50, v73, s0
	v_lshl_add_u32 v54, v130, 1, v66
	ds_write_b16 v54, v50
	v_cvt_pk_bf16_f32 v50, v72, s0
	ds_write_b16 v54, v50 offset:32
	v_cvt_pk_bf16_f32 v50, v71, s0
	ds_write_b16 v54, v50 offset:256
	v_cvt_pk_bf16_f32 v50, v70, s0
	ds_write_b16 v54, v50 offset:288
	v_mov_b32_e32 v54, v237
	v_mov_b32_e32 v50, v55
	v_mov_b32_e32 v58, v63
	s_cmp_gt_i32 s5, 1
	s_mov_b64 s[8:9], -1
	v_pk_mul_f32 v[50:51], v[50:51], v[54:55] op_sel_hi:[1,0]
	v_pk_mul_f32 v[54:55], v[58:59], v[54:55] op_sel_hi:[1,0]
	s_cbranch_scc0 .LBB0_954
	v_mul_f32_e32 v58, 0xbfb8aa3b, v51
	v_exp_f32_e32 v58, v58
	v_mul_f32_e32 v59, 0xbfb8aa3b, v50
	v_exp_f32_e32 v59, v59
	s_mov_b64 s[8:9], 0
	v_add_f32_e32 v58, 1.0, v58
	v_add_f32_e32 v62, 1.0, v59
	v_rcp_f32_e32 v59, v58
	v_mul_f32_e32 v58, 0xbfb8aa3b, v55
	v_exp_f32_e32 v63, v58
	v_mul_f32_e32 v58, 0xbfb8aa3b, v54
	v_exp_f32_e32 v67, v58
	v_rcp_f32_e32 v58, v62
	v_add_f32_e32 v62, 1.0, v63
	v_rcp_f32_e32 v69, v62
	v_add_f32_e32 v62, 1.0, v67
	v_rcp_f32_e32 v68, v62
	v_pk_mul_f32 v[62:63], v[50:51], v[58:59]
	v_pk_mul_f32 v[58:59], v[54:55], v[68:69]
.LBB0_954:
	s_andn2_b64 vcc, exec, s[8:9]
	s_cbranch_vccnz .LBB0_958
	s_cmp_eq_u32 s5, 1
	s_cbranch_scc0 .LBB0_957
	v_add_u32_e32 v58, s4, v138
	v_add_u32_e32 v58, 0x81, v58
	v_readlane_b32 s8, v254, 53
	s_nop 1
	v_and_b32_e32 v58, s8, v58
	v_lshlrev_b32_e32 v58, 7, v58
	v_or3_b32 v58, v58, v139, v1
	v_lshlrev_b32_e32 v62, 3, v58
	v_mov_b32_e32 v58, v150
	v_mov_b32_e32 v59, v151
	v_mov_b32_e32 v62, v152
	v_mov_b32_e32 v63, v153
	s_nop 0
	s_waitcnt vmcnt(1)
	v_mov_b32_e32 v68, v58
	s_waitcnt vmcnt(0)
	v_mov_b32_e32 v69, v62
	v_mov_b32_e32 v62, v59
	v_pk_mul_f32 v[58:59], v[50:51], v[62:63]
	v_pk_mul_f32 v[62:63], v[54:55], v[62:63]
	v_pk_fma_f32 v[54:55], v[54:55], v[68:69], v[58:59]
	v_pk_fma_f32 v[50:51], v[50:51], v[68:69], v[62:63] neg_lo:[0,0,1] neg_hi:[0,0,1]

.LBB0_958:
	v_add_u32_e32 v66, 0x210, v66
	v_cvt_pk_bf16_f32 v50, v63, s0
	v_lshl_add_u32 v51, v130, 1, v66
	v_mov_b32_e32 v54, v238
	ds_write_b16 v51, v50
	v_cvt_pk_bf16_f32 v50, v62, s0
	ds_write_b16 v51, v50 offset:32
	v_cvt_pk_bf16_f32 v50, v59, s0
	ds_write_b16 v51, v50 offset:256
	v_cvt_pk_bf16_f32 v50, v58, s0
	ds_write_b16 v51, v50 offset:288
	v_mov_b32_e32 v50, v56
	v_mov_b32_e32 v51, v52
	v_mov_b32_e32 v58, v64
	v_mov_b32_e32 v59, v60
	v_pk_mul_f32 v[50:51], v[50:51], v[54:55] op_sel_hi:[1,0]
	v_pk_mul_f32 v[54:55], v[58:59], v[54:55] op_sel_hi:[1,0]
	s_cmp_gt_i32 s5, 1
	s_mov_b64 s[8:9], -1
	s_cbranch_scc0 .LBB0_960
	v_mul_f32_e32 v52, 0xbfb8aa3b, v51
	v_exp_f32_e32 v52, v52
	v_mul_f32_e32 v56, 0xbfb8aa3b, v50
	v_mul_f32_e32 v58, 0xbfb8aa3b, v54
	v_exp_f32_e32 v56, v56
	v_add_f32_e32 v52, 1.0, v52
	v_rcp_f32_e32 v59, v52
	v_mul_f32_e32 v52, 0xbfb8aa3b, v55
	v_exp_f32_e32 v52, v52
	v_exp_f32_e32 v60, v58
	v_add_f32_e32 v56, 1.0, v56
	v_rcp_f32_e32 v58, v56
	v_add_f32_e32 v52, 1.0, v52
	v_rcp_f32_e32 v69, v52
	v_add_f32_e32 v52, 1.0, v60
	v_rcp_f32_e32 v68, v52
	v_pk_mul_f32 v[62:63], v[50:51], v[58:59]
	s_mov_b64 s[8:9], 0
	v_pk_mul_f32 v[58:59], v[54:55], v[68:69]
.LBB0_960:
	s_andn2_b64 vcc, exec, s[8:9]
	s_cbranch_vccnz .LBB0_964
	s_cmp_eq_u32 s5, 1
	s_cbranch_scc0 .LBB0_963
	v_add_u32_e32 v52, s4, v138
	v_add_u32_e32 v52, 0x82, v52
	v_readlane_b32 s8, v254, 53
	s_nop 1
	v_and_b32_e32 v52, s8, v52
	v_lshlrev_b32_e32 v52, 7, v52
	v_or3_b32 v52, v52, v139, v1
	v_lshlrev_b32_e32 v52, 3, v52
	v_mov_b32_e32 v58, v154
	v_mov_b32_e32 v59, v155
	v_mov_b32_e32 v62, v156
	v_mov_b32_e32 v63, v157
	s_waitcnt vmcnt(1)
	v_mov_b32_e32 v68, v58
	s_waitcnt vmcnt(0)
	v_mov_b32_e32 v69, v62
	v_mov_b32_e32 v62, v59
	v_pk_mul_f32 v[58:59], v[50:51], v[62:63]
	v_pk_mul_f32 v[62:63], v[54:55], v[62:63]
	v_pk_fma_f32 v[54:55], v[54:55], v[68:69], v[58:59]
	v_pk_fma_f32 v[50:51], v[50:51], v[68:69], v[62:63] neg_lo:[0,0,1] neg_hi:[0,0,1]

.LBB0_964:
	v_cvt_pk_bf16_f32 v50, v63, s0
	v_add_u32_e32 v63, 0x210, v66
	v_mov_b32_e32 v54, v239
	v_lshl_add_u32 v51, v130, 1, v63
	ds_write_b16 v51, v50
	v_cvt_pk_bf16_f32 v50, v62, s0
	ds_write_b16 v51, v50 offset:32
	v_cvt_pk_bf16_f32 v50, v59, s0
	ds_write_b16 v51, v50 offset:256
	v_cvt_pk_bf16_f32 v50, v58, s0
	v_mov_b32_e32 v52, v57
	v_mov_b32_e32 v60, v65
	ds_write_b16 v51, v50 offset:288
	s_cmp_gt_i32 s5, 1
	v_pk_mul_f32 v[50:51], v[52:53], v[54:55] op_sel_hi:[1,0]
	v_pk_mul_f32 v[52:53], v[60:61], v[54:55] op_sel_hi:[1,0]
	s_mov_b64 s[8:9], -1
	s_cbranch_scc0 .LBB0_966
	v_mul_f32_e32 v54, 0xbfb8aa3b, v51
	v_exp_f32_e32 v54, v54
	v_mul_f32_e32 v55, 0xbfb8aa3b, v50
	v_exp_f32_e32 v55, v55
	s_mov_b64 s[8:9], 0
	v_add_f32_e32 v54, 1.0, v54
	v_add_f32_e32 v56, 1.0, v55
	v_rcp_f32_e32 v55, v54
	v_mul_f32_e32 v54, 0xbfb8aa3b, v53
	v_exp_f32_e32 v57, v54
	v_mul_f32_e32 v54, 0xbfb8aa3b, v52
	v_exp_f32_e32 v58, v54
	v_rcp_f32_e32 v54, v56
	v_add_f32_e32 v56, 1.0, v57
	v_rcp_f32_e32 v59, v56
	v_add_f32_e32 v56, 1.0, v58
	v_rcp_f32_e32 v58, v56
	v_pk_mul_f32 v[56:57], v[50:51], v[54:55]
	v_pk_mul_f32 v[54:55], v[52:53], v[58:59]
.LBB0_966:
	s_andn2_b64 vcc, exec, s[8:9]
	s_cbranch_vccnz .LBB0_970
	s_cmp_eq_u32 s5, 1
	s_cbranch_scc0 .LBB0_969
	v_add_u32_e32 v54, s4, v138
	v_add_u32_e32 v54, 0x83, v54
	v_readlane_b32 s8, v254, 53
	s_nop 1
	v_and_b32_e32 v54, s8, v54
	v_lshlrev_b32_e32 v54, 7, v54
	v_or3_b32 v54, v54, v139, v1
	v_lshlrev_b32_e32 v56, 3, v54
	v_mov_b32_e32 v54, v158
	v_mov_b32_e32 v55, v159
	v_mov_b32_e32 v56, v160
	v_mov_b32_e32 v57, v161
	s_nop 0
	s_waitcnt vmcnt(1)
	v_mov_b32_e32 v58, v54
	s_waitcnt vmcnt(0)
	v_mov_b32_e32 v59, v56
	v_mov_b32_e32 v56, v55
	v_pk_mul_f32 v[54:55], v[50:51], v[56:57]
	v_pk_mul_f32 v[56:57], v[52:53], v[56:57]
	v_pk_fma_f32 v[52:53], v[52:53], v[58:59], v[54:55]
	v_pk_fma_f32 v[50:51], v[50:51], v[58:59], v[56:57] neg_lo:[0,0,1] neg_hi:[0,0,1]

.LBB0_970:
	v_add_u32_e32 v58, 0x210, v63
	v_cvt_pk_bf16_f32 v50, v57, s0
	v_lshl_add_u32 v51, v130, 1, v58
	v_mov_b32_e32 v52, v240
	ds_write_b16 v51, v50
	v_cvt_pk_bf16_f32 v50, v56, s0
	ds_write_b16 v51, v50 offset:32
	v_cvt_pk_bf16_f32 v50, v55, s0
	ds_write_b16 v51, v50 offset:256
	v_cvt_pk_bf16_f32 v50, v54, s0
	ds_write_b16 v51, v50 offset:288
	v_mov_b32_e32 v50, v38
	v_mov_b32_e32 v51, v34
	v_mov_b32_e32 v54, v46
	v_mov_b32_e32 v55, v42
	v_pk_mul_f32 v[50:51], v[50:51], v[52:53] op_sel_hi:[1,0]
	v_pk_mul_f32 v[52:53], v[54:55], v[52:53] op_sel_hi:[1,0]
	s_cmp_gt_i32 s5, 1
	s_mov_b64 s[8:9], -1
	s_cbranch_scc0 .LBB0_972
	v_mul_f32_e32 v34, 0xbfb8aa3b, v51
	v_exp_f32_e32 v34, v34
	v_mul_f32_e32 v38, 0xbfb8aa3b, v50
	v_mul_f32_e32 v42, 0xbfb8aa3b, v52
	v_exp_f32_e32 v38, v38
	v_add_f32_e32 v34, 1.0, v34
	v_rcp_f32_e32 v55, v34
	v_mul_f32_e32 v34, 0xbfb8aa3b, v53
	v_exp_f32_e32 v34, v34
	v_exp_f32_e32 v42, v42
	v_add_f32_e32 v38, 1.0, v38
	v_rcp_f32_e32 v54, v38
	v_add_f32_e32 v34, 1.0, v34
	v_rcp_f32_e32 v61, v34
	v_add_f32_e32 v34, 1.0, v42
	v_rcp_f32_e32 v60, v34
	v_pk_mul_f32 v[56:57], v[50:51], v[54:55]
	s_mov_b64 s[8:9], 0
	v_pk_mul_f32 v[54:55], v[52:53], v[60:61]
.LBB0_972:
	s_andn2_b64 vcc, exec, s[8:9]
	s_cbranch_vccnz .LBB0_976
	s_cmp_eq_u32 s5, 1
	s_cbranch_scc0 .LBB0_975
	v_add_u32_e32 v34, s4, v138
	v_add_u32_e32 v34, 0x90, v34
	v_readlane_b32 s8, v254, 53
	s_nop 1
	v_and_b32_e32 v34, s8, v34
	v_lshlrev_b32_e32 v34, 7, v34
	v_or3_b32 v34, v34, v139, v1
	v_lshlrev_b32_e32 v34, 3, v34
	v_mov_b32_e32 v54, v162
	v_mov_b32_e32 v55, v163
	v_mov_b32_e32 v56, v164
	v_mov_b32_e32 v57, v165
	s_waitcnt vmcnt(1)
	v_mov_b32_e32 v60, v54
	s_waitcnt vmcnt(0)
	v_mov_b32_e32 v61, v56
	v_mov_b32_e32 v56, v55
	v_pk_mul_f32 v[54:55], v[50:51], v[56:57]
	v_pk_mul_f32 v[56:57], v[52:53], v[56:57]
	v_pk_fma_f32 v[52:53], v[52:53], v[60:61], v[54:55]
	v_pk_fma_f32 v[50:51], v[50:51], v[60:61], v[56:57] neg_lo:[0,0,1] neg_hi:[0,0,1]

.LBB0_976:
	v_add_u32_e32 v50, 0x1ad0, v58
	v_cvt_pk_bf16_f32 v34, v57, s0
	v_lshl_add_u32 v38, v130, 1, v50
	ds_write_b16 v38, v34
	v_cvt_pk_bf16_f32 v34, v56, s0
	ds_write_b16 v38, v34 offset:32
	v_cvt_pk_bf16_f32 v34, v55, s0
	ds_write_b16 v38, v34 offset:256
	v_cvt_pk_bf16_f32 v34, v54, s0
	ds_write_b16 v38, v34 offset:288
	v_mov_b32_e32 v38, v241
	v_mov_b32_e32 v34, v39
	v_mov_b32_e32 v42, v47
	s_cmp_gt_i32 s5, 1
	s_mov_b64 s[8:9], -1
	v_pk_mul_f32 v[34:35], v[34:35], v[38:39] op_sel_hi:[1,0]
	v_pk_mul_f32 v[38:39], v[42:43], v[38:39] op_sel_hi:[1,0]
	s_cbranch_scc0 .LBB0_978
	v_mul_f32_e32 v42, 0xbfb8aa3b, v35
	v_exp_f32_e32 v42, v42
	v_mul_f32_e32 v43, 0xbfb8aa3b, v34
	v_exp_f32_e32 v43, v43
	s_mov_b64 s[8:9], 0
	v_add_f32_e32 v42, 1.0, v42
	v_add_f32_e32 v46, 1.0, v43
	v_rcp_f32_e32 v43, v42
	v_mul_f32_e32 v42, 0xbfb8aa3b, v39
	v_exp_f32_e32 v47, v42
	v_mul_f32_e32 v42, 0xbfb8aa3b, v38
	v_exp_f32_e32 v51, v42
	v_rcp_f32_e32 v42, v46
	v_add_f32_e32 v46, 1.0, v47
	v_rcp_f32_e32 v53, v46
	v_add_f32_e32 v46, 1.0, v51
	v_rcp_f32_e32 v52, v46
	v_pk_mul_f32 v[46:47], v[34:35], v[42:43]
	v_pk_mul_f32 v[42:43], v[38:39], v[52:53]
.LBB0_978:
	s_andn2_b64 vcc, exec, s[8:9]
	s_cbranch_vccnz .LBB0_982
	s_cmp_eq_u32 s5, 1
	s_cbranch_scc0 .LBB0_981
	v_add_u32_e32 v42, s4, v138
	v_add_u32_e32 v42, 0x91, v42
	v_readlane_b32 s8, v254, 53
	s_nop 1
	v_and_b32_e32 v42, s8, v42
	v_lshlrev_b32_e32 v42, 7, v42
	v_or3_b32 v42, v42, v139, v1
	v_lshlrev_b32_e32 v46, 3, v42
	v_mov_b32_e32 v42, v166
	v_mov_b32_e32 v43, v167
	v_mov_b32_e32 v46, v168
	v_mov_b32_e32 v47, v169
	s_nop 0
	s_waitcnt vmcnt(1)
	v_mov_b32_e32 v52, v42
	s_waitcnt vmcnt(0)
	v_mov_b32_e32 v53, v46
	v_mov_b32_e32 v46, v43
	v_pk_mul_f32 v[42:43], v[34:35], v[46:47]
	v_pk_mul_f32 v[46:47], v[38:39], v[46:47]
	v_pk_fma_f32 v[38:39], v[38:39], v[52:53], v[42:43]
	v_pk_fma_f32 v[34:35], v[34:35], v[52:53], v[46:47] neg_lo:[0,0,1] neg_hi:[0,0,1]

.LBB0_982:
	v_add_u32_e32 v50, 0x210, v50
	v_cvt_pk_bf16_f32 v34, v47, s0
	v_lshl_add_u32 v35, v130, 1, v50
	v_mov_b32_e32 v38, v242
	ds_write_b16 v35, v34
	v_cvt_pk_bf16_f32 v34, v46, s0
	ds_write_b16 v35, v34 offset:32
	v_cvt_pk_bf16_f32 v34, v43, s0
	ds_write_b16 v35, v34 offset:256
	v_cvt_pk_bf16_f32 v34, v42, s0
	ds_write_b16 v35, v34 offset:288
	v_mov_b32_e32 v34, v40
	v_mov_b32_e32 v35, v36
	v_mov_b32_e32 v42, v48
	v_mov_b32_e32 v43, v44
	v_pk_mul_f32 v[34:35], v[34:35], v[38:39] op_sel_hi:[1,0]
	v_pk_mul_f32 v[38:39], v[42:43], v[38:39] op_sel_hi:[1,0]
	s_cmp_gt_i32 s5, 1
	s_mov_b64 s[8:9], -1
	s_cbranch_scc0 .LBB0_984
	v_mul_f32_e32 v36, 0xbfb8aa3b, v35
	v_exp_f32_e32 v36, v36
	v_mul_f32_e32 v40, 0xbfb8aa3b, v34
	v_mul_f32_e32 v42, 0xbfb8aa3b, v38
	v_exp_f32_e32 v40, v40
	v_add_f32_e32 v36, 1.0, v36
	v_rcp_f32_e32 v43, v36
	v_mul_f32_e32 v36, 0xbfb8aa3b, v39
	v_exp_f32_e32 v36, v36
	v_exp_f32_e32 v44, v42
	v_add_f32_e32 v40, 1.0, v40
	v_rcp_f32_e32 v42, v40
	v_add_f32_e32 v36, 1.0, v36
	v_rcp_f32_e32 v53, v36
	v_add_f32_e32 v36, 1.0, v44
	v_rcp_f32_e32 v52, v36
	v_pk_mul_f32 v[46:47], v[34:35], v[42:43]
	s_mov_b64 s[8:9], 0
	v_pk_mul_f32 v[42:43], v[38:39], v[52:53]
.LBB0_984:
	s_andn2_b64 vcc, exec, s[8:9]
	s_cbranch_vccnz .LBB0_988
	s_cmp_eq_u32 s5, 1
	s_cbranch_scc0 .LBB0_987
	v_add_u32_e32 v36, s4, v138
	v_add_u32_e32 v36, 0x92, v36
	v_readlane_b32 s8, v254, 53
	s_nop 1
	v_and_b32_e32 v36, s8, v36
	v_lshlrev_b32_e32 v36, 7, v36
	v_or3_b32 v36, v36, v139, v1
	v_lshlrev_b32_e32 v36, 3, v36
	v_mov_b32_e32 v42, v170
	v_mov_b32_e32 v43, v171
	v_mov_b32_e32 v46, v172
	v_mov_b32_e32 v47, v173
	s_waitcnt vmcnt(1)
	v_mov_b32_e32 v52, v42
	s_waitcnt vmcnt(0)
	v_mov_b32_e32 v53, v46
	v_mov_b32_e32 v46, v43
	v_pk_mul_f32 v[42:43], v[34:35], v[46:47]
	v_pk_mul_f32 v[46:47], v[38:39], v[46:47]
	v_pk_fma_f32 v[38:39], v[38:39], v[52:53], v[42:43]
	v_pk_fma_f32 v[34:35], v[34:35], v[52:53], v[46:47] neg_lo:[0,0,1] neg_hi:[0,0,1]

.LBB0_988:
	v_cvt_pk_bf16_f32 v34, v47, s0
	v_add_u32_e32 v47, 0x210, v50
	v_mov_b32_e32 v38, v243
	v_lshl_add_u32 v35, v130, 1, v47
	ds_write_b16 v35, v34
	v_cvt_pk_bf16_f32 v34, v46, s0
	ds_write_b16 v35, v34 offset:32
	v_cvt_pk_bf16_f32 v34, v43, s0
	ds_write_b16 v35, v34 offset:256
	v_cvt_pk_bf16_f32 v34, v42, s0
	v_mov_b32_e32 v36, v41
	v_mov_b32_e32 v44, v49
	ds_write_b16 v35, v34 offset:288
	s_cmp_gt_i32 s5, 1
	v_pk_mul_f32 v[34:35], v[36:37], v[38:39] op_sel_hi:[1,0]
	v_pk_mul_f32 v[36:37], v[44:45], v[38:39] op_sel_hi:[1,0]
	s_mov_b64 s[8:9], -1
	s_cbranch_scc0 .LBB0_990
	v_mul_f32_e32 v38, 0xbfb8aa3b, v35
	v_exp_f32_e32 v38, v38
	v_mul_f32_e32 v39, 0xbfb8aa3b, v34
	v_exp_f32_e32 v39, v39
	s_mov_b64 s[8:9], 0
	v_add_f32_e32 v38, 1.0, v38
	v_add_f32_e32 v40, 1.0, v39
	v_rcp_f32_e32 v39, v38
	v_mul_f32_e32 v38, 0xbfb8aa3b, v37
	v_exp_f32_e32 v41, v38
	v_mul_f32_e32 v38, 0xbfb8aa3b, v36
	v_exp_f32_e32 v42, v38
	v_rcp_f32_e32 v38, v40
	v_add_f32_e32 v40, 1.0, v41
	v_rcp_f32_e32 v43, v40
	v_add_f32_e32 v40, 1.0, v42
	v_rcp_f32_e32 v42, v40
	v_pk_mul_f32 v[40:41], v[34:35], v[38:39]
	v_pk_mul_f32 v[38:39], v[36:37], v[42:43]
.LBB0_990:
	s_andn2_b64 vcc, exec, s[8:9]
	s_cbranch_vccnz .LBB0_994
	s_cmp_eq_u32 s5, 1
	s_cbranch_scc0 .LBB0_993
	v_add_u32_e32 v38, s4, v138
	v_add_u32_e32 v38, 0x93, v38
	v_readlane_b32 s8, v254, 53
	s_nop 1
	v_and_b32_e32 v38, s8, v38
	v_lshlrev_b32_e32 v38, 7, v38
	v_or3_b32 v38, v38, v139, v1
	v_lshlrev_b32_e32 v40, 3, v38
	v_mov_b32_e32 v38, v174
	v_mov_b32_e32 v39, v175
	v_mov_b32_e32 v40, v176
	v_mov_b32_e32 v41, v177
	s_nop 0
	s_waitcnt vmcnt(1)
	v_mov_b32_e32 v42, v38
	s_waitcnt vmcnt(0)
	v_mov_b32_e32 v43, v40
	v_mov_b32_e32 v40, v39
	v_pk_mul_f32 v[38:39], v[34:35], v[40:41]
	v_pk_mul_f32 v[40:41], v[36:37], v[40:41]
	v_pk_fma_f32 v[36:37], v[36:37], v[42:43], v[38:39]
	v_pk_fma_f32 v[34:35], v[34:35], v[42:43], v[40:41] neg_lo:[0,0,1] neg_hi:[0,0,1]

.LBB0_994:
	v_add_u32_e32 v42, 0x210, v47
	v_cvt_pk_bf16_f32 v34, v41, s0
	v_lshl_add_u32 v35, v130, 1, v42
	v_mov_b32_e32 v36, v244
	ds_write_b16 v35, v34
	v_cvt_pk_bf16_f32 v34, v40, s0
	ds_write_b16 v35, v34 offset:32
	v_cvt_pk_bf16_f32 v34, v39, s0
	ds_write_b16 v35, v34 offset:256
	v_cvt_pk_bf16_f32 v34, v38, s0
	ds_write_b16 v35, v34 offset:288
	v_mov_b32_e32 v34, v22
	v_mov_b32_e32 v35, v18
	v_mov_b32_e32 v38, v30
	v_mov_b32_e32 v39, v26
	v_pk_mul_f32 v[34:35], v[34:35], v[36:37] op_sel_hi:[1,0]
	v_pk_mul_f32 v[36:37], v[38:39], v[36:37] op_sel_hi:[1,0]
	s_cmp_gt_i32 s5, 1
	s_mov_b64 s[8:9], -1
	s_cbranch_scc0 .LBB0_996
	v_mul_f32_e32 v18, 0xbfb8aa3b, v35
	v_exp_f32_e32 v18, v18
	v_mul_f32_e32 v22, 0xbfb8aa3b, v34
	v_mul_f32_e32 v26, 0xbfb8aa3b, v36
	v_exp_f32_e32 v22, v22
	v_add_f32_e32 v18, 1.0, v18
	v_rcp_f32_e32 v39, v18
	v_mul_f32_e32 v18, 0xbfb8aa3b, v37
	v_exp_f32_e32 v18, v18
	v_exp_f32_e32 v26, v26
	v_add_f32_e32 v22, 1.0, v22
	v_rcp_f32_e32 v38, v22
	v_add_f32_e32 v18, 1.0, v18
	v_rcp_f32_e32 v45, v18
	v_add_f32_e32 v18, 1.0, v26
	v_rcp_f32_e32 v44, v18
	v_pk_mul_f32 v[40:41], v[34:35], v[38:39]
	s_mov_b64 s[8:9], 0
	v_pk_mul_f32 v[38:39], v[36:37], v[44:45]
.LBB0_996:
	s_andn2_b64 vcc, exec, s[8:9]
	s_cbranch_vccnz .LBB0_1000
	s_cmp_eq_u32 s5, 1
	s_cbranch_scc0 .LBB0_999
	v_add_u32_e32 v18, s4, v138
	v_add_u32_e32 v18, 0xa0, v18
	v_readlane_b32 s8, v254, 53
	s_nop 1
	v_and_b32_e32 v18, s8, v18
	v_lshlrev_b32_e32 v18, 7, v18
	v_or3_b32 v18, v18, v139, v1
	v_lshlrev_b32_e32 v18, 3, v18
	v_mov_b32_e32 v38, v178
	v_mov_b32_e32 v39, v179
	v_mov_b32_e32 v40, v180
	v_mov_b32_e32 v41, v181
	s_waitcnt vmcnt(1)
	v_mov_b32_e32 v44, v38
	s_waitcnt vmcnt(0)
	v_mov_b32_e32 v45, v40
	v_mov_b32_e32 v40, v39
	v_pk_mul_f32 v[38:39], v[34:35], v[40:41]
	v_pk_mul_f32 v[40:41], v[36:37], v[40:41]
	v_pk_fma_f32 v[36:37], v[36:37], v[44:45], v[38:39]
	v_pk_fma_f32 v[34:35], v[34:35], v[44:45], v[40:41] neg_lo:[0,0,1] neg_hi:[0,0,1]

.LBB0_1000:
	v_add_u32_e32 v34, 0x1ad0, v42
	v_cvt_pk_bf16_f32 v18, v41, s0
	v_lshl_add_u32 v22, v130, 1, v34
	ds_write_b16 v22, v18
	v_cvt_pk_bf16_f32 v18, v40, s0
	ds_write_b16 v22, v18 offset:32
	v_cvt_pk_bf16_f32 v18, v39, s0
	ds_write_b16 v22, v18 offset:256
	v_cvt_pk_bf16_f32 v18, v38, s0
	ds_write_b16 v22, v18 offset:288
	v_mov_b32_e32 v22, v245
	v_mov_b32_e32 v18, v23
	v_mov_b32_e32 v26, v31
	s_cmp_gt_i32 s5, 1
	s_mov_b64 s[8:9], -1
	v_pk_mul_f32 v[18:19], v[18:19], v[22:23] op_sel_hi:[1,0]
	v_pk_mul_f32 v[22:23], v[26:27], v[22:23] op_sel_hi:[1,0]
	s_cbranch_scc0 .LBB0_1002
	v_mul_f32_e32 v26, 0xbfb8aa3b, v19
	v_exp_f32_e32 v26, v26
	v_mul_f32_e32 v27, 0xbfb8aa3b, v18
	v_exp_f32_e32 v27, v27
	s_mov_b64 s[8:9], 0
	v_add_f32_e32 v26, 1.0, v26
	v_add_f32_e32 v30, 1.0, v27
	v_rcp_f32_e32 v27, v26
	v_mul_f32_e32 v26, 0xbfb8aa3b, v23
	v_exp_f32_e32 v31, v26
	v_mul_f32_e32 v26, 0xbfb8aa3b, v22
	v_exp_f32_e32 v35, v26
	v_rcp_f32_e32 v26, v30
	v_add_f32_e32 v30, 1.0, v31
	v_rcp_f32_e32 v37, v30
	v_add_f32_e32 v30, 1.0, v35
	v_rcp_f32_e32 v36, v30
	v_pk_mul_f32 v[30:31], v[18:19], v[26:27]
	v_pk_mul_f32 v[26:27], v[22:23], v[36:37]
.LBB0_1002:
	s_andn2_b64 vcc, exec, s[8:9]
	s_cbranch_vccnz .LBB0_1006
	s_cmp_eq_u32 s5, 1
	s_cbranch_scc0 .LBB0_1005
	v_add_u32_e32 v26, s4, v138
	v_add_u32_e32 v26, 0xa1, v26
	v_readlane_b32 s8, v254, 53
	s_nop 1
	v_and_b32_e32 v26, s8, v26
	v_lshlrev_b32_e32 v26, 7, v26
	v_or3_b32 v26, v26, v139, v1
	v_lshlrev_b32_e32 v30, 3, v26
	v_mov_b32_e32 v26, v182
	v_mov_b32_e32 v27, v183
	v_mov_b32_e32 v30, v184
	v_mov_b32_e32 v31, v185
	s_nop 0
	s_waitcnt vmcnt(1)
	v_mov_b32_e32 v36, v26
	s_waitcnt vmcnt(0)
	v_mov_b32_e32 v37, v30
	v_mov_b32_e32 v30, v27
	v_pk_mul_f32 v[26:27], v[18:19], v[30:31]
	v_pk_mul_f32 v[30:31], v[22:23], v[30:31]
	v_pk_fma_f32 v[22:23], v[22:23], v[36:37], v[26:27]
	v_pk_fma_f32 v[18:19], v[18:19], v[36:37], v[30:31] neg_lo:[0,0,1] neg_hi:[0,0,1]

.LBB0_1006:
	v_add_u32_e32 v34, 0x210, v34
	v_cvt_pk_bf16_f32 v18, v31, s0
	v_lshl_add_u32 v19, v130, 1, v34
	v_mov_b32_e32 v22, v246
	ds_write_b16 v19, v18
	v_cvt_pk_bf16_f32 v18, v30, s0
	ds_write_b16 v19, v18 offset:32
	v_cvt_pk_bf16_f32 v18, v27, s0
	ds_write_b16 v19, v18 offset:256
	v_cvt_pk_bf16_f32 v18, v26, s0
	ds_write_b16 v19, v18 offset:288
	v_mov_b32_e32 v18, v24
	v_mov_b32_e32 v19, v20
	v_mov_b32_e32 v26, v32
	v_mov_b32_e32 v27, v28
	v_pk_mul_f32 v[18:19], v[18:19], v[22:23] op_sel_hi:[1,0]
	v_pk_mul_f32 v[22:23], v[26:27], v[22:23] op_sel_hi:[1,0]
	s_cmp_gt_i32 s5, 1
	s_mov_b64 s[8:9], -1
	s_cbranch_scc0 .LBB0_1008
	v_mul_f32_e32 v20, 0xbfb8aa3b, v19
	v_exp_f32_e32 v20, v20
	v_mul_f32_e32 v24, 0xbfb8aa3b, v18
	v_mul_f32_e32 v26, 0xbfb8aa3b, v22
	v_exp_f32_e32 v24, v24
	v_add_f32_e32 v20, 1.0, v20
	v_rcp_f32_e32 v27, v20
	v_mul_f32_e32 v20, 0xbfb8aa3b, v23
	v_exp_f32_e32 v20, v20
	v_exp_f32_e32 v28, v26
	v_add_f32_e32 v24, 1.0, v24
	v_rcp_f32_e32 v26, v24
	v_add_f32_e32 v20, 1.0, v20
	v_rcp_f32_e32 v37, v20
	v_add_f32_e32 v20, 1.0, v28
	v_rcp_f32_e32 v36, v20
	v_pk_mul_f32 v[30:31], v[18:19], v[26:27]
	s_mov_b64 s[8:9], 0
	v_pk_mul_f32 v[26:27], v[22:23], v[36:37]
.LBB0_1008:
	s_andn2_b64 vcc, exec, s[8:9]
	s_cbranch_vccnz .LBB0_1012
	s_cmp_eq_u32 s5, 1
	s_cbranch_scc0 .LBB0_1011
	v_add_u32_e32 v20, s4, v138
	v_add_u32_e32 v20, 0xa2, v20
	v_readlane_b32 s8, v254, 53
	s_nop 1
	v_and_b32_e32 v20, s8, v20
	v_lshlrev_b32_e32 v20, 7, v20
	v_or3_b32 v20, v20, v139, v1
	v_lshlrev_b32_e32 v20, 3, v20
	v_mov_b32_e32 v26, v186
	v_mov_b32_e32 v27, v187
	v_mov_b32_e32 v30, v188
	v_mov_b32_e32 v31, v189
	s_waitcnt vmcnt(1)
	v_mov_b32_e32 v36, v26
	s_waitcnt vmcnt(0)
	v_mov_b32_e32 v37, v30
	v_mov_b32_e32 v30, v27
	v_pk_mul_f32 v[26:27], v[18:19], v[30:31]
	v_pk_mul_f32 v[30:31], v[22:23], v[30:31]
	v_pk_fma_f32 v[22:23], v[22:23], v[36:37], v[26:27]
	v_pk_fma_f32 v[18:19], v[18:19], v[36:37], v[30:31] neg_lo:[0,0,1] neg_hi:[0,0,1]

.LBB0_1012:
	v_cvt_pk_bf16_f32 v18, v31, s0
	v_add_u32_e32 v31, 0x210, v34
	v_mov_b32_e32 v22, v247
	v_lshl_add_u32 v19, v130, 1, v31
	ds_write_b16 v19, v18
	v_cvt_pk_bf16_f32 v18, v30, s0
	ds_write_b16 v19, v18 offset:32
	v_cvt_pk_bf16_f32 v18, v27, s0
	ds_write_b16 v19, v18 offset:256
	v_cvt_pk_bf16_f32 v18, v26, s0
	v_mov_b32_e32 v20, v25
	v_mov_b32_e32 v28, v33
	ds_write_b16 v19, v18 offset:288
	s_cmp_gt_i32 s5, 1
	v_pk_mul_f32 v[18:19], v[20:21], v[22:23] op_sel_hi:[1,0]
	v_pk_mul_f32 v[20:21], v[28:29], v[22:23] op_sel_hi:[1,0]
	s_mov_b64 s[8:9], -1
	s_cbranch_scc0 .LBB0_1014
	v_mul_f32_e32 v22, 0xbfb8aa3b, v19
	v_exp_f32_e32 v22, v22
	v_mul_f32_e32 v23, 0xbfb8aa3b, v18
	v_exp_f32_e32 v23, v23
	s_mov_b64 s[8:9], 0
	v_add_f32_e32 v22, 1.0, v22
	v_add_f32_e32 v24, 1.0, v23
	v_rcp_f32_e32 v23, v22
	v_mul_f32_e32 v22, 0xbfb8aa3b, v21
	v_exp_f32_e32 v25, v22
	v_mul_f32_e32 v22, 0xbfb8aa3b, v20
	v_exp_f32_e32 v26, v22
	v_rcp_f32_e32 v22, v24
	v_add_f32_e32 v24, 1.0, v25
	v_rcp_f32_e32 v27, v24
	v_add_f32_e32 v24, 1.0, v26
	v_rcp_f32_e32 v26, v24
	v_pk_mul_f32 v[24:25], v[18:19], v[22:23]
	v_pk_mul_f32 v[22:23], v[20:21], v[26:27]
.LBB0_1014:
	s_andn2_b64 vcc, exec, s[8:9]
	s_cbranch_vccnz .LBB0_1018
	s_cmp_eq_u32 s5, 1
	s_cbranch_scc0 .LBB0_1017
	v_add_u32_e32 v22, s4, v138
	v_add_u32_e32 v22, 0xa3, v22
	v_readlane_b32 s8, v254, 53
	s_nop 1
	v_and_b32_e32 v22, s8, v22
	v_lshlrev_b32_e32 v22, 7, v22
	v_or3_b32 v22, v22, v139, v1
	v_lshlrev_b32_e32 v24, 3, v22
	v_mov_b32_e32 v22, v190
	v_mov_b32_e32 v23, v191
	v_mov_b32_e32 v24, v192
	v_mov_b32_e32 v25, v193
	s_nop 0
	s_waitcnt vmcnt(1)
	v_mov_b32_e32 v26, v22
	s_waitcnt vmcnt(0)
	v_mov_b32_e32 v27, v24
	v_mov_b32_e32 v24, v23
	v_pk_mul_f32 v[22:23], v[18:19], v[24:25]
	v_pk_mul_f32 v[24:25], v[20:21], v[24:25]
	v_pk_fma_f32 v[20:21], v[20:21], v[26:27], v[22:23]
	v_pk_fma_f32 v[18:19], v[18:19], v[26:27], v[24:25] neg_lo:[0,0,1] neg_hi:[0,0,1]

.LBB0_1018:
	v_add_u32_e32 v26, 0x210, v31
	v_cvt_pk_bf16_f32 v18, v25, s0
	v_lshl_add_u32 v19, v130, 1, v26
	v_mov_b32_e32 v20, v248
	ds_write_b16 v19, v18
	v_cvt_pk_bf16_f32 v18, v24, s0
	ds_write_b16 v19, v18 offset:32
	v_cvt_pk_bf16_f32 v18, v23, s0
	ds_write_b16 v19, v18 offset:256
	v_cvt_pk_bf16_f32 v18, v22, s0
	ds_write_b16 v19, v18 offset:288
	v_mov_b32_e32 v18, v6
	v_mov_b32_e32 v19, v2
	v_mov_b32_e32 v22, v14
	v_mov_b32_e32 v23, v10
	v_pk_mul_f32 v[18:19], v[18:19], v[20:21] op_sel_hi:[1,0]
	v_pk_mul_f32 v[20:21], v[22:23], v[20:21] op_sel_hi:[1,0]
	s_cmp_gt_i32 s5, 1
	s_mov_b64 s[8:9], -1
	s_cbranch_scc0 .LBB0_1020
	v_mul_f32_e32 v2, 0xbfb8aa3b, v19
	v_exp_f32_e32 v2, v2
	v_mul_f32_e32 v6, 0xbfb8aa3b, v18
	v_mul_f32_e32 v10, 0xbfb8aa3b, v20
	v_exp_f32_e32 v6, v6
	v_add_f32_e32 v2, 1.0, v2
	v_rcp_f32_e32 v23, v2
	v_mul_f32_e32 v2, 0xbfb8aa3b, v21
	v_exp_f32_e32 v2, v2
	v_exp_f32_e32 v10, v10
	v_add_f32_e32 v6, 1.0, v6
	v_rcp_f32_e32 v22, v6
	v_add_f32_e32 v2, 1.0, v2
	v_rcp_f32_e32 v29, v2
	v_add_f32_e32 v2, 1.0, v10
	v_rcp_f32_e32 v28, v2
	v_pk_mul_f32 v[24:25], v[18:19], v[22:23]
	s_mov_b64 s[8:9], 0
	v_pk_mul_f32 v[22:23], v[20:21], v[28:29]
.LBB0_1020:
	s_andn2_b64 vcc, exec, s[8:9]
	s_cbranch_vccnz .LBB0_1024
	s_cmp_eq_u32 s5, 1
	s_cbranch_scc0 .LBB0_1023
	v_add_u32_e32 v2, s4, v138
	v_add_u32_e32 v2, 0xb0, v2
	v_readlane_b32 s8, v254, 53
	s_nop 1
	v_and_b32_e32 v2, s8, v2
	v_lshlrev_b32_e32 v2, 7, v2
	v_or3_b32 v2, v2, v139, v1
	v_lshlrev_b32_e32 v2, 3, v2
	v_mov_b32_e32 v22, v194
	v_mov_b32_e32 v23, v195
	v_mov_b32_e32 v24, v196
	v_mov_b32_e32 v25, v197
	s_waitcnt vmcnt(1)
	v_mov_b32_e32 v28, v22
	s_waitcnt vmcnt(0)
	v_mov_b32_e32 v29, v24
	v_mov_b32_e32 v24, v23
	v_pk_mul_f32 v[22:23], v[18:19], v[24:25]
	v_pk_mul_f32 v[24:25], v[20:21], v[24:25]
	v_pk_fma_f32 v[20:21], v[20:21], v[28:29], v[22:23]
	v_pk_fma_f32 v[18:19], v[18:19], v[28:29], v[24:25] neg_lo:[0,0,1] neg_hi:[0,0,1]

.LBB0_1024:
	v_add_u32_e32 v18, 0x1ad0, v26
	v_cvt_pk_bf16_f32 v2, v25, s0
	v_lshl_add_u32 v6, v130, 1, v18
	ds_write_b16 v6, v2
	v_cvt_pk_bf16_f32 v2, v24, s0
	ds_write_b16 v6, v2 offset:32
	v_cvt_pk_bf16_f32 v2, v23, s0
	ds_write_b16 v6, v2 offset:256
	v_cvt_pk_bf16_f32 v2, v22, s0
	ds_write_b16 v6, v2 offset:288
	v_mov_b32_e32 v6, v249
	v_mov_b32_e32 v2, v7
	v_mov_b32_e32 v10, v15
	s_cmp_gt_i32 s5, 1
	s_mov_b64 s[8:9], -1
	v_pk_mul_f32 v[2:3], v[2:3], v[6:7] op_sel_hi:[1,0]
	v_pk_mul_f32 v[6:7], v[10:11], v[6:7] op_sel_hi:[1,0]
	s_cbranch_scc0 .LBB0_1026
	v_mul_f32_e32 v10, 0xbfb8aa3b, v3
	v_exp_f32_e32 v10, v10
	v_mul_f32_e32 v11, 0xbfb8aa3b, v2
	v_exp_f32_e32 v11, v11
	s_mov_b64 s[8:9], 0
	v_add_f32_e32 v10, 1.0, v10
	v_add_f32_e32 v14, 1.0, v11
	v_rcp_f32_e32 v11, v10
	v_mul_f32_e32 v10, 0xbfb8aa3b, v7
	v_exp_f32_e32 v15, v10
	v_mul_f32_e32 v10, 0xbfb8aa3b, v6
	v_exp_f32_e32 v19, v10
	v_rcp_f32_e32 v10, v14
	v_add_f32_e32 v14, 1.0, v15
	v_rcp_f32_e32 v21, v14
	v_add_f32_e32 v14, 1.0, v19
	v_rcp_f32_e32 v20, v14
	v_pk_mul_f32 v[14:15], v[2:3], v[10:11]
	v_pk_mul_f32 v[10:11], v[6:7], v[20:21]
.LBB0_1026:
	s_andn2_b64 vcc, exec, s[8:9]
	s_cbranch_vccnz .LBB0_1030
	s_cmp_eq_u32 s5, 1
	s_cbranch_scc0 .LBB0_1029
	v_add_u32_e32 v10, s4, v138
	v_add_u32_e32 v10, 0xb1, v10
	v_readlane_b32 s8, v254, 53
	s_nop 1
	v_and_b32_e32 v10, s8, v10
	v_lshlrev_b32_e32 v10, 7, v10
	v_or3_b32 v10, v10, v139, v1
	v_lshlrev_b32_e32 v14, 3, v10
	v_mov_b32_e32 v10, v198
	v_mov_b32_e32 v11, v199
	v_mov_b32_e32 v14, v200
	v_mov_b32_e32 v15, v201
	s_nop 0
	s_waitcnt vmcnt(1)
	v_mov_b32_e32 v20, v10
	s_waitcnt vmcnt(0)
	v_mov_b32_e32 v21, v14
	v_mov_b32_e32 v14, v11
	v_pk_mul_f32 v[10:11], v[2:3], v[14:15]
	v_pk_mul_f32 v[14:15], v[6:7], v[14:15]
	v_pk_fma_f32 v[6:7], v[6:7], v[20:21], v[10:11]
	v_pk_fma_f32 v[2:3], v[2:3], v[20:21], v[14:15] neg_lo:[0,0,1] neg_hi:[0,0,1]

.LBB0_1030:
	v_add_u32_e32 v18, 0x210, v18
	v_cvt_pk_bf16_f32 v2, v15, s0
	v_lshl_add_u32 v3, v130, 1, v18
	v_mov_b32_e32 v6, v250
	ds_write_b16 v3, v2
	v_cvt_pk_bf16_f32 v2, v14, s0
	ds_write_b16 v3, v2 offset:32
	v_cvt_pk_bf16_f32 v2, v11, s0
	ds_write_b16 v3, v2 offset:256
	v_cvt_pk_bf16_f32 v2, v10, s0
	ds_write_b16 v3, v2 offset:288
	v_mov_b32_e32 v2, v8
	v_mov_b32_e32 v3, v4
	v_mov_b32_e32 v10, v16
	v_mov_b32_e32 v11, v12
	v_pk_mul_f32 v[2:3], v[2:3], v[6:7] op_sel_hi:[1,0]
	v_pk_mul_f32 v[6:7], v[10:11], v[6:7] op_sel_hi:[1,0]
	s_cmp_gt_i32 s5, 1
	s_mov_b64 s[8:9], -1
	s_cbranch_scc0 .LBB0_1032
	v_mul_f32_e32 v4, 0xbfb8aa3b, v3
	v_exp_f32_e32 v4, v4
	v_mul_f32_e32 v8, 0xbfb8aa3b, v2
	v_mul_f32_e32 v10, 0xbfb8aa3b, v6
	v_exp_f32_e32 v8, v8
	v_add_f32_e32 v4, 1.0, v4
	v_rcp_f32_e32 v11, v4
	v_mul_f32_e32 v4, 0xbfb8aa3b, v7
	v_exp_f32_e32 v4, v4
	v_exp_f32_e32 v12, v10
	v_add_f32_e32 v8, 1.0, v8
	v_rcp_f32_e32 v10, v8
	v_add_f32_e32 v4, 1.0, v4
	v_rcp_f32_e32 v21, v4
	v_add_f32_e32 v4, 1.0, v12
	v_rcp_f32_e32 v20, v4
	v_pk_mul_f32 v[14:15], v[2:3], v[10:11]
	s_mov_b64 s[8:9], 0
	v_pk_mul_f32 v[10:11], v[6:7], v[20:21]
.LBB0_1032:
	s_andn2_b64 vcc, exec, s[8:9]
	s_cbranch_vccnz .LBB0_1036
	s_cmp_eq_u32 s5, 1
	s_cbranch_scc0 .LBB0_1035
	v_add_u32_e32 v4, s4, v138
	v_add_u32_e32 v4, 0xb2, v4
	v_readlane_b32 s8, v254, 53
	s_nop 1
	v_and_b32_e32 v4, s8, v4
	v_lshlrev_b32_e32 v4, 7, v4
	v_or3_b32 v4, v4, v139, v1
	v_lshlrev_b32_e32 v4, 3, v4
	v_mov_b32_e32 v10, v202
	v_mov_b32_e32 v11, v203
	v_mov_b32_e32 v14, v204
	v_mov_b32_e32 v15, v205
	s_waitcnt vmcnt(1)
	v_mov_b32_e32 v20, v10
	s_waitcnt vmcnt(0)
	v_mov_b32_e32 v21, v14
	v_mov_b32_e32 v14, v11
	v_pk_mul_f32 v[10:11], v[2:3], v[14:15]
	v_pk_mul_f32 v[14:15], v[6:7], v[14:15]
	v_pk_fma_f32 v[6:7], v[6:7], v[20:21], v[10:11]
	v_pk_fma_f32 v[2:3], v[2:3], v[20:21], v[14:15] neg_lo:[0,0,1] neg_hi:[0,0,1]

.LBB0_1036:
	v_add_u32_e32 v3, 0x210, v18
	v_mov_b32_e32 v6, v251
	v_cvt_pk_bf16_f32 v2, v15, s0
	v_lshl_add_u32 v15, v130, 1, v3
	ds_write_b16 v15, v2
	v_cvt_pk_bf16_f32 v2, v14, s0
	ds_write_b16 v15, v2 offset:32
	v_cvt_pk_bf16_f32 v2, v11, s0
	ds_write_b16 v15, v2 offset:256
	v_cvt_pk_bf16_f32 v2, v10, s0
	v_mov_b32_e32 v4, v9
	v_mov_b32_e32 v12, v17
	ds_write_b16 v15, v2 offset:288
	s_cmp_gt_i32 s5, 1
	v_pk_mul_f32 v[2:3], v[4:5], v[6:7] op_sel_hi:[1,0]
	v_pk_mul_f32 v[4:5], v[12:13], v[6:7] op_sel_hi:[1,0]
	s_mov_b64 s[8:9], -1
	s_cbranch_scc0 .LBB0_1038
	v_mul_f32_e32 v6, 0xbfb8aa3b, v3
	v_exp_f32_e32 v6, v6
	v_mul_f32_e32 v7, 0xbfb8aa3b, v2
	v_exp_f32_e32 v7, v7
	s_mov_b64 s[8:9], 0
	v_add_f32_e32 v6, 1.0, v6
	v_add_f32_e32 v8, 1.0, v7
	v_rcp_f32_e32 v7, v6
	v_mul_f32_e32 v6, 0xbfb8aa3b, v5
	v_exp_f32_e32 v9, v6
	v_mul_f32_e32 v6, 0xbfb8aa3b, v4
	v_exp_f32_e32 v10, v6
	v_rcp_f32_e32 v6, v8
	v_add_f32_e32 v8, 1.0, v9
	v_rcp_f32_e32 v11, v8
	v_add_f32_e32 v8, 1.0, v10
	v_rcp_f32_e32 v10, v8
	v_pk_mul_f32 v[8:9], v[2:3], v[6:7]
	v_pk_mul_f32 v[6:7], v[4:5], v[10:11]
.LBB0_1038:
	s_andn2_b64 vcc, exec, s[8:9]
	s_cbranch_vccnz .LBB0_1042
	s_cmp_eq_u32 s5, 1
	s_cbranch_scc0 .LBB0_1041
	v_add_u32_e32 v6, s4, v138
	v_add_u32_e32 v6, 0xb3, v6
	v_readlane_b32 s5, v254, 53
	s_nop 1
	v_and_b32_e32 v6, s5, v6
	v_lshlrev_b32_e32 v6, 7, v6
	v_or3_b32 v1, v6, v139, v1
	v_lshlrev_b32_e32 v1, 3, v1
	v_mov_b32_e32 v6, v206
	v_mov_b32_e32 v7, v207
	v_mov_b32_e32 v8, v208
	v_mov_b32_e32 v9, v209
	s_waitcnt vmcnt(1)
	v_mov_b32_e32 v10, v6
	s_waitcnt vmcnt(0)
	v_mov_b32_e32 v11, v8
	v_mov_b32_e32 v8, v7
	v_pk_mul_f32 v[6:7], v[2:3], v[8:9]
	v_pk_mul_f32 v[8:9], v[4:5], v[8:9]
	v_pk_fma_f32 v[4:5], v[4:5], v[10:11], v[6:7]
	v_pk_fma_f32 v[2:3], v[2:3], v[10:11], v[8:9] neg_lo:[0,0,1] neg_hi:[0,0,1]

.LBB0_1350:
	v_mov_b32_e32 v1, v210
	s_ashr_i32 s1, s0, 31
	v_bfe_i32 v3, v1, 27, 1
	v_lshlrev_b32_e32 v142, 4, v1
	v_lshrrev_b32_e32 v3, 22, v3
	v_add_u32_e32 v3, v142, v3
	v_and_b32_e32 v3, 0xfffffc00, v3
	v_ashrrev_i32_e32 v2, 31, v1
	v_sub_u32_e32 v3, v142, v3
	v_lshrrev_b32_e32 v2, 26, v2
	v_lshrrev_b32_e32 v4, 4, v3
	v_add_u32_e32 v2, v1, v2
	v_bitop3_b32 v4, v4, v3, 32 bitop3:0x6c
	v_ashrrev_i32_e32 v3, 31, v3
	v_ashrrev_i32_e32 v2, 6, v2
	v_lshrrev_b32_e32 v3, 26, v3
	v_lshlrev_b32_e32 v5, 3, v2
	v_add_u32_e32 v3, v4, v3
	v_and_b32_e32 v5, -16, v5
	v_ashrrev_i32_e32 v3, 6, v3
	v_add_u32_e32 v5, v3, v5
	v_mul_i32_i24_e32 v3, 64, v3
	v_lshlrev_b32_e32 v2, 5, v2
	v_sub_u32_e32 v3, v4, v3
	v_and_b32_e32 v2, 32, v2
	v_ashrrev_i16_sdwa v3, v252, sext(v3) dst_sel:DWORD dst_unused:UNUSED_PAD src0_sel:DWORD src1_sel:BYTE_0
	v_add_u32_e32 v143, 0x2000, v142
	v_add_u32_sdwa v2, v2, sext(v3) dst_sel:DWORD dst_unused:UNUSED_PAD src0_sel:DWORD src1_sel:WORD_0
	v_ashrrev_i32_e32 v3, 31, v143
	v_lshrrev_b32_e32 v3, 22, v3
	v_add_u32_e32 v3, v143, v3
	v_ashrrev_i32_e32 v3, 10, v3
	v_mul_i32_i24_e32 v4, 0x400, v3
	v_sub_u32_e32 v4, v143, v4
	s_lshr_b32 s1, s1, 30
	v_lshrrev_b32_e32 v6, 4, v4
	s_add_i32 s1, s0, s1
	v_bitop3_b32 v4, v6, v4, 32 bitop3:0x6c
	s_and_b32 s1, s1, 0xfffffc
	v_ashrrev_i32_e32 v7, 31, v4
	s_sub_i32 s0, s0, s1
	v_lshrrev_b32_e32 v7, 26, v7
	s_lshl_b32 s0, s0, 8
	v_add_u32_e32 v7, v4, v7
	v_ashrrev_i32_e32 v8, 6, v7
	v_and_b32_e32 v7, 0xc0, v7
	s_ashr_i32 s1, s0, 31
	s_lshl_b32 s19, s7, 8
	v_lshlrev_b32_e32 v6, 3, v3
	v_lshlrev_b32_e32 v3, 5, v3
	v_sub_u32_e32 v4, v4, v7
	s_lshl_b64 s[4:5], s[0:1], 12
	v_and_b32_e32 v3, 32, v3
	v_ashrrev_i16_sdwa v4, v252, sext(v4) dst_sel:DWORD dst_unused:UNUSED_PAD src0_sel:DWORD src1_sel:BYTE_0
	s_add_u32 s4, s15, s4
	v_add_u32_e32 v148, 0x10000, v142
	v_and_b32_e32 v6, -16, v6
	v_add_u32_sdwa v3, v3, sext(v4) dst_sel:DWORD dst_unused:UNUSED_PAD src0_sel:DWORD src1_sel:WORD_0
	v_mul_lo_u32 v4, v5, s50
	v_lshlrev_b32_e32 v5, 12, v5
	s_addc_u32 s5, s16, s5
	v_readfirstlane_b32 s6, v148
	v_add_u32_e32 v149, 0x12000, v142
	v_add_u32_e32 v6, v8, v6
	v_lshl_add_u32 v134, v2, 1, v5
	s_mov_b64 s[8:9], s[4:5]
	s_mov_b32 m0, s6
	v_readfirstlane_b32 s6, v149
	s_mul_i32 s22, s7, 0x300000
	v_add_lshl_u32 v132, v2, v4, 1
	v_lshlrev_b32_e32 v2, 12, v6
	s_barrier
	s_mul_hi_i32 s23, s19, 0x3000
	global_load_lds_dwordx4 v134, s[8:9]
	s_mov_b32 m0, s6
	s_add_u32 s6, s48, s22
	v_lshl_add_u32 v136, v3, 1, v2
	s_addc_u32 s7, s49, s23
	v_readfirstlane_b32 s10, v142
	v_mul_lo_u32 v7, v6, s50
	global_load_lds_dwordx4 v136, s[8:9]
	s_mov_b64 s[8:9], s[6:7]
	s_mov_b32 m0, s10
	v_readfirstlane_b32 s10, v143
	v_add_lshl_u32 v130, v3, v7, 1
	v_add_u32_e32 v150, 0x14000, v142
	global_load_lds_dwordx4 v132, s[8:9]
	s_mov_b32 m0, s10
	v_readfirstlane_b32 s12, v150
	global_load_lds_dwordx4 v130, s[8:9]
	s_or_b32 s8, s0, 0x80
	s_ashr_i32 s9, s8, 31
	s_lshl_b64 s[8:9], s[8:9], 12
	s_add_u32 s8, s15, s8
	s_addc_u32 s9, s16, s9
	v_add_u32_e32 v151, 0x16000, v142
	s_mov_b64 s[10:11], s[8:9]
	s_mov_b32 m0, s12
	v_readfirstlane_b32 s12, v151
	v_add_u32_e32 v152, 0x4000, v142
	global_load_lds_dwordx4 v134, s[10:11]
	s_mov_b32 m0, s12
	v_readfirstlane_b32 s20, v152
	global_load_lds_dwordx4 v136, s[10:11]
	s_or_b32 s10, s19, 0x80
	s_mul_hi_i32 s11, s10, 0x3000
	s_mulk_i32 s10, 0x3000
	s_add_u32 s10, s48, s10
	s_addc_u32 s11, s49, s11
	v_add_u32_e32 v153, 0x6000, v142
	s_mov_b64 s[12:13], s[10:11]
	s_mov_b32 m0, s20
	v_readfirstlane_b32 s20, v153
	v_ashrrev_i32_e32 v2, 8, v1
	global_load_lds_dwordx4 v132, s[12:13]
	s_mov_b32 m0, s20
	v_mov_b32_e32 v223, 1
	global_load_lds_dwordx4 v130, s[12:13]
	v_cmp_eq_u32_e32 vcc, 1, v2
	s_and_saveexec_b64 s[12:13], vcc
	s_cbranch_execz .LBB0_1352
	s_barrier

.LBB0_1488:
	v_mov_b32_e32 v134, v210
	s_ashr_i32 s13, s12, 31
	v_bfe_i32 v3, v134, 27, 1
	v_lshlrev_b32_e32 v139, 4, v134
	v_lshrrev_b32_e32 v3, 22, v3
	v_add_u32_e32 v3, v139, v3
	v_and_b32_e32 v3, 0xfffffc00, v3
	v_sub_u32_e32 v3, v139, v3
	v_lshrrev_b32_e32 v4, 4, v3
	v_bitop3_b32 v4, v4, v3, 32 bitop3:0x6c
	v_ashrrev_i32_e32 v3, 31, v3
	v_ashrrev_i32_e32 v2, 31, v134
	v_lshrrev_b32_e32 v3, 26, v3
	v_lshrrev_b32_e32 v2, 26, v2
	v_add_u32_e32 v3, v4, v3
	v_add_u32_e32 v2, v134, v2
	v_ashrrev_i32_e32 v3, 6, v3
	v_ashrrev_i32_e32 v2, 6, v2
	v_mul_i32_i24_e32 v6, 64, v3
	v_lshlrev_b32_e32 v5, 3, v2
	v_lshlrev_b32_e32 v2, 5, v2
	v_sub_u32_e32 v4, v4, v6
	v_and_b32_e32 v2, 32, v2
	v_ashrrev_i16_sdwa v4, v252, sext(v4) dst_sel:DWORD dst_unused:UNUSED_PAD src0_sel:DWORD src1_sel:BYTE_0
	v_add_u32_e32 v140, 0x2000, v139
	v_add_u32_sdwa v2, v2, sext(v4) dst_sel:DWORD dst_unused:UNUSED_PAD src0_sel:DWORD src1_sel:WORD_0
	v_ashrrev_i32_e32 v4, 31, v140
	v_lshrrev_b32_e32 v4, 22, v4
	v_add_u32_e32 v4, v140, v4
	v_ashrrev_i32_e32 v4, 10, v4
	v_mul_i32_i24_e32 v6, 0x400, v4
	s_lshr_b32 s13, s13, 29
	v_sub_u32_e32 v6, v140, v6
	s_add_i32 s13, s12, s13
	v_lshrrev_b32_e32 v7, 4, v6
	s_and_b32 s13, s13, 0xfffff8
	v_bitop3_b32 v6, v7, v6, 32 bitop3:0x6c
	s_sub_i32 s12, s12, s13
	v_ashrrev_i32_e32 v8, 31, v6
	s_lshl_b32 s12, s12, 8
	v_lshrrev_b32_e32 v8, 26, v8
	v_add_u32_e32 v8, v6, v8
	s_ashr_i32 s13, s12, 31
	v_and_b32_e32 v5, 0x1ffff0, v5
	v_lshrrev_b32_e32 v9, 6, v8
	v_and_b32_e32 v8, 0xc0, v8
	s_lshl_b64 s[14:15], s[12:13], 11
	v_lshlrev_b32_e32 v7, 3, v4
	v_lshlrev_b32_e32 v4, 5, v4
	v_sub_u32_e32 v6, v6, v8
	v_add_lshl_u32 v3, v3, v5, 11
	s_add_u32 s14, s29, s14
	v_add_u32_e32 v145, 0x10000, v139
	v_and_b32_e32 v4, 32, v4
	v_ashrrev_i16_sdwa v6, v252, sext(v6) dst_sel:DWORD dst_unused:UNUSED_PAD src0_sel:DWORD src1_sel:BYTE_0
	v_lshl_add_u32 v132, v2, 1, v3
	v_and_b32_e32 v2, 0x1ffff0, v7
	s_addc_u32 s15, s30, s15
	v_readfirstlane_b32 s18, v145
	v_add_u32_e32 v146, 0x12000, v139
	v_add_u32_sdwa v4, v4, sext(v6) dst_sel:DWORD dst_unused:UNUSED_PAD src0_sel:DWORD src1_sel:WORD_0
	v_add_lshl_u32 v2, v9, v2, 11
	s_mov_b64 s[16:17], s[14:15]
	s_mov_b32 m0, s18
	v_readfirstlane_b32 s18, v146
	v_lshl_add_u32 v130, v4, 1, v2
	s_waitcnt lgkmcnt(0)
	s_barrier
	s_lshl_b64 s[22:23], s[10:11], 11
	global_load_lds_dwordx4 v132, s[16:17]
	s_mov_b32 m0, s18
	v_readfirstlane_b32 s11, v139
	global_load_lds_dwordx4 v130, s[16:17]
	s_add_u32 s16, s31, s22
	s_addc_u32 s17, s34, s23
	s_mov_b64 s[18:19], s[16:17]
	s_mov_b32 m0, s11
	v_readfirstlane_b32 s11, v140
	v_add_u32_e32 v147, 0x14000, v139
	global_load_lds_dwordx4 v132, s[18:19]
	s_mov_b32 m0, s11
	v_readfirstlane_b32 s11, v147
	global_load_lds_dwordx4 v130, s[18:19]
	s_or_b32 s18, s12, 0x80
	s_ashr_i32 s19, s18, 31
	s_lshl_b64 s[18:19], s[18:19], 11
	s_add_u32 s18, s29, s18
	s_addc_u32 s19, s30, s19
	v_add_u32_e32 v148, 0x16000, v139
	s_mov_b64 s[20:21], s[18:19]
	s_mov_b32 m0, s11
	v_readfirstlane_b32 s11, v148
	v_add_u32_e32 v149, 0x4000, v139
	global_load_lds_dwordx4 v132, s[20:21]
	s_mov_b32 m0, s11
	v_readfirstlane_b32 s11, v149
	global_load_lds_dwordx4 v130, s[20:21]
	s_or_b32 s20, s10, 0x80
	s_ashr_i32 s21, s20, 31
	s_lshl_b64 s[20:21], s[20:21], 11
	s_add_u32 s20, s31, s20
	s_addc_u32 s21, s34, s21
	v_add_u32_e32 v150, 0x6000, v139
	s_mov_b64 s[24:25], s[20:21]
	s_mov_b32 m0, s11
	v_readfirstlane_b32 s11, v150
	v_ashrrev_i32_e32 v2, 8, v134
	global_load_lds_dwordx4 v132, s[24:25]
	s_mov_b32 m0, s11
	v_cmp_eq_u32_e32 vcc, 1, v2
	global_load_lds_dwordx4 v130, s[24:25]
	s_and_saveexec_b64 s[24:25], vcc
	s_cbranch_execz .LBB0_1490
	s_barrier

.LBB0_1730:
	v_mov_b32_e32 v1, v210
	s_ashr_i32 s1, s0, 31
	v_bfe_i32 v3, v1, 27, 1
	v_lshlrev_b32_e32 v138, 4, v1
	v_lshrrev_b32_e32 v3, 22, v3
	v_add_u32_e32 v3, v138, v3
	v_and_b32_e32 v3, 0xfffffc00, v3
	v_sub_u32_e32 v3, v138, v3
	v_lshrrev_b32_e32 v4, 4, v3
	v_bitop3_b32 v4, v4, v3, 32 bitop3:0x6c
	v_ashrrev_i32_e32 v3, 31, v3
	v_ashrrev_i32_e32 v2, 31, v1
	v_lshrrev_b32_e32 v3, 26, v3
	v_lshrrev_b32_e32 v2, 26, v2
	v_add_u32_e32 v3, v4, v3
	v_add_u32_e32 v2, v1, v2
	v_ashrrev_i32_e32 v3, 6, v3
	v_ashrrev_i32_e32 v2, 6, v2
	v_mul_i32_i24_e32 v6, 64, v3
	v_lshlrev_b32_e32 v5, 3, v2
	v_lshlrev_b32_e32 v2, 5, v2
	v_sub_u32_e32 v4, v4, v6
	v_and_b32_e32 v2, 32, v2
	v_ashrrev_i16_sdwa v4, v252, sext(v4) dst_sel:DWORD dst_unused:UNUSED_PAD src0_sel:DWORD src1_sel:BYTE_0
	v_add_u32_e32 v139, 0x2000, v138
	v_add_u32_sdwa v2, v2, sext(v4) dst_sel:DWORD dst_unused:UNUSED_PAD src0_sel:DWORD src1_sel:WORD_0
	v_ashrrev_i32_e32 v4, 31, v139
	v_lshrrev_b32_e32 v4, 22, v4
	v_add_u32_e32 v4, v139, v4
	v_ashrrev_i32_e32 v4, 10, v4
	s_lshr_b32 s1, s1, 30
	v_mul_i32_i24_e32 v6, 0x400, v4
	s_add_i32 s1, s0, s1
	v_sub_u32_e32 v6, v139, v6
	s_and_b32 s1, s1, 0xfffffc
	v_lshrrev_b32_e32 v7, 4, v6
	s_sub_i32 s1, s0, s1
	v_bitop3_b32 v6, v7, v6, 32 bitop3:0x6c
	s_lshl_b32 s0, s4, 8
	s_lshl_b32 s4, s1, 8
	v_ashrrev_i32_e32 v8, 31, v6
	v_lshrrev_b32_e32 v8, 26, v8
	s_ashr_i32 s5, s4, 31
	v_add_u32_e32 v8, v6, v8
	s_lshl_b64 s[6:7], s[4:5], 12
	v_and_b32_e32 v5, 0xffff0, v5
	v_lshrrev_b32_e32 v9, 6, v8
	v_and_b32_e32 v8, 0xc0, v8
	s_add_u32 s6, s19, s6
	v_add_u32_e32 v144, 0x10000, v138
	v_lshlrev_b32_e32 v7, 3, v4
	v_lshlrev_b32_e32 v4, 5, v4
	v_sub_u32_e32 v6, v6, v8
	v_add_lshl_u32 v3, v3, v5, 12
	s_addc_u32 s7, s20, s7
	v_readfirstlane_b32 s1, v144
	v_add_u32_e32 v145, 0x12000, v138
	v_and_b32_e32 v7, 0xffff0, v7
	v_and_b32_e32 v4, 32, v4
	v_ashrrev_i16_sdwa v6, v252, sext(v6) dst_sel:DWORD dst_unused:UNUSED_PAD src0_sel:DWORD src1_sel:BYTE_0
	v_lshl_add_u32 v132, v2, 1, v3
	s_mov_b64 s[8:9], s[6:7]
	s_mov_b32 m0, s1
	v_readfirstlane_b32 s1, v145
	v_add_u32_sdwa v4, v4, sext(v6) dst_sel:DWORD dst_unused:UNUSED_PAD src0_sel:DWORD src1_sel:WORD_0
	v_add_lshl_u32 v2, v9, v7, 12
	s_barrier
	v_lshl_add_u32 v130, v4, 1, v2
	global_load_lds_dwordx4 v132, s[8:9]
	s_mov_b32 m0, s1
	s_ashr_i32 s1, s0, 31
	s_lshl_b64 s[14:15], s[0:1], 12
	global_load_lds_dwordx4 v130, s[8:9]
	s_add_u32 s8, s48, s14
	s_addc_u32 s9, s49, s15
	v_readfirstlane_b32 s1, v138
	s_mov_b64 s[10:11], s[8:9]
	s_mov_b32 m0, s1
	v_readfirstlane_b32 s1, v139
	v_add_u32_e32 v146, 0x14000, v138
	global_load_lds_dwordx4 v132, s[10:11]
	s_mov_b32 m0, s1
	v_readfirstlane_b32 s1, v146
	global_load_lds_dwordx4 v130, s[10:11]
	s_or_b32 s10, s4, 0x80
	s_ashr_i32 s11, s10, 31
	s_lshl_b64 s[10:11], s[10:11], 12
	s_add_u32 s10, s19, s10
	s_addc_u32 s11, s20, s11
	v_add_u32_e32 v147, 0x16000, v138
	s_mov_b64 s[12:13], s[10:11]
	s_mov_b32 m0, s1
	v_readfirstlane_b32 s1, v147
	v_add_u32_e32 v148, 0x4000, v138
	global_load_lds_dwordx4 v132, s[12:13]
	s_mov_b32 m0, s1
	v_readfirstlane_b32 s1, v148
	global_load_lds_dwordx4 v130, s[12:13]
	s_or_b32 s12, s0, 0x80
	s_ashr_i32 s13, s12, 31
	s_lshl_b64 s[12:13], s[12:13], 12
	s_add_u32 s12, s48, s12
	s_addc_u32 s13, s49, s13
	v_add_u32_e32 v149, 0x6000, v138
	s_mov_b64 s[16:17], s[12:13]
	s_mov_b32 m0, s1
	v_readfirstlane_b32 s1, v149
	v_ashrrev_i32_e32 v2, 8, v1
	global_load_lds_dwordx4 v132, s[16:17]
	s_mov_b32 m0, s1
	v_cmp_eq_u32_e32 vcc, 1, v2
	global_load_lds_dwordx4 v130, s[16:17]
	s_and_saveexec_b64 s[16:17], vcc
	s_cbranch_execz .LBB0_1732
	s_barrier

.LBB0_1868:
	v_mov_b32_e32 v134, v210
	s_mul_hi_i32 s1, s0, 0x38e38e39
	v_bfe_i32 v2, v134, 27, 1
	v_lshlrev_b32_e32 v137, 4, v134
	v_lshrrev_b32_e32 v2, 22, v2
	v_add_u32_e32 v2, v137, v2
	v_and_b32_e32 v2, 0xfffffc00, v2
	v_sub_u32_e32 v2, v137, v2
	v_lshrrev_b32_e32 v3, 4, v2
	v_bitop3_b32 v3, v3, v2, 32 bitop3:0x6c
	v_ashrrev_i32_e32 v2, 31, v2
	v_ashrrev_i32_e32 v1, 31, v134
	v_lshrrev_b32_e32 v2, 26, v2
	v_lshrrev_b32_e32 v1, 26, v1
	v_add_u32_e32 v2, v3, v2
	v_add_u32_e32 v1, v134, v1
	v_ashrrev_i32_e32 v2, 6, v2
	v_ashrrev_i32_e32 v1, 6, v1
	v_mul_i32_i24_e32 v5, 64, v2
	v_lshlrev_b32_e32 v4, 3, v1
	v_lshlrev_b32_e32 v1, 5, v1
	v_sub_u32_e32 v3, v3, v5
	v_and_b32_e32 v1, 32, v1
	v_ashrrev_i16_sdwa v3, v252, sext(v3) dst_sel:DWORD dst_unused:UNUSED_PAD src0_sel:DWORD src1_sel:BYTE_0
	v_add_u32_e32 v138, 0x2000, v137
	v_add_u32_sdwa v1, v1, sext(v3) dst_sel:DWORD dst_unused:UNUSED_PAD src0_sel:DWORD src1_sel:WORD_0
	v_ashrrev_i32_e32 v3, 31, v138
	v_lshrrev_b32_e32 v3, 22, v3
	v_add_u32_e32 v3, v138, v3
	v_ashrrev_i32_e32 v3, 10, v3
	v_mul_i32_i24_e32 v5, 0x400, v3
	s_lshr_b32 s8, s1, 31
	s_ashr_i32 s1, s1, 2
	v_sub_u32_e32 v5, v138, v5
	s_add_i32 s1, s1, s8
	v_lshrrev_b32_e32 v6, 4, v5
	s_mul_i32 s1, s1, 18
	v_bitop3_b32 v5, v6, v5, 32 bitop3:0x6c
	s_sub_i32 s31, s0, s1
	v_ashrrev_i32_e32 v7, 31, v5
	s_lshl_b32 s8, s31, 8
	v_lshrrev_b32_e32 v7, 26, v7
	v_add_u32_e32 v7, v5, v7
	s_ashr_i32 s9, s8, 31
	v_and_b32_e32 v4, 0x1ffff0, v4
	v_lshrrev_b32_e32 v8, 6, v7
	v_and_b32_e32 v7, 0xc0, v7
	s_lshl_b64 s[0:1], s[8:9], 11
	v_lshlrev_b32_e32 v6, 3, v3
	v_lshlrev_b32_e32 v3, 5, v3
	v_sub_u32_e32 v5, v5, v7
	v_add_lshl_u32 v2, v2, v4, 11
	s_add_u32 s0, s21, s0
	v_add_u32_e32 v143, 0x10000, v137
	v_and_b32_e32 v3, 32, v3
	v_ashrrev_i16_sdwa v5, v252, sext(v5) dst_sel:DWORD dst_unused:UNUSED_PAD src0_sel:DWORD src1_sel:BYTE_0
	v_lshl_add_u32 v132, v1, 1, v2
	v_and_b32_e32 v1, 0x1ffff0, v6
	s_addc_u32 s1, s22, s1
	v_readfirstlane_b32 s12, v143
	v_add_u32_e32 v144, 0x12000, v137
	v_add_u32_sdwa v3, v3, sext(v5) dst_sel:DWORD dst_unused:UNUSED_PAD src0_sel:DWORD src1_sel:WORD_0
	v_add_lshl_u32 v1, v8, v1, 11
	s_mov_b64 s[10:11], s[0:1]
	s_mov_b32 m0, s12
	v_readfirstlane_b32 s12, v144
	v_lshl_add_u32 v130, v3, 1, v1
	s_waitcnt lgkmcnt(0)
	s_barrier
	s_lshl_b64 s[16:17], s[6:7], 11
	global_load_lds_dwordx4 v132, s[10:11]
	s_mov_b32 m0, s12
	v_readfirstlane_b32 s7, v137
	global_load_lds_dwordx4 v130, s[10:11]
	s_add_u32 s10, s23, s16
	s_addc_u32 s11, s24, s17
	s_mov_b64 s[12:13], s[10:11]
	s_mov_b32 m0, s7
	v_readfirstlane_b32 s7, v138
	v_add_u32_e32 v146, 0x14000, v137
	global_load_lds_dwordx4 v132, s[12:13]
	s_mov_b32 m0, s7
	v_readfirstlane_b32 s7, v146
	global_load_lds_dwordx4 v130, s[12:13]
	s_or_b32 s12, s8, 0x80
	s_ashr_i32 s13, s12, 31
	s_lshl_b64 s[12:13], s[12:13], 11
	s_add_u32 s12, s21, s12
	s_addc_u32 s13, s22, s13
	v_add_u32_e32 v147, 0x16000, v137
	s_mov_b64 s[14:15], s[12:13]
	s_mov_b32 m0, s7
	v_readfirstlane_b32 s7, v147
	v_add_u32_e32 v148, 0x4000, v137
	global_load_lds_dwordx4 v132, s[14:15]
	s_mov_b32 m0, s7
	v_readfirstlane_b32 s7, v148
	global_load_lds_dwordx4 v130, s[14:15]
	s_or_b32 s14, s6, 0x80
	s_ashr_i32 s15, s14, 31
	s_lshl_b64 s[14:15], s[14:15], 11
	s_add_u32 s14, s23, s14
	s_addc_u32 s15, s24, s15
	v_add_u32_e32 v149, 0x6000, v137
	s_mov_b64 s[18:19], s[14:15]
	s_mov_b32 m0, s7
	v_readfirstlane_b32 s7, v149
	v_ashrrev_i32_e32 v2, 8, v134
	global_load_lds_dwordx4 v132, s[18:19]
	s_mov_b32 m0, s7
	v_cmp_eq_u32_e32 vcc, 1, v2
	global_load_lds_dwordx4 v130, s[18:19]
	s_and_saveexec_b64 s[18:19], vcc
	s_cbranch_execz .LBB0_1870
	s_barrier

.LBB0_1874:
	s_or_b64 exec, exec, s[0:1]
	v_lshl_or_b32 v144, v135, 2, v136
	v_lshl_add_u32 v143, v144, 2, v220
	s_cmp_gt_i32 s31, 8
	s_cbranch_scc1 .Lrp_A1_skip
	v_and_b32_e32 v248, 64, v134
	v_cmp_gt_u32_e64 s[10:11], 8, v1
	v_cmp_eq_u32_e32 vcc, 0, v248
	s_nop 1
	s_and_b64 vcc, vcc, s[10:11]
	s_and_saveexec_b64 s[10:11], vcc
	s_cbranch_execz .Lrp_A1_join
	v_readlane_b32 s12, v254, 53
	v_add_u32_e32 v248, s6, v144
	v_lshlrev_b32_e32 v249, 3, v1
	s_nop 0
	v_and_b32_e32 v248, s12, v248
	v_lshl_or_b32 v248, v248, 6, v249
	v_add_u32_e32 v249, 0x2000, v248
	global_load_dwordx2 v[146:147], v248, s[4:5]
	global_load_dwordx2 v[148:149], v248, s[4:5] offset:64
	global_load_dwordx2 v[150:151], v248, s[4:5] offset:128
	global_load_dwordx2 v[152:153], v248, s[4:5] offset:192
	global_load_dwordx2 v[154:155], v248, s[4:5] offset:1024
	global_load_dwordx2 v[156:157], v248, s[4:5] offset:1088
	global_load_dwordx2 v[158:159], v248, s[4:5] offset:1152
	global_load_dwordx2 v[160:161], v248, s[4:5] offset:1216
	global_load_dwordx2 v[162:163], v248, s[4:5] offset:2048
	global_load_dwordx2 v[164:165], v248, s[4:5] offset:2112
	global_load_dwordx2 v[166:167], v248, s[4:5] offset:2176
	global_load_dwordx2 v[168:169], v248, s[4:5] offset:2240
	global_load_dwordx2 v[170:171], v248, s[4:5] offset:3072
	global_load_dwordx2 v[172:173], v248, s[4:5] offset:3136
	global_load_dwordx2 v[174:175], v248, s[4:5] offset:3200
	global_load_dwordx2 v[176:177], v248, s[4:5] offset:3264
	global_load_dwordx2 v[178:179], v249, s[4:5]
	global_load_dwordx2 v[180:181], v249, s[4:5] offset:64
	global_load_dwordx2 v[182:183], v249, s[4:5] offset:128
	global_load_dwordx2 v[184:185], v249, s[4:5] offset:192
	global_load_dwordx2 v[186:187], v249, s[4:5] offset:1024
	global_load_dwordx2 v[188:189], v249, s[4:5] offset:1088
	global_load_dwordx2 v[190:191], v249, s[4:5] offset:1152
	global_load_dwordx2 v[192:193], v249, s[4:5] offset:1216
	global_load_dwordx2 v[194:195], v249, s[4:5] offset:2048
	global_load_dwordx2 v[196:197], v249, s[4:5] offset:2112
	global_load_dwordx2 v[198:199], v249, s[4:5] offset:2176
	global_load_dwordx2 v[200:201], v249, s[4:5] offset:2240
	global_load_dwordx2 v[202:203], v249, s[4:5] offset:3072
	global_load_dwordx2 v[204:205], v249, s[4:5] offset:3136
	global_load_dwordx2 v[206:207], v249, s[4:5] offset:3200
	global_load_dwordx2 v[208:209], v249, s[4:5] offset:3264

.Lrp_A1_skip:
	s_barrier
	ds_read_b128 v[212:215], v143
	ds_read_b128 v[216:219], v143 offset:64
	ds_read_b128 v[224:227], v143 offset:128
	ds_read_b128 v[228:231], v143 offset:192
	ds_read_b128 v[232:235], v143 offset:512
	ds_read_b128 v[236:239], v143 offset:576
	ds_read_b128 v[240:243], v143 offset:640
	ds_read_b128 v[244:247], v143 offset:704
	s_cmp_eq_u32 s31, 9
	s_cselect_b32 s0, 0, 2
	s_cmp_gt_i32 s31, 8
	v_and_b32_e32 v131, 64, v134
	v_mov_b32_e32 v132, v126
	v_mov_b32_e32 v133, v118
	v_mov_b32_e32 v136, v122
	v_mov_b32_e32 v137, v114
	s_cselect_b32 s7, s0, 1
	s_waitcnt lgkmcnt(0)
	v_mov_b32_e32 v130, v212
	v_pk_mul_f32 v[134:135], v[132:133], v[130:131] op_sel_hi:[1,0]
	v_mov_b32_e32 v132, v122
	v_pk_mul_f32 v[136:137], v[136:137], v[130:131] op_sel_hi:[1,0]
	v_cmp_eq_u32_e32 vcc, 0, v131
	v_cmp_gt_u32_e64 s[0:1], 8, v1
	v_pk_mul_f32 v[132:133], v[132:133], v[130:131] op_sel_hi:[1,0]
	v_mov_b32_e32 v130, v134
	v_mov_b32_e32 v131, v137
	s_cmp_gt_i32 s7, 1
	s_mov_b64 s[10:11], -1
	s_cbranch_scc0 .LBB0_1876
	v_mul_f32_e32 v114, 0xbfb8aa3b, v137
	v_exp_f32_e32 v114, v114
	v_mul_f32_e32 v118, 0xbfb8aa3b, v133
	v_mul_f32_e32 v122, 0xbfb8aa3b, v132
	v_exp_f32_e32 v118, v118
	v_add_f32_e32 v114, 1.0, v114
	v_rcp_f32_e32 v139, v114
	v_mul_f32_e32 v114, 0xbfb8aa3b, v134
	v_exp_f32_e32 v114, v114
	v_exp_f32_e32 v122, v122
	v_add_f32_e32 v118, 1.0, v118
	v_rcp_f32_e32 v141, v118
	v_add_f32_e32 v114, 1.0, v114
	v_rcp_f32_e32 v138, v114
	v_add_f32_e32 v114, 1.0, v122
	v_rcp_f32_e32 v140, v114
	s_mov_b64 s[10:11], 0
	v_pk_mul_f32 v[138:139], v[130:131], v[138:139]
	v_pk_mul_f32 v[140:141], v[132:133], v[140:141]

.LBB0_1906:
	v_add_u32_e32 v126, 0x210, v126
	v_cvt_pk_bf16_f32 v114, v121, s0
	v_lshl_add_u32 v115, v134, 1, v126
	ds_write_b16 v115, v114
	v_cvt_pk_bf16_f32 v114, v125, s0
	ds_write_b16 v115, v114 offset:32
	v_cvt_pk_bf16_f32 v114, v120, s0
	ds_write_b16 v115, v114 offset:256
	v_cvt_pk_bf16_f32 v114, v124, s0
	v_or_b32_e32 v127, 16, v144
	ds_write_b16 v115, v114 offset:288
	v_lshl_add_u32 v114, v127, 2, v220
	v_mov_b32_e32 v114, v216
	v_mov_b32_e32 v116, v110
	v_mov_b32_e32 v117, v102
	v_mov_b32_e32 v120, v106
	v_mov_b32_e32 v121, v102
	v_mov_b32_e32 v122, v106
	v_mov_b32_e32 v123, v98
	v_pk_mul_f32 v[118:119], v[116:117], v[114:115] op_sel_hi:[1,0]
	v_pk_mul_f32 v[116:117], v[120:121], v[114:115] op_sel_hi:[1,0]
	v_pk_mul_f32 v[120:121], v[122:123], v[114:115] op_sel_hi:[1,0]
	v_mov_b32_e32 v114, v118
	v_mov_b32_e32 v115, v121
	s_cmp_gt_i32 s7, 1
	s_mov_b64 s[10:11], -1
	s_cbranch_scc0 .LBB0_1908
	v_mul_f32_e32 v98, 0xbfb8aa3b, v121
	v_exp_f32_e32 v98, v98
	v_mul_f32_e32 v102, 0xbfb8aa3b, v117
	v_mul_f32_e32 v106, 0xbfb8aa3b, v116
	v_exp_f32_e32 v102, v102
	v_add_f32_e32 v98, 1.0, v98
	v_rcp_f32_e32 v123, v98
	v_mul_f32_e32 v98, 0xbfb8aa3b, v118
	v_exp_f32_e32 v98, v98
	v_exp_f32_e32 v106, v106
	v_add_f32_e32 v102, 1.0, v102
	v_rcp_f32_e32 v125, v102
	v_add_f32_e32 v98, 1.0, v98
	v_rcp_f32_e32 v122, v98
	v_add_f32_e32 v98, 1.0, v106
	v_rcp_f32_e32 v124, v98
	s_mov_b64 s[10:11], 0
	v_pk_mul_f32 v[122:123], v[114:115], v[122:123]
	v_pk_mul_f32 v[124:125], v[116:117], v[124:125]

.LBB0_1914:
	v_add_u32_e32 v118, 0x1ad0, v126
	v_cvt_pk_bf16_f32 v98, v123, s0
	v_lshl_add_u32 v102, v134, 1, v118
	ds_write_b16 v102, v98
	v_cvt_pk_bf16_f32 v98, v125, s0
	ds_write_b16 v102, v98 offset:32
	v_cvt_pk_bf16_f32 v98, v122, s0
	ds_write_b16 v102, v98 offset:256
	v_cvt_pk_bf16_f32 v98, v124, s0
	v_or_b32_e32 v119, 17, v144
	ds_write_b16 v102, v98 offset:288
	v_lshl_add_u32 v98, v119, 2, v220
	v_mov_b32_e32 v114, v217
	v_mov_b32_e32 v102, v111
	v_mov_b32_e32 v98, v107
	s_cmp_gt_i32 s7, 1
	s_mov_b64 s[10:11], -1
	v_pk_mul_f32 v[110:111], v[102:103], v[114:115] op_sel_hi:[1,0]
	v_mov_b32_e32 v102, v107
	v_pk_mul_f32 v[106:107], v[98:99], v[114:115] op_sel_hi:[1,0]
	v_pk_mul_f32 v[102:103], v[102:103], v[114:115] op_sel_hi:[1,0]
	v_mov_b32_e32 v98, v110
	v_mov_b32_e32 v99, v107
	s_cbranch_scc0 .LBB0_1916
	v_mul_f32_e32 v114, 0xbfb8aa3b, v107
	v_exp_f32_e32 v114, v114
	v_mul_f32_e32 v115, 0xbfb8aa3b, v103
	v_exp_f32_e32 v115, v115
	v_mul_f32_e32 v117, 0xbfb8aa3b, v102
	v_add_f32_e32 v114, 1.0, v114
	v_exp_f32_e32 v120, v117
	v_add_f32_e32 v116, 1.0, v115
	v_rcp_f32_e32 v115, v114
	v_mul_f32_e32 v114, 0xbfb8aa3b, v110
	v_exp_f32_e32 v114, v114
	v_rcp_f32_e32 v117, v116
	v_add_f32_e32 v116, 1.0, v120
	v_rcp_f32_e32 v116, v116
	v_add_f32_e32 v114, 1.0, v114
	v_rcp_f32_e32 v114, v114
	s_mov_b64 s[10:11], 0
	v_pk_mul_f32 v[116:117], v[102:103], v[116:117]
	v_pk_mul_f32 v[114:115], v[98:99], v[114:115]

.LBB0_1922:
	v_add_u32_e32 v118, 0x210, v118
	v_cvt_pk_bf16_f32 v98, v115, s0
	v_lshl_add_u32 v99, v134, 1, v118
	ds_write_b16 v99, v98
	v_cvt_pk_bf16_f32 v98, v117, s0
	ds_write_b16 v99, v98 offset:32
	v_cvt_pk_bf16_f32 v98, v114, s0
	ds_write_b16 v99, v98 offset:256
	v_cvt_pk_bf16_f32 v98, v116, s0
	v_or_b32_e32 v119, 18, v144
	ds_write_b16 v99, v98 offset:288
	v_lshl_add_u32 v98, v119, 2, v220
	v_mov_b32_e32 v98, v218
	v_mov_b32_e32 v102, v112
	v_mov_b32_e32 v103, v104
	v_mov_b32_e32 v110, v108
	v_mov_b32_e32 v111, v104
	v_mov_b32_e32 v114, v108
	v_mov_b32_e32 v115, v100
	v_pk_mul_f32 v[106:107], v[102:103], v[98:99] op_sel_hi:[1,0]
	v_pk_mul_f32 v[102:103], v[110:111], v[98:99] op_sel_hi:[1,0]
	v_pk_mul_f32 v[110:111], v[114:115], v[98:99] op_sel_hi:[1,0]
	v_mov_b32_e32 v98, v106
	v_mov_b32_e32 v99, v111
	s_cmp_gt_i32 s7, 1
	s_mov_b64 s[10:11], -1
	s_cbranch_scc0 .LBB0_1924
	v_mul_f32_e32 v100, 0xbfb8aa3b, v111
	v_exp_f32_e32 v100, v100
	v_mul_f32_e32 v104, 0xbfb8aa3b, v103
	v_mul_f32_e32 v108, 0xbfb8aa3b, v102
	v_exp_f32_e32 v104, v104
	v_add_f32_e32 v100, 1.0, v100
	v_rcp_f32_e32 v115, v100
	v_mul_f32_e32 v100, 0xbfb8aa3b, v106
	v_exp_f32_e32 v100, v100
	v_exp_f32_e32 v108, v108
	v_add_f32_e32 v104, 1.0, v104
	v_rcp_f32_e32 v117, v104
	v_add_f32_e32 v100, 1.0, v100
	v_rcp_f32_e32 v114, v100
	v_add_f32_e32 v100, 1.0, v108
	v_rcp_f32_e32 v116, v100
	s_mov_b64 s[10:11], 0
	v_pk_mul_f32 v[114:115], v[98:99], v[114:115]
	v_pk_mul_f32 v[116:117], v[102:103], v[116:117]

.LBB0_1930:
	v_add_u32_e32 v110, 0x210, v118
	v_cvt_pk_bf16_f32 v98, v115, s0
	v_lshl_add_u32 v99, v134, 1, v110
	ds_write_b16 v99, v98
	v_cvt_pk_bf16_f32 v98, v117, s0
	ds_write_b16 v99, v98 offset:32
	v_cvt_pk_bf16_f32 v98, v114, s0
	ds_write_b16 v99, v98 offset:256
	v_cvt_pk_bf16_f32 v98, v116, s0
	v_or_b32_e32 v111, 19, v144
	ds_write_b16 v99, v98 offset:288
	v_lshl_add_u32 v98, v111, 2, v220
	v_mov_b32_e32 v98, v219
	v_mov_b32_e32 v104, v113
	v_mov_b32_e32 v100, v109
	s_cmp_gt_i32 s7, 1
	s_mov_b64 s[10:11], -1
	v_pk_mul_f32 v[102:103], v[104:105], v[98:99] op_sel_hi:[1,0]
	v_mov_b32_e32 v104, v109
	v_pk_mul_f32 v[106:107], v[100:101], v[98:99] op_sel_hi:[1,0]
	v_pk_mul_f32 v[100:101], v[104:105], v[98:99] op_sel_hi:[1,0]
	v_mov_b32_e32 v98, v102
	v_mov_b32_e32 v99, v107
	s_cbranch_scc0 .LBB0_1932
	v_mul_f32_e32 v104, 0xbfb8aa3b, v107
	v_exp_f32_e32 v104, v104
	v_mul_f32_e32 v105, 0xbfb8aa3b, v101
	v_exp_f32_e32 v105, v105
	v_mul_f32_e32 v109, 0xbfb8aa3b, v100
	v_add_f32_e32 v104, 1.0, v104
	v_exp_f32_e32 v112, v109
	v_add_f32_e32 v108, 1.0, v105
	v_rcp_f32_e32 v105, v104
	v_mul_f32_e32 v104, 0xbfb8aa3b, v102
	v_exp_f32_e32 v104, v104
	v_rcp_f32_e32 v109, v108
	v_add_f32_e32 v108, 1.0, v112
	v_rcp_f32_e32 v108, v108
	v_add_f32_e32 v104, 1.0, v104
	v_rcp_f32_e32 v104, v104
	s_mov_b64 s[10:11], 0
	v_pk_mul_f32 v[108:109], v[100:101], v[108:109]
	v_pk_mul_f32 v[104:105], v[98:99], v[104:105]

.LBB0_1938:
	v_add_u32_e32 v110, 0x210, v110
	v_cvt_pk_bf16_f32 v98, v105, s0
	v_lshl_add_u32 v99, v134, 1, v110
	ds_write_b16 v99, v98
	v_cvt_pk_bf16_f32 v98, v109, s0
	ds_write_b16 v99, v98 offset:32
	v_cvt_pk_bf16_f32 v98, v104, s0
	ds_write_b16 v99, v98 offset:256
	v_cvt_pk_bf16_f32 v98, v108, s0
	v_or_b32_e32 v111, 32, v144
	ds_write_b16 v99, v98 offset:288
	v_lshl_add_u32 v98, v111, 2, v220
	v_mov_b32_e32 v98, v224
	v_mov_b32_e32 v100, v94
	v_mov_b32_e32 v101, v86
	v_mov_b32_e32 v104, v90
	v_mov_b32_e32 v105, v86
	v_mov_b32_e32 v106, v90
	v_mov_b32_e32 v107, v82
	v_pk_mul_f32 v[102:103], v[100:101], v[98:99] op_sel_hi:[1,0]
	v_pk_mul_f32 v[100:101], v[104:105], v[98:99] op_sel_hi:[1,0]
	v_pk_mul_f32 v[104:105], v[106:107], v[98:99] op_sel_hi:[1,0]
	v_mov_b32_e32 v98, v102
	v_mov_b32_e32 v99, v105
	s_cmp_gt_i32 s7, 1
	s_mov_b64 s[10:11], -1
	s_cbranch_scc0 .LBB0_1940
	v_mul_f32_e32 v82, 0xbfb8aa3b, v105
	v_exp_f32_e32 v82, v82
	v_mul_f32_e32 v86, 0xbfb8aa3b, v101
	v_mul_f32_e32 v90, 0xbfb8aa3b, v100
	v_exp_f32_e32 v86, v86
	v_add_f32_e32 v82, 1.0, v82
	v_rcp_f32_e32 v107, v82
	v_mul_f32_e32 v82, 0xbfb8aa3b, v102
	v_exp_f32_e32 v82, v82
	v_exp_f32_e32 v90, v90
	v_add_f32_e32 v86, 1.0, v86
	v_rcp_f32_e32 v109, v86
	v_add_f32_e32 v82, 1.0, v82
	v_rcp_f32_e32 v106, v82
	v_add_f32_e32 v82, 1.0, v90
	v_rcp_f32_e32 v108, v82
	s_mov_b64 s[10:11], 0
	v_pk_mul_f32 v[106:107], v[98:99], v[106:107]
	v_pk_mul_f32 v[108:109], v[100:101], v[108:109]

.LBB0_1946:
	v_add_u32_e32 v102, 0x1ad0, v110
	v_cvt_pk_bf16_f32 v82, v107, s0
	v_lshl_add_u32 v86, v134, 1, v102
	ds_write_b16 v86, v82
	v_cvt_pk_bf16_f32 v82, v109, s0
	ds_write_b16 v86, v82 offset:32
	v_cvt_pk_bf16_f32 v82, v106, s0
	ds_write_b16 v86, v82 offset:256
	v_cvt_pk_bf16_f32 v82, v108, s0
	v_or_b32_e32 v103, 33, v144
	ds_write_b16 v86, v82 offset:288
	v_lshl_add_u32 v82, v103, 2, v220
	v_mov_b32_e32 v98, v225
	v_mov_b32_e32 v86, v95
	v_mov_b32_e32 v82, v91
	s_cmp_gt_i32 s7, 1
	s_mov_b64 s[10:11], -1
	v_pk_mul_f32 v[94:95], v[86:87], v[98:99] op_sel_hi:[1,0]
	v_mov_b32_e32 v86, v91
	v_pk_mul_f32 v[90:91], v[82:83], v[98:99] op_sel_hi:[1,0]
	v_pk_mul_f32 v[86:87], v[86:87], v[98:99] op_sel_hi:[1,0]
	v_mov_b32_e32 v82, v94
	v_mov_b32_e32 v83, v91
	s_cbranch_scc0 .LBB0_1948
	v_mul_f32_e32 v98, 0xbfb8aa3b, v91
	v_exp_f32_e32 v98, v98
	v_mul_f32_e32 v99, 0xbfb8aa3b, v87
	v_exp_f32_e32 v99, v99
	v_mul_f32_e32 v101, 0xbfb8aa3b, v86
	v_add_f32_e32 v98, 1.0, v98
	v_exp_f32_e32 v104, v101
	v_add_f32_e32 v100, 1.0, v99
	v_rcp_f32_e32 v99, v98
	v_mul_f32_e32 v98, 0xbfb8aa3b, v94
	v_exp_f32_e32 v98, v98
	v_rcp_f32_e32 v101, v100
	v_add_f32_e32 v100, 1.0, v104
	v_rcp_f32_e32 v100, v100
	v_add_f32_e32 v98, 1.0, v98
	v_rcp_f32_e32 v98, v98
	s_mov_b64 s[10:11], 0
	v_pk_mul_f32 v[100:101], v[86:87], v[100:101]
	v_pk_mul_f32 v[98:99], v[82:83], v[98:99]

.LBB0_1954:
	v_add_u32_e32 v102, 0x210, v102
	v_cvt_pk_bf16_f32 v82, v99, s0
	v_lshl_add_u32 v83, v134, 1, v102
	ds_write_b16 v83, v82
	v_cvt_pk_bf16_f32 v82, v101, s0
	ds_write_b16 v83, v82 offset:32
	v_cvt_pk_bf16_f32 v82, v98, s0
	ds_write_b16 v83, v82 offset:256
	v_cvt_pk_bf16_f32 v82, v100, s0
	v_or_b32_e32 v103, 34, v144
	ds_write_b16 v83, v82 offset:288
	v_lshl_add_u32 v82, v103, 2, v220
	v_mov_b32_e32 v82, v226
	v_mov_b32_e32 v86, v96
	v_mov_b32_e32 v87, v88
	v_mov_b32_e32 v94, v92
	v_mov_b32_e32 v95, v88
	v_mov_b32_e32 v98, v92
	v_mov_b32_e32 v99, v84
	v_pk_mul_f32 v[90:91], v[86:87], v[82:83] op_sel_hi:[1,0]
	v_pk_mul_f32 v[86:87], v[94:95], v[82:83] op_sel_hi:[1,0]
	v_pk_mul_f32 v[94:95], v[98:99], v[82:83] op_sel_hi:[1,0]
	v_mov_b32_e32 v82, v90
	v_mov_b32_e32 v83, v95
	s_cmp_gt_i32 s7, 1
	s_mov_b64 s[10:11], -1
	s_cbranch_scc0 .LBB0_1956
	v_mul_f32_e32 v84, 0xbfb8aa3b, v95
	v_exp_f32_e32 v84, v84
	v_mul_f32_e32 v88, 0xbfb8aa3b, v87
	v_mul_f32_e32 v92, 0xbfb8aa3b, v86
	v_exp_f32_e32 v88, v88
	v_add_f32_e32 v84, 1.0, v84
	v_rcp_f32_e32 v99, v84
	v_mul_f32_e32 v84, 0xbfb8aa3b, v90
	v_exp_f32_e32 v84, v84
	v_exp_f32_e32 v92, v92
	v_add_f32_e32 v88, 1.0, v88
	v_rcp_f32_e32 v101, v88
	v_add_f32_e32 v84, 1.0, v84
	v_rcp_f32_e32 v98, v84
	v_add_f32_e32 v84, 1.0, v92
	v_rcp_f32_e32 v100, v84
	s_mov_b64 s[10:11], 0
	v_pk_mul_f32 v[98:99], v[82:83], v[98:99]
	v_pk_mul_f32 v[100:101], v[86:87], v[100:101]

.LBB0_1962:
	v_add_u32_e32 v94, 0x210, v102
	v_cvt_pk_bf16_f32 v82, v99, s0
	v_lshl_add_u32 v83, v134, 1, v94
	ds_write_b16 v83, v82
	v_cvt_pk_bf16_f32 v82, v101, s0
	ds_write_b16 v83, v82 offset:32
	v_cvt_pk_bf16_f32 v82, v98, s0
	ds_write_b16 v83, v82 offset:256
	v_cvt_pk_bf16_f32 v82, v100, s0
	v_or_b32_e32 v95, 35, v144
	ds_write_b16 v83, v82 offset:288
	v_lshl_add_u32 v82, v95, 2, v220
	v_mov_b32_e32 v82, v227
	v_mov_b32_e32 v88, v97
	v_mov_b32_e32 v84, v93
	s_cmp_gt_i32 s7, 1
	s_mov_b64 s[10:11], -1
	v_pk_mul_f32 v[86:87], v[88:89], v[82:83] op_sel_hi:[1,0]
	v_mov_b32_e32 v88, v93
	v_pk_mul_f32 v[90:91], v[84:85], v[82:83] op_sel_hi:[1,0]
	v_pk_mul_f32 v[84:85], v[88:89], v[82:83] op_sel_hi:[1,0]
	v_mov_b32_e32 v82, v86
	v_mov_b32_e32 v83, v91
	s_cbranch_scc0 .LBB0_1964
	v_mul_f32_e32 v88, 0xbfb8aa3b, v91
	v_exp_f32_e32 v88, v88
	v_mul_f32_e32 v89, 0xbfb8aa3b, v85
	v_exp_f32_e32 v89, v89
	v_mul_f32_e32 v93, 0xbfb8aa3b, v84
	v_add_f32_e32 v88, 1.0, v88
	v_exp_f32_e32 v96, v93
	v_add_f32_e32 v92, 1.0, v89
	v_rcp_f32_e32 v89, v88
	v_mul_f32_e32 v88, 0xbfb8aa3b, v86
	v_exp_f32_e32 v88, v88
	v_rcp_f32_e32 v93, v92
	v_add_f32_e32 v92, 1.0, v96
	v_rcp_f32_e32 v92, v92
	v_add_f32_e32 v88, 1.0, v88
	v_rcp_f32_e32 v88, v88
	s_mov_b64 s[10:11], 0
	v_pk_mul_f32 v[92:93], v[84:85], v[92:93]
	v_pk_mul_f32 v[88:89], v[82:83], v[88:89]

.LBB0_1970:
	v_add_u32_e32 v94, 0x210, v94
	v_cvt_pk_bf16_f32 v82, v89, s0
	v_lshl_add_u32 v83, v134, 1, v94
	ds_write_b16 v83, v82
	v_cvt_pk_bf16_f32 v82, v93, s0
	ds_write_b16 v83, v82 offset:32
	v_cvt_pk_bf16_f32 v82, v88, s0
	ds_write_b16 v83, v82 offset:256
	v_cvt_pk_bf16_f32 v82, v92, s0
	v_or_b32_e32 v95, 48, v144
	ds_write_b16 v83, v82 offset:288
	v_lshl_add_u32 v82, v95, 2, v220
	v_mov_b32_e32 v82, v228
	v_mov_b32_e32 v84, v78
	v_mov_b32_e32 v85, v70
	v_mov_b32_e32 v88, v74
	v_mov_b32_e32 v89, v70
	v_mov_b32_e32 v90, v74
	v_mov_b32_e32 v91, v66
	v_pk_mul_f32 v[86:87], v[84:85], v[82:83] op_sel_hi:[1,0]
	v_pk_mul_f32 v[84:85], v[88:89], v[82:83] op_sel_hi:[1,0]
	v_pk_mul_f32 v[88:89], v[90:91], v[82:83] op_sel_hi:[1,0]
	v_mov_b32_e32 v82, v86
	v_mov_b32_e32 v83, v89
	s_cmp_gt_i32 s7, 1
	s_mov_b64 s[10:11], -1
	s_cbranch_scc0 .LBB0_1972
	v_mul_f32_e32 v66, 0xbfb8aa3b, v89
	v_exp_f32_e32 v66, v66
	v_mul_f32_e32 v70, 0xbfb8aa3b, v85
	v_mul_f32_e32 v74, 0xbfb8aa3b, v84
	v_exp_f32_e32 v70, v70
	v_add_f32_e32 v66, 1.0, v66
	v_rcp_f32_e32 v91, v66
	v_mul_f32_e32 v66, 0xbfb8aa3b, v86
	v_exp_f32_e32 v66, v66
	v_exp_f32_e32 v74, v74
	v_add_f32_e32 v70, 1.0, v70
	v_rcp_f32_e32 v93, v70
	v_add_f32_e32 v66, 1.0, v66
	v_rcp_f32_e32 v90, v66
	v_add_f32_e32 v66, 1.0, v74
	v_rcp_f32_e32 v92, v66
	s_mov_b64 s[10:11], 0
	v_pk_mul_f32 v[90:91], v[82:83], v[90:91]
	v_pk_mul_f32 v[92:93], v[84:85], v[92:93]

.LBB0_1978:
	v_add_u32_e32 v86, 0x1ad0, v94
	v_cvt_pk_bf16_f32 v66, v91, s0
	v_lshl_add_u32 v70, v134, 1, v86
	ds_write_b16 v70, v66
	v_cvt_pk_bf16_f32 v66, v93, s0
	ds_write_b16 v70, v66 offset:32
	v_cvt_pk_bf16_f32 v66, v90, s0
	ds_write_b16 v70, v66 offset:256
	v_cvt_pk_bf16_f32 v66, v92, s0
	v_or_b32_e32 v87, 49, v144
	ds_write_b16 v70, v66 offset:288
	v_lshl_add_u32 v66, v87, 2, v220
	v_mov_b32_e32 v82, v229
	v_mov_b32_e32 v70, v79
	v_mov_b32_e32 v66, v75
	s_cmp_gt_i32 s7, 1
	s_mov_b64 s[10:11], -1
	v_pk_mul_f32 v[78:79], v[70:71], v[82:83] op_sel_hi:[1,0]
	v_mov_b32_e32 v70, v75
	v_pk_mul_f32 v[74:75], v[66:67], v[82:83] op_sel_hi:[1,0]
	v_pk_mul_f32 v[70:71], v[70:71], v[82:83] op_sel_hi:[1,0]
	v_mov_b32_e32 v66, v78
	v_mov_b32_e32 v67, v75
	s_cbranch_scc0 .LBB0_1980
	v_mul_f32_e32 v82, 0xbfb8aa3b, v75
	v_exp_f32_e32 v82, v82
	v_mul_f32_e32 v83, 0xbfb8aa3b, v71
	v_exp_f32_e32 v83, v83
	v_mul_f32_e32 v85, 0xbfb8aa3b, v70
	v_add_f32_e32 v82, 1.0, v82
	v_exp_f32_e32 v88, v85
	v_add_f32_e32 v84, 1.0, v83
	v_rcp_f32_e32 v83, v82
	v_mul_f32_e32 v82, 0xbfb8aa3b, v78
	v_exp_f32_e32 v82, v82
	v_rcp_f32_e32 v85, v84
	v_add_f32_e32 v84, 1.0, v88
	v_rcp_f32_e32 v84, v84
	v_add_f32_e32 v82, 1.0, v82
	v_rcp_f32_e32 v82, v82
	s_mov_b64 s[10:11], 0
	v_pk_mul_f32 v[84:85], v[70:71], v[84:85]
	v_pk_mul_f32 v[82:83], v[66:67], v[82:83]

.LBB0_1986:
	v_add_u32_e32 v86, 0x210, v86
	v_cvt_pk_bf16_f32 v66, v83, s0
	v_lshl_add_u32 v67, v134, 1, v86
	ds_write_b16 v67, v66
	v_cvt_pk_bf16_f32 v66, v85, s0
	ds_write_b16 v67, v66 offset:32
	v_cvt_pk_bf16_f32 v66, v82, s0
	ds_write_b16 v67, v66 offset:256
	v_cvt_pk_bf16_f32 v66, v84, s0
	v_or_b32_e32 v87, 50, v144
	ds_write_b16 v67, v66 offset:288
	v_lshl_add_u32 v66, v87, 2, v220
	v_mov_b32_e32 v66, v230
	v_mov_b32_e32 v70, v80
	v_mov_b32_e32 v71, v72
	v_mov_b32_e32 v78, v76
	v_mov_b32_e32 v79, v72
	v_mov_b32_e32 v82, v76
	v_mov_b32_e32 v83, v68
	v_pk_mul_f32 v[74:75], v[70:71], v[66:67] op_sel_hi:[1,0]
	v_pk_mul_f32 v[70:71], v[78:79], v[66:67] op_sel_hi:[1,0]
	v_pk_mul_f32 v[78:79], v[82:83], v[66:67] op_sel_hi:[1,0]
	v_mov_b32_e32 v66, v74
	v_mov_b32_e32 v67, v79
	s_cmp_gt_i32 s7, 1
	s_mov_b64 s[10:11], -1
	s_cbranch_scc0 .LBB0_1988
	v_mul_f32_e32 v68, 0xbfb8aa3b, v79
	v_exp_f32_e32 v68, v68
	v_mul_f32_e32 v72, 0xbfb8aa3b, v71
	v_mul_f32_e32 v76, 0xbfb8aa3b, v70
	v_exp_f32_e32 v72, v72
	v_add_f32_e32 v68, 1.0, v68
	v_rcp_f32_e32 v83, v68
	v_mul_f32_e32 v68, 0xbfb8aa3b, v74
	v_exp_f32_e32 v68, v68
	v_exp_f32_e32 v76, v76
	v_add_f32_e32 v72, 1.0, v72
	v_rcp_f32_e32 v85, v72
	v_add_f32_e32 v68, 1.0, v68
	v_rcp_f32_e32 v82, v68
	v_add_f32_e32 v68, 1.0, v76
	v_rcp_f32_e32 v84, v68
	s_mov_b64 s[10:11], 0
	v_pk_mul_f32 v[82:83], v[66:67], v[82:83]
	v_pk_mul_f32 v[84:85], v[70:71], v[84:85]

.LBB0_1994:
	v_add_u32_e32 v78, 0x210, v86
	v_cvt_pk_bf16_f32 v66, v83, s0
	v_lshl_add_u32 v67, v134, 1, v78
	ds_write_b16 v67, v66
	v_cvt_pk_bf16_f32 v66, v85, s0
	ds_write_b16 v67, v66 offset:32
	v_cvt_pk_bf16_f32 v66, v82, s0
	ds_write_b16 v67, v66 offset:256
	v_cvt_pk_bf16_f32 v66, v84, s0
	v_or_b32_e32 v79, 51, v144
	ds_write_b16 v67, v66 offset:288
	v_lshl_add_u32 v66, v79, 2, v220
	v_mov_b32_e32 v66, v231
	v_mov_b32_e32 v72, v81
	v_mov_b32_e32 v68, v77
	s_cmp_gt_i32 s7, 1
	s_mov_b64 s[10:11], -1
	v_pk_mul_f32 v[70:71], v[72:73], v[66:67] op_sel_hi:[1,0]
	v_mov_b32_e32 v72, v77
	v_pk_mul_f32 v[74:75], v[68:69], v[66:67] op_sel_hi:[1,0]
	v_pk_mul_f32 v[68:69], v[72:73], v[66:67] op_sel_hi:[1,0]
	v_mov_b32_e32 v66, v70
	v_mov_b32_e32 v67, v75
	s_cbranch_scc0 .LBB0_1996
	v_mul_f32_e32 v72, 0xbfb8aa3b, v75
	v_exp_f32_e32 v72, v72
	v_mul_f32_e32 v73, 0xbfb8aa3b, v69
	v_exp_f32_e32 v73, v73
	v_mul_f32_e32 v77, 0xbfb8aa3b, v68
	v_add_f32_e32 v72, 1.0, v72
	v_exp_f32_e32 v80, v77
	v_add_f32_e32 v76, 1.0, v73
	v_rcp_f32_e32 v73, v72
	v_mul_f32_e32 v72, 0xbfb8aa3b, v70
	v_exp_f32_e32 v72, v72
	v_rcp_f32_e32 v77, v76
	v_add_f32_e32 v76, 1.0, v80
	v_rcp_f32_e32 v76, v76
	v_add_f32_e32 v72, 1.0, v72
	v_rcp_f32_e32 v72, v72
	s_mov_b64 s[10:11], 0
	v_pk_mul_f32 v[76:77], v[68:69], v[76:77]
	v_pk_mul_f32 v[72:73], v[66:67], v[72:73]

.LBB0_2002:
	v_add_u32_e32 v78, 0x210, v78
	v_cvt_pk_bf16_f32 v66, v73, s0
	v_lshl_add_u32 v67, v134, 1, v78
	ds_write_b16 v67, v66
	v_cvt_pk_bf16_f32 v66, v77, s0
	ds_write_b16 v67, v66 offset:32
	v_cvt_pk_bf16_f32 v66, v72, s0
	ds_write_b16 v67, v66 offset:256
	v_cvt_pk_bf16_f32 v66, v76, s0
	ds_write_b16 v67, v66 offset:288
	v_mov_b32_e32 v66, v232
	v_mov_b32_e32 v68, v62
	v_mov_b32_e32 v69, v54
	v_mov_b32_e32 v72, v58
	v_mov_b32_e32 v73, v54
	v_mov_b32_e32 v74, v58
	v_mov_b32_e32 v75, v50
	v_pk_mul_f32 v[70:71], v[68:69], v[66:67] op_sel_hi:[1,0]
	v_pk_mul_f32 v[68:69], v[72:73], v[66:67] op_sel_hi:[1,0]
	v_pk_mul_f32 v[72:73], v[74:75], v[66:67] op_sel_hi:[1,0]
	v_mov_b32_e32 v66, v70
	v_mov_b32_e32 v67, v73
	s_cmp_gt_i32 s7, 1
	s_mov_b64 s[10:11], -1
	s_cbranch_scc0 .LBB0_2004
	v_mul_f32_e32 v50, 0xbfb8aa3b, v73
	v_exp_f32_e32 v50, v50
	v_mul_f32_e32 v54, 0xbfb8aa3b, v69
	v_mul_f32_e32 v58, 0xbfb8aa3b, v68
	v_exp_f32_e32 v54, v54
	v_add_f32_e32 v50, 1.0, v50
	v_rcp_f32_e32 v75, v50
	v_mul_f32_e32 v50, 0xbfb8aa3b, v70
	v_exp_f32_e32 v50, v50
	v_exp_f32_e32 v58, v58
	v_add_f32_e32 v54, 1.0, v54
	v_rcp_f32_e32 v77, v54
	v_add_f32_e32 v50, 1.0, v50
	v_rcp_f32_e32 v74, v50
	v_add_f32_e32 v50, 1.0, v58
	v_rcp_f32_e32 v76, v50
	s_mov_b64 s[10:11], 0
	v_pk_mul_f32 v[74:75], v[66:67], v[74:75]
	v_pk_mul_f32 v[76:77], v[68:69], v[76:77]

.LBB0_2010:
	v_add_u32_e32 v70, 0x9ed0, v78
	v_cvt_pk_bf16_f32 v50, v75, s0
	v_lshl_add_u32 v54, v134, 1, v70
	v_mov_b32_e32 v66, v233
	ds_write_b16 v54, v50
	v_cvt_pk_bf16_f32 v50, v77, s0
	ds_write_b16 v54, v50 offset:32
	v_cvt_pk_bf16_f32 v50, v74, s0
	ds_write_b16 v54, v50 offset:256
	v_cvt_pk_bf16_f32 v50, v76, s0
	ds_write_b16 v54, v50 offset:288
	v_mov_b32_e32 v54, v63
	v_mov_b32_e32 v50, v59
	v_pk_mul_f32 v[62:63], v[54:55], v[66:67] op_sel_hi:[1,0]
	v_mov_b32_e32 v54, v59
	v_pk_mul_f32 v[58:59], v[50:51], v[66:67] op_sel_hi:[1,0]
	v_pk_mul_f32 v[54:55], v[54:55], v[66:67] op_sel_hi:[1,0]
	v_mov_b32_e32 v50, v62
	v_mov_b32_e32 v51, v59
	s_cmp_gt_i32 s7, 1
	s_mov_b64 s[10:11], -1
	s_cbranch_scc0 .LBB0_2012
	v_mul_f32_e32 v66, 0xbfb8aa3b, v59
	v_exp_f32_e32 v66, v66
	v_mul_f32_e32 v67, 0xbfb8aa3b, v55
	v_exp_f32_e32 v67, v67
	v_mul_f32_e32 v69, 0xbfb8aa3b, v54
	v_add_f32_e32 v66, 1.0, v66
	v_exp_f32_e32 v71, v69
	v_add_f32_e32 v68, 1.0, v67
	v_rcp_f32_e32 v67, v66
	v_mul_f32_e32 v66, 0xbfb8aa3b, v62
	v_exp_f32_e32 v66, v66
	v_rcp_f32_e32 v69, v68
	v_add_f32_e32 v68, 1.0, v71
	v_rcp_f32_e32 v68, v68
	v_add_f32_e32 v66, 1.0, v66
	v_rcp_f32_e32 v66, v66
	s_mov_b64 s[10:11], 0
	v_pk_mul_f32 v[68:69], v[54:55], v[68:69]
	v_pk_mul_f32 v[66:67], v[50:51], v[66:67]

.LBB0_2018:
	v_add_u32_e32 v70, 0x210, v70
	v_cvt_pk_bf16_f32 v50, v67, s0
	v_lshl_add_u32 v51, v134, 1, v70
	ds_write_b16 v51, v50
	v_cvt_pk_bf16_f32 v50, v69, s0
	ds_write_b16 v51, v50 offset:32
	v_cvt_pk_bf16_f32 v50, v66, s0
	ds_write_b16 v51, v50 offset:256
	v_cvt_pk_bf16_f32 v50, v68, s0
	ds_write_b16 v51, v50 offset:288
	v_mov_b32_e32 v50, v234
	v_mov_b32_e32 v54, v64
	v_mov_b32_e32 v55, v56
	v_mov_b32_e32 v62, v60
	v_mov_b32_e32 v63, v56
	v_mov_b32_e32 v66, v60
	v_mov_b32_e32 v67, v52
	v_pk_mul_f32 v[58:59], v[54:55], v[50:51] op_sel_hi:[1,0]
	v_pk_mul_f32 v[54:55], v[62:63], v[50:51] op_sel_hi:[1,0]
	v_pk_mul_f32 v[62:63], v[66:67], v[50:51] op_sel_hi:[1,0]
	v_mov_b32_e32 v50, v58
	v_mov_b32_e32 v51, v63
	s_cmp_gt_i32 s7, 1
	s_mov_b64 s[10:11], -1
	s_cbranch_scc0 .LBB0_2020
	v_mul_f32_e32 v52, 0xbfb8aa3b, v63
	v_exp_f32_e32 v52, v52
	v_mul_f32_e32 v56, 0xbfb8aa3b, v55
	v_mul_f32_e32 v60, 0xbfb8aa3b, v54
	v_exp_f32_e32 v56, v56
	v_add_f32_e32 v52, 1.0, v52
	v_rcp_f32_e32 v67, v52
	v_mul_f32_e32 v52, 0xbfb8aa3b, v58
	v_exp_f32_e32 v52, v52
	v_exp_f32_e32 v60, v60
	v_add_f32_e32 v56, 1.0, v56
	v_rcp_f32_e32 v69, v56
	v_add_f32_e32 v52, 1.0, v52
	v_rcp_f32_e32 v66, v52
	v_add_f32_e32 v52, 1.0, v60
	v_rcp_f32_e32 v68, v52
	s_mov_b64 s[10:11], 0
	v_pk_mul_f32 v[66:67], v[50:51], v[66:67]
	v_pk_mul_f32 v[68:69], v[54:55], v[68:69]

.LBB0_2026:
	v_add_u32_e32 v62, 0x210, v70
	v_cvt_pk_bf16_f32 v50, v67, s0
	v_lshl_add_u32 v51, v134, 1, v62
	ds_write_b16 v51, v50
	v_cvt_pk_bf16_f32 v50, v69, s0
	ds_write_b16 v51, v50 offset:32
	v_cvt_pk_bf16_f32 v50, v66, s0
	ds_write_b16 v51, v50 offset:256
	v_cvt_pk_bf16_f32 v50, v68, s0
	ds_write_b16 v51, v50 offset:288
	v_mov_b32_e32 v50, v235
	v_mov_b32_e32 v56, v65
	v_mov_b32_e32 v52, v61
	s_cmp_gt_i32 s7, 1
	s_mov_b64 s[10:11], -1
	v_pk_mul_f32 v[54:55], v[56:57], v[50:51] op_sel_hi:[1,0]
	v_mov_b32_e32 v56, v61
	v_pk_mul_f32 v[58:59], v[52:53], v[50:51] op_sel_hi:[1,0]
	v_pk_mul_f32 v[52:53], v[56:57], v[50:51] op_sel_hi:[1,0]
	v_mov_b32_e32 v50, v54
	v_mov_b32_e32 v51, v59
	s_cbranch_scc0 .LBB0_2028
	v_mul_f32_e32 v56, 0xbfb8aa3b, v59
	v_exp_f32_e32 v56, v56
	v_mul_f32_e32 v57, 0xbfb8aa3b, v53
	v_exp_f32_e32 v57, v57
	v_mul_f32_e32 v61, 0xbfb8aa3b, v52
	v_add_f32_e32 v56, 1.0, v56
	v_exp_f32_e32 v63, v61
	v_add_f32_e32 v60, 1.0, v57
	v_rcp_f32_e32 v57, v56
	v_mul_f32_e32 v56, 0xbfb8aa3b, v54
	v_exp_f32_e32 v56, v56
	v_rcp_f32_e32 v61, v60
	v_add_f32_e32 v60, 1.0, v63
	v_rcp_f32_e32 v60, v60
	v_add_f32_e32 v56, 1.0, v56
	v_rcp_f32_e32 v56, v56
	s_mov_b64 s[10:11], 0
	v_pk_mul_f32 v[60:61], v[52:53], v[60:61]
	v_pk_mul_f32 v[56:57], v[50:51], v[56:57]

.LBB0_2034:
	v_add_u32_e32 v62, 0x210, v62
	v_cvt_pk_bf16_f32 v50, v57, s0
	v_lshl_add_u32 v51, v134, 1, v62
	ds_write_b16 v51, v50
	v_cvt_pk_bf16_f32 v50, v61, s0
	ds_write_b16 v51, v50 offset:32
	v_cvt_pk_bf16_f32 v50, v56, s0
	ds_write_b16 v51, v50 offset:256
	v_cvt_pk_bf16_f32 v50, v60, s0
	ds_write_b16 v51, v50 offset:288
	v_mov_b32_e32 v50, v236
	v_mov_b32_e32 v52, v46
	v_mov_b32_e32 v53, v38
	v_mov_b32_e32 v56, v42
	v_mov_b32_e32 v57, v38
	v_mov_b32_e32 v58, v42
	v_mov_b32_e32 v59, v34
	v_pk_mul_f32 v[54:55], v[52:53], v[50:51] op_sel_hi:[1,0]
	v_pk_mul_f32 v[52:53], v[56:57], v[50:51] op_sel_hi:[1,0]
	v_pk_mul_f32 v[56:57], v[58:59], v[50:51] op_sel_hi:[1,0]
	v_mov_b32_e32 v50, v54
	v_mov_b32_e32 v51, v57
	s_cmp_gt_i32 s7, 1
	s_mov_b64 s[10:11], -1
	s_cbranch_scc0 .LBB0_2036
	v_mul_f32_e32 v34, 0xbfb8aa3b, v57
	v_exp_f32_e32 v34, v34
	v_mul_f32_e32 v38, 0xbfb8aa3b, v53
	v_mul_f32_e32 v42, 0xbfb8aa3b, v52
	v_exp_f32_e32 v38, v38
	v_add_f32_e32 v34, 1.0, v34
	v_rcp_f32_e32 v59, v34
	v_mul_f32_e32 v34, 0xbfb8aa3b, v54
	v_exp_f32_e32 v34, v34
	v_exp_f32_e32 v42, v42
	v_add_f32_e32 v38, 1.0, v38
	v_rcp_f32_e32 v61, v38
	v_add_f32_e32 v34, 1.0, v34
	v_rcp_f32_e32 v58, v34
	v_add_f32_e32 v34, 1.0, v42
	v_rcp_f32_e32 v60, v34
	s_mov_b64 s[10:11], 0
	v_pk_mul_f32 v[58:59], v[50:51], v[58:59]
	v_pk_mul_f32 v[60:61], v[52:53], v[60:61]

.LBB0_2042:
	v_add_u32_e32 v54, 0x1ad0, v62
	v_cvt_pk_bf16_f32 v34, v59, s0
	v_lshl_add_u32 v38, v134, 1, v54
	v_mov_b32_e32 v50, v237
	ds_write_b16 v38, v34
	v_cvt_pk_bf16_f32 v34, v61, s0
	ds_write_b16 v38, v34 offset:32
	v_cvt_pk_bf16_f32 v34, v58, s0
	ds_write_b16 v38, v34 offset:256
	v_cvt_pk_bf16_f32 v34, v60, s0
	ds_write_b16 v38, v34 offset:288
	v_mov_b32_e32 v38, v47
	v_mov_b32_e32 v34, v43
	v_pk_mul_f32 v[46:47], v[38:39], v[50:51] op_sel_hi:[1,0]
	v_mov_b32_e32 v38, v43
	v_pk_mul_f32 v[42:43], v[34:35], v[50:51] op_sel_hi:[1,0]
	v_pk_mul_f32 v[38:39], v[38:39], v[50:51] op_sel_hi:[1,0]
	v_mov_b32_e32 v34, v46
	v_mov_b32_e32 v35, v43
	s_cmp_gt_i32 s7, 1
	s_mov_b64 s[10:11], -1
	s_cbranch_scc0 .LBB0_2044
	v_mul_f32_e32 v50, 0xbfb8aa3b, v43
	v_exp_f32_e32 v50, v50
	v_mul_f32_e32 v51, 0xbfb8aa3b, v39
	v_exp_f32_e32 v51, v51
	v_mul_f32_e32 v53, 0xbfb8aa3b, v38
	v_add_f32_e32 v50, 1.0, v50
	v_exp_f32_e32 v55, v53
	v_add_f32_e32 v52, 1.0, v51
	v_rcp_f32_e32 v51, v50
	v_mul_f32_e32 v50, 0xbfb8aa3b, v46
	v_exp_f32_e32 v50, v50
	v_rcp_f32_e32 v53, v52
	v_add_f32_e32 v52, 1.0, v55
	v_rcp_f32_e32 v52, v52
	v_add_f32_e32 v50, 1.0, v50
	v_rcp_f32_e32 v50, v50
	s_mov_b64 s[10:11], 0
	v_pk_mul_f32 v[52:53], v[38:39], v[52:53]
	v_pk_mul_f32 v[50:51], v[34:35], v[50:51]

.LBB0_2050:
	v_add_u32_e32 v54, 0x210, v54
	v_cvt_pk_bf16_f32 v34, v51, s0
	v_lshl_add_u32 v35, v134, 1, v54
	ds_write_b16 v35, v34
	v_cvt_pk_bf16_f32 v34, v53, s0
	ds_write_b16 v35, v34 offset:32
	v_cvt_pk_bf16_f32 v34, v50, s0
	ds_write_b16 v35, v34 offset:256
	v_cvt_pk_bf16_f32 v34, v52, s0
	ds_write_b16 v35, v34 offset:288
	v_mov_b32_e32 v34, v238
	v_mov_b32_e32 v38, v48
	v_mov_b32_e32 v39, v40
	v_mov_b32_e32 v46, v44
	v_mov_b32_e32 v47, v40
	v_mov_b32_e32 v50, v44
	v_mov_b32_e32 v51, v36
	v_pk_mul_f32 v[42:43], v[38:39], v[34:35] op_sel_hi:[1,0]
	v_pk_mul_f32 v[38:39], v[46:47], v[34:35] op_sel_hi:[1,0]
	v_pk_mul_f32 v[46:47], v[50:51], v[34:35] op_sel_hi:[1,0]
	v_mov_b32_e32 v34, v42
	v_mov_b32_e32 v35, v47
	s_cmp_gt_i32 s7, 1
	s_mov_b64 s[10:11], -1
	s_cbranch_scc0 .LBB0_2052
	v_mul_f32_e32 v36, 0xbfb8aa3b, v47
	v_exp_f32_e32 v36, v36
	v_mul_f32_e32 v40, 0xbfb8aa3b, v39
	v_mul_f32_e32 v44, 0xbfb8aa3b, v38
	v_exp_f32_e32 v40, v40
	v_add_f32_e32 v36, 1.0, v36
	v_rcp_f32_e32 v51, v36
	v_mul_f32_e32 v36, 0xbfb8aa3b, v42
	v_exp_f32_e32 v36, v36
	v_exp_f32_e32 v44, v44
	v_add_f32_e32 v40, 1.0, v40
	v_rcp_f32_e32 v53, v40
	v_add_f32_e32 v36, 1.0, v36
	v_rcp_f32_e32 v50, v36
	v_add_f32_e32 v36, 1.0, v44
	v_rcp_f32_e32 v52, v36
	s_mov_b64 s[10:11], 0
	v_pk_mul_f32 v[50:51], v[34:35], v[50:51]
	v_pk_mul_f32 v[52:53], v[38:39], v[52:53]

.LBB0_2058:
	v_add_u32_e32 v46, 0x210, v54
	v_cvt_pk_bf16_f32 v34, v51, s0
	v_lshl_add_u32 v35, v134, 1, v46
	ds_write_b16 v35, v34
	v_cvt_pk_bf16_f32 v34, v53, s0
	ds_write_b16 v35, v34 offset:32
	v_cvt_pk_bf16_f32 v34, v50, s0
	ds_write_b16 v35, v34 offset:256
	v_cvt_pk_bf16_f32 v34, v52, s0
	ds_write_b16 v35, v34 offset:288
	v_mov_b32_e32 v34, v239
	v_mov_b32_e32 v40, v49
	v_mov_b32_e32 v36, v45
	s_cmp_gt_i32 s7, 1
	s_mov_b64 s[10:11], -1
	v_pk_mul_f32 v[38:39], v[40:41], v[34:35] op_sel_hi:[1,0]
	v_mov_b32_e32 v40, v45
	v_pk_mul_f32 v[42:43], v[36:37], v[34:35] op_sel_hi:[1,0]
	v_pk_mul_f32 v[36:37], v[40:41], v[34:35] op_sel_hi:[1,0]
	v_mov_b32_e32 v34, v38
	v_mov_b32_e32 v35, v43
	s_cbranch_scc0 .LBB0_2060
	v_mul_f32_e32 v40, 0xbfb8aa3b, v43
	v_exp_f32_e32 v40, v40
	v_mul_f32_e32 v41, 0xbfb8aa3b, v37
	v_exp_f32_e32 v41, v41
	v_mul_f32_e32 v45, 0xbfb8aa3b, v36
	v_add_f32_e32 v40, 1.0, v40
	v_exp_f32_e32 v47, v45
	v_add_f32_e32 v44, 1.0, v41
	v_rcp_f32_e32 v41, v40
	v_mul_f32_e32 v40, 0xbfb8aa3b, v38
	v_exp_f32_e32 v40, v40
	v_rcp_f32_e32 v45, v44
	v_add_f32_e32 v44, 1.0, v47
	v_rcp_f32_e32 v44, v44
	v_add_f32_e32 v40, 1.0, v40
	v_rcp_f32_e32 v40, v40
	s_mov_b64 s[10:11], 0
	v_pk_mul_f32 v[44:45], v[36:37], v[44:45]
	v_pk_mul_f32 v[40:41], v[34:35], v[40:41]

.LBB0_2066:
	v_add_u32_e32 v46, 0x210, v46
	v_cvt_pk_bf16_f32 v34, v41, s0
	v_lshl_add_u32 v35, v134, 1, v46
	ds_write_b16 v35, v34
	v_cvt_pk_bf16_f32 v34, v45, s0
	ds_write_b16 v35, v34 offset:32
	v_cvt_pk_bf16_f32 v34, v40, s0
	ds_write_b16 v35, v34 offset:256
	v_cvt_pk_bf16_f32 v34, v44, s0
	ds_write_b16 v35, v34 offset:288
	v_mov_b32_e32 v34, v240
	v_mov_b32_e32 v36, v30
	v_mov_b32_e32 v37, v22
	v_mov_b32_e32 v40, v26
	v_mov_b32_e32 v41, v22
	v_mov_b32_e32 v42, v26
	v_mov_b32_e32 v43, v18
	v_pk_mul_f32 v[38:39], v[36:37], v[34:35] op_sel_hi:[1,0]
	v_pk_mul_f32 v[36:37], v[40:41], v[34:35] op_sel_hi:[1,0]
	v_pk_mul_f32 v[40:41], v[42:43], v[34:35] op_sel_hi:[1,0]
	v_mov_b32_e32 v34, v38
	v_mov_b32_e32 v35, v41
	s_cmp_gt_i32 s7, 1
	s_mov_b64 s[10:11], -1
	s_cbranch_scc0 .LBB0_2068
	v_mul_f32_e32 v18, 0xbfb8aa3b, v41
	v_exp_f32_e32 v18, v18
	v_mul_f32_e32 v22, 0xbfb8aa3b, v37
	v_mul_f32_e32 v26, 0xbfb8aa3b, v36
	v_exp_f32_e32 v22, v22
	v_add_f32_e32 v18, 1.0, v18
	v_rcp_f32_e32 v43, v18
	v_mul_f32_e32 v18, 0xbfb8aa3b, v38
	v_exp_f32_e32 v18, v18
	v_exp_f32_e32 v26, v26
	v_add_f32_e32 v22, 1.0, v22
	v_rcp_f32_e32 v45, v22
	v_add_f32_e32 v18, 1.0, v18
	v_rcp_f32_e32 v42, v18
	v_add_f32_e32 v18, 1.0, v26
	v_rcp_f32_e32 v44, v18
	s_mov_b64 s[10:11], 0
	v_pk_mul_f32 v[42:43], v[34:35], v[42:43]
	v_pk_mul_f32 v[44:45], v[36:37], v[44:45]

.LBB0_2074:
	v_add_u32_e32 v38, 0x1ad0, v46
	v_cvt_pk_bf16_f32 v18, v43, s0
	v_lshl_add_u32 v22, v134, 1, v38
	v_mov_b32_e32 v34, v241
	ds_write_b16 v22, v18
	v_cvt_pk_bf16_f32 v18, v45, s0
	ds_write_b16 v22, v18 offset:32
	v_cvt_pk_bf16_f32 v18, v42, s0
	ds_write_b16 v22, v18 offset:256
	v_cvt_pk_bf16_f32 v18, v44, s0
	ds_write_b16 v22, v18 offset:288
	v_mov_b32_e32 v22, v31
	v_mov_b32_e32 v18, v27
	v_pk_mul_f32 v[30:31], v[22:23], v[34:35] op_sel_hi:[1,0]
	v_mov_b32_e32 v22, v27
	v_pk_mul_f32 v[26:27], v[18:19], v[34:35] op_sel_hi:[1,0]
	v_pk_mul_f32 v[22:23], v[22:23], v[34:35] op_sel_hi:[1,0]
	v_mov_b32_e32 v18, v30
	v_mov_b32_e32 v19, v27
	s_cmp_gt_i32 s7, 1
	s_mov_b64 s[10:11], -1
	s_cbranch_scc0 .LBB0_2076
	v_mul_f32_e32 v34, 0xbfb8aa3b, v27
	v_exp_f32_e32 v34, v34
	v_mul_f32_e32 v35, 0xbfb8aa3b, v23
	v_exp_f32_e32 v35, v35
	v_mul_f32_e32 v37, 0xbfb8aa3b, v22
	v_add_f32_e32 v34, 1.0, v34
	v_exp_f32_e32 v39, v37
	v_add_f32_e32 v36, 1.0, v35
	v_rcp_f32_e32 v35, v34
	v_mul_f32_e32 v34, 0xbfb8aa3b, v30
	v_exp_f32_e32 v34, v34
	v_rcp_f32_e32 v37, v36
	v_add_f32_e32 v36, 1.0, v39
	v_rcp_f32_e32 v36, v36
	v_add_f32_e32 v34, 1.0, v34
	v_rcp_f32_e32 v34, v34
	s_mov_b64 s[10:11], 0
	v_pk_mul_f32 v[36:37], v[22:23], v[36:37]
	v_pk_mul_f32 v[34:35], v[18:19], v[34:35]

.LBB0_2082:
	v_add_u32_e32 v38, 0x210, v38
	v_cvt_pk_bf16_f32 v18, v35, s0
	v_lshl_add_u32 v19, v134, 1, v38
	ds_write_b16 v19, v18
	v_cvt_pk_bf16_f32 v18, v37, s0
	ds_write_b16 v19, v18 offset:32
	v_cvt_pk_bf16_f32 v18, v34, s0
	ds_write_b16 v19, v18 offset:256
	v_cvt_pk_bf16_f32 v18, v36, s0
	ds_write_b16 v19, v18 offset:288
	v_mov_b32_e32 v18, v242
	v_mov_b32_e32 v22, v32
	v_mov_b32_e32 v23, v24
	v_mov_b32_e32 v30, v28
	v_mov_b32_e32 v31, v24
	v_mov_b32_e32 v34, v28
	v_mov_b32_e32 v35, v20
	v_pk_mul_f32 v[26:27], v[22:23], v[18:19] op_sel_hi:[1,0]
	v_pk_mul_f32 v[22:23], v[30:31], v[18:19] op_sel_hi:[1,0]
	v_pk_mul_f32 v[30:31], v[34:35], v[18:19] op_sel_hi:[1,0]
	v_mov_b32_e32 v18, v26
	v_mov_b32_e32 v19, v31
	s_cmp_gt_i32 s7, 1
	s_mov_b64 s[10:11], -1
	s_cbranch_scc0 .LBB0_2084
	v_mul_f32_e32 v20, 0xbfb8aa3b, v31
	v_exp_f32_e32 v20, v20
	v_mul_f32_e32 v24, 0xbfb8aa3b, v23
	v_mul_f32_e32 v28, 0xbfb8aa3b, v22
	v_exp_f32_e32 v24, v24
	v_add_f32_e32 v20, 1.0, v20
	v_rcp_f32_e32 v35, v20
	v_mul_f32_e32 v20, 0xbfb8aa3b, v26
	v_exp_f32_e32 v20, v20
	v_exp_f32_e32 v28, v28
	v_add_f32_e32 v24, 1.0, v24
	v_rcp_f32_e32 v37, v24
	v_add_f32_e32 v20, 1.0, v20
	v_rcp_f32_e32 v34, v20
	v_add_f32_e32 v20, 1.0, v28
	v_rcp_f32_e32 v36, v20
	s_mov_b64 s[10:11], 0
	v_pk_mul_f32 v[34:35], v[18:19], v[34:35]
	v_pk_mul_f32 v[36:37], v[22:23], v[36:37]

.LBB0_2090:
	v_add_u32_e32 v30, 0x210, v38
	v_cvt_pk_bf16_f32 v18, v35, s0
	v_lshl_add_u32 v19, v134, 1, v30
	ds_write_b16 v19, v18
	v_cvt_pk_bf16_f32 v18, v37, s0
	ds_write_b16 v19, v18 offset:32
	v_cvt_pk_bf16_f32 v18, v34, s0
	ds_write_b16 v19, v18 offset:256
	v_cvt_pk_bf16_f32 v18, v36, s0
	ds_write_b16 v19, v18 offset:288
	v_mov_b32_e32 v18, v243
	v_mov_b32_e32 v24, v33
	v_mov_b32_e32 v20, v29
	s_cmp_gt_i32 s7, 1
	s_mov_b64 s[10:11], -1
	v_pk_mul_f32 v[22:23], v[24:25], v[18:19] op_sel_hi:[1,0]
	v_mov_b32_e32 v24, v29
	v_pk_mul_f32 v[26:27], v[20:21], v[18:19] op_sel_hi:[1,0]
	v_pk_mul_f32 v[20:21], v[24:25], v[18:19] op_sel_hi:[1,0]
	v_mov_b32_e32 v18, v22
	v_mov_b32_e32 v19, v27
	s_cbranch_scc0 .LBB0_2092
	v_mul_f32_e32 v24, 0xbfb8aa3b, v27
	v_exp_f32_e32 v24, v24
	v_mul_f32_e32 v25, 0xbfb8aa3b, v21
	v_exp_f32_e32 v25, v25
	v_mul_f32_e32 v29, 0xbfb8aa3b, v20
	v_add_f32_e32 v24, 1.0, v24
	v_exp_f32_e32 v31, v29
	v_add_f32_e32 v28, 1.0, v25
	v_rcp_f32_e32 v25, v24
	v_mul_f32_e32 v24, 0xbfb8aa3b, v22
	v_exp_f32_e32 v24, v24
	v_rcp_f32_e32 v29, v28
	v_add_f32_e32 v28, 1.0, v31
	v_rcp_f32_e32 v28, v28
	v_add_f32_e32 v24, 1.0, v24
	v_rcp_f32_e32 v24, v24
	s_mov_b64 s[10:11], 0
	v_pk_mul_f32 v[28:29], v[20:21], v[28:29]
	v_pk_mul_f32 v[24:25], v[18:19], v[24:25]

.LBB0_2098:
	v_add_u32_e32 v30, 0x210, v30
	v_cvt_pk_bf16_f32 v18, v25, s0
	v_lshl_add_u32 v19, v134, 1, v30
	ds_write_b16 v19, v18
	v_cvt_pk_bf16_f32 v18, v29, s0
	ds_write_b16 v19, v18 offset:32
	v_cvt_pk_bf16_f32 v18, v24, s0
	ds_write_b16 v19, v18 offset:256
	v_cvt_pk_bf16_f32 v18, v28, s0
	ds_write_b16 v19, v18 offset:288
	v_mov_b32_e32 v18, v244
	v_mov_b32_e32 v20, v14
	v_mov_b32_e32 v21, v6
	v_mov_b32_e32 v24, v10
	v_mov_b32_e32 v25, v6
	v_mov_b32_e32 v26, v10
	v_mov_b32_e32 v27, v2
	v_pk_mul_f32 v[22:23], v[20:21], v[18:19] op_sel_hi:[1,0]
	v_pk_mul_f32 v[20:21], v[24:25], v[18:19] op_sel_hi:[1,0]
	v_pk_mul_f32 v[24:25], v[26:27], v[18:19] op_sel_hi:[1,0]
	v_mov_b32_e32 v18, v22
	v_mov_b32_e32 v19, v25
	s_cmp_gt_i32 s7, 1
	s_mov_b64 s[10:11], -1
	s_cbranch_scc0 .LBB0_2100
	v_mul_f32_e32 v2, 0xbfb8aa3b, v25
	v_exp_f32_e32 v2, v2
	v_mul_f32_e32 v6, 0xbfb8aa3b, v21
	v_mul_f32_e32 v10, 0xbfb8aa3b, v20
	v_exp_f32_e32 v6, v6
	v_add_f32_e32 v2, 1.0, v2
	v_rcp_f32_e32 v27, v2
	v_mul_f32_e32 v2, 0xbfb8aa3b, v22
	v_exp_f32_e32 v2, v2
	v_exp_f32_e32 v10, v10
	v_add_f32_e32 v6, 1.0, v6
	v_rcp_f32_e32 v29, v6
	v_add_f32_e32 v2, 1.0, v2
	v_rcp_f32_e32 v26, v2
	v_add_f32_e32 v2, 1.0, v10
	v_rcp_f32_e32 v28, v2
	s_mov_b64 s[10:11], 0
	v_pk_mul_f32 v[26:27], v[18:19], v[26:27]
	v_pk_mul_f32 v[28:29], v[20:21], v[28:29]

.LBB0_2106:
	v_add_u32_e32 v22, 0x1ad0, v30
	v_cvt_pk_bf16_f32 v2, v27, s0
	v_lshl_add_u32 v6, v134, 1, v22
	v_mov_b32_e32 v18, v245
	ds_write_b16 v6, v2
	v_cvt_pk_bf16_f32 v2, v29, s0
	ds_write_b16 v6, v2 offset:32
	v_cvt_pk_bf16_f32 v2, v26, s0
	ds_write_b16 v6, v2 offset:256
	v_cvt_pk_bf16_f32 v2, v28, s0
	ds_write_b16 v6, v2 offset:288
	v_mov_b32_e32 v6, v15
	v_mov_b32_e32 v2, v11
	v_pk_mul_f32 v[14:15], v[6:7], v[18:19] op_sel_hi:[1,0]
	v_mov_b32_e32 v6, v11
	v_pk_mul_f32 v[10:11], v[2:3], v[18:19] op_sel_hi:[1,0]
	v_pk_mul_f32 v[6:7], v[6:7], v[18:19] op_sel_hi:[1,0]
	v_mov_b32_e32 v2, v14
	v_mov_b32_e32 v3, v11
	s_cmp_gt_i32 s7, 1
	s_mov_b64 s[10:11], -1
	s_cbranch_scc0 .LBB0_2108
	v_mul_f32_e32 v18, 0xbfb8aa3b, v11
	v_exp_f32_e32 v18, v18
	v_mul_f32_e32 v19, 0xbfb8aa3b, v7
	v_exp_f32_e32 v19, v19
	v_mul_f32_e32 v21, 0xbfb8aa3b, v6
	v_add_f32_e32 v18, 1.0, v18
	v_exp_f32_e32 v23, v21
	v_add_f32_e32 v20, 1.0, v19
	v_rcp_f32_e32 v19, v18
	v_mul_f32_e32 v18, 0xbfb8aa3b, v14
	v_exp_f32_e32 v18, v18
	v_rcp_f32_e32 v21, v20
	v_add_f32_e32 v20, 1.0, v23
	v_rcp_f32_e32 v20, v20
	v_add_f32_e32 v18, 1.0, v18
	v_rcp_f32_e32 v18, v18
	s_mov_b64 s[10:11], 0
	v_pk_mul_f32 v[20:21], v[6:7], v[20:21]
	v_pk_mul_f32 v[18:19], v[2:3], v[18:19]

.LBB0_2114:
	v_add_u32_e32 v22, 0x210, v22
	v_cvt_pk_bf16_f32 v2, v19, s0
	v_lshl_add_u32 v3, v134, 1, v22
	ds_write_b16 v3, v2
	v_cvt_pk_bf16_f32 v2, v21, s0
	ds_write_b16 v3, v2 offset:32
	v_cvt_pk_bf16_f32 v2, v18, s0
	ds_write_b16 v3, v2 offset:256
	v_cvt_pk_bf16_f32 v2, v20, s0
	ds_write_b16 v3, v2 offset:288
	v_mov_b32_e32 v2, v246
	v_mov_b32_e32 v6, v16
	v_mov_b32_e32 v7, v8
	v_mov_b32_e32 v14, v12
	v_mov_b32_e32 v15, v8
	v_mov_b32_e32 v18, v12
	v_mov_b32_e32 v19, v4
	v_pk_mul_f32 v[10:11], v[6:7], v[2:3] op_sel_hi:[1,0]
	v_pk_mul_f32 v[6:7], v[14:15], v[2:3] op_sel_hi:[1,0]
	v_pk_mul_f32 v[14:15], v[18:19], v[2:3] op_sel_hi:[1,0]
	v_mov_b32_e32 v2, v10
	v_mov_b32_e32 v3, v15
	s_cmp_gt_i32 s7, 1
	s_mov_b64 s[10:11], -1
	s_cbranch_scc0 .LBB0_2116
	v_mul_f32_e32 v4, 0xbfb8aa3b, v15
	v_exp_f32_e32 v4, v4
	v_mul_f32_e32 v8, 0xbfb8aa3b, v7
	v_mul_f32_e32 v12, 0xbfb8aa3b, v6
	v_exp_f32_e32 v8, v8
	v_add_f32_e32 v4, 1.0, v4
	v_rcp_f32_e32 v19, v4
	v_mul_f32_e32 v4, 0xbfb8aa3b, v10
	v_exp_f32_e32 v4, v4
	v_exp_f32_e32 v12, v12
	v_add_f32_e32 v8, 1.0, v8
	v_rcp_f32_e32 v21, v8
	v_add_f32_e32 v4, 1.0, v4
	v_rcp_f32_e32 v18, v4
	v_add_f32_e32 v4, 1.0, v12
	v_rcp_f32_e32 v20, v4
	s_mov_b64 s[10:11], 0
	v_pk_mul_f32 v[18:19], v[2:3], v[18:19]
	v_pk_mul_f32 v[20:21], v[6:7], v[20:21]

.LBB0_2122:
	v_add_u32_e32 v3, 0x210, v22
	v_cvt_pk_bf16_f32 v2, v19, s0
	v_lshl_add_u32 v14, v134, 1, v3
	ds_write_b16 v14, v2
	v_cvt_pk_bf16_f32 v2, v21, s0
	ds_write_b16 v14, v2 offset:32
	v_cvt_pk_bf16_f32 v2, v18, s0
	ds_write_b16 v14, v2 offset:256
	v_cvt_pk_bf16_f32 v2, v20, s0
	ds_write_b16 v14, v2 offset:288
	v_mov_b32_e32 v2, v247
	v_mov_b32_e32 v8, v17
	v_mov_b32_e32 v4, v13
	s_cmp_gt_i32 s7, 1
	s_mov_b64 s[10:11], -1
	v_pk_mul_f32 v[6:7], v[8:9], v[2:3] op_sel_hi:[1,0]
	v_mov_b32_e32 v8, v13
	v_pk_mul_f32 v[10:11], v[4:5], v[2:3] op_sel_hi:[1,0]
	v_pk_mul_f32 v[4:5], v[8:9], v[2:3] op_sel_hi:[1,0]
	v_mov_b32_e32 v2, v6
	v_mov_b32_e32 v3, v11
	s_cbranch_scc0 .LBB0_2124
	v_mul_f32_e32 v8, 0xbfb8aa3b, v11
	v_exp_f32_e32 v8, v8
	v_mul_f32_e32 v9, 0xbfb8aa3b, v5
	v_exp_f32_e32 v9, v9
	v_mul_f32_e32 v13, 0xbfb8aa3b, v4
	v_add_f32_e32 v8, 1.0, v8
	v_exp_f32_e32 v15, v13
	v_add_f32_e32 v12, 1.0, v9
	v_rcp_f32_e32 v9, v8
	v_mul_f32_e32 v8, 0xbfb8aa3b, v6
	v_exp_f32_e32 v8, v8
	v_rcp_f32_e32 v13, v12
	v_add_f32_e32 v12, 1.0, v15
	v_rcp_f32_e32 v12, v12
	v_add_f32_e32 v8, 1.0, v8
	v_rcp_f32_e32 v8, v8
	s_mov_b64 s[10:11], 0
	v_pk_mul_f32 v[12:13], v[4:5], v[12:13]
	v_pk_mul_f32 v[8:9], v[2:3], v[8:9]

.LBB0_2288:
	v_mov_b32_e32 v1, v210
	s_ashr_i32 s1, s0, 31
	v_bfe_i32 v3, v1, 27, 1
	v_lshlrev_b32_e32 v138, 4, v1
	v_lshrrev_b32_e32 v3, 22, v3
	v_add_u32_e32 v3, v138, v3
	v_and_b32_e32 v3, 0xfffffc00, v3
	v_sub_u32_e32 v3, v138, v3
	v_lshrrev_b32_e32 v4, 4, v3
	v_bitop3_b32 v4, v4, v3, 32 bitop3:0x6c
	v_ashrrev_i32_e32 v3, 31, v3
	v_ashrrev_i32_e32 v2, 31, v1
	v_lshrrev_b32_e32 v3, 26, v3
	v_lshrrev_b32_e32 v2, 26, v2
	v_add_u32_e32 v3, v4, v3
	v_add_u32_e32 v2, v1, v2
	v_ashrrev_i32_e32 v3, 6, v3
	v_ashrrev_i32_e32 v2, 6, v2
	v_mul_i32_i24_e32 v6, 64, v3
	v_lshlrev_b32_e32 v5, 3, v2
	v_lshlrev_b32_e32 v2, 5, v2
	v_sub_u32_e32 v4, v4, v6
	v_and_b32_e32 v2, 32, v2
	v_ashrrev_i16_sdwa v4, v252, sext(v4) dst_sel:DWORD dst_unused:UNUSED_PAD src0_sel:DWORD src1_sel:BYTE_0
	v_add_u32_e32 v139, 0x2000, v138
	v_add_u32_sdwa v2, v2, sext(v4) dst_sel:DWORD dst_unused:UNUSED_PAD src0_sel:DWORD src1_sel:WORD_0
	v_ashrrev_i32_e32 v4, 31, v139
	v_lshrrev_b32_e32 v4, 22, v4
	v_add_u32_e32 v4, v139, v4
	v_ashrrev_i32_e32 v4, 10, v4
	s_lshr_b32 s1, s1, 30
	v_mul_i32_i24_e32 v6, 0x400, v4
	s_add_i32 s1, s0, s1
	v_sub_u32_e32 v6, v139, v6
	s_and_b32 s1, s1, 0xfffffc
	v_lshrrev_b32_e32 v7, 4, v6
	s_sub_i32 s1, s0, s1
	v_bitop3_b32 v6, v7, v6, 32 bitop3:0x6c
	s_lshl_b32 s0, s4, 8
	s_lshl_b32 s4, s1, 8
	v_ashrrev_i32_e32 v8, 31, v6
	v_lshrrev_b32_e32 v8, 26, v8
	s_ashr_i32 s5, s4, 31
	v_add_u32_e32 v8, v6, v8
	s_lshl_b64 s[6:7], s[4:5], 12
	v_and_b32_e32 v5, 0xffff0, v5
	v_lshrrev_b32_e32 v9, 6, v8
	v_and_b32_e32 v8, 0xc0, v8
	s_add_u32 s6, s19, s6
	v_add_u32_e32 v144, 0x10000, v138
	v_lshlrev_b32_e32 v7, 3, v4
	v_lshlrev_b32_e32 v4, 5, v4
	v_sub_u32_e32 v6, v6, v8
	v_add_lshl_u32 v3, v3, v5, 12
	s_addc_u32 s7, s20, s7
	v_readfirstlane_b32 s1, v144
	v_add_u32_e32 v145, 0x12000, v138
	v_and_b32_e32 v7, 0xffff0, v7
	v_and_b32_e32 v4, 32, v4
	v_ashrrev_i16_sdwa v6, v252, sext(v6) dst_sel:DWORD dst_unused:UNUSED_PAD src0_sel:DWORD src1_sel:BYTE_0
	v_lshl_add_u32 v132, v2, 1, v3
	s_mov_b64 s[8:9], s[6:7]
	s_mov_b32 m0, s1
	v_readfirstlane_b32 s1, v145
	v_add_u32_sdwa v4, v4, sext(v6) dst_sel:DWORD dst_unused:UNUSED_PAD src0_sel:DWORD src1_sel:WORD_0
	v_add_lshl_u32 v2, v9, v7, 12
	s_barrier
	v_lshl_add_u32 v130, v4, 1, v2
	global_load_lds_dwordx4 v132, s[8:9]
	s_mov_b32 m0, s1
	s_ashr_i32 s1, s0, 31
	s_lshl_b64 s[14:15], s[0:1], 12
	v_readlane_b32 s16, v254, 58
	global_load_lds_dwordx4 v130, s[8:9]
	s_add_u32 s8, s16, s14
	v_readlane_b32 s17, v254, 59
	s_addc_u32 s9, s17, s15
	v_readfirstlane_b32 s1, v138
	s_mov_b64 s[10:11], s[8:9]
	s_mov_b32 m0, s1
	v_readfirstlane_b32 s1, v139
	v_add_u32_e32 v146, 0x14000, v138
	global_load_lds_dwordx4 v132, s[10:11]
	s_mov_b32 m0, s1
	v_readfirstlane_b32 s1, v146
	global_load_lds_dwordx4 v130, s[10:11]
	s_or_b32 s10, s4, 0x80
	s_ashr_i32 s11, s10, 31
	s_lshl_b64 s[10:11], s[10:11], 12
	s_add_u32 s10, s19, s10
	s_addc_u32 s11, s20, s11
	v_add_u32_e32 v147, 0x16000, v138
	s_mov_b64 s[12:13], s[10:11]
	s_mov_b32 m0, s1
	v_readfirstlane_b32 s1, v147
	v_add_u32_e32 v148, 0x4000, v138
	global_load_lds_dwordx4 v132, s[12:13]
	s_mov_b32 m0, s1
	v_readfirstlane_b32 s1, v148
	global_load_lds_dwordx4 v130, s[12:13]
	s_or_b32 s12, s0, 0x80
	s_ashr_i32 s13, s12, 31
	s_lshl_b64 s[12:13], s[12:13], 12
	s_add_u32 s12, s16, s12
	s_addc_u32 s13, s17, s13
	v_add_u32_e32 v149, 0x6000, v138
	s_mov_b64 s[16:17], s[12:13]
	s_mov_b32 m0, s1
	v_readfirstlane_b32 s1, v149
	v_ashrrev_i32_e32 v2, 8, v1
	global_load_lds_dwordx4 v132, s[16:17]
	s_mov_b32 m0, s1
	v_cmp_eq_u32_e32 vcc, 1, v2
	global_load_lds_dwordx4 v130, s[16:17]
	s_and_saveexec_b64 s[16:17], vcc
	s_cbranch_execz .LBB0_2290
	s_barrier
.LBB0_2290:
	s_or_b64 exec, exec, s[16:17]
	s_add_u32 s16, s6, 0x80
	v_add_u32_e32 v150, 0x18000, v138
	v_mov_b32_e32 v133, v0
	s_addc_u32 s17, s7, 0
	v_readfirstlane_b32 s1, v150
	v_mov_b32_e32 v131, v0
	s_waitcnt vmcnt(4)
	s_barrier
	s_mov_b32 m0, s1
	v_lshl_add_u64 v[4:5], s[16:17], 0, v[132:133]
	v_add_u32_e32 v151, 0x1a000, v138
	global_load_lds_dwordx4 v[4:5], off
	v_lshl_add_u64 v[4:5], s[16:17], 0, v[130:131]
	v_readfirstlane_b32 s1, v151
	s_add_u32 s16, s8, 0x80
	v_add_u32_e32 v152, 0x8000, v138
	s_mov_b32 m0, s1
	s_addc_u32 s17, s9, 0
	v_readfirstlane_b32 s1, v152
	global_load_lds_dwordx4 v[4:5], off
	s_mov_b32 m0, s1
	v_lshl_add_u64 v[4:5], s[16:17], 0, v[132:133]
	v_add_u32_e32 v153, 0xa000, v138
	global_load_lds_dwordx4 v[4:5], off
	v_lshl_add_u64 v[4:5], s[16:17], 0, v[130:131]
	v_readfirstlane_b32 s1, v153
	s_add_u32 s16, s10, 0x80
	v_add_u32_e32 v154, 0x1c000, v138
	s_mov_b32 m0, s1
	s_addc_u32 s17, s11, 0
	v_readfirstlane_b32 s1, v154
	v_add_u32_e32 v155, 0x1e000, v138
	global_load_lds_dwordx4 v[4:5], off
	s_mov_b32 m0, s1
	v_lshl_add_u64 v[4:5], s[16:17], 0, v[132:133]
	v_readfirstlane_b32 s1, v155
	global_load_lds_dwordx4 v[4:5], off
	v_lshl_add_u64 v[4:5], s[16:17], 0, v[130:131]
	s_mov_b32 m0, s1
	v_bfe_u32 v136, v1, 4, 2
	global_load_lds_dwordx4 v[4:5], off
	v_bfe_u32 v134, v1, 6, 2
	v_and_b32_e32 v135, 15, v1
	v_lshlrev_b32_e32 v4, 4, v136
	v_lshlrev_b32_e32 v6, 2, v1
	v_lshlrev_b32_e32 v3, 12, v134
	v_lshl_or_b32 v5, v135, 6, v4
	v_and_b32_e32 v6, 32, v6
	v_bitop3_b32 v156, v5, v3, v6 bitop3:0xde
	v_lshlrev_b32_e32 v3, 6, v1
	s_movk_i32 s1, 0x3c0
	v_lshlrev_b32_e32 v137, 6, v2
	v_lshlrev_b32_e32 v2, 13, v2
	v_and_or_b32 v3, v3, s1, v4
	s_add_u32 s1, s12, 0x100
	s_waitcnt vmcnt(6)
	v_bitop3_b32 v140, v5, v2, v6 bitop3:0xde
	v_bitop3_b32 v2, v2, v3, v6 bitop3:0xf6
	s_addc_u32 s16, s13, 0
	v_or_b32_e32 v143, 0x800, v2
	v_or_b32_e32 v142, 0x1000, v2
	v_or_b32_e32 v141, 0x1800, v2
	s_add_u32 s17, s21, s14
	v_mov_b32_e32 v2, 0
	v_or_b32_e32 v157, 0x400, v156
	v_or_b32_e32 v158, 0x800, v156
	v_or_b32_e32 v159, 0xc00, v156
	s_addc_u32 s23, s22, s15
	s_mov_b32 s24, -2
	s_mov_b64 s[14:15], 0
	v_mov_b32_e32 v3, v2
	v_mov_b32_e32 v4, v2
	v_mov_b32_e32 v5, v2
	v_mov_b32_e32 v6, v2
	v_mov_b32_e32 v7, v2
	v_mov_b32_e32 v8, v2
	v_mov_b32_e32 v9, v2
	v_mov_b32_e32 v10, v2
	v_mov_b32_e32 v11, v2
	v_mov_b32_e32 v12, v2
	v_mov_b32_e32 v13, v2
	v_mov_b32_e32 v14, v2
	v_mov_b32_e32 v15, v2
	v_mov_b32_e32 v16, v2
	v_mov_b32_e32 v17, v2
	v_mov_b32_e32 v18, v2
	v_mov_b32_e32 v19, v2
	v_mov_b32_e32 v20, v2
	v_mov_b32_e32 v21, v2
	v_mov_b32_e32 v22, v2
	v_mov_b32_e32 v23, v2
	v_mov_b32_e32 v24, v2
	v_mov_b32_e32 v25, v2
	v_mov_b32_e32 v26, v2
	v_mov_b32_e32 v27, v2
	v_mov_b32_e32 v28, v2
	v_mov_b32_e32 v29, v2
	v_mov_b32_e32 v30, v2
	v_mov_b32_e32 v31, v2
	v_mov_b32_e32 v32, v2
	v_mov_b32_e32 v33, v2
	v_mov_b32_e32 v34, v2
	v_mov_b32_e32 v35, v2
	v_mov_b32_e32 v36, v2
	v_mov_b32_e32 v37, v2
	v_mov_b32_e32 v38, v2
	v_mov_b32_e32 v39, v2
	v_mov_b32_e32 v40, v2
	v_mov_b32_e32 v41, v2
	v_mov_b32_e32 v42, v2
	v_mov_b32_e32 v43, v2
	v_mov_b32_e32 v44, v2
	v_mov_b32_e32 v45, v2
	v_mov_b32_e32 v46, v2
	v_mov_b32_e32 v47, v2
	v_mov_b32_e32 v48, v2
	v_mov_b32_e32 v49, v2
	v_mov_b32_e32 v50, v2
	v_mov_b32_e32 v51, v2
	v_mov_b32_e32 v52, v2
	v_mov_b32_e32 v53, v2
	v_mov_b32_e32 v54, v2
	v_mov_b32_e32 v55, v2
	v_mov_b32_e32 v56, v2
	v_mov_b32_e32 v57, v2
	v_mov_b32_e32 v58, v2
	v_mov_b32_e32 v59, v2
	v_mov_b32_e32 v60, v2
	v_mov_b32_e32 v61, v2
	v_mov_b32_e32 v62, v2
	v_mov_b32_e32 v63, v2
	v_mov_b32_e32 v64, v2
	v_mov_b32_e32 v65, v2
	v_mov_b32_e32 v66, v2
	v_mov_b32_e32 v67, v2
	v_mov_b32_e32 v68, v2
	v_mov_b32_e32 v69, v2
	v_mov_b32_e32 v70, v2
	v_mov_b32_e32 v71, v2
	v_mov_b32_e32 v72, v2
	v_mov_b32_e32 v73, v2
	v_mov_b32_e32 v74, v2
	v_mov_b32_e32 v75, v2
	v_mov_b32_e32 v76, v2
	v_mov_b32_e32 v77, v2
	v_mov_b32_e32 v78, v2
	v_mov_b32_e32 v79, v2
	v_mov_b32_e32 v80, v2
	v_mov_b32_e32 v81, v2
	v_mov_b32_e32 v82, v2
	v_mov_b32_e32 v83, v2
	v_mov_b32_e32 v84, v2
	v_mov_b32_e32 v85, v2
	v_mov_b32_e32 v86, v2
	v_mov_b32_e32 v87, v2
	v_mov_b32_e32 v88, v2
	v_mov_b32_e32 v89, v2
	v_mov_b32_e32 v90, v2
	v_mov_b32_e32 v91, v2
	v_mov_b32_e32 v92, v2
	v_mov_b32_e32 v93, v2
	v_mov_b32_e32 v94, v2
	v_mov_b32_e32 v95, v2
	v_mov_b32_e32 v96, v2
	v_mov_b32_e32 v97, v2
	v_mov_b32_e32 v98, v2
	v_mov_b32_e32 v99, v2
	v_mov_b32_e32 v100, v2
	v_mov_b32_e32 v101, v2
	v_mov_b32_e32 v102, v2
	v_mov_b32_e32 v103, v2
	v_mov_b32_e32 v104, v2
	v_mov_b32_e32 v105, v2
	v_mov_b32_e32 v106, v2
	v_mov_b32_e32 v107, v2
	v_mov_b32_e32 v108, v2
	v_mov_b32_e32 v109, v2
	v_mov_b32_e32 v110, v2
	v_mov_b32_e32 v111, v2
	v_mov_b32_e32 v112, v2
	v_mov_b32_e32 v113, v2
	v_mov_b32_e32 v114, v2
	v_mov_b32_e32 v115, v2
	v_mov_b32_e32 v116, v2
	v_mov_b32_e32 v117, v2
	v_mov_b32_e32 v118, v2
	v_mov_b32_e32 v119, v2
	v_mov_b32_e32 v120, v2
	v_mov_b32_e32 v121, v2
	v_mov_b32_e32 v122, v2
	v_mov_b32_e32 v123, v2
	v_mov_b32_e32 v124, v2
	v_mov_b32_e32 v125, v2
	v_mov_b32_e32 v126, v2
	v_mov_b32_e32 v127, v2
	v_mov_b32_e32 v128, v2
	v_mov_b32_e32 v129, v2
	s_barrier
